# as v13 plus paired v loads and paired partial-y stores in the unrolled recurrence
# speedup vs baseline: 1.0202x; 1.0024x over previous
.LBB0_131:
	s_or_b64 exec, exec, s[10:11]
	v_add_u32_e32 v227, 0x100, v156
	ds_read_b128 v[198:201], v156 offset:57344
	ds_read_b128 v[202:205], v227 offset:57344
	ds_read_b128 v[206:209], v156 offset:8192
	ds_read_b128 v[210:213], v156 offset:16384
	ds_read_b128 v[214:217], v156 offset:24576
	ds_read_b128 v[218:221], v156 offset:32768
	v_mov_b32_e32 v226, 1.0
	v_cmp_lt_u32_e32 vcc, 495, v134
	s_waitcnt lgkmcnt(4)
	v_rcp_f32_e32 v222, v198
	v_rcp_f32_e32 v223, v199
	v_rcp_f32_e32 v224, v200
	v_rcp_f32_e32 v225, v201
	v_cndmask_b32_e32 v202, v202, v226, vcc
	v_cndmask_b32_e32 v203, v203, v226, vcc
	v_cndmask_b32_e32 v204, v204, v226, vcc
	v_cndmask_b32_e32 v205, v205, v226, vcc
	s_waitcnt lgkmcnt(0)
	v_mul_f32_e32 v206, v206, v202
	v_mul_f32_e32 v207, v207, v203
	v_mul_f32_e32 v208, v208, v204
	v_mul_f32_e32 v209, v209, v205
	v_mul_f32_e32 v218, v218, v202
	v_mul_f32_e32 v219, v219, v203
	v_mul_f32_e32 v220, v220, v204
	v_mul_f32_e32 v221, v221, v205
	v_mul_f32_e32 v210, v210, v222
	v_mul_f32_e32 v211, v211, v223
	v_mul_f32_e32 v212, v212, v224
	v_mul_f32_e32 v213, v213, v225
	v_mul_f32_e32 v214, v214, v222
	v_mul_f32_e32 v215, v215, v223
	v_mul_f32_e32 v216, v216, v224
	v_mul_f32_e32 v217, v217, v225
	ds_write_b128 v156, v[206:209] offset:8192
	ds_write_b128 v156, v[218:221] offset:32768
	ds_write_b128 v156, v[210:213] offset:16384
	ds_write_b128 v156, v[214:217] offset:24576
	s_waitcnt lgkmcnt(0)
	s_barrier
	v_mbcnt_lo_u32_b32 v197, -1, 0
	v_mbcnt_hi_u32_b32 v197, -1, v197
	v_lshlrev_b32_e32 v197, 3, v197
	v_add_u32_e32 v197, 0xe000, v197
	v_cndmask_b32_e64 v196, v197, v161, s[8:9]
	v_add_u32_e32 v69, 0xffffe800, v185
	ds_read_b128 v[8:11], v152 offset:16128
	ds_read_b128 v[12:15], v152 offset:24320
	ds_read_b128 v[16:19], v152 offset:32512
	ds_read_b128 v[20:23], v152 offset:40704
	ds_read_b64 v[64:65], v69 offset:7936
	ds_read_b128 v[28:31], v152 offset:15872
	ds_read_b128 v[32:35], v152 offset:24064
	ds_read_b128 v[36:39], v152 offset:32256
	ds_read_b128 v[40:43], v152 offset:40448
	ds_read_b64 v[66:67], v69 offset:7680
	ds_read_b128 v[48:51], v152 offset:15616
	ds_read_b128 v[52:55], v152 offset:23808
	ds_read_b128 v[56:59], v152 offset:32000
	ds_read_b128 v[60:63], v152 offset:40192
	ds_read_b64 v[130:131], v69 offset:7424
	s_waitcnt lgkmcnt(10)
	v_mul_f32_e32 v194, v186, v8
	v_mul_f32_e32 v195, v190, v8
	v_mul_f32_e32 v132, v186, v20
	v_mul_f32_e32 v133, v190, v20
	v_fmac_f32_e32 v194, v187, v9
	v_fmac_f32_e32 v195, v191, v9
	v_fmac_f32_e32 v132, v187, v21
	v_fmac_f32_e32 v133, v191, v21
	v_fmac_f32_e32 v194, v188, v10
	v_fmac_f32_e32 v195, v192, v10
	v_fmac_f32_e32 v132, v188, v22
	v_fmac_f32_e32 v133, v192, v22
	v_fmac_f32_e32 v194, v189, v11
	v_fmac_f32_e32 v195, v193, v11
	v_fmac_f32_e32 v132, v189, v23
	v_fmac_f32_e32 v133, v193, v23
	v_add_f32_dpp v194, v194, v194 quad_perm:[1,0,3,2] row_mask:0xf bank_mask:0xf bound_ctrl:1
	v_add_f32_dpp v195, v195, v195 quad_perm:[1,0,3,2] row_mask:0xf bank_mask:0xf bound_ctrl:1
	v_add_f32_dpp v132, v132, v132 quad_perm:[1,0,3,2] row_mask:0xf bank_mask:0xf bound_ctrl:1
	v_add_f32_dpp v133, v133, v133 quad_perm:[1,0,3,2] row_mask:0xf bank_mask:0xf bound_ctrl:1
	v_add_f32_dpp v194, v194, v194 quad_perm:[2,3,0,1] row_mask:0xf bank_mask:0xf bound_ctrl:1
	v_add_f32_dpp v195, v195, v195 quad_perm:[2,3,0,1] row_mask:0xf bank_mask:0xf bound_ctrl:1
	v_add_f32_dpp v132, v132, v132 quad_perm:[2,3,0,1] row_mask:0xf bank_mask:0xf bound_ctrl:1
	v_add_f32_dpp v133, v133, v133 quad_perm:[2,3,0,1] row_mask:0xf bank_mask:0xf bound_ctrl:1
	v_add_f32_dpp v194, v194, v194 row_half_mirror row_mask:0xf bank_mask:0xf bound_ctrl:1
	v_add_f32_dpp v195, v195, v195 row_half_mirror row_mask:0xf bank_mask:0xf bound_ctrl:1
	v_add_f32_dpp v132, v132, v132 row_half_mirror row_mask:0xf bank_mask:0xf bound_ctrl:1
	v_add_f32_dpp v133, v133, v133 row_half_mirror row_mask:0xf bank_mask:0xf bound_ctrl:1
	v_add_f32_dpp v194, v194, v194 row_mirror row_mask:0xf bank_mask:0xf bound_ctrl:1
	v_add_f32_dpp v195, v195, v195 row_mirror row_mask:0xf bank_mask:0xf bound_ctrl:1
	v_fmac_f32_e32 v186, v64, v16
	v_fmac_f32_e32 v187, v64, v17
	v_fmac_f32_e32 v188, v64, v18
	v_fmac_f32_e32 v189, v64, v19
	v_fmac_f32_e32 v190, v65, v16
	v_fmac_f32_e32 v191, v65, v17
	v_fmac_f32_e32 v192, v65, v18
	v_fmac_f32_e32 v193, v65, v19
	v_fmac_f32_e32 v186, v194, v12
	v_fmac_f32_e32 v187, v194, v13
	v_fmac_f32_e32 v188, v194, v14
	v_fmac_f32_e32 v189, v194, v15
	v_fmac_f32_e32 v190, v195, v12
	v_fmac_f32_e32 v191, v195, v13
	v_fmac_f32_e32 v192, v195, v14
	v_fmac_f32_e32 v193, v195, v15
	ds_read_b128 v[8:11], v152 offset:15360
	ds_read_b128 v[12:15], v152 offset:23552
	ds_read_b128 v[16:19], v152 offset:31744
	ds_read_b128 v[20:23], v152 offset:39936
	ds_read_b64 v[64:65], v69 offset:7168
	s_waitcnt lgkmcnt(10)
	v_mul_f32_e32 v194, v186, v28
	v_mul_f32_e32 v195, v190, v28
	v_mul_f32_e32 v238, v186, v40
	v_mul_f32_e32 v239, v190, v40
	v_fmac_f32_e32 v194, v187, v29
	v_fmac_f32_e32 v195, v191, v29
	v_fmac_f32_e32 v238, v187, v41
	v_fmac_f32_e32 v239, v191, v41
	v_fmac_f32_e32 v194, v188, v30
	v_fmac_f32_e32 v195, v192, v30
	v_fmac_f32_e32 v238, v188, v42
	v_fmac_f32_e32 v239, v192, v42
	v_fmac_f32_e32 v194, v189, v31
	v_fmac_f32_e32 v195, v193, v31
	v_fmac_f32_e32 v238, v189, v43
	v_fmac_f32_e32 v239, v193, v43
	v_add_f32_dpp v194, v194, v194 quad_perm:[1,0,3,2] row_mask:0xf bank_mask:0xf bound_ctrl:1
	v_add_f32_dpp v195, v195, v195 quad_perm:[1,0,3,2] row_mask:0xf bank_mask:0xf bound_ctrl:1
	v_add_f32_dpp v238, v238, v238 quad_perm:[1,0,3,2] row_mask:0xf bank_mask:0xf bound_ctrl:1
	v_add_f32_dpp v239, v239, v239 quad_perm:[1,0,3,2] row_mask:0xf bank_mask:0xf bound_ctrl:1
	v_add_f32_dpp v194, v194, v194 quad_perm:[2,3,0,1] row_mask:0xf bank_mask:0xf bound_ctrl:1
	v_add_f32_dpp v195, v195, v195 quad_perm:[2,3,0,1] row_mask:0xf bank_mask:0xf bound_ctrl:1
	v_add_f32_dpp v238, v238, v238 quad_perm:[2,3,0,1] row_mask:0xf bank_mask:0xf bound_ctrl:1
	v_add_f32_dpp v239, v239, v239 quad_perm:[2,3,0,1] row_mask:0xf bank_mask:0xf bound_ctrl:1
	v_add_f32_dpp v194, v194, v194 row_half_mirror row_mask:0xf bank_mask:0xf bound_ctrl:1
	v_add_f32_dpp v195, v195, v195 row_half_mirror row_mask:0xf bank_mask:0xf bound_ctrl:1
	v_add_f32_dpp v238, v238, v238 row_half_mirror row_mask:0xf bank_mask:0xf bound_ctrl:1
	v_add_f32_dpp v239, v239, v239 row_half_mirror row_mask:0xf bank_mask:0xf bound_ctrl:1
	v_add_f32_dpp v194, v194, v194 row_mirror row_mask:0xf bank_mask:0xf bound_ctrl:1
	v_add_f32_dpp v195, v195, v195 row_mirror row_mask:0xf bank_mask:0xf bound_ctrl:1
	v_fmac_f32_e32 v186, v66, v36
	v_fmac_f32_e32 v187, v66, v37
	v_fmac_f32_e32 v188, v66, v38
	v_fmac_f32_e32 v189, v66, v39
	v_fmac_f32_e32 v190, v67, v36
	v_fmac_f32_e32 v191, v67, v37
	v_fmac_f32_e32 v192, v67, v38
	v_fmac_f32_e32 v193, v67, v39
	v_fmac_f32_e32 v186, v194, v32
	v_fmac_f32_e32 v187, v194, v33
	v_fmac_f32_e32 v188, v194, v34
	v_fmac_f32_e32 v189, v194, v35
	v_fmac_f32_e32 v190, v195, v32
	v_fmac_f32_e32 v191, v195, v33
	v_fmac_f32_e32 v192, v195, v34
	v_fmac_f32_e32 v193, v195, v35
	s_mov_b64 exec, s[8:9]
	ds_write2st64_b64 v161, v[132:133], v[238:239] offset0:31 offset1:30
	s_mov_b64 exec, -1
	ds_read_b128 v[28:31], v152 offset:15104
	ds_read_b128 v[32:35], v152 offset:23296
	ds_read_b128 v[36:39], v152 offset:31488
	ds_read_b128 v[40:43], v152 offset:39680
	ds_read_b64 v[66:67], v69 offset:6912
	s_waitcnt lgkmcnt(11)
	v_mul_f32_e32 v194, v186, v48
	v_mul_f32_e32 v195, v190, v48
	v_mul_f32_e32 v132, v186, v60
	v_mul_f32_e32 v133, v190, v60
	v_fmac_f32_e32 v194, v187, v49
	v_fmac_f32_e32 v195, v191, v49
	v_fmac_f32_e32 v132, v187, v61
	v_fmac_f32_e32 v133, v191, v61
	v_fmac_f32_e32 v194, v188, v50
	v_fmac_f32_e32 v195, v192, v50
	v_fmac_f32_e32 v132, v188, v62
	v_fmac_f32_e32 v133, v192, v62
	v_fmac_f32_e32 v194, v189, v51
	v_fmac_f32_e32 v195, v193, v51
	v_fmac_f32_e32 v132, v189, v63
	v_fmac_f32_e32 v133, v193, v63
	v_add_f32_dpp v194, v194, v194 quad_perm:[1,0,3,2] row_mask:0xf bank_mask:0xf bound_ctrl:1
	v_add_f32_dpp v195, v195, v195 quad_perm:[1,0,3,2] row_mask:0xf bank_mask:0xf bound_ctrl:1
	v_add_f32_dpp v132, v132, v132 quad_perm:[1,0,3,2] row_mask:0xf bank_mask:0xf bound_ctrl:1
	v_add_f32_dpp v133, v133, v133 quad_perm:[1,0,3,2] row_mask:0xf bank_mask:0xf bound_ctrl:1
	v_add_f32_dpp v194, v194, v194 quad_perm:[2,3,0,1] row_mask:0xf bank_mask:0xf bound_ctrl:1
	v_add_f32_dpp v195, v195, v195 quad_perm:[2,3,0,1] row_mask:0xf bank_mask:0xf bound_ctrl:1
	v_add_f32_dpp v132, v132, v132 quad_perm:[2,3,0,1] row_mask:0xf bank_mask:0xf bound_ctrl:1
	v_add_f32_dpp v133, v133, v133 quad_perm:[2,3,0,1] row_mask:0xf bank_mask:0xf bound_ctrl:1
	v_add_f32_dpp v194, v194, v194 row_half_mirror row_mask:0xf bank_mask:0xf bound_ctrl:1
	v_add_f32_dpp v195, v195, v195 row_half_mirror row_mask:0xf bank_mask:0xf bound_ctrl:1
	v_add_f32_dpp v132, v132, v132 row_half_mirror row_mask:0xf bank_mask:0xf bound_ctrl:1
	v_add_f32_dpp v133, v133, v133 row_half_mirror row_mask:0xf bank_mask:0xf bound_ctrl:1
	v_add_f32_dpp v194, v194, v194 row_mirror row_mask:0xf bank_mask:0xf bound_ctrl:1
	v_add_f32_dpp v195, v195, v195 row_mirror row_mask:0xf bank_mask:0xf bound_ctrl:1
	v_fmac_f32_e32 v186, v130, v56
	v_fmac_f32_e32 v187, v130, v57
	v_fmac_f32_e32 v188, v130, v58
	v_fmac_f32_e32 v189, v130, v59
	v_fmac_f32_e32 v190, v131, v56
	v_fmac_f32_e32 v191, v131, v57
	v_fmac_f32_e32 v192, v131, v58
	v_fmac_f32_e32 v193, v131, v59
	v_fmac_f32_e32 v186, v194, v52
	v_fmac_f32_e32 v187, v194, v53
	v_fmac_f32_e32 v188, v194, v54
	v_fmac_f32_e32 v189, v194, v55
	v_fmac_f32_e32 v190, v195, v52
	v_fmac_f32_e32 v191, v195, v53
	v_fmac_f32_e32 v192, v195, v54
	v_fmac_f32_e32 v193, v195, v55
	ds_read_b128 v[48:51], v152 offset:14848
	ds_read_b128 v[52:55], v152 offset:23040
	ds_read_b128 v[56:59], v152 offset:31232
	ds_read_b128 v[60:63], v152 offset:39424
	ds_read_b64 v[130:131], v69 offset:6656
	s_waitcnt lgkmcnt(11)
	v_mul_f32_e32 v194, v186, v8
	v_mul_f32_e32 v195, v190, v8
	v_mul_f32_e32 v238, v186, v20
	v_mul_f32_e32 v239, v190, v20
	v_fmac_f32_e32 v194, v187, v9
	v_fmac_f32_e32 v195, v191, v9
	v_fmac_f32_e32 v238, v187, v21
	v_fmac_f32_e32 v239, v191, v21
	v_fmac_f32_e32 v194, v188, v10
	v_fmac_f32_e32 v195, v192, v10
	v_fmac_f32_e32 v238, v188, v22
	v_fmac_f32_e32 v239, v192, v22
	v_fmac_f32_e32 v194, v189, v11
	v_fmac_f32_e32 v195, v193, v11
	v_fmac_f32_e32 v238, v189, v23
	v_fmac_f32_e32 v239, v193, v23
	v_add_f32_dpp v194, v194, v194 quad_perm:[1,0,3,2] row_mask:0xf bank_mask:0xf bound_ctrl:1
	v_add_f32_dpp v195, v195, v195 quad_perm:[1,0,3,2] row_mask:0xf bank_mask:0xf bound_ctrl:1
	v_add_f32_dpp v238, v238, v238 quad_perm:[1,0,3,2] row_mask:0xf bank_mask:0xf bound_ctrl:1
	v_add_f32_dpp v239, v239, v239 quad_perm:[1,0,3,2] row_mask:0xf bank_mask:0xf bound_ctrl:1
	v_add_f32_dpp v194, v194, v194 quad_perm:[2,3,0,1] row_mask:0xf bank_mask:0xf bound_ctrl:1
	v_add_f32_dpp v195, v195, v195 quad_perm:[2,3,0,1] row_mask:0xf bank_mask:0xf bound_ctrl:1
	v_add_f32_dpp v238, v238, v238 quad_perm:[2,3,0,1] row_mask:0xf bank_mask:0xf bound_ctrl:1
	v_add_f32_dpp v239, v239, v239 quad_perm:[2,3,0,1] row_mask:0xf bank_mask:0xf bound_ctrl:1
	v_add_f32_dpp v194, v194, v194 row_half_mirror row_mask:0xf bank_mask:0xf bound_ctrl:1
	v_add_f32_dpp v195, v195, v195 row_half_mirror row_mask:0xf bank_mask:0xf bound_ctrl:1
	v_add_f32_dpp v238, v238, v238 row_half_mirror row_mask:0xf bank_mask:0xf bound_ctrl:1
	v_add_f32_dpp v239, v239, v239 row_half_mirror row_mask:0xf bank_mask:0xf bound_ctrl:1
	v_add_f32_dpp v194, v194, v194 row_mirror row_mask:0xf bank_mask:0xf bound_ctrl:1
	v_add_f32_dpp v195, v195, v195 row_mirror row_mask:0xf bank_mask:0xf bound_ctrl:1
	v_fmac_f32_e32 v186, v64, v16
	v_fmac_f32_e32 v187, v64, v17
	v_fmac_f32_e32 v188, v64, v18
	v_fmac_f32_e32 v189, v64, v19
	v_fmac_f32_e32 v190, v65, v16
	v_fmac_f32_e32 v191, v65, v17
	v_fmac_f32_e32 v192, v65, v18
	v_fmac_f32_e32 v193, v65, v19
	v_fmac_f32_e32 v186, v194, v12
	v_fmac_f32_e32 v187, v194, v13
	v_fmac_f32_e32 v188, v194, v14
	v_fmac_f32_e32 v189, v194, v15
	v_fmac_f32_e32 v190, v195, v12
	v_fmac_f32_e32 v191, v195, v13
	v_fmac_f32_e32 v192, v195, v14
	v_fmac_f32_e32 v193, v195, v15
	s_mov_b64 exec, s[8:9]
	ds_write2st64_b64 v161, v[132:133], v[238:239] offset0:29 offset1:28
	s_mov_b64 exec, -1
	ds_read_b128 v[8:11], v152 offset:14592
	ds_read_b128 v[12:15], v152 offset:22784
	ds_read_b128 v[16:19], v152 offset:30976
	ds_read_b128 v[20:23], v152 offset:39168
	ds_read_b64 v[64:65], v69 offset:6400
	s_waitcnt lgkmcnt(11)
	v_mul_f32_e32 v194, v186, v28
	v_mul_f32_e32 v195, v190, v28
	v_mul_f32_e32 v132, v186, v40
	v_mul_f32_e32 v133, v190, v40
	v_fmac_f32_e32 v194, v187, v29
	v_fmac_f32_e32 v195, v191, v29
	v_fmac_f32_e32 v132, v187, v41
	v_fmac_f32_e32 v133, v191, v41
	v_fmac_f32_e32 v194, v188, v30
	v_fmac_f32_e32 v195, v192, v30
	v_fmac_f32_e32 v132, v188, v42
	v_fmac_f32_e32 v133, v192, v42
	v_fmac_f32_e32 v194, v189, v31
	v_fmac_f32_e32 v195, v193, v31
	v_fmac_f32_e32 v132, v189, v43
	v_fmac_f32_e32 v133, v193, v43
	v_add_f32_dpp v194, v194, v194 quad_perm:[1,0,3,2] row_mask:0xf bank_mask:0xf bound_ctrl:1
	v_add_f32_dpp v195, v195, v195 quad_perm:[1,0,3,2] row_mask:0xf bank_mask:0xf bound_ctrl:1
	v_add_f32_dpp v132, v132, v132 quad_perm:[1,0,3,2] row_mask:0xf bank_mask:0xf bound_ctrl:1
	v_add_f32_dpp v133, v133, v133 quad_perm:[1,0,3,2] row_mask:0xf bank_mask:0xf bound_ctrl:1
	v_add_f32_dpp v194, v194, v194 quad_perm:[2,3,0,1] row_mask:0xf bank_mask:0xf bound_ctrl:1
	v_add_f32_dpp v195, v195, v195 quad_perm:[2,3,0,1] row_mask:0xf bank_mask:0xf bound_ctrl:1
	v_add_f32_dpp v132, v132, v132 quad_perm:[2,3,0,1] row_mask:0xf bank_mask:0xf bound_ctrl:1
	v_add_f32_dpp v133, v133, v133 quad_perm:[2,3,0,1] row_mask:0xf bank_mask:0xf bound_ctrl:1
	v_add_f32_dpp v194, v194, v194 row_half_mirror row_mask:0xf bank_mask:0xf bound_ctrl:1
	v_add_f32_dpp v195, v195, v195 row_half_mirror row_mask:0xf bank_mask:0xf bound_ctrl:1
	v_add_f32_dpp v132, v132, v132 row_half_mirror row_mask:0xf bank_mask:0xf bound_ctrl:1
	v_add_f32_dpp v133, v133, v133 row_half_mirror row_mask:0xf bank_mask:0xf bound_ctrl:1
	v_add_f32_dpp v194, v194, v194 row_mirror row_mask:0xf bank_mask:0xf bound_ctrl:1
	v_add_f32_dpp v195, v195, v195 row_mirror row_mask:0xf bank_mask:0xf bound_ctrl:1
	v_fmac_f32_e32 v186, v66, v36
	v_fmac_f32_e32 v187, v66, v37
	v_fmac_f32_e32 v188, v66, v38
	v_fmac_f32_e32 v189, v66, v39
	v_fmac_f32_e32 v190, v67, v36
	v_fmac_f32_e32 v191, v67, v37
	v_fmac_f32_e32 v192, v67, v38
	v_fmac_f32_e32 v193, v67, v39
	v_fmac_f32_e32 v186, v194, v32
	v_fmac_f32_e32 v187, v194, v33
	v_fmac_f32_e32 v188, v194, v34
	v_fmac_f32_e32 v189, v194, v35
	v_fmac_f32_e32 v190, v195, v32
	v_fmac_f32_e32 v191, v195, v33
	v_fmac_f32_e32 v192, v195, v34
	v_fmac_f32_e32 v193, v195, v35
	ds_read_b128 v[28:31], v152 offset:14336
	ds_read_b128 v[32:35], v152 offset:22528
	ds_read_b128 v[36:39], v152 offset:30720
	ds_read_b128 v[40:43], v152 offset:38912
	ds_read_b64 v[66:67], v69 offset:6144
	s_waitcnt lgkmcnt(11)
	v_mul_f32_e32 v194, v186, v48
	v_mul_f32_e32 v195, v190, v48
	v_mul_f32_e32 v238, v186, v60
	v_mul_f32_e32 v239, v190, v60
	v_fmac_f32_e32 v194, v187, v49
	v_fmac_f32_e32 v195, v191, v49
	v_fmac_f32_e32 v238, v187, v61
	v_fmac_f32_e32 v239, v191, v61
	v_fmac_f32_e32 v194, v188, v50
	v_fmac_f32_e32 v195, v192, v50
	v_fmac_f32_e32 v238, v188, v62
	v_fmac_f32_e32 v239, v192, v62
	v_fmac_f32_e32 v194, v189, v51
	v_fmac_f32_e32 v195, v193, v51
	v_fmac_f32_e32 v238, v189, v63
	v_fmac_f32_e32 v239, v193, v63
	v_add_f32_dpp v194, v194, v194 quad_perm:[1,0,3,2] row_mask:0xf bank_mask:0xf bound_ctrl:1
	v_add_f32_dpp v195, v195, v195 quad_perm:[1,0,3,2] row_mask:0xf bank_mask:0xf bound_ctrl:1
	v_add_f32_dpp v238, v238, v238 quad_perm:[1,0,3,2] row_mask:0xf bank_mask:0xf bound_ctrl:1
	v_add_f32_dpp v239, v239, v239 quad_perm:[1,0,3,2] row_mask:0xf bank_mask:0xf bound_ctrl:1
	v_add_f32_dpp v194, v194, v194 quad_perm:[2,3,0,1] row_mask:0xf bank_mask:0xf bound_ctrl:1
	v_add_f32_dpp v195, v195, v195 quad_perm:[2,3,0,1] row_mask:0xf bank_mask:0xf bound_ctrl:1
	v_add_f32_dpp v238, v238, v238 quad_perm:[2,3,0,1] row_mask:0xf bank_mask:0xf bound_ctrl:1
	v_add_f32_dpp v239, v239, v239 quad_perm:[2,3,0,1] row_mask:0xf bank_mask:0xf bound_ctrl:1
	v_add_f32_dpp v194, v194, v194 row_half_mirror row_mask:0xf bank_mask:0xf bound_ctrl:1
	v_add_f32_dpp v195, v195, v195 row_half_mirror row_mask:0xf bank_mask:0xf bound_ctrl:1
	v_add_f32_dpp v238, v238, v238 row_half_mirror row_mask:0xf bank_mask:0xf bound_ctrl:1
	v_add_f32_dpp v239, v239, v239 row_half_mirror row_mask:0xf bank_mask:0xf bound_ctrl:1
	v_add_f32_dpp v194, v194, v194 row_mirror row_mask:0xf bank_mask:0xf bound_ctrl:1
	v_add_f32_dpp v195, v195, v195 row_mirror row_mask:0xf bank_mask:0xf bound_ctrl:1
	v_fmac_f32_e32 v186, v130, v56
	v_fmac_f32_e32 v187, v130, v57
	v_fmac_f32_e32 v188, v130, v58
	v_fmac_f32_e32 v189, v130, v59
	v_fmac_f32_e32 v190, v131, v56
	v_fmac_f32_e32 v191, v131, v57
	v_fmac_f32_e32 v192, v131, v58
	v_fmac_f32_e32 v193, v131, v59
	v_fmac_f32_e32 v186, v194, v52
	v_fmac_f32_e32 v187, v194, v53
	v_fmac_f32_e32 v188, v194, v54
	v_fmac_f32_e32 v189, v194, v55
	v_fmac_f32_e32 v190, v195, v52
	v_fmac_f32_e32 v191, v195, v53
	v_fmac_f32_e32 v192, v195, v54
	v_fmac_f32_e32 v193, v195, v55
	s_mov_b64 exec, s[8:9]
	ds_write2st64_b64 v161, v[132:133], v[238:239] offset0:27 offset1:26
	s_mov_b64 exec, -1
	ds_read_b128 v[48:51], v152 offset:14080
	ds_read_b128 v[52:55], v152 offset:22272
	ds_read_b128 v[56:59], v152 offset:30464
	ds_read_b128 v[60:63], v152 offset:38656
	ds_read_b64 v[130:131], v69 offset:5888
	s_waitcnt lgkmcnt(11)
	v_mul_f32_e32 v194, v186, v8
	v_mul_f32_e32 v195, v190, v8
	v_mul_f32_e32 v132, v186, v20
	v_mul_f32_e32 v133, v190, v20
	v_fmac_f32_e32 v194, v187, v9
	v_fmac_f32_e32 v195, v191, v9
	v_fmac_f32_e32 v132, v187, v21
	v_fmac_f32_e32 v133, v191, v21
	v_fmac_f32_e32 v194, v188, v10
	v_fmac_f32_e32 v195, v192, v10
	v_fmac_f32_e32 v132, v188, v22
	v_fmac_f32_e32 v133, v192, v22
	v_fmac_f32_e32 v194, v189, v11
	v_fmac_f32_e32 v195, v193, v11
	v_fmac_f32_e32 v132, v189, v23
	v_fmac_f32_e32 v133, v193, v23
	v_add_f32_dpp v194, v194, v194 quad_perm:[1,0,3,2] row_mask:0xf bank_mask:0xf bound_ctrl:1
	v_add_f32_dpp v195, v195, v195 quad_perm:[1,0,3,2] row_mask:0xf bank_mask:0xf bound_ctrl:1
	v_add_f32_dpp v132, v132, v132 quad_perm:[1,0,3,2] row_mask:0xf bank_mask:0xf bound_ctrl:1
	v_add_f32_dpp v133, v133, v133 quad_perm:[1,0,3,2] row_mask:0xf bank_mask:0xf bound_ctrl:1
	v_add_f32_dpp v194, v194, v194 quad_perm:[2,3,0,1] row_mask:0xf bank_mask:0xf bound_ctrl:1
	v_add_f32_dpp v195, v195, v195 quad_perm:[2,3,0,1] row_mask:0xf bank_mask:0xf bound_ctrl:1
	v_add_f32_dpp v132, v132, v132 quad_perm:[2,3,0,1] row_mask:0xf bank_mask:0xf bound_ctrl:1
	v_add_f32_dpp v133, v133, v133 quad_perm:[2,3,0,1] row_mask:0xf bank_mask:0xf bound_ctrl:1
	v_add_f32_dpp v194, v194, v194 row_half_mirror row_mask:0xf bank_mask:0xf bound_ctrl:1
	v_add_f32_dpp v195, v195, v195 row_half_mirror row_mask:0xf bank_mask:0xf bound_ctrl:1
	v_add_f32_dpp v132, v132, v132 row_half_mirror row_mask:0xf bank_mask:0xf bound_ctrl:1
	v_add_f32_dpp v133, v133, v133 row_half_mirror row_mask:0xf bank_mask:0xf bound_ctrl:1
	v_add_f32_dpp v194, v194, v194 row_mirror row_mask:0xf bank_mask:0xf bound_ctrl:1
	v_add_f32_dpp v195, v195, v195 row_mirror row_mask:0xf bank_mask:0xf bound_ctrl:1
	v_fmac_f32_e32 v186, v64, v16
	v_fmac_f32_e32 v187, v64, v17
	v_fmac_f32_e32 v188, v64, v18
	v_fmac_f32_e32 v189, v64, v19
	v_fmac_f32_e32 v190, v65, v16
	v_fmac_f32_e32 v191, v65, v17
	v_fmac_f32_e32 v192, v65, v18
	v_fmac_f32_e32 v193, v65, v19
	v_fmac_f32_e32 v186, v194, v12
	v_fmac_f32_e32 v187, v194, v13
	v_fmac_f32_e32 v188, v194, v14
	v_fmac_f32_e32 v189, v194, v15
	v_fmac_f32_e32 v190, v195, v12
	v_fmac_f32_e32 v191, v195, v13
	v_fmac_f32_e32 v192, v195, v14
	v_fmac_f32_e32 v193, v195, v15
	ds_read_b128 v[8:11], v152 offset:13824
	ds_read_b128 v[12:15], v152 offset:22016
	ds_read_b128 v[16:19], v152 offset:30208
	ds_read_b128 v[20:23], v152 offset:38400
	ds_read_b64 v[64:65], v69 offset:5632
	s_waitcnt lgkmcnt(11)
	v_mul_f32_e32 v194, v186, v28
	v_mul_f32_e32 v195, v190, v28
	v_mul_f32_e32 v238, v186, v40
	v_mul_f32_e32 v239, v190, v40
	v_fmac_f32_e32 v194, v187, v29
	v_fmac_f32_e32 v195, v191, v29
	v_fmac_f32_e32 v238, v187, v41
	v_fmac_f32_e32 v239, v191, v41
	v_fmac_f32_e32 v194, v188, v30
	v_fmac_f32_e32 v195, v192, v30
	v_fmac_f32_e32 v238, v188, v42
	v_fmac_f32_e32 v239, v192, v42
	v_fmac_f32_e32 v194, v189, v31
	v_fmac_f32_e32 v195, v193, v31
	v_fmac_f32_e32 v238, v189, v43
	v_fmac_f32_e32 v239, v193, v43
	v_add_f32_dpp v194, v194, v194 quad_perm:[1,0,3,2] row_mask:0xf bank_mask:0xf bound_ctrl:1
	v_add_f32_dpp v195, v195, v195 quad_perm:[1,0,3,2] row_mask:0xf bank_mask:0xf bound_ctrl:1
	v_add_f32_dpp v238, v238, v238 quad_perm:[1,0,3,2] row_mask:0xf bank_mask:0xf bound_ctrl:1
	v_add_f32_dpp v239, v239, v239 quad_perm:[1,0,3,2] row_mask:0xf bank_mask:0xf bound_ctrl:1
	v_add_f32_dpp v194, v194, v194 quad_perm:[2,3,0,1] row_mask:0xf bank_mask:0xf bound_ctrl:1
	v_add_f32_dpp v195, v195, v195 quad_perm:[2,3,0,1] row_mask:0xf bank_mask:0xf bound_ctrl:1
	v_add_f32_dpp v238, v238, v238 quad_perm:[2,3,0,1] row_mask:0xf bank_mask:0xf bound_ctrl:1
	v_add_f32_dpp v239, v239, v239 quad_perm:[2,3,0,1] row_mask:0xf bank_mask:0xf bound_ctrl:1
	v_add_f32_dpp v194, v194, v194 row_half_mirror row_mask:0xf bank_mask:0xf bound_ctrl:1
	v_add_f32_dpp v195, v195, v195 row_half_mirror row_mask:0xf bank_mask:0xf bound_ctrl:1
	v_add_f32_dpp v238, v238, v238 row_half_mirror row_mask:0xf bank_mask:0xf bound_ctrl:1
	v_add_f32_dpp v239, v239, v239 row_half_mirror row_mask:0xf bank_mask:0xf bound_ctrl:1
	v_add_f32_dpp v194, v194, v194 row_mirror row_mask:0xf bank_mask:0xf bound_ctrl:1
	v_add_f32_dpp v195, v195, v195 row_mirror row_mask:0xf bank_mask:0xf bound_ctrl:1
	v_fmac_f32_e32 v186, v66, v36
	v_fmac_f32_e32 v187, v66, v37
	v_fmac_f32_e32 v188, v66, v38
	v_fmac_f32_e32 v189, v66, v39
	v_fmac_f32_e32 v190, v67, v36
	v_fmac_f32_e32 v191, v67, v37
	v_fmac_f32_e32 v192, v67, v38
	v_fmac_f32_e32 v193, v67, v39
	v_fmac_f32_e32 v186, v194, v32
	v_fmac_f32_e32 v187, v194, v33
	v_fmac_f32_e32 v188, v194, v34
	v_fmac_f32_e32 v189, v194, v35
	v_fmac_f32_e32 v190, v195, v32
	v_fmac_f32_e32 v191, v195, v33
	v_fmac_f32_e32 v192, v195, v34
	v_fmac_f32_e32 v193, v195, v35
	s_mov_b64 exec, s[8:9]
	ds_write2st64_b64 v161, v[132:133], v[238:239] offset0:25 offset1:24
	s_mov_b64 exec, -1
	ds_read_b128 v[28:31], v152 offset:13568
	ds_read_b128 v[32:35], v152 offset:21760
	ds_read_b128 v[36:39], v152 offset:29952
	ds_read_b128 v[40:43], v152 offset:38144
	ds_read_b64 v[66:67], v69 offset:5376
	s_waitcnt lgkmcnt(11)
	v_mul_f32_e32 v194, v186, v48
	v_mul_f32_e32 v195, v190, v48
	v_mul_f32_e32 v132, v186, v60
	v_mul_f32_e32 v133, v190, v60
	v_fmac_f32_e32 v194, v187, v49
	v_fmac_f32_e32 v195, v191, v49
	v_fmac_f32_e32 v132, v187, v61
	v_fmac_f32_e32 v133, v191, v61
	v_fmac_f32_e32 v194, v188, v50
	v_fmac_f32_e32 v195, v192, v50
	v_fmac_f32_e32 v132, v188, v62
	v_fmac_f32_e32 v133, v192, v62
	v_fmac_f32_e32 v194, v189, v51
	v_fmac_f32_e32 v195, v193, v51
	v_fmac_f32_e32 v132, v189, v63
	v_fmac_f32_e32 v133, v193, v63
	v_add_f32_dpp v194, v194, v194 quad_perm:[1,0,3,2] row_mask:0xf bank_mask:0xf bound_ctrl:1
	v_add_f32_dpp v195, v195, v195 quad_perm:[1,0,3,2] row_mask:0xf bank_mask:0xf bound_ctrl:1
	v_add_f32_dpp v132, v132, v132 quad_perm:[1,0,3,2] row_mask:0xf bank_mask:0xf bound_ctrl:1
	v_add_f32_dpp v133, v133, v133 quad_perm:[1,0,3,2] row_mask:0xf bank_mask:0xf bound_ctrl:1
	v_add_f32_dpp v194, v194, v194 quad_perm:[2,3,0,1] row_mask:0xf bank_mask:0xf bound_ctrl:1
	v_add_f32_dpp v195, v195, v195 quad_perm:[2,3,0,1] row_mask:0xf bank_mask:0xf bound_ctrl:1
	v_add_f32_dpp v132, v132, v132 quad_perm:[2,3,0,1] row_mask:0xf bank_mask:0xf bound_ctrl:1
	v_add_f32_dpp v133, v133, v133 quad_perm:[2,3,0,1] row_mask:0xf bank_mask:0xf bound_ctrl:1
	v_add_f32_dpp v194, v194, v194 row_half_mirror row_mask:0xf bank_mask:0xf bound_ctrl:1
	v_add_f32_dpp v195, v195, v195 row_half_mirror row_mask:0xf bank_mask:0xf bound_ctrl:1
	v_add_f32_dpp v132, v132, v132 row_half_mirror row_mask:0xf bank_mask:0xf bound_ctrl:1
	v_add_f32_dpp v133, v133, v133 row_half_mirror row_mask:0xf bank_mask:0xf bound_ctrl:1
	v_add_f32_dpp v194, v194, v194 row_mirror row_mask:0xf bank_mask:0xf bound_ctrl:1
	v_add_f32_dpp v195, v195, v195 row_mirror row_mask:0xf bank_mask:0xf bound_ctrl:1
	v_fmac_f32_e32 v186, v130, v56
	v_fmac_f32_e32 v187, v130, v57
	v_fmac_f32_e32 v188, v130, v58
	v_fmac_f32_e32 v189, v130, v59
	v_fmac_f32_e32 v190, v131, v56
	v_fmac_f32_e32 v191, v131, v57
	v_fmac_f32_e32 v192, v131, v58
	v_fmac_f32_e32 v193, v131, v59
	v_fmac_f32_e32 v186, v194, v52
	v_fmac_f32_e32 v187, v194, v53
	v_fmac_f32_e32 v188, v194, v54
	v_fmac_f32_e32 v189, v194, v55
	v_fmac_f32_e32 v190, v195, v52
	v_fmac_f32_e32 v191, v195, v53
	v_fmac_f32_e32 v192, v195, v54
	v_fmac_f32_e32 v193, v195, v55
	ds_read_b128 v[48:51], v152 offset:13312
	ds_read_b128 v[52:55], v152 offset:21504
	ds_read_b128 v[56:59], v152 offset:29696
	ds_read_b128 v[60:63], v152 offset:37888
	ds_read_b64 v[130:131], v69 offset:5120
	s_waitcnt lgkmcnt(11)
	v_mul_f32_e32 v194, v186, v8
	v_mul_f32_e32 v195, v190, v8
	v_mul_f32_e32 v238, v186, v20
	v_mul_f32_e32 v239, v190, v20
	v_fmac_f32_e32 v194, v187, v9
	v_fmac_f32_e32 v195, v191, v9
	v_fmac_f32_e32 v238, v187, v21
	v_fmac_f32_e32 v239, v191, v21
	v_fmac_f32_e32 v194, v188, v10
	v_fmac_f32_e32 v195, v192, v10
	v_fmac_f32_e32 v238, v188, v22
	v_fmac_f32_e32 v239, v192, v22
	v_fmac_f32_e32 v194, v189, v11
	v_fmac_f32_e32 v195, v193, v11
	v_fmac_f32_e32 v238, v189, v23
	v_fmac_f32_e32 v239, v193, v23
	v_add_f32_dpp v194, v194, v194 quad_perm:[1,0,3,2] row_mask:0xf bank_mask:0xf bound_ctrl:1
	v_add_f32_dpp v195, v195, v195 quad_perm:[1,0,3,2] row_mask:0xf bank_mask:0xf bound_ctrl:1
	v_add_f32_dpp v238, v238, v238 quad_perm:[1,0,3,2] row_mask:0xf bank_mask:0xf bound_ctrl:1
	v_add_f32_dpp v239, v239, v239 quad_perm:[1,0,3,2] row_mask:0xf bank_mask:0xf bound_ctrl:1
	v_add_f32_dpp v194, v194, v194 quad_perm:[2,3,0,1] row_mask:0xf bank_mask:0xf bound_ctrl:1
	v_add_f32_dpp v195, v195, v195 quad_perm:[2,3,0,1] row_mask:0xf bank_mask:0xf bound_ctrl:1
	v_add_f32_dpp v238, v238, v238 quad_perm:[2,3,0,1] row_mask:0xf bank_mask:0xf bound_ctrl:1
	v_add_f32_dpp v239, v239, v239 quad_perm:[2,3,0,1] row_mask:0xf bank_mask:0xf bound_ctrl:1
	v_add_f32_dpp v194, v194, v194 row_half_mirror row_mask:0xf bank_mask:0xf bound_ctrl:1
	v_add_f32_dpp v195, v195, v195 row_half_mirror row_mask:0xf bank_mask:0xf bound_ctrl:1
	v_add_f32_dpp v238, v238, v238 row_half_mirror row_mask:0xf bank_mask:0xf bound_ctrl:1
	v_add_f32_dpp v239, v239, v239 row_half_mirror row_mask:0xf bank_mask:0xf bound_ctrl:1
	v_add_f32_dpp v194, v194, v194 row_mirror row_mask:0xf bank_mask:0xf bound_ctrl:1
	v_add_f32_dpp v195, v195, v195 row_mirror row_mask:0xf bank_mask:0xf bound_ctrl:1
	v_fmac_f32_e32 v186, v64, v16
	v_fmac_f32_e32 v187, v64, v17
	v_fmac_f32_e32 v188, v64, v18
	v_fmac_f32_e32 v189, v64, v19
	v_fmac_f32_e32 v190, v65, v16
	v_fmac_f32_e32 v191, v65, v17
	v_fmac_f32_e32 v192, v65, v18
	v_fmac_f32_e32 v193, v65, v19
	v_fmac_f32_e32 v186, v194, v12
	v_fmac_f32_e32 v187, v194, v13
	v_fmac_f32_e32 v188, v194, v14
	v_fmac_f32_e32 v189, v194, v15
	v_fmac_f32_e32 v190, v195, v12
	v_fmac_f32_e32 v191, v195, v13
	v_fmac_f32_e32 v192, v195, v14
	v_fmac_f32_e32 v193, v195, v15
	s_mov_b64 exec, s[8:9]
	ds_write2st64_b64 v161, v[132:133], v[238:239] offset0:23 offset1:22
	s_mov_b64 exec, -1
	ds_read_b128 v[8:11], v152 offset:13056
	ds_read_b128 v[12:15], v152 offset:21248
	ds_read_b128 v[16:19], v152 offset:29440
	ds_read_b128 v[20:23], v152 offset:37632
	ds_read_b64 v[64:65], v69 offset:4864
	s_waitcnt lgkmcnt(11)
	v_mul_f32_e32 v194, v186, v28
	v_mul_f32_e32 v195, v190, v28
	v_mul_f32_e32 v132, v186, v40
	v_mul_f32_e32 v133, v190, v40
	v_fmac_f32_e32 v194, v187, v29
	v_fmac_f32_e32 v195, v191, v29
	v_fmac_f32_e32 v132, v187, v41
	v_fmac_f32_e32 v133, v191, v41
	v_fmac_f32_e32 v194, v188, v30
	v_fmac_f32_e32 v195, v192, v30
	v_fmac_f32_e32 v132, v188, v42
	v_fmac_f32_e32 v133, v192, v42
	v_fmac_f32_e32 v194, v189, v31
	v_fmac_f32_e32 v195, v193, v31
	v_fmac_f32_e32 v132, v189, v43
	v_fmac_f32_e32 v133, v193, v43
	v_add_f32_dpp v194, v194, v194 quad_perm:[1,0,3,2] row_mask:0xf bank_mask:0xf bound_ctrl:1
	v_add_f32_dpp v195, v195, v195 quad_perm:[1,0,3,2] row_mask:0xf bank_mask:0xf bound_ctrl:1
	v_add_f32_dpp v132, v132, v132 quad_perm:[1,0,3,2] row_mask:0xf bank_mask:0xf bound_ctrl:1
	v_add_f32_dpp v133, v133, v133 quad_perm:[1,0,3,2] row_mask:0xf bank_mask:0xf bound_ctrl:1
	v_add_f32_dpp v194, v194, v194 quad_perm:[2,3,0,1] row_mask:0xf bank_mask:0xf bound_ctrl:1
	v_add_f32_dpp v195, v195, v195 quad_perm:[2,3,0,1] row_mask:0xf bank_mask:0xf bound_ctrl:1
	v_add_f32_dpp v132, v132, v132 quad_perm:[2,3,0,1] row_mask:0xf bank_mask:0xf bound_ctrl:1
	v_add_f32_dpp v133, v133, v133 quad_perm:[2,3,0,1] row_mask:0xf bank_mask:0xf bound_ctrl:1
	v_add_f32_dpp v194, v194, v194 row_half_mirror row_mask:0xf bank_mask:0xf bound_ctrl:1
	v_add_f32_dpp v195, v195, v195 row_half_mirror row_mask:0xf bank_mask:0xf bound_ctrl:1
	v_add_f32_dpp v132, v132, v132 row_half_mirror row_mask:0xf bank_mask:0xf bound_ctrl:1
	v_add_f32_dpp v133, v133, v133 row_half_mirror row_mask:0xf bank_mask:0xf bound_ctrl:1
	v_add_f32_dpp v194, v194, v194 row_mirror row_mask:0xf bank_mask:0xf bound_ctrl:1
	v_add_f32_dpp v195, v195, v195 row_mirror row_mask:0xf bank_mask:0xf bound_ctrl:1
	v_fmac_f32_e32 v186, v66, v36
	v_fmac_f32_e32 v187, v66, v37
	v_fmac_f32_e32 v188, v66, v38
	v_fmac_f32_e32 v189, v66, v39
	v_fmac_f32_e32 v190, v67, v36
	v_fmac_f32_e32 v191, v67, v37
	v_fmac_f32_e32 v192, v67, v38
	v_fmac_f32_e32 v193, v67, v39
	v_fmac_f32_e32 v186, v194, v32
	v_fmac_f32_e32 v187, v194, v33
	v_fmac_f32_e32 v188, v194, v34
	v_fmac_f32_e32 v189, v194, v35
	v_fmac_f32_e32 v190, v195, v32
	v_fmac_f32_e32 v191, v195, v33
	v_fmac_f32_e32 v192, v195, v34
	v_fmac_f32_e32 v193, v195, v35
	ds_read_b128 v[28:31], v152 offset:12800
	ds_read_b128 v[32:35], v152 offset:20992
	ds_read_b128 v[36:39], v152 offset:29184
	ds_read_b128 v[40:43], v152 offset:37376
	ds_read_b64 v[66:67], v69 offset:4608
	s_waitcnt lgkmcnt(11)
	v_mul_f32_e32 v194, v186, v48
	v_mul_f32_e32 v195, v190, v48
	v_mul_f32_e32 v238, v186, v60
	v_mul_f32_e32 v239, v190, v60
	v_fmac_f32_e32 v194, v187, v49
	v_fmac_f32_e32 v195, v191, v49
	v_fmac_f32_e32 v238, v187, v61
	v_fmac_f32_e32 v239, v191, v61
	v_fmac_f32_e32 v194, v188, v50
	v_fmac_f32_e32 v195, v192, v50
	v_fmac_f32_e32 v238, v188, v62
	v_fmac_f32_e32 v239, v192, v62
	v_fmac_f32_e32 v194, v189, v51
	v_fmac_f32_e32 v195, v193, v51
	v_fmac_f32_e32 v238, v189, v63
	v_fmac_f32_e32 v239, v193, v63
	v_add_f32_dpp v194, v194, v194 quad_perm:[1,0,3,2] row_mask:0xf bank_mask:0xf bound_ctrl:1
	v_add_f32_dpp v195, v195, v195 quad_perm:[1,0,3,2] row_mask:0xf bank_mask:0xf bound_ctrl:1
	v_add_f32_dpp v238, v238, v238 quad_perm:[1,0,3,2] row_mask:0xf bank_mask:0xf bound_ctrl:1
	v_add_f32_dpp v239, v239, v239 quad_perm:[1,0,3,2] row_mask:0xf bank_mask:0xf bound_ctrl:1
	v_add_f32_dpp v194, v194, v194 quad_perm:[2,3,0,1] row_mask:0xf bank_mask:0xf bound_ctrl:1
	v_add_f32_dpp v195, v195, v195 quad_perm:[2,3,0,1] row_mask:0xf bank_mask:0xf bound_ctrl:1
	v_add_f32_dpp v238, v238, v238 quad_perm:[2,3,0,1] row_mask:0xf bank_mask:0xf bound_ctrl:1
	v_add_f32_dpp v239, v239, v239 quad_perm:[2,3,0,1] row_mask:0xf bank_mask:0xf bound_ctrl:1
	v_add_f32_dpp v194, v194, v194 row_half_mirror row_mask:0xf bank_mask:0xf bound_ctrl:1
	v_add_f32_dpp v195, v195, v195 row_half_mirror row_mask:0xf bank_mask:0xf bound_ctrl:1
	v_add_f32_dpp v238, v238, v238 row_half_mirror row_mask:0xf bank_mask:0xf bound_ctrl:1
	v_add_f32_dpp v239, v239, v239 row_half_mirror row_mask:0xf bank_mask:0xf bound_ctrl:1
	v_add_f32_dpp v194, v194, v194 row_mirror row_mask:0xf bank_mask:0xf bound_ctrl:1
	v_add_f32_dpp v195, v195, v195 row_mirror row_mask:0xf bank_mask:0xf bound_ctrl:1
	v_fmac_f32_e32 v186, v130, v56
	v_fmac_f32_e32 v187, v130, v57
	v_fmac_f32_e32 v188, v130, v58
	v_fmac_f32_e32 v189, v130, v59
	v_fmac_f32_e32 v190, v131, v56
	v_fmac_f32_e32 v191, v131, v57
	v_fmac_f32_e32 v192, v131, v58
	v_fmac_f32_e32 v193, v131, v59
	v_fmac_f32_e32 v186, v194, v52
	v_fmac_f32_e32 v187, v194, v53
	v_fmac_f32_e32 v188, v194, v54
	v_fmac_f32_e32 v189, v194, v55
	v_fmac_f32_e32 v190, v195, v52
	v_fmac_f32_e32 v191, v195, v53
	v_fmac_f32_e32 v192, v195, v54
	v_fmac_f32_e32 v193, v195, v55
	s_mov_b64 exec, s[8:9]
	ds_write2st64_b64 v161, v[132:133], v[238:239] offset0:21 offset1:20
	s_mov_b64 exec, -1
	ds_read_b128 v[48:51], v152 offset:12544
	ds_read_b128 v[52:55], v152 offset:20736
	ds_read_b128 v[56:59], v152 offset:28928
	ds_read_b128 v[60:63], v152 offset:37120
	ds_read_b64 v[130:131], v69 offset:4352
	s_waitcnt lgkmcnt(11)
	v_mul_f32_e32 v194, v186, v8
	v_mul_f32_e32 v195, v190, v8
	v_mul_f32_e32 v132, v186, v20
	v_mul_f32_e32 v133, v190, v20
	v_fmac_f32_e32 v194, v187, v9
	v_fmac_f32_e32 v195, v191, v9
	v_fmac_f32_e32 v132, v187, v21
	v_fmac_f32_e32 v133, v191, v21
	v_fmac_f32_e32 v194, v188, v10
	v_fmac_f32_e32 v195, v192, v10
	v_fmac_f32_e32 v132, v188, v22
	v_fmac_f32_e32 v133, v192, v22
	v_fmac_f32_e32 v194, v189, v11
	v_fmac_f32_e32 v195, v193, v11
	v_fmac_f32_e32 v132, v189, v23
	v_fmac_f32_e32 v133, v193, v23
	v_add_f32_dpp v194, v194, v194 quad_perm:[1,0,3,2] row_mask:0xf bank_mask:0xf bound_ctrl:1
	v_add_f32_dpp v195, v195, v195 quad_perm:[1,0,3,2] row_mask:0xf bank_mask:0xf bound_ctrl:1
	v_add_f32_dpp v132, v132, v132 quad_perm:[1,0,3,2] row_mask:0xf bank_mask:0xf bound_ctrl:1
	v_add_f32_dpp v133, v133, v133 quad_perm:[1,0,3,2] row_mask:0xf bank_mask:0xf bound_ctrl:1
	v_add_f32_dpp v194, v194, v194 quad_perm:[2,3,0,1] row_mask:0xf bank_mask:0xf bound_ctrl:1
	v_add_f32_dpp v195, v195, v195 quad_perm:[2,3,0,1] row_mask:0xf bank_mask:0xf bound_ctrl:1
	v_add_f32_dpp v132, v132, v132 quad_perm:[2,3,0,1] row_mask:0xf bank_mask:0xf bound_ctrl:1
	v_add_f32_dpp v133, v133, v133 quad_perm:[2,3,0,1] row_mask:0xf bank_mask:0xf bound_ctrl:1
	v_add_f32_dpp v194, v194, v194 row_half_mirror row_mask:0xf bank_mask:0xf bound_ctrl:1
	v_add_f32_dpp v195, v195, v195 row_half_mirror row_mask:0xf bank_mask:0xf bound_ctrl:1
	v_add_f32_dpp v132, v132, v132 row_half_mirror row_mask:0xf bank_mask:0xf bound_ctrl:1
	v_add_f32_dpp v133, v133, v133 row_half_mirror row_mask:0xf bank_mask:0xf bound_ctrl:1
	v_add_f32_dpp v194, v194, v194 row_mirror row_mask:0xf bank_mask:0xf bound_ctrl:1
	v_add_f32_dpp v195, v195, v195 row_mirror row_mask:0xf bank_mask:0xf bound_ctrl:1
	v_fmac_f32_e32 v186, v64, v16
	v_fmac_f32_e32 v187, v64, v17
	v_fmac_f32_e32 v188, v64, v18
	v_fmac_f32_e32 v189, v64, v19
	v_fmac_f32_e32 v190, v65, v16
	v_fmac_f32_e32 v191, v65, v17
	v_fmac_f32_e32 v192, v65, v18
	v_fmac_f32_e32 v193, v65, v19
	v_fmac_f32_e32 v186, v194, v12
	v_fmac_f32_e32 v187, v194, v13
	v_fmac_f32_e32 v188, v194, v14
	v_fmac_f32_e32 v189, v194, v15
	v_fmac_f32_e32 v190, v195, v12
	v_fmac_f32_e32 v191, v195, v13
	v_fmac_f32_e32 v192, v195, v14
	v_fmac_f32_e32 v193, v195, v15
	ds_read_b128 v[8:11], v152 offset:12288
	ds_read_b128 v[12:15], v152 offset:20480
	ds_read_b128 v[16:19], v152 offset:28672
	ds_read_b128 v[20:23], v152 offset:36864
	ds_read_b64 v[64:65], v69 offset:4096
	s_waitcnt lgkmcnt(11)
	v_mul_f32_e32 v194, v186, v28
	v_mul_f32_e32 v195, v190, v28
	v_mul_f32_e32 v238, v186, v40
	v_mul_f32_e32 v239, v190, v40
	v_fmac_f32_e32 v194, v187, v29
	v_fmac_f32_e32 v195, v191, v29
	v_fmac_f32_e32 v238, v187, v41
	v_fmac_f32_e32 v239, v191, v41
	v_fmac_f32_e32 v194, v188, v30
	v_fmac_f32_e32 v195, v192, v30
	v_fmac_f32_e32 v238, v188, v42
	v_fmac_f32_e32 v239, v192, v42
	v_fmac_f32_e32 v194, v189, v31
	v_fmac_f32_e32 v195, v193, v31
	v_fmac_f32_e32 v238, v189, v43
	v_fmac_f32_e32 v239, v193, v43
	v_add_f32_dpp v194, v194, v194 quad_perm:[1,0,3,2] row_mask:0xf bank_mask:0xf bound_ctrl:1
	v_add_f32_dpp v195, v195, v195 quad_perm:[1,0,3,2] row_mask:0xf bank_mask:0xf bound_ctrl:1
	v_add_f32_dpp v238, v238, v238 quad_perm:[1,0,3,2] row_mask:0xf bank_mask:0xf bound_ctrl:1
	v_add_f32_dpp v239, v239, v239 quad_perm:[1,0,3,2] row_mask:0xf bank_mask:0xf bound_ctrl:1
	v_add_f32_dpp v194, v194, v194 quad_perm:[2,3,0,1] row_mask:0xf bank_mask:0xf bound_ctrl:1
	v_add_f32_dpp v195, v195, v195 quad_perm:[2,3,0,1] row_mask:0xf bank_mask:0xf bound_ctrl:1
	v_add_f32_dpp v238, v238, v238 quad_perm:[2,3,0,1] row_mask:0xf bank_mask:0xf bound_ctrl:1
	v_add_f32_dpp v239, v239, v239 quad_perm:[2,3,0,1] row_mask:0xf bank_mask:0xf bound_ctrl:1
	v_add_f32_dpp v194, v194, v194 row_half_mirror row_mask:0xf bank_mask:0xf bound_ctrl:1
	v_add_f32_dpp v195, v195, v195 row_half_mirror row_mask:0xf bank_mask:0xf bound_ctrl:1
	v_add_f32_dpp v238, v238, v238 row_half_mirror row_mask:0xf bank_mask:0xf bound_ctrl:1
	v_add_f32_dpp v239, v239, v239 row_half_mirror row_mask:0xf bank_mask:0xf bound_ctrl:1
	v_add_f32_dpp v194, v194, v194 row_mirror row_mask:0xf bank_mask:0xf bound_ctrl:1
	v_add_f32_dpp v195, v195, v195 row_mirror row_mask:0xf bank_mask:0xf bound_ctrl:1
	v_fmac_f32_e32 v186, v66, v36
	v_fmac_f32_e32 v187, v66, v37
	v_fmac_f32_e32 v188, v66, v38
	v_fmac_f32_e32 v189, v66, v39
	v_fmac_f32_e32 v190, v67, v36
	v_fmac_f32_e32 v191, v67, v37
	v_fmac_f32_e32 v192, v67, v38
	v_fmac_f32_e32 v193, v67, v39
	v_fmac_f32_e32 v186, v194, v32
	v_fmac_f32_e32 v187, v194, v33
	v_fmac_f32_e32 v188, v194, v34
	v_fmac_f32_e32 v189, v194, v35
	v_fmac_f32_e32 v190, v195, v32
	v_fmac_f32_e32 v191, v195, v33
	v_fmac_f32_e32 v192, v195, v34
	v_fmac_f32_e32 v193, v195, v35
	s_mov_b64 exec, s[8:9]
	ds_write2st64_b64 v161, v[132:133], v[238:239] offset0:19 offset1:18
	s_mov_b64 exec, -1
	ds_read_b128 v[28:31], v152 offset:12032
	ds_read_b128 v[32:35], v152 offset:20224
	ds_read_b128 v[36:39], v152 offset:28416
	ds_read_b128 v[40:43], v152 offset:36608
	ds_read_b64 v[66:67], v69 offset:3840
	s_waitcnt lgkmcnt(11)
	v_mul_f32_e32 v194, v186, v48
	v_mul_f32_e32 v195, v190, v48
	v_mul_f32_e32 v132, v186, v60
	v_mul_f32_e32 v133, v190, v60
	v_fmac_f32_e32 v194, v187, v49
	v_fmac_f32_e32 v195, v191, v49
	v_fmac_f32_e32 v132, v187, v61
	v_fmac_f32_e32 v133, v191, v61
	v_fmac_f32_e32 v194, v188, v50
	v_fmac_f32_e32 v195, v192, v50
	v_fmac_f32_e32 v132, v188, v62
	v_fmac_f32_e32 v133, v192, v62
	v_fmac_f32_e32 v194, v189, v51
	v_fmac_f32_e32 v195, v193, v51
	v_fmac_f32_e32 v132, v189, v63
	v_fmac_f32_e32 v133, v193, v63
	v_add_f32_dpp v194, v194, v194 quad_perm:[1,0,3,2] row_mask:0xf bank_mask:0xf bound_ctrl:1
	v_add_f32_dpp v195, v195, v195 quad_perm:[1,0,3,2] row_mask:0xf bank_mask:0xf bound_ctrl:1
	v_add_f32_dpp v132, v132, v132 quad_perm:[1,0,3,2] row_mask:0xf bank_mask:0xf bound_ctrl:1
	v_add_f32_dpp v133, v133, v133 quad_perm:[1,0,3,2] row_mask:0xf bank_mask:0xf bound_ctrl:1
	v_add_f32_dpp v194, v194, v194 quad_perm:[2,3,0,1] row_mask:0xf bank_mask:0xf bound_ctrl:1
	v_add_f32_dpp v195, v195, v195 quad_perm:[2,3,0,1] row_mask:0xf bank_mask:0xf bound_ctrl:1
	v_add_f32_dpp v132, v132, v132 quad_perm:[2,3,0,1] row_mask:0xf bank_mask:0xf bound_ctrl:1
	v_add_f32_dpp v133, v133, v133 quad_perm:[2,3,0,1] row_mask:0xf bank_mask:0xf bound_ctrl:1
	v_add_f32_dpp v194, v194, v194 row_half_mirror row_mask:0xf bank_mask:0xf bound_ctrl:1
	v_add_f32_dpp v195, v195, v195 row_half_mirror row_mask:0xf bank_mask:0xf bound_ctrl:1
	v_add_f32_dpp v132, v132, v132 row_half_mirror row_mask:0xf bank_mask:0xf bound_ctrl:1
	v_add_f32_dpp v133, v133, v133 row_half_mirror row_mask:0xf bank_mask:0xf bound_ctrl:1
	v_add_f32_dpp v194, v194, v194 row_mirror row_mask:0xf bank_mask:0xf bound_ctrl:1
	v_add_f32_dpp v195, v195, v195 row_mirror row_mask:0xf bank_mask:0xf bound_ctrl:1
	v_fmac_f32_e32 v186, v130, v56
	v_fmac_f32_e32 v187, v130, v57
	v_fmac_f32_e32 v188, v130, v58
	v_fmac_f32_e32 v189, v130, v59
	v_fmac_f32_e32 v190, v131, v56
	v_fmac_f32_e32 v191, v131, v57
	v_fmac_f32_e32 v192, v131, v58
	v_fmac_f32_e32 v193, v131, v59
	v_fmac_f32_e32 v186, v194, v52
	v_fmac_f32_e32 v187, v194, v53
	v_fmac_f32_e32 v188, v194, v54
	v_fmac_f32_e32 v189, v194, v55
	v_fmac_f32_e32 v190, v195, v52
	v_fmac_f32_e32 v191, v195, v53
	v_fmac_f32_e32 v192, v195, v54
	v_fmac_f32_e32 v193, v195, v55
	ds_read_b128 v[48:51], v152 offset:11776
	ds_read_b128 v[52:55], v152 offset:19968
	ds_read_b128 v[56:59], v152 offset:28160
	ds_read_b128 v[60:63], v152 offset:36352
	ds_read_b64 v[130:131], v69 offset:3584
	s_waitcnt lgkmcnt(11)
	v_mul_f32_e32 v194, v186, v8
	v_mul_f32_e32 v195, v190, v8
	v_mul_f32_e32 v238, v186, v20
	v_mul_f32_e32 v239, v190, v20
	v_fmac_f32_e32 v194, v187, v9
	v_fmac_f32_e32 v195, v191, v9
	v_fmac_f32_e32 v238, v187, v21
	v_fmac_f32_e32 v239, v191, v21
	v_fmac_f32_e32 v194, v188, v10
	v_fmac_f32_e32 v195, v192, v10
	v_fmac_f32_e32 v238, v188, v22
	v_fmac_f32_e32 v239, v192, v22
	v_fmac_f32_e32 v194, v189, v11
	v_fmac_f32_e32 v195, v193, v11
	v_fmac_f32_e32 v238, v189, v23
	v_fmac_f32_e32 v239, v193, v23
	v_add_f32_dpp v194, v194, v194 quad_perm:[1,0,3,2] row_mask:0xf bank_mask:0xf bound_ctrl:1
	v_add_f32_dpp v195, v195, v195 quad_perm:[1,0,3,2] row_mask:0xf bank_mask:0xf bound_ctrl:1
	v_add_f32_dpp v238, v238, v238 quad_perm:[1,0,3,2] row_mask:0xf bank_mask:0xf bound_ctrl:1
	v_add_f32_dpp v239, v239, v239 quad_perm:[1,0,3,2] row_mask:0xf bank_mask:0xf bound_ctrl:1
	v_add_f32_dpp v194, v194, v194 quad_perm:[2,3,0,1] row_mask:0xf bank_mask:0xf bound_ctrl:1
	v_add_f32_dpp v195, v195, v195 quad_perm:[2,3,0,1] row_mask:0xf bank_mask:0xf bound_ctrl:1
	v_add_f32_dpp v238, v238, v238 quad_perm:[2,3,0,1] row_mask:0xf bank_mask:0xf bound_ctrl:1
	v_add_f32_dpp v239, v239, v239 quad_perm:[2,3,0,1] row_mask:0xf bank_mask:0xf bound_ctrl:1
	v_add_f32_dpp v194, v194, v194 row_half_mirror row_mask:0xf bank_mask:0xf bound_ctrl:1
	v_add_f32_dpp v195, v195, v195 row_half_mirror row_mask:0xf bank_mask:0xf bound_ctrl:1
	v_add_f32_dpp v238, v238, v238 row_half_mirror row_mask:0xf bank_mask:0xf bound_ctrl:1
	v_add_f32_dpp v239, v239, v239 row_half_mirror row_mask:0xf bank_mask:0xf bound_ctrl:1
	v_add_f32_dpp v194, v194, v194 row_mirror row_mask:0xf bank_mask:0xf bound_ctrl:1
	v_add_f32_dpp v195, v195, v195 row_mirror row_mask:0xf bank_mask:0xf bound_ctrl:1
	v_fmac_f32_e32 v186, v64, v16
	v_fmac_f32_e32 v187, v64, v17
	v_fmac_f32_e32 v188, v64, v18
	v_fmac_f32_e32 v189, v64, v19
	v_fmac_f32_e32 v190, v65, v16
	v_fmac_f32_e32 v191, v65, v17
	v_fmac_f32_e32 v192, v65, v18
	v_fmac_f32_e32 v193, v65, v19
	v_fmac_f32_e32 v186, v194, v12
	v_fmac_f32_e32 v187, v194, v13
	v_fmac_f32_e32 v188, v194, v14
	v_fmac_f32_e32 v189, v194, v15
	v_fmac_f32_e32 v190, v195, v12
	v_fmac_f32_e32 v191, v195, v13
	v_fmac_f32_e32 v192, v195, v14
	v_fmac_f32_e32 v193, v195, v15
	s_mov_b64 exec, s[8:9]
	ds_write2st64_b64 v161, v[132:133], v[238:239] offset0:17 offset1:16
	s_mov_b64 exec, -1
	ds_read_b128 v[8:11], v152 offset:11520
	ds_read_b128 v[12:15], v152 offset:19712
	ds_read_b128 v[16:19], v152 offset:27904
	ds_read_b128 v[20:23], v152 offset:36096
	ds_read_b64 v[64:65], v69 offset:3328
	s_waitcnt lgkmcnt(11)
	v_mul_f32_e32 v194, v186, v28
	v_mul_f32_e32 v195, v190, v28
	v_mul_f32_e32 v132, v186, v40
	v_mul_f32_e32 v133, v190, v40
	v_fmac_f32_e32 v194, v187, v29
	v_fmac_f32_e32 v195, v191, v29
	v_fmac_f32_e32 v132, v187, v41
	v_fmac_f32_e32 v133, v191, v41
	v_fmac_f32_e32 v194, v188, v30
	v_fmac_f32_e32 v195, v192, v30
	v_fmac_f32_e32 v132, v188, v42
	v_fmac_f32_e32 v133, v192, v42
	v_fmac_f32_e32 v194, v189, v31
	v_fmac_f32_e32 v195, v193, v31
	v_fmac_f32_e32 v132, v189, v43
	v_fmac_f32_e32 v133, v193, v43
	v_add_f32_dpp v194, v194, v194 quad_perm:[1,0,3,2] row_mask:0xf bank_mask:0xf bound_ctrl:1
	v_add_f32_dpp v195, v195, v195 quad_perm:[1,0,3,2] row_mask:0xf bank_mask:0xf bound_ctrl:1
	v_add_f32_dpp v132, v132, v132 quad_perm:[1,0,3,2] row_mask:0xf bank_mask:0xf bound_ctrl:1
	v_add_f32_dpp v133, v133, v133 quad_perm:[1,0,3,2] row_mask:0xf bank_mask:0xf bound_ctrl:1
	v_add_f32_dpp v194, v194, v194 quad_perm:[2,3,0,1] row_mask:0xf bank_mask:0xf bound_ctrl:1
	v_add_f32_dpp v195, v195, v195 quad_perm:[2,3,0,1] row_mask:0xf bank_mask:0xf bound_ctrl:1
	v_add_f32_dpp v132, v132, v132 quad_perm:[2,3,0,1] row_mask:0xf bank_mask:0xf bound_ctrl:1
	v_add_f32_dpp v133, v133, v133 quad_perm:[2,3,0,1] row_mask:0xf bank_mask:0xf bound_ctrl:1
	v_add_f32_dpp v194, v194, v194 row_half_mirror row_mask:0xf bank_mask:0xf bound_ctrl:1
	v_add_f32_dpp v195, v195, v195 row_half_mirror row_mask:0xf bank_mask:0xf bound_ctrl:1
	v_add_f32_dpp v132, v132, v132 row_half_mirror row_mask:0xf bank_mask:0xf bound_ctrl:1
	v_add_f32_dpp v133, v133, v133 row_half_mirror row_mask:0xf bank_mask:0xf bound_ctrl:1
	v_add_f32_dpp v194, v194, v194 row_mirror row_mask:0xf bank_mask:0xf bound_ctrl:1
	v_add_f32_dpp v195, v195, v195 row_mirror row_mask:0xf bank_mask:0xf bound_ctrl:1
	v_fmac_f32_e32 v186, v66, v36
	v_fmac_f32_e32 v187, v66, v37
	v_fmac_f32_e32 v188, v66, v38
	v_fmac_f32_e32 v189, v66, v39
	v_fmac_f32_e32 v190, v67, v36
	v_fmac_f32_e32 v191, v67, v37
	v_fmac_f32_e32 v192, v67, v38
	v_fmac_f32_e32 v193, v67, v39
	v_fmac_f32_e32 v186, v194, v32
	v_fmac_f32_e32 v187, v194, v33
	v_fmac_f32_e32 v188, v194, v34
	v_fmac_f32_e32 v189, v194, v35
	v_fmac_f32_e32 v190, v195, v32
	v_fmac_f32_e32 v191, v195, v33
	v_fmac_f32_e32 v192, v195, v34
	v_fmac_f32_e32 v193, v195, v35
	ds_read_b128 v[28:31], v152 offset:11264
	ds_read_b128 v[32:35], v152 offset:19456
	ds_read_b128 v[36:39], v152 offset:27648
	ds_read_b128 v[40:43], v152 offset:35840
	ds_read_b64 v[66:67], v69 offset:3072
	s_waitcnt lgkmcnt(11)
	v_mul_f32_e32 v194, v186, v48
	v_mul_f32_e32 v195, v190, v48
	v_mul_f32_e32 v238, v186, v60
	v_mul_f32_e32 v239, v190, v60
	v_fmac_f32_e32 v194, v187, v49
	v_fmac_f32_e32 v195, v191, v49
	v_fmac_f32_e32 v238, v187, v61
	v_fmac_f32_e32 v239, v191, v61
	v_fmac_f32_e32 v194, v188, v50
	v_fmac_f32_e32 v195, v192, v50
	v_fmac_f32_e32 v238, v188, v62
	v_fmac_f32_e32 v239, v192, v62
	v_fmac_f32_e32 v194, v189, v51
	v_fmac_f32_e32 v195, v193, v51
	v_fmac_f32_e32 v238, v189, v63
	v_fmac_f32_e32 v239, v193, v63
	v_add_f32_dpp v194, v194, v194 quad_perm:[1,0,3,2] row_mask:0xf bank_mask:0xf bound_ctrl:1
	v_add_f32_dpp v195, v195, v195 quad_perm:[1,0,3,2] row_mask:0xf bank_mask:0xf bound_ctrl:1
	v_add_f32_dpp v238, v238, v238 quad_perm:[1,0,3,2] row_mask:0xf bank_mask:0xf bound_ctrl:1
	v_add_f32_dpp v239, v239, v239 quad_perm:[1,0,3,2] row_mask:0xf bank_mask:0xf bound_ctrl:1
	v_add_f32_dpp v194, v194, v194 quad_perm:[2,3,0,1] row_mask:0xf bank_mask:0xf bound_ctrl:1
	v_add_f32_dpp v195, v195, v195 quad_perm:[2,3,0,1] row_mask:0xf bank_mask:0xf bound_ctrl:1
	v_add_f32_dpp v238, v238, v238 quad_perm:[2,3,0,1] row_mask:0xf bank_mask:0xf bound_ctrl:1
	v_add_f32_dpp v239, v239, v239 quad_perm:[2,3,0,1] row_mask:0xf bank_mask:0xf bound_ctrl:1
	v_add_f32_dpp v194, v194, v194 row_half_mirror row_mask:0xf bank_mask:0xf bound_ctrl:1
	v_add_f32_dpp v195, v195, v195 row_half_mirror row_mask:0xf bank_mask:0xf bound_ctrl:1
	v_add_f32_dpp v238, v238, v238 row_half_mirror row_mask:0xf bank_mask:0xf bound_ctrl:1
	v_add_f32_dpp v239, v239, v239 row_half_mirror row_mask:0xf bank_mask:0xf bound_ctrl:1
	v_add_f32_dpp v194, v194, v194 row_mirror row_mask:0xf bank_mask:0xf bound_ctrl:1
	v_add_f32_dpp v195, v195, v195 row_mirror row_mask:0xf bank_mask:0xf bound_ctrl:1
	v_fmac_f32_e32 v186, v130, v56
	v_fmac_f32_e32 v187, v130, v57
	v_fmac_f32_e32 v188, v130, v58
	v_fmac_f32_e32 v189, v130, v59
	v_fmac_f32_e32 v190, v131, v56
	v_fmac_f32_e32 v191, v131, v57
	v_fmac_f32_e32 v192, v131, v58
	v_fmac_f32_e32 v193, v131, v59
	v_fmac_f32_e32 v186, v194, v52
	v_fmac_f32_e32 v187, v194, v53
	v_fmac_f32_e32 v188, v194, v54
	v_fmac_f32_e32 v189, v194, v55
	v_fmac_f32_e32 v190, v195, v52
	v_fmac_f32_e32 v191, v195, v53
	v_fmac_f32_e32 v192, v195, v54
	v_fmac_f32_e32 v193, v195, v55
	s_mov_b64 exec, s[8:9]
	ds_write2st64_b64 v161, v[132:133], v[238:239] offset0:15 offset1:14
	s_mov_b64 exec, -1
	ds_read_b128 v[48:51], v152 offset:11008
	ds_read_b128 v[52:55], v152 offset:19200
	ds_read_b128 v[56:59], v152 offset:27392
	ds_read_b128 v[60:63], v152 offset:35584
	ds_read_b64 v[130:131], v69 offset:2816
	s_waitcnt lgkmcnt(11)
	v_mul_f32_e32 v194, v186, v8
	v_mul_f32_e32 v195, v190, v8
	v_mul_f32_e32 v132, v186, v20
	v_mul_f32_e32 v133, v190, v20
	v_fmac_f32_e32 v194, v187, v9
	v_fmac_f32_e32 v195, v191, v9
	v_fmac_f32_e32 v132, v187, v21
	v_fmac_f32_e32 v133, v191, v21
	v_fmac_f32_e32 v194, v188, v10
	v_fmac_f32_e32 v195, v192, v10
	v_fmac_f32_e32 v132, v188, v22
	v_fmac_f32_e32 v133, v192, v22
	v_fmac_f32_e32 v194, v189, v11
	v_fmac_f32_e32 v195, v193, v11
	v_fmac_f32_e32 v132, v189, v23
	v_fmac_f32_e32 v133, v193, v23
	v_add_f32_dpp v194, v194, v194 quad_perm:[1,0,3,2] row_mask:0xf bank_mask:0xf bound_ctrl:1
	v_add_f32_dpp v195, v195, v195 quad_perm:[1,0,3,2] row_mask:0xf bank_mask:0xf bound_ctrl:1
	v_add_f32_dpp v132, v132, v132 quad_perm:[1,0,3,2] row_mask:0xf bank_mask:0xf bound_ctrl:1
	v_add_f32_dpp v133, v133, v133 quad_perm:[1,0,3,2] row_mask:0xf bank_mask:0xf bound_ctrl:1
	v_add_f32_dpp v194, v194, v194 quad_perm:[2,3,0,1] row_mask:0xf bank_mask:0xf bound_ctrl:1
	v_add_f32_dpp v195, v195, v195 quad_perm:[2,3,0,1] row_mask:0xf bank_mask:0xf bound_ctrl:1
	v_add_f32_dpp v132, v132, v132 quad_perm:[2,3,0,1] row_mask:0xf bank_mask:0xf bound_ctrl:1
	v_add_f32_dpp v133, v133, v133 quad_perm:[2,3,0,1] row_mask:0xf bank_mask:0xf bound_ctrl:1
	v_add_f32_dpp v194, v194, v194 row_half_mirror row_mask:0xf bank_mask:0xf bound_ctrl:1
	v_add_f32_dpp v195, v195, v195 row_half_mirror row_mask:0xf bank_mask:0xf bound_ctrl:1
	v_add_f32_dpp v132, v132, v132 row_half_mirror row_mask:0xf bank_mask:0xf bound_ctrl:1
	v_add_f32_dpp v133, v133, v133 row_half_mirror row_mask:0xf bank_mask:0xf bound_ctrl:1
	v_add_f32_dpp v194, v194, v194 row_mirror row_mask:0xf bank_mask:0xf bound_ctrl:1
	v_add_f32_dpp v195, v195, v195 row_mirror row_mask:0xf bank_mask:0xf bound_ctrl:1
	v_fmac_f32_e32 v186, v64, v16
	v_fmac_f32_e32 v187, v64, v17
	v_fmac_f32_e32 v188, v64, v18
	v_fmac_f32_e32 v189, v64, v19
	v_fmac_f32_e32 v190, v65, v16
	v_fmac_f32_e32 v191, v65, v17
	v_fmac_f32_e32 v192, v65, v18
	v_fmac_f32_e32 v193, v65, v19
	v_fmac_f32_e32 v186, v194, v12
	v_fmac_f32_e32 v187, v194, v13
	v_fmac_f32_e32 v188, v194, v14
	v_fmac_f32_e32 v189, v194, v15
	v_fmac_f32_e32 v190, v195, v12
	v_fmac_f32_e32 v191, v195, v13
	v_fmac_f32_e32 v192, v195, v14
	v_fmac_f32_e32 v193, v195, v15
	ds_read_b128 v[8:11], v152 offset:10752
	ds_read_b128 v[12:15], v152 offset:18944
	ds_read_b128 v[16:19], v152 offset:27136
	ds_read_b128 v[20:23], v152 offset:35328
	ds_read_b64 v[64:65], v69 offset:2560
	s_waitcnt lgkmcnt(11)
	v_mul_f32_e32 v194, v186, v28
	v_mul_f32_e32 v195, v190, v28
	v_mul_f32_e32 v238, v186, v40
	v_mul_f32_e32 v239, v190, v40
	v_fmac_f32_e32 v194, v187, v29
	v_fmac_f32_e32 v195, v191, v29
	v_fmac_f32_e32 v238, v187, v41
	v_fmac_f32_e32 v239, v191, v41
	v_fmac_f32_e32 v194, v188, v30
	v_fmac_f32_e32 v195, v192, v30
	v_fmac_f32_e32 v238, v188, v42
	v_fmac_f32_e32 v239, v192, v42
	v_fmac_f32_e32 v194, v189, v31
	v_fmac_f32_e32 v195, v193, v31
	v_fmac_f32_e32 v238, v189, v43
	v_fmac_f32_e32 v239, v193, v43
	v_add_f32_dpp v194, v194, v194 quad_perm:[1,0,3,2] row_mask:0xf bank_mask:0xf bound_ctrl:1
	v_add_f32_dpp v195, v195, v195 quad_perm:[1,0,3,2] row_mask:0xf bank_mask:0xf bound_ctrl:1
	v_add_f32_dpp v238, v238, v238 quad_perm:[1,0,3,2] row_mask:0xf bank_mask:0xf bound_ctrl:1
	v_add_f32_dpp v239, v239, v239 quad_perm:[1,0,3,2] row_mask:0xf bank_mask:0xf bound_ctrl:1
	v_add_f32_dpp v194, v194, v194 quad_perm:[2,3,0,1] row_mask:0xf bank_mask:0xf bound_ctrl:1
	v_add_f32_dpp v195, v195, v195 quad_perm:[2,3,0,1] row_mask:0xf bank_mask:0xf bound_ctrl:1
	v_add_f32_dpp v238, v238, v238 quad_perm:[2,3,0,1] row_mask:0xf bank_mask:0xf bound_ctrl:1
	v_add_f32_dpp v239, v239, v239 quad_perm:[2,3,0,1] row_mask:0xf bank_mask:0xf bound_ctrl:1
	v_add_f32_dpp v194, v194, v194 row_half_mirror row_mask:0xf bank_mask:0xf bound_ctrl:1
	v_add_f32_dpp v195, v195, v195 row_half_mirror row_mask:0xf bank_mask:0xf bound_ctrl:1
	v_add_f32_dpp v238, v238, v238 row_half_mirror row_mask:0xf bank_mask:0xf bound_ctrl:1
	v_add_f32_dpp v239, v239, v239 row_half_mirror row_mask:0xf bank_mask:0xf bound_ctrl:1
	v_add_f32_dpp v194, v194, v194 row_mirror row_mask:0xf bank_mask:0xf bound_ctrl:1
	v_add_f32_dpp v195, v195, v195 row_mirror row_mask:0xf bank_mask:0xf bound_ctrl:1
	v_fmac_f32_e32 v186, v66, v36
	v_fmac_f32_e32 v187, v66, v37
	v_fmac_f32_e32 v188, v66, v38
	v_fmac_f32_e32 v189, v66, v39
	v_fmac_f32_e32 v190, v67, v36
	v_fmac_f32_e32 v191, v67, v37
	v_fmac_f32_e32 v192, v67, v38
	v_fmac_f32_e32 v193, v67, v39
	v_fmac_f32_e32 v186, v194, v32
	v_fmac_f32_e32 v187, v194, v33
	v_fmac_f32_e32 v188, v194, v34
	v_fmac_f32_e32 v189, v194, v35
	v_fmac_f32_e32 v190, v195, v32
	v_fmac_f32_e32 v191, v195, v33
	v_fmac_f32_e32 v192, v195, v34
	v_fmac_f32_e32 v193, v195, v35
	s_mov_b64 exec, s[8:9]
	ds_write2st64_b64 v161, v[132:133], v[238:239] offset0:13 offset1:12
	s_mov_b64 exec, -1
	ds_read_b128 v[28:31], v152 offset:10496
	ds_read_b128 v[32:35], v152 offset:18688
	ds_read_b128 v[36:39], v152 offset:26880
	ds_read_b128 v[40:43], v152 offset:35072
	ds_read_b64 v[66:67], v69 offset:2304
	s_waitcnt lgkmcnt(11)
	v_mul_f32_e32 v194, v186, v48
	v_mul_f32_e32 v195, v190, v48
	v_mul_f32_e32 v132, v186, v60
	v_mul_f32_e32 v133, v190, v60
	v_fmac_f32_e32 v194, v187, v49
	v_fmac_f32_e32 v195, v191, v49
	v_fmac_f32_e32 v132, v187, v61
	v_fmac_f32_e32 v133, v191, v61
	v_fmac_f32_e32 v194, v188, v50
	v_fmac_f32_e32 v195, v192, v50
	v_fmac_f32_e32 v132, v188, v62
	v_fmac_f32_e32 v133, v192, v62
	v_fmac_f32_e32 v194, v189, v51
	v_fmac_f32_e32 v195, v193, v51
	v_fmac_f32_e32 v132, v189, v63
	v_fmac_f32_e32 v133, v193, v63
	v_add_f32_dpp v194, v194, v194 quad_perm:[1,0,3,2] row_mask:0xf bank_mask:0xf bound_ctrl:1
	v_add_f32_dpp v195, v195, v195 quad_perm:[1,0,3,2] row_mask:0xf bank_mask:0xf bound_ctrl:1
	v_add_f32_dpp v132, v132, v132 quad_perm:[1,0,3,2] row_mask:0xf bank_mask:0xf bound_ctrl:1
	v_add_f32_dpp v133, v133, v133 quad_perm:[1,0,3,2] row_mask:0xf bank_mask:0xf bound_ctrl:1
	v_add_f32_dpp v194, v194, v194 quad_perm:[2,3,0,1] row_mask:0xf bank_mask:0xf bound_ctrl:1
	v_add_f32_dpp v195, v195, v195 quad_perm:[2,3,0,1] row_mask:0xf bank_mask:0xf bound_ctrl:1
	v_add_f32_dpp v132, v132, v132 quad_perm:[2,3,0,1] row_mask:0xf bank_mask:0xf bound_ctrl:1
	v_add_f32_dpp v133, v133, v133 quad_perm:[2,3,0,1] row_mask:0xf bank_mask:0xf bound_ctrl:1
	v_add_f32_dpp v194, v194, v194 row_half_mirror row_mask:0xf bank_mask:0xf bound_ctrl:1
	v_add_f32_dpp v195, v195, v195 row_half_mirror row_mask:0xf bank_mask:0xf bound_ctrl:1
	v_add_f32_dpp v132, v132, v132 row_half_mirror row_mask:0xf bank_mask:0xf bound_ctrl:1
	v_add_f32_dpp v133, v133, v133 row_half_mirror row_mask:0xf bank_mask:0xf bound_ctrl:1
	v_add_f32_dpp v194, v194, v194 row_mirror row_mask:0xf bank_mask:0xf bound_ctrl:1
	v_add_f32_dpp v195, v195, v195 row_mirror row_mask:0xf bank_mask:0xf bound_ctrl:1
	v_fmac_f32_e32 v186, v130, v56
	v_fmac_f32_e32 v187, v130, v57
	v_fmac_f32_e32 v188, v130, v58
	v_fmac_f32_e32 v189, v130, v59
	v_fmac_f32_e32 v190, v131, v56
	v_fmac_f32_e32 v191, v131, v57
	v_fmac_f32_e32 v192, v131, v58
	v_fmac_f32_e32 v193, v131, v59
	v_fmac_f32_e32 v186, v194, v52
	v_fmac_f32_e32 v187, v194, v53
	v_fmac_f32_e32 v188, v194, v54
	v_fmac_f32_e32 v189, v194, v55
	v_fmac_f32_e32 v190, v195, v52
	v_fmac_f32_e32 v191, v195, v53
	v_fmac_f32_e32 v192, v195, v54
	v_fmac_f32_e32 v193, v195, v55
	ds_read_b128 v[48:51], v152 offset:10240
	ds_read_b128 v[52:55], v152 offset:18432
	ds_read_b128 v[56:59], v152 offset:26624
	ds_read_b128 v[60:63], v152 offset:34816
	ds_read_b64 v[130:131], v69 offset:2048
	s_waitcnt lgkmcnt(11)
	v_mul_f32_e32 v194, v186, v8
	v_mul_f32_e32 v195, v190, v8
	v_mul_f32_e32 v238, v186, v20
	v_mul_f32_e32 v239, v190, v20
	v_fmac_f32_e32 v194, v187, v9
	v_fmac_f32_e32 v195, v191, v9
	v_fmac_f32_e32 v238, v187, v21
	v_fmac_f32_e32 v239, v191, v21
	v_fmac_f32_e32 v194, v188, v10
	v_fmac_f32_e32 v195, v192, v10
	v_fmac_f32_e32 v238, v188, v22
	v_fmac_f32_e32 v239, v192, v22
	v_fmac_f32_e32 v194, v189, v11
	v_fmac_f32_e32 v195, v193, v11
	v_fmac_f32_e32 v238, v189, v23
	v_fmac_f32_e32 v239, v193, v23
	v_add_f32_dpp v194, v194, v194 quad_perm:[1,0,3,2] row_mask:0xf bank_mask:0xf bound_ctrl:1
	v_add_f32_dpp v195, v195, v195 quad_perm:[1,0,3,2] row_mask:0xf bank_mask:0xf bound_ctrl:1
	v_add_f32_dpp v238, v238, v238 quad_perm:[1,0,3,2] row_mask:0xf bank_mask:0xf bound_ctrl:1
	v_add_f32_dpp v239, v239, v239 quad_perm:[1,0,3,2] row_mask:0xf bank_mask:0xf bound_ctrl:1
	v_add_f32_dpp v194, v194, v194 quad_perm:[2,3,0,1] row_mask:0xf bank_mask:0xf bound_ctrl:1
	v_add_f32_dpp v195, v195, v195 quad_perm:[2,3,0,1] row_mask:0xf bank_mask:0xf bound_ctrl:1
	v_add_f32_dpp v238, v238, v238 quad_perm:[2,3,0,1] row_mask:0xf bank_mask:0xf bound_ctrl:1
	v_add_f32_dpp v239, v239, v239 quad_perm:[2,3,0,1] row_mask:0xf bank_mask:0xf bound_ctrl:1
	v_add_f32_dpp v194, v194, v194 row_half_mirror row_mask:0xf bank_mask:0xf bound_ctrl:1
	v_add_f32_dpp v195, v195, v195 row_half_mirror row_mask:0xf bank_mask:0xf bound_ctrl:1
	v_add_f32_dpp v238, v238, v238 row_half_mirror row_mask:0xf bank_mask:0xf bound_ctrl:1
	v_add_f32_dpp v239, v239, v239 row_half_mirror row_mask:0xf bank_mask:0xf bound_ctrl:1
	v_add_f32_dpp v194, v194, v194 row_mirror row_mask:0xf bank_mask:0xf bound_ctrl:1
	v_add_f32_dpp v195, v195, v195 row_mirror row_mask:0xf bank_mask:0xf bound_ctrl:1
	v_fmac_f32_e32 v186, v64, v16
	v_fmac_f32_e32 v187, v64, v17
	v_fmac_f32_e32 v188, v64, v18
	v_fmac_f32_e32 v189, v64, v19
	v_fmac_f32_e32 v190, v65, v16
	v_fmac_f32_e32 v191, v65, v17
	v_fmac_f32_e32 v192, v65, v18
	v_fmac_f32_e32 v193, v65, v19
	v_fmac_f32_e32 v186, v194, v12
	v_fmac_f32_e32 v187, v194, v13
	v_fmac_f32_e32 v188, v194, v14
	v_fmac_f32_e32 v189, v194, v15
	v_fmac_f32_e32 v190, v195, v12
	v_fmac_f32_e32 v191, v195, v13
	v_fmac_f32_e32 v192, v195, v14
	v_fmac_f32_e32 v193, v195, v15
	s_mov_b64 exec, s[8:9]
	ds_write2st64_b64 v161, v[132:133], v[238:239] offset0:11 offset1:10
	s_mov_b64 exec, -1
	ds_read_b128 v[8:11], v152 offset:9984
	ds_read_b128 v[12:15], v152 offset:18176
	ds_read_b128 v[16:19], v152 offset:26368
	ds_read_b128 v[20:23], v152 offset:34560
	ds_read_b64 v[64:65], v69 offset:1792
	s_waitcnt lgkmcnt(11)
	v_mul_f32_e32 v194, v186, v28
	v_mul_f32_e32 v195, v190, v28
	v_mul_f32_e32 v132, v186, v40
	v_mul_f32_e32 v133, v190, v40
	v_fmac_f32_e32 v194, v187, v29
	v_fmac_f32_e32 v195, v191, v29
	v_fmac_f32_e32 v132, v187, v41
	v_fmac_f32_e32 v133, v191, v41
	v_fmac_f32_e32 v194, v188, v30
	v_fmac_f32_e32 v195, v192, v30
	v_fmac_f32_e32 v132, v188, v42
	v_fmac_f32_e32 v133, v192, v42
	v_fmac_f32_e32 v194, v189, v31
	v_fmac_f32_e32 v195, v193, v31
	v_fmac_f32_e32 v132, v189, v43
	v_fmac_f32_e32 v133, v193, v43
	v_add_f32_dpp v194, v194, v194 quad_perm:[1,0,3,2] row_mask:0xf bank_mask:0xf bound_ctrl:1
	v_add_f32_dpp v195, v195, v195 quad_perm:[1,0,3,2] row_mask:0xf bank_mask:0xf bound_ctrl:1
	v_add_f32_dpp v132, v132, v132 quad_perm:[1,0,3,2] row_mask:0xf bank_mask:0xf bound_ctrl:1
	v_add_f32_dpp v133, v133, v133 quad_perm:[1,0,3,2] row_mask:0xf bank_mask:0xf bound_ctrl:1
	v_add_f32_dpp v194, v194, v194 quad_perm:[2,3,0,1] row_mask:0xf bank_mask:0xf bound_ctrl:1
	v_add_f32_dpp v195, v195, v195 quad_perm:[2,3,0,1] row_mask:0xf bank_mask:0xf bound_ctrl:1
	v_add_f32_dpp v132, v132, v132 quad_perm:[2,3,0,1] row_mask:0xf bank_mask:0xf bound_ctrl:1
	v_add_f32_dpp v133, v133, v133 quad_perm:[2,3,0,1] row_mask:0xf bank_mask:0xf bound_ctrl:1
	v_add_f32_dpp v194, v194, v194 row_half_mirror row_mask:0xf bank_mask:0xf bound_ctrl:1
	v_add_f32_dpp v195, v195, v195 row_half_mirror row_mask:0xf bank_mask:0xf bound_ctrl:1
	v_add_f32_dpp v132, v132, v132 row_half_mirror row_mask:0xf bank_mask:0xf bound_ctrl:1
	v_add_f32_dpp v133, v133, v133 row_half_mirror row_mask:0xf bank_mask:0xf bound_ctrl:1
	v_add_f32_dpp v194, v194, v194 row_mirror row_mask:0xf bank_mask:0xf bound_ctrl:1
	v_add_f32_dpp v195, v195, v195 row_mirror row_mask:0xf bank_mask:0xf bound_ctrl:1
	v_fmac_f32_e32 v186, v66, v36
	v_fmac_f32_e32 v187, v66, v37
	v_fmac_f32_e32 v188, v66, v38
	v_fmac_f32_e32 v189, v66, v39
	v_fmac_f32_e32 v190, v67, v36
	v_fmac_f32_e32 v191, v67, v37
	v_fmac_f32_e32 v192, v67, v38
	v_fmac_f32_e32 v193, v67, v39
	v_fmac_f32_e32 v186, v194, v32
	v_fmac_f32_e32 v187, v194, v33
	v_fmac_f32_e32 v188, v194, v34
	v_fmac_f32_e32 v189, v194, v35
	v_fmac_f32_e32 v190, v195, v32
	v_fmac_f32_e32 v191, v195, v33
	v_fmac_f32_e32 v192, v195, v34
	v_fmac_f32_e32 v193, v195, v35
	ds_read_b128 v[28:31], v152 offset:9728
	ds_read_b128 v[32:35], v152 offset:17920
	ds_read_b128 v[36:39], v152 offset:26112
	ds_read_b128 v[40:43], v152 offset:34304
	ds_read_b64 v[66:67], v69 offset:1536
	s_waitcnt lgkmcnt(11)
	v_mul_f32_e32 v194, v186, v48
	v_mul_f32_e32 v195, v190, v48
	v_mul_f32_e32 v238, v186, v60
	v_mul_f32_e32 v239, v190, v60
	v_fmac_f32_e32 v194, v187, v49
	v_fmac_f32_e32 v195, v191, v49
	v_fmac_f32_e32 v238, v187, v61
	v_fmac_f32_e32 v239, v191, v61
	v_fmac_f32_e32 v194, v188, v50
	v_fmac_f32_e32 v195, v192, v50
	v_fmac_f32_e32 v238, v188, v62
	v_fmac_f32_e32 v239, v192, v62
	v_fmac_f32_e32 v194, v189, v51
	v_fmac_f32_e32 v195, v193, v51
	v_fmac_f32_e32 v238, v189, v63
	v_fmac_f32_e32 v239, v193, v63
	v_add_f32_dpp v194, v194, v194 quad_perm:[1,0,3,2] row_mask:0xf bank_mask:0xf bound_ctrl:1
	v_add_f32_dpp v195, v195, v195 quad_perm:[1,0,3,2] row_mask:0xf bank_mask:0xf bound_ctrl:1
	v_add_f32_dpp v238, v238, v238 quad_perm:[1,0,3,2] row_mask:0xf bank_mask:0xf bound_ctrl:1
	v_add_f32_dpp v239, v239, v239 quad_perm:[1,0,3,2] row_mask:0xf bank_mask:0xf bound_ctrl:1
	v_add_f32_dpp v194, v194, v194 quad_perm:[2,3,0,1] row_mask:0xf bank_mask:0xf bound_ctrl:1
	v_add_f32_dpp v195, v195, v195 quad_perm:[2,3,0,1] row_mask:0xf bank_mask:0xf bound_ctrl:1
	v_add_f32_dpp v238, v238, v238 quad_perm:[2,3,0,1] row_mask:0xf bank_mask:0xf bound_ctrl:1
	v_add_f32_dpp v239, v239, v239 quad_perm:[2,3,0,1] row_mask:0xf bank_mask:0xf bound_ctrl:1
	v_add_f32_dpp v194, v194, v194 row_half_mirror row_mask:0xf bank_mask:0xf bound_ctrl:1
	v_add_f32_dpp v195, v195, v195 row_half_mirror row_mask:0xf bank_mask:0xf bound_ctrl:1
	v_add_f32_dpp v238, v238, v238 row_half_mirror row_mask:0xf bank_mask:0xf bound_ctrl:1
	v_add_f32_dpp v239, v239, v239 row_half_mirror row_mask:0xf bank_mask:0xf bound_ctrl:1
	v_add_f32_dpp v194, v194, v194 row_mirror row_mask:0xf bank_mask:0xf bound_ctrl:1
	v_add_f32_dpp v195, v195, v195 row_mirror row_mask:0xf bank_mask:0xf bound_ctrl:1
	v_fmac_f32_e32 v186, v130, v56
	v_fmac_f32_e32 v187, v130, v57
	v_fmac_f32_e32 v188, v130, v58
	v_fmac_f32_e32 v189, v130, v59
	v_fmac_f32_e32 v190, v131, v56
	v_fmac_f32_e32 v191, v131, v57
	v_fmac_f32_e32 v192, v131, v58
	v_fmac_f32_e32 v193, v131, v59
	v_fmac_f32_e32 v186, v194, v52
	v_fmac_f32_e32 v187, v194, v53
	v_fmac_f32_e32 v188, v194, v54
	v_fmac_f32_e32 v189, v194, v55
	v_fmac_f32_e32 v190, v195, v52
	v_fmac_f32_e32 v191, v195, v53
	v_fmac_f32_e32 v192, v195, v54
	v_fmac_f32_e32 v193, v195, v55
	s_mov_b64 exec, s[8:9]
	ds_write2st64_b64 v161, v[132:133], v[238:239] offset0:9 offset1:8
	s_mov_b64 exec, -1
	ds_read_b128 v[48:51], v152 offset:9472
	ds_read_b128 v[52:55], v152 offset:17664
	ds_read_b128 v[56:59], v152 offset:25856
	ds_read_b128 v[60:63], v152 offset:34048
	ds_read_b64 v[130:131], v69 offset:1280
	s_waitcnt lgkmcnt(11)
	v_mul_f32_e32 v194, v186, v8
	v_mul_f32_e32 v195, v190, v8
	v_mul_f32_e32 v132, v186, v20
	v_mul_f32_e32 v133, v190, v20
	v_fmac_f32_e32 v194, v187, v9
	v_fmac_f32_e32 v195, v191, v9
	v_fmac_f32_e32 v132, v187, v21
	v_fmac_f32_e32 v133, v191, v21
	v_fmac_f32_e32 v194, v188, v10
	v_fmac_f32_e32 v195, v192, v10
	v_fmac_f32_e32 v132, v188, v22
	v_fmac_f32_e32 v133, v192, v22
	v_fmac_f32_e32 v194, v189, v11
	v_fmac_f32_e32 v195, v193, v11
	v_fmac_f32_e32 v132, v189, v23
	v_fmac_f32_e32 v133, v193, v23
	v_add_f32_dpp v194, v194, v194 quad_perm:[1,0,3,2] row_mask:0xf bank_mask:0xf bound_ctrl:1
	v_add_f32_dpp v195, v195, v195 quad_perm:[1,0,3,2] row_mask:0xf bank_mask:0xf bound_ctrl:1
	v_add_f32_dpp v132, v132, v132 quad_perm:[1,0,3,2] row_mask:0xf bank_mask:0xf bound_ctrl:1
	v_add_f32_dpp v133, v133, v133 quad_perm:[1,0,3,2] row_mask:0xf bank_mask:0xf bound_ctrl:1
	v_add_f32_dpp v194, v194, v194 quad_perm:[2,3,0,1] row_mask:0xf bank_mask:0xf bound_ctrl:1
	v_add_f32_dpp v195, v195, v195 quad_perm:[2,3,0,1] row_mask:0xf bank_mask:0xf bound_ctrl:1
	v_add_f32_dpp v132, v132, v132 quad_perm:[2,3,0,1] row_mask:0xf bank_mask:0xf bound_ctrl:1
	v_add_f32_dpp v133, v133, v133 quad_perm:[2,3,0,1] row_mask:0xf bank_mask:0xf bound_ctrl:1
	v_add_f32_dpp v194, v194, v194 row_half_mirror row_mask:0xf bank_mask:0xf bound_ctrl:1
	v_add_f32_dpp v195, v195, v195 row_half_mirror row_mask:0xf bank_mask:0xf bound_ctrl:1
	v_add_f32_dpp v132, v132, v132 row_half_mirror row_mask:0xf bank_mask:0xf bound_ctrl:1
	v_add_f32_dpp v133, v133, v133 row_half_mirror row_mask:0xf bank_mask:0xf bound_ctrl:1
	v_add_f32_dpp v194, v194, v194 row_mirror row_mask:0xf bank_mask:0xf bound_ctrl:1
	v_add_f32_dpp v195, v195, v195 row_mirror row_mask:0xf bank_mask:0xf bound_ctrl:1
	v_fmac_f32_e32 v186, v64, v16
	v_fmac_f32_e32 v187, v64, v17
	v_fmac_f32_e32 v188, v64, v18
	v_fmac_f32_e32 v189, v64, v19
	v_fmac_f32_e32 v190, v65, v16
	v_fmac_f32_e32 v191, v65, v17
	v_fmac_f32_e32 v192, v65, v18
	v_fmac_f32_e32 v193, v65, v19
	v_fmac_f32_e32 v186, v194, v12
	v_fmac_f32_e32 v187, v194, v13
	v_fmac_f32_e32 v188, v194, v14
	v_fmac_f32_e32 v189, v194, v15
	v_fmac_f32_e32 v190, v195, v12
	v_fmac_f32_e32 v191, v195, v13
	v_fmac_f32_e32 v192, v195, v14
	v_fmac_f32_e32 v193, v195, v15
	ds_read_b128 v[8:11], v152 offset:9216
	ds_read_b128 v[12:15], v152 offset:17408
	ds_read_b128 v[16:19], v152 offset:25600
	ds_read_b128 v[20:23], v152 offset:33792
	ds_read_b64 v[64:65], v69 offset:1024
	s_waitcnt lgkmcnt(11)
	v_mul_f32_e32 v194, v186, v28
	v_mul_f32_e32 v195, v190, v28
	v_mul_f32_e32 v238, v186, v40
	v_mul_f32_e32 v239, v190, v40
	v_fmac_f32_e32 v194, v187, v29
	v_fmac_f32_e32 v195, v191, v29
	v_fmac_f32_e32 v238, v187, v41
	v_fmac_f32_e32 v239, v191, v41
	v_fmac_f32_e32 v194, v188, v30
	v_fmac_f32_e32 v195, v192, v30
	v_fmac_f32_e32 v238, v188, v42
	v_fmac_f32_e32 v239, v192, v42
	v_fmac_f32_e32 v194, v189, v31
	v_fmac_f32_e32 v195, v193, v31
	v_fmac_f32_e32 v238, v189, v43
	v_fmac_f32_e32 v239, v193, v43
	v_add_f32_dpp v194, v194, v194 quad_perm:[1,0,3,2] row_mask:0xf bank_mask:0xf bound_ctrl:1
	v_add_f32_dpp v195, v195, v195 quad_perm:[1,0,3,2] row_mask:0xf bank_mask:0xf bound_ctrl:1
	v_add_f32_dpp v238, v238, v238 quad_perm:[1,0,3,2] row_mask:0xf bank_mask:0xf bound_ctrl:1
	v_add_f32_dpp v239, v239, v239 quad_perm:[1,0,3,2] row_mask:0xf bank_mask:0xf bound_ctrl:1
	v_add_f32_dpp v194, v194, v194 quad_perm:[2,3,0,1] row_mask:0xf bank_mask:0xf bound_ctrl:1
	v_add_f32_dpp v195, v195, v195 quad_perm:[2,3,0,1] row_mask:0xf bank_mask:0xf bound_ctrl:1
	v_add_f32_dpp v238, v238, v238 quad_perm:[2,3,0,1] row_mask:0xf bank_mask:0xf bound_ctrl:1
	v_add_f32_dpp v239, v239, v239 quad_perm:[2,3,0,1] row_mask:0xf bank_mask:0xf bound_ctrl:1
	v_add_f32_dpp v194, v194, v194 row_half_mirror row_mask:0xf bank_mask:0xf bound_ctrl:1
	v_add_f32_dpp v195, v195, v195 row_half_mirror row_mask:0xf bank_mask:0xf bound_ctrl:1
	v_add_f32_dpp v238, v238, v238 row_half_mirror row_mask:0xf bank_mask:0xf bound_ctrl:1
	v_add_f32_dpp v239, v239, v239 row_half_mirror row_mask:0xf bank_mask:0xf bound_ctrl:1
	v_add_f32_dpp v194, v194, v194 row_mirror row_mask:0xf bank_mask:0xf bound_ctrl:1
	v_add_f32_dpp v195, v195, v195 row_mirror row_mask:0xf bank_mask:0xf bound_ctrl:1
	v_fmac_f32_e32 v186, v66, v36
	v_fmac_f32_e32 v187, v66, v37
	v_fmac_f32_e32 v188, v66, v38
	v_fmac_f32_e32 v189, v66, v39
	v_fmac_f32_e32 v190, v67, v36
	v_fmac_f32_e32 v191, v67, v37
	v_fmac_f32_e32 v192, v67, v38
	v_fmac_f32_e32 v193, v67, v39
	v_fmac_f32_e32 v186, v194, v32
	v_fmac_f32_e32 v187, v194, v33
	v_fmac_f32_e32 v188, v194, v34
	v_fmac_f32_e32 v189, v194, v35
	v_fmac_f32_e32 v190, v195, v32
	v_fmac_f32_e32 v191, v195, v33
	v_fmac_f32_e32 v192, v195, v34
	v_fmac_f32_e32 v193, v195, v35
	s_mov_b64 exec, s[8:9]
	ds_write2st64_b64 v161, v[132:133], v[238:239] offset0:7 offset1:6
	s_mov_b64 exec, -1
	ds_read_b128 v[28:31], v152 offset:8960
	ds_read_b128 v[32:35], v152 offset:17152
	ds_read_b128 v[36:39], v152 offset:25344
	ds_read_b128 v[40:43], v152 offset:33536
	ds_read_b64 v[66:67], v69 offset:768
	s_waitcnt lgkmcnt(11)
	v_mul_f32_e32 v194, v186, v48
	v_mul_f32_e32 v195, v190, v48
	v_mul_f32_e32 v132, v186, v60
	v_mul_f32_e32 v133, v190, v60
	v_fmac_f32_e32 v194, v187, v49
	v_fmac_f32_e32 v195, v191, v49
	v_fmac_f32_e32 v132, v187, v61
	v_fmac_f32_e32 v133, v191, v61
	v_fmac_f32_e32 v194, v188, v50
	v_fmac_f32_e32 v195, v192, v50
	v_fmac_f32_e32 v132, v188, v62
	v_fmac_f32_e32 v133, v192, v62
	v_fmac_f32_e32 v194, v189, v51
	v_fmac_f32_e32 v195, v193, v51
	v_fmac_f32_e32 v132, v189, v63
	v_fmac_f32_e32 v133, v193, v63
	v_add_f32_dpp v194, v194, v194 quad_perm:[1,0,3,2] row_mask:0xf bank_mask:0xf bound_ctrl:1
	v_add_f32_dpp v195, v195, v195 quad_perm:[1,0,3,2] row_mask:0xf bank_mask:0xf bound_ctrl:1
	v_add_f32_dpp v132, v132, v132 quad_perm:[1,0,3,2] row_mask:0xf bank_mask:0xf bound_ctrl:1
	v_add_f32_dpp v133, v133, v133 quad_perm:[1,0,3,2] row_mask:0xf bank_mask:0xf bound_ctrl:1
	v_add_f32_dpp v194, v194, v194 quad_perm:[2,3,0,1] row_mask:0xf bank_mask:0xf bound_ctrl:1
	v_add_f32_dpp v195, v195, v195 quad_perm:[2,3,0,1] row_mask:0xf bank_mask:0xf bound_ctrl:1
	v_add_f32_dpp v132, v132, v132 quad_perm:[2,3,0,1] row_mask:0xf bank_mask:0xf bound_ctrl:1
	v_add_f32_dpp v133, v133, v133 quad_perm:[2,3,0,1] row_mask:0xf bank_mask:0xf bound_ctrl:1
	v_add_f32_dpp v194, v194, v194 row_half_mirror row_mask:0xf bank_mask:0xf bound_ctrl:1
	v_add_f32_dpp v195, v195, v195 row_half_mirror row_mask:0xf bank_mask:0xf bound_ctrl:1
	v_add_f32_dpp v132, v132, v132 row_half_mirror row_mask:0xf bank_mask:0xf bound_ctrl:1
	v_add_f32_dpp v133, v133, v133 row_half_mirror row_mask:0xf bank_mask:0xf bound_ctrl:1
	v_add_f32_dpp v194, v194, v194 row_mirror row_mask:0xf bank_mask:0xf bound_ctrl:1
	v_add_f32_dpp v195, v195, v195 row_mirror row_mask:0xf bank_mask:0xf bound_ctrl:1
	v_fmac_f32_e32 v186, v130, v56
	v_fmac_f32_e32 v187, v130, v57
	v_fmac_f32_e32 v188, v130, v58
	v_fmac_f32_e32 v189, v130, v59
	v_fmac_f32_e32 v190, v131, v56
	v_fmac_f32_e32 v191, v131, v57
	v_fmac_f32_e32 v192, v131, v58
	v_fmac_f32_e32 v193, v131, v59
	v_fmac_f32_e32 v186, v194, v52
	v_fmac_f32_e32 v187, v194, v53
	v_fmac_f32_e32 v188, v194, v54
	v_fmac_f32_e32 v189, v194, v55
	v_fmac_f32_e32 v190, v195, v52
	v_fmac_f32_e32 v191, v195, v53
	v_fmac_f32_e32 v192, v195, v54
	v_fmac_f32_e32 v193, v195, v55
	ds_read_b128 v[48:51], v152 offset:8704
	ds_read_b128 v[52:55], v152 offset:16896
	ds_read_b128 v[56:59], v152 offset:25088
	ds_read_b128 v[60:63], v152 offset:33280
	ds_read_b64 v[130:131], v69 offset:512
	s_waitcnt lgkmcnt(11)
	v_mul_f32_e32 v194, v186, v8
	v_mul_f32_e32 v195, v190, v8
	v_mul_f32_e32 v238, v186, v20
	v_mul_f32_e32 v239, v190, v20
	v_fmac_f32_e32 v194, v187, v9
	v_fmac_f32_e32 v195, v191, v9
	v_fmac_f32_e32 v238, v187, v21
	v_fmac_f32_e32 v239, v191, v21
	v_fmac_f32_e32 v194, v188, v10
	v_fmac_f32_e32 v195, v192, v10
	v_fmac_f32_e32 v238, v188, v22
	v_fmac_f32_e32 v239, v192, v22
	v_fmac_f32_e32 v194, v189, v11
	v_fmac_f32_e32 v195, v193, v11
	v_fmac_f32_e32 v238, v189, v23
	v_fmac_f32_e32 v239, v193, v23
	v_add_f32_dpp v194, v194, v194 quad_perm:[1,0,3,2] row_mask:0xf bank_mask:0xf bound_ctrl:1
	v_add_f32_dpp v195, v195, v195 quad_perm:[1,0,3,2] row_mask:0xf bank_mask:0xf bound_ctrl:1
	v_add_f32_dpp v238, v238, v238 quad_perm:[1,0,3,2] row_mask:0xf bank_mask:0xf bound_ctrl:1
	v_add_f32_dpp v239, v239, v239 quad_perm:[1,0,3,2] row_mask:0xf bank_mask:0xf bound_ctrl:1
	v_add_f32_dpp v194, v194, v194 quad_perm:[2,3,0,1] row_mask:0xf bank_mask:0xf bound_ctrl:1
	v_add_f32_dpp v195, v195, v195 quad_perm:[2,3,0,1] row_mask:0xf bank_mask:0xf bound_ctrl:1
	v_add_f32_dpp v238, v238, v238 quad_perm:[2,3,0,1] row_mask:0xf bank_mask:0xf bound_ctrl:1
	v_add_f32_dpp v239, v239, v239 quad_perm:[2,3,0,1] row_mask:0xf bank_mask:0xf bound_ctrl:1
	v_add_f32_dpp v194, v194, v194 row_half_mirror row_mask:0xf bank_mask:0xf bound_ctrl:1
	v_add_f32_dpp v195, v195, v195 row_half_mirror row_mask:0xf bank_mask:0xf bound_ctrl:1
	v_add_f32_dpp v238, v238, v238 row_half_mirror row_mask:0xf bank_mask:0xf bound_ctrl:1
	v_add_f32_dpp v239, v239, v239 row_half_mirror row_mask:0xf bank_mask:0xf bound_ctrl:1
	v_add_f32_dpp v194, v194, v194 row_mirror row_mask:0xf bank_mask:0xf bound_ctrl:1
	v_add_f32_dpp v195, v195, v195 row_mirror row_mask:0xf bank_mask:0xf bound_ctrl:1
	v_fmac_f32_e32 v186, v64, v16
	v_fmac_f32_e32 v187, v64, v17
	v_fmac_f32_e32 v188, v64, v18
	v_fmac_f32_e32 v189, v64, v19
	v_fmac_f32_e32 v190, v65, v16
	v_fmac_f32_e32 v191, v65, v17
	v_fmac_f32_e32 v192, v65, v18
	v_fmac_f32_e32 v193, v65, v19
	v_fmac_f32_e32 v186, v194, v12
	v_fmac_f32_e32 v187, v194, v13
	v_fmac_f32_e32 v188, v194, v14
	v_fmac_f32_e32 v189, v194, v15
	v_fmac_f32_e32 v190, v195, v12
	v_fmac_f32_e32 v191, v195, v13
	v_fmac_f32_e32 v192, v195, v14
	v_fmac_f32_e32 v193, v195, v15
	s_mov_b64 exec, s[8:9]
	ds_write2st64_b64 v161, v[132:133], v[238:239] offset0:5 offset1:4
	s_mov_b64 exec, -1
	ds_read_b128 v[8:11], v152 offset:8448
	ds_read_b128 v[12:15], v152 offset:16640
	ds_read_b128 v[16:19], v152 offset:24832
	ds_read_b128 v[20:23], v152 offset:33024
	ds_read_b64 v[64:65], v69 offset:256
	s_waitcnt lgkmcnt(11)
	v_mul_f32_e32 v194, v186, v28
	v_mul_f32_e32 v195, v190, v28
	v_mul_f32_e32 v132, v186, v40
	v_mul_f32_e32 v133, v190, v40
	v_fmac_f32_e32 v194, v187, v29
	v_fmac_f32_e32 v195, v191, v29
	v_fmac_f32_e32 v132, v187, v41
	v_fmac_f32_e32 v133, v191, v41
	v_fmac_f32_e32 v194, v188, v30
	v_fmac_f32_e32 v195, v192, v30
	v_fmac_f32_e32 v132, v188, v42
	v_fmac_f32_e32 v133, v192, v42
	v_fmac_f32_e32 v194, v189, v31
	v_fmac_f32_e32 v195, v193, v31
	v_fmac_f32_e32 v132, v189, v43
	v_fmac_f32_e32 v133, v193, v43
	v_add_f32_dpp v194, v194, v194 quad_perm:[1,0,3,2] row_mask:0xf bank_mask:0xf bound_ctrl:1
	v_add_f32_dpp v195, v195, v195 quad_perm:[1,0,3,2] row_mask:0xf bank_mask:0xf bound_ctrl:1
	v_add_f32_dpp v132, v132, v132 quad_perm:[1,0,3,2] row_mask:0xf bank_mask:0xf bound_ctrl:1
	v_add_f32_dpp v133, v133, v133 quad_perm:[1,0,3,2] row_mask:0xf bank_mask:0xf bound_ctrl:1
	v_add_f32_dpp v194, v194, v194 quad_perm:[2,3,0,1] row_mask:0xf bank_mask:0xf bound_ctrl:1
	v_add_f32_dpp v195, v195, v195 quad_perm:[2,3,0,1] row_mask:0xf bank_mask:0xf bound_ctrl:1
	v_add_f32_dpp v132, v132, v132 quad_perm:[2,3,0,1] row_mask:0xf bank_mask:0xf bound_ctrl:1
	v_add_f32_dpp v133, v133, v133 quad_perm:[2,3,0,1] row_mask:0xf bank_mask:0xf bound_ctrl:1
	v_add_f32_dpp v194, v194, v194 row_half_mirror row_mask:0xf bank_mask:0xf bound_ctrl:1
	v_add_f32_dpp v195, v195, v195 row_half_mirror row_mask:0xf bank_mask:0xf bound_ctrl:1
	v_add_f32_dpp v132, v132, v132 row_half_mirror row_mask:0xf bank_mask:0xf bound_ctrl:1
	v_add_f32_dpp v133, v133, v133 row_half_mirror row_mask:0xf bank_mask:0xf bound_ctrl:1
	v_add_f32_dpp v194, v194, v194 row_mirror row_mask:0xf bank_mask:0xf bound_ctrl:1
	v_add_f32_dpp v195, v195, v195 row_mirror row_mask:0xf bank_mask:0xf bound_ctrl:1
	v_fmac_f32_e32 v186, v66, v36
	v_fmac_f32_e32 v187, v66, v37
	v_fmac_f32_e32 v188, v66, v38
	v_fmac_f32_e32 v189, v66, v39
	v_fmac_f32_e32 v190, v67, v36
	v_fmac_f32_e32 v191, v67, v37
	v_fmac_f32_e32 v192, v67, v38
	v_fmac_f32_e32 v193, v67, v39
	v_fmac_f32_e32 v186, v194, v32
	v_fmac_f32_e32 v187, v194, v33
	v_fmac_f32_e32 v188, v194, v34
	v_fmac_f32_e32 v189, v194, v35
	v_fmac_f32_e32 v190, v195, v32
	v_fmac_f32_e32 v191, v195, v33
	v_fmac_f32_e32 v192, v195, v34
	v_fmac_f32_e32 v193, v195, v35
	ds_read_b128 v[28:31], v152 offset:8192
	ds_read_b128 v[32:35], v152 offset:16384
	ds_read_b128 v[36:39], v152 offset:24576
	ds_read_b128 v[40:43], v152 offset:32768
	ds_read_b64 v[66:67], v69
	s_waitcnt lgkmcnt(11)
	v_mul_f32_e32 v194, v186, v48
	v_mul_f32_e32 v195, v190, v48
	v_mul_f32_e32 v238, v186, v60
	v_mul_f32_e32 v239, v190, v60
	v_fmac_f32_e32 v194, v187, v49
	v_fmac_f32_e32 v195, v191, v49
	v_fmac_f32_e32 v238, v187, v61
	v_fmac_f32_e32 v239, v191, v61
	v_fmac_f32_e32 v194, v188, v50
	v_fmac_f32_e32 v195, v192, v50
	v_fmac_f32_e32 v238, v188, v62
	v_fmac_f32_e32 v239, v192, v62
	v_fmac_f32_e32 v194, v189, v51
	v_fmac_f32_e32 v195, v193, v51
	v_fmac_f32_e32 v238, v189, v63
	v_fmac_f32_e32 v239, v193, v63
	v_add_f32_dpp v194, v194, v194 quad_perm:[1,0,3,2] row_mask:0xf bank_mask:0xf bound_ctrl:1
	v_add_f32_dpp v195, v195, v195 quad_perm:[1,0,3,2] row_mask:0xf bank_mask:0xf bound_ctrl:1
	v_add_f32_dpp v238, v238, v238 quad_perm:[1,0,3,2] row_mask:0xf bank_mask:0xf bound_ctrl:1
	v_add_f32_dpp v239, v239, v239 quad_perm:[1,0,3,2] row_mask:0xf bank_mask:0xf bound_ctrl:1
	v_add_f32_dpp v194, v194, v194 quad_perm:[2,3,0,1] row_mask:0xf bank_mask:0xf bound_ctrl:1
	v_add_f32_dpp v195, v195, v195 quad_perm:[2,3,0,1] row_mask:0xf bank_mask:0xf bound_ctrl:1
	v_add_f32_dpp v238, v238, v238 quad_perm:[2,3,0,1] row_mask:0xf bank_mask:0xf bound_ctrl:1
	v_add_f32_dpp v239, v239, v239 quad_perm:[2,3,0,1] row_mask:0xf bank_mask:0xf bound_ctrl:1
	v_add_f32_dpp v194, v194, v194 row_half_mirror row_mask:0xf bank_mask:0xf bound_ctrl:1
	v_add_f32_dpp v195, v195, v195 row_half_mirror row_mask:0xf bank_mask:0xf bound_ctrl:1
	v_add_f32_dpp v238, v238, v238 row_half_mirror row_mask:0xf bank_mask:0xf bound_ctrl:1
	v_add_f32_dpp v239, v239, v239 row_half_mirror row_mask:0xf bank_mask:0xf bound_ctrl:1
	v_add_f32_dpp v194, v194, v194 row_mirror row_mask:0xf bank_mask:0xf bound_ctrl:1
	v_add_f32_dpp v195, v195, v195 row_mirror row_mask:0xf bank_mask:0xf bound_ctrl:1
	v_fmac_f32_e32 v186, v130, v56
	v_fmac_f32_e32 v187, v130, v57
	v_fmac_f32_e32 v188, v130, v58
	v_fmac_f32_e32 v189, v130, v59
	v_fmac_f32_e32 v190, v131, v56
	v_fmac_f32_e32 v191, v131, v57
	v_fmac_f32_e32 v192, v131, v58
	v_fmac_f32_e32 v193, v131, v59
	v_fmac_f32_e32 v186, v194, v52
	v_fmac_f32_e32 v187, v194, v53
	v_fmac_f32_e32 v188, v194, v54
	v_fmac_f32_e32 v189, v194, v55
	v_fmac_f32_e32 v190, v195, v52
	v_fmac_f32_e32 v191, v195, v53
	v_fmac_f32_e32 v192, v195, v54
	v_fmac_f32_e32 v193, v195, v55
	s_mov_b64 exec, s[8:9]
	ds_write2st64_b64 v161, v[132:133], v[238:239] offset0:3 offset1:2
	s_mov_b64 exec, -1
	s_waitcnt lgkmcnt(6)
	v_mul_f32_e32 v194, v186, v8
	v_mul_f32_e32 v195, v190, v8
	v_mul_f32_e32 v132, v186, v20
	v_mul_f32_e32 v133, v190, v20
	v_fmac_f32_e32 v194, v187, v9
	v_fmac_f32_e32 v195, v191, v9
	v_fmac_f32_e32 v132, v187, v21
	v_fmac_f32_e32 v133, v191, v21
	v_fmac_f32_e32 v194, v188, v10
	v_fmac_f32_e32 v195, v192, v10
	v_fmac_f32_e32 v132, v188, v22
	v_fmac_f32_e32 v133, v192, v22
	v_fmac_f32_e32 v194, v189, v11
	v_fmac_f32_e32 v195, v193, v11
	v_fmac_f32_e32 v132, v189, v23
	v_fmac_f32_e32 v133, v193, v23
	v_add_f32_dpp v194, v194, v194 quad_perm:[1,0,3,2] row_mask:0xf bank_mask:0xf bound_ctrl:1
	v_add_f32_dpp v195, v195, v195 quad_perm:[1,0,3,2] row_mask:0xf bank_mask:0xf bound_ctrl:1
	v_add_f32_dpp v132, v132, v132 quad_perm:[1,0,3,2] row_mask:0xf bank_mask:0xf bound_ctrl:1
	v_add_f32_dpp v133, v133, v133 quad_perm:[1,0,3,2] row_mask:0xf bank_mask:0xf bound_ctrl:1
	v_add_f32_dpp v194, v194, v194 quad_perm:[2,3,0,1] row_mask:0xf bank_mask:0xf bound_ctrl:1
	v_add_f32_dpp v195, v195, v195 quad_perm:[2,3,0,1] row_mask:0xf bank_mask:0xf bound_ctrl:1
	v_add_f32_dpp v132, v132, v132 quad_perm:[2,3,0,1] row_mask:0xf bank_mask:0xf bound_ctrl:1
	v_add_f32_dpp v133, v133, v133 quad_perm:[2,3,0,1] row_mask:0xf bank_mask:0xf bound_ctrl:1
	v_add_f32_dpp v194, v194, v194 row_half_mirror row_mask:0xf bank_mask:0xf bound_ctrl:1
	v_add_f32_dpp v195, v195, v195 row_half_mirror row_mask:0xf bank_mask:0xf bound_ctrl:1
	v_add_f32_dpp v132, v132, v132 row_half_mirror row_mask:0xf bank_mask:0xf bound_ctrl:1
	v_add_f32_dpp v133, v133, v133 row_half_mirror row_mask:0xf bank_mask:0xf bound_ctrl:1
	v_add_f32_dpp v194, v194, v194 row_mirror row_mask:0xf bank_mask:0xf bound_ctrl:1
	v_add_f32_dpp v195, v195, v195 row_mirror row_mask:0xf bank_mask:0xf bound_ctrl:1
	v_fmac_f32_e32 v186, v64, v16
	v_fmac_f32_e32 v187, v64, v17
	v_fmac_f32_e32 v188, v64, v18
	v_fmac_f32_e32 v189, v64, v19
	v_fmac_f32_e32 v190, v65, v16
	v_fmac_f32_e32 v191, v65, v17
	v_fmac_f32_e32 v192, v65, v18
	v_fmac_f32_e32 v193, v65, v19
	v_fmac_f32_e32 v186, v194, v12
	v_fmac_f32_e32 v187, v194, v13
	v_fmac_f32_e32 v188, v194, v14
	v_fmac_f32_e32 v189, v194, v15
	v_fmac_f32_e32 v190, v195, v12
	v_fmac_f32_e32 v191, v195, v13
	v_fmac_f32_e32 v192, v195, v14
	v_fmac_f32_e32 v193, v195, v15
	s_waitcnt lgkmcnt(1)
	v_mul_f32_e32 v194, v186, v28
	v_mul_f32_e32 v195, v190, v28
	v_mul_f32_e32 v238, v186, v40
	v_mul_f32_e32 v239, v190, v40
	v_fmac_f32_e32 v194, v187, v29
	v_fmac_f32_e32 v195, v191, v29
	v_fmac_f32_e32 v238, v187, v41
	v_fmac_f32_e32 v239, v191, v41
	v_fmac_f32_e32 v194, v188, v30
	v_fmac_f32_e32 v195, v192, v30
	v_fmac_f32_e32 v238, v188, v42
	v_fmac_f32_e32 v239, v192, v42
	v_fmac_f32_e32 v194, v189, v31
	v_fmac_f32_e32 v195, v193, v31
	v_fmac_f32_e32 v238, v189, v43
	v_fmac_f32_e32 v239, v193, v43
	v_add_f32_dpp v194, v194, v194 quad_perm:[1,0,3,2] row_mask:0xf bank_mask:0xf bound_ctrl:1
	v_add_f32_dpp v195, v195, v195 quad_perm:[1,0,3,2] row_mask:0xf bank_mask:0xf bound_ctrl:1
	v_add_f32_dpp v238, v238, v238 quad_perm:[1,0,3,2] row_mask:0xf bank_mask:0xf bound_ctrl:1
	v_add_f32_dpp v239, v239, v239 quad_perm:[1,0,3,2] row_mask:0xf bank_mask:0xf bound_ctrl:1
	v_add_f32_dpp v194, v194, v194 quad_perm:[2,3,0,1] row_mask:0xf bank_mask:0xf bound_ctrl:1
	v_add_f32_dpp v195, v195, v195 quad_perm:[2,3,0,1] row_mask:0xf bank_mask:0xf bound_ctrl:1
	v_add_f32_dpp v238, v238, v238 quad_perm:[2,3,0,1] row_mask:0xf bank_mask:0xf bound_ctrl:1
	v_add_f32_dpp v239, v239, v239 quad_perm:[2,3,0,1] row_mask:0xf bank_mask:0xf bound_ctrl:1
	v_add_f32_dpp v194, v194, v194 row_half_mirror row_mask:0xf bank_mask:0xf bound_ctrl:1
	v_add_f32_dpp v195, v195, v195 row_half_mirror row_mask:0xf bank_mask:0xf bound_ctrl:1
	v_add_f32_dpp v238, v238, v238 row_half_mirror row_mask:0xf bank_mask:0xf bound_ctrl:1
	v_add_f32_dpp v239, v239, v239 row_half_mirror row_mask:0xf bank_mask:0xf bound_ctrl:1
	v_add_f32_dpp v194, v194, v194 row_mirror row_mask:0xf bank_mask:0xf bound_ctrl:1
	v_add_f32_dpp v195, v195, v195 row_mirror row_mask:0xf bank_mask:0xf bound_ctrl:1
	v_fmac_f32_e32 v186, v66, v36
	v_fmac_f32_e32 v187, v66, v37
	v_fmac_f32_e32 v188, v66, v38
	v_fmac_f32_e32 v189, v66, v39
	v_fmac_f32_e32 v190, v67, v36
	v_fmac_f32_e32 v191, v67, v37
	v_fmac_f32_e32 v192, v67, v38
	v_fmac_f32_e32 v193, v67, v39
	v_fmac_f32_e32 v186, v194, v32
	v_fmac_f32_e32 v187, v194, v33
	v_fmac_f32_e32 v188, v194, v34
	v_fmac_f32_e32 v189, v194, v35
	v_fmac_f32_e32 v190, v195, v32
	v_fmac_f32_e32 v191, v195, v33
	v_fmac_f32_e32 v192, v195, v34
	v_fmac_f32_e32 v193, v195, v35
	s_mov_b64 exec, s[8:9]
	ds_write2st64_b64 v161, v[132:133], v[238:239] offset0:1 offset1:0
	s_mov_b64 exec, -1
	ds_read_b128 v[4:7], v152 offset:57344
	s_waitcnt lgkmcnt(0)
	v_mul_f32_e32 v186, v186, v4
	v_mul_f32_e32 v187, v187, v5
	v_mul_f32_e32 v188, v188, v6
	v_mul_f32_e32 v189, v189, v7
	v_mul_f32_e32 v190, v190, v4
	v_mul_f32_e32 v191, v191, v5
	v_mul_f32_e32 v192, v192, v6
	v_mul_f32_e32 v193, v193, v7
	s_branch .LBB0_100

.LBB0_213:
	s_or_b64 exec, exec, s[10:11]
	v_add_u32_e32 v227, 0xffffff00, v152
	ds_read_b128 v[198:201], v152 offset:57344
	ds_read_b128 v[202:205], v227 offset:57344
	ds_read_b128 v[206:209], v152 offset:8192
	ds_read_b128 v[210:213], v152 offset:16384
	ds_read_b128 v[214:217], v152 offset:24576
	ds_read_b128 v[218:221], v152 offset:32768
	v_mov_b32_e32 v226, 1.0
	v_cmp_gt_u32_e32 vcc, 16, v134
	s_waitcnt lgkmcnt(4)
	v_rcp_f32_e32 v222, v198
	v_rcp_f32_e32 v223, v199
	v_rcp_f32_e32 v224, v200
	v_rcp_f32_e32 v225, v201
	v_cndmask_b32_e32 v202, v202, v226, vcc
	v_cndmask_b32_e32 v203, v203, v226, vcc
	v_cndmask_b32_e32 v204, v204, v226, vcc
	v_cndmask_b32_e32 v205, v205, v226, vcc
	s_waitcnt lgkmcnt(0)
	v_mul_f32_e32 v206, v206, v202
	v_mul_f32_e32 v207, v207, v203
	v_mul_f32_e32 v208, v208, v204
	v_mul_f32_e32 v209, v209, v205
	v_mul_f32_e32 v218, v218, v202
	v_mul_f32_e32 v219, v219, v203
	v_mul_f32_e32 v220, v220, v204
	v_mul_f32_e32 v221, v221, v205
	v_mul_f32_e32 v210, v210, v222
	v_mul_f32_e32 v211, v211, v223
	v_mul_f32_e32 v212, v212, v224
	v_mul_f32_e32 v213, v213, v225
	v_mul_f32_e32 v214, v214, v222
	v_mul_f32_e32 v215, v215, v223
	v_mul_f32_e32 v216, v216, v224
	v_mul_f32_e32 v217, v217, v225
	ds_write_b128 v152, v[206:209] offset:8192
	ds_write_b128 v152, v[218:221] offset:32768
	ds_write_b128 v152, v[210:213] offset:16384
	ds_write_b128 v152, v[214:217] offset:24576
	s_waitcnt lgkmcnt(0)
	s_barrier
	v_mbcnt_lo_u32_b32 v193, -1, 0
	v_mbcnt_hi_u32_b32 v193, -1, v193
	v_lshlrev_b32_e32 v193, 3, v193
	v_add_u32_e32 v193, 0xe000, v193
	v_cndmask_b32_e64 v192, v193, v146, s[8:9]
	ds_read_b128 v[8:11], v151 offset:8192
	ds_read_b128 v[12:15], v151 offset:16384
	ds_read_b128 v[16:19], v151 offset:24576
	ds_read_b128 v[20:23], v151 offset:32768
	ds_read_b64 v[64:65], v181
	ds_read_b128 v[28:31], v151 offset:8448
	ds_read_b128 v[32:35], v151 offset:16640
	ds_read_b128 v[36:39], v151 offset:24832
	ds_read_b128 v[40:43], v151 offset:33024
	ds_read_b64 v[66:67], v181 offset:256
	ds_read_b128 v[48:51], v151 offset:8704
	ds_read_b128 v[52:55], v151 offset:16896
	ds_read_b128 v[56:59], v151 offset:25088
	ds_read_b128 v[60:63], v151 offset:33280
	ds_read_b64 v[126:127], v181 offset:512
	s_waitcnt lgkmcnt(10)
	v_mul_f32_e32 v190, v182, v8
	v_mul_f32_e32 v191, v186, v8
	v_mul_f32_e32 v128, v182, v20
	v_mul_f32_e32 v129, v186, v20
	v_fmac_f32_e32 v190, v183, v9
	v_fmac_f32_e32 v191, v187, v9
	v_fmac_f32_e32 v128, v183, v21
	v_fmac_f32_e32 v129, v187, v21
	v_fmac_f32_e32 v190, v184, v10
	v_fmac_f32_e32 v191, v188, v10
	v_fmac_f32_e32 v128, v184, v22
	v_fmac_f32_e32 v129, v188, v22
	v_fmac_f32_e32 v190, v185, v11
	v_fmac_f32_e32 v191, v189, v11
	v_fmac_f32_e32 v128, v185, v23
	v_fmac_f32_e32 v129, v189, v23
	v_add_f32_dpp v190, v190, v190 quad_perm:[1,0,3,2] row_mask:0xf bank_mask:0xf bound_ctrl:1
	v_add_f32_dpp v191, v191, v191 quad_perm:[1,0,3,2] row_mask:0xf bank_mask:0xf bound_ctrl:1
	v_add_f32_dpp v128, v128, v128 quad_perm:[1,0,3,2] row_mask:0xf bank_mask:0xf bound_ctrl:1
	v_add_f32_dpp v129, v129, v129 quad_perm:[1,0,3,2] row_mask:0xf bank_mask:0xf bound_ctrl:1
	v_add_f32_dpp v190, v190, v190 quad_perm:[2,3,0,1] row_mask:0xf bank_mask:0xf bound_ctrl:1
	v_add_f32_dpp v191, v191, v191 quad_perm:[2,3,0,1] row_mask:0xf bank_mask:0xf bound_ctrl:1
	v_add_f32_dpp v128, v128, v128 quad_perm:[2,3,0,1] row_mask:0xf bank_mask:0xf bound_ctrl:1
	v_add_f32_dpp v129, v129, v129 quad_perm:[2,3,0,1] row_mask:0xf bank_mask:0xf bound_ctrl:1
	v_add_f32_dpp v190, v190, v190 row_half_mirror row_mask:0xf bank_mask:0xf bound_ctrl:1
	v_add_f32_dpp v191, v191, v191 row_half_mirror row_mask:0xf bank_mask:0xf bound_ctrl:1
	v_add_f32_dpp v128, v128, v128 row_half_mirror row_mask:0xf bank_mask:0xf bound_ctrl:1
	v_add_f32_dpp v129, v129, v129 row_half_mirror row_mask:0xf bank_mask:0xf bound_ctrl:1
	v_add_f32_dpp v190, v190, v190 row_mirror row_mask:0xf bank_mask:0xf bound_ctrl:1
	v_add_f32_dpp v191, v191, v191 row_mirror row_mask:0xf bank_mask:0xf bound_ctrl:1
	v_fmac_f32_e32 v182, v64, v16
	v_fmac_f32_e32 v183, v64, v17
	v_fmac_f32_e32 v184, v64, v18
	v_fmac_f32_e32 v185, v64, v19
	v_fmac_f32_e32 v186, v65, v16
	v_fmac_f32_e32 v187, v65, v17
	v_fmac_f32_e32 v188, v65, v18
	v_fmac_f32_e32 v189, v65, v19
	v_fmac_f32_e32 v182, v190, v12
	v_fmac_f32_e32 v183, v190, v13
	v_fmac_f32_e32 v184, v190, v14
	v_fmac_f32_e32 v185, v190, v15
	v_fmac_f32_e32 v186, v191, v12
	v_fmac_f32_e32 v187, v191, v13
	v_fmac_f32_e32 v188, v191, v14
	v_fmac_f32_e32 v189, v191, v15
	ds_read_b128 v[8:11], v151 offset:8960
	ds_read_b128 v[12:15], v151 offset:17152
	ds_read_b128 v[16:19], v151 offset:25344
	ds_read_b128 v[20:23], v151 offset:33536
	ds_read_b64 v[64:65], v181 offset:768
	s_waitcnt lgkmcnt(10)
	v_mul_f32_e32 v190, v182, v28
	v_mul_f32_e32 v191, v186, v28
	v_mul_f32_e32 v238, v182, v40
	v_mul_f32_e32 v239, v186, v40
	v_fmac_f32_e32 v190, v183, v29
	v_fmac_f32_e32 v191, v187, v29
	v_fmac_f32_e32 v238, v183, v41
	v_fmac_f32_e32 v239, v187, v41
	v_fmac_f32_e32 v190, v184, v30
	v_fmac_f32_e32 v191, v188, v30
	v_fmac_f32_e32 v238, v184, v42
	v_fmac_f32_e32 v239, v188, v42
	v_fmac_f32_e32 v190, v185, v31
	v_fmac_f32_e32 v191, v189, v31
	v_fmac_f32_e32 v238, v185, v43
	v_fmac_f32_e32 v239, v189, v43
	v_add_f32_dpp v190, v190, v190 quad_perm:[1,0,3,2] row_mask:0xf bank_mask:0xf bound_ctrl:1
	v_add_f32_dpp v191, v191, v191 quad_perm:[1,0,3,2] row_mask:0xf bank_mask:0xf bound_ctrl:1
	v_add_f32_dpp v238, v238, v238 quad_perm:[1,0,3,2] row_mask:0xf bank_mask:0xf bound_ctrl:1
	v_add_f32_dpp v239, v239, v239 quad_perm:[1,0,3,2] row_mask:0xf bank_mask:0xf bound_ctrl:1
	v_add_f32_dpp v190, v190, v190 quad_perm:[2,3,0,1] row_mask:0xf bank_mask:0xf bound_ctrl:1
	v_add_f32_dpp v191, v191, v191 quad_perm:[2,3,0,1] row_mask:0xf bank_mask:0xf bound_ctrl:1
	v_add_f32_dpp v238, v238, v238 quad_perm:[2,3,0,1] row_mask:0xf bank_mask:0xf bound_ctrl:1
	v_add_f32_dpp v239, v239, v239 quad_perm:[2,3,0,1] row_mask:0xf bank_mask:0xf bound_ctrl:1
	v_add_f32_dpp v190, v190, v190 row_half_mirror row_mask:0xf bank_mask:0xf bound_ctrl:1
	v_add_f32_dpp v191, v191, v191 row_half_mirror row_mask:0xf bank_mask:0xf bound_ctrl:1
	v_add_f32_dpp v238, v238, v238 row_half_mirror row_mask:0xf bank_mask:0xf bound_ctrl:1
	v_add_f32_dpp v239, v239, v239 row_half_mirror row_mask:0xf bank_mask:0xf bound_ctrl:1
	v_add_f32_dpp v190, v190, v190 row_mirror row_mask:0xf bank_mask:0xf bound_ctrl:1
	v_add_f32_dpp v191, v191, v191 row_mirror row_mask:0xf bank_mask:0xf bound_ctrl:1
	v_fmac_f32_e32 v182, v66, v36
	v_fmac_f32_e32 v183, v66, v37
	v_fmac_f32_e32 v184, v66, v38
	v_fmac_f32_e32 v185, v66, v39
	v_fmac_f32_e32 v186, v67, v36
	v_fmac_f32_e32 v187, v67, v37
	v_fmac_f32_e32 v188, v67, v38
	v_fmac_f32_e32 v189, v67, v39
	v_fmac_f32_e32 v182, v190, v32
	v_fmac_f32_e32 v183, v190, v33
	v_fmac_f32_e32 v184, v190, v34
	v_fmac_f32_e32 v185, v190, v35
	v_fmac_f32_e32 v186, v191, v32
	v_fmac_f32_e32 v187, v191, v33
	v_fmac_f32_e32 v188, v191, v34
	v_fmac_f32_e32 v189, v191, v35
	s_mov_b64 exec, s[8:9]
	ds_write2st64_b64 v146, v[128:129], v[238:239] offset0:0 offset1:1
	s_mov_b64 exec, -1
	ds_read_b128 v[28:31], v151 offset:9216
	ds_read_b128 v[32:35], v151 offset:17408
	ds_read_b128 v[36:39], v151 offset:25600
	ds_read_b128 v[40:43], v151 offset:33792
	ds_read_b64 v[66:67], v181 offset:1024
	s_waitcnt lgkmcnt(11)
	v_mul_f32_e32 v190, v182, v48
	v_mul_f32_e32 v191, v186, v48
	v_mul_f32_e32 v128, v182, v60
	v_mul_f32_e32 v129, v186, v60
	v_fmac_f32_e32 v190, v183, v49
	v_fmac_f32_e32 v191, v187, v49
	v_fmac_f32_e32 v128, v183, v61
	v_fmac_f32_e32 v129, v187, v61
	v_fmac_f32_e32 v190, v184, v50
	v_fmac_f32_e32 v191, v188, v50
	v_fmac_f32_e32 v128, v184, v62
	v_fmac_f32_e32 v129, v188, v62
	v_fmac_f32_e32 v190, v185, v51
	v_fmac_f32_e32 v191, v189, v51
	v_fmac_f32_e32 v128, v185, v63
	v_fmac_f32_e32 v129, v189, v63
	v_add_f32_dpp v190, v190, v190 quad_perm:[1,0,3,2] row_mask:0xf bank_mask:0xf bound_ctrl:1
	v_add_f32_dpp v191, v191, v191 quad_perm:[1,0,3,2] row_mask:0xf bank_mask:0xf bound_ctrl:1
	v_add_f32_dpp v128, v128, v128 quad_perm:[1,0,3,2] row_mask:0xf bank_mask:0xf bound_ctrl:1
	v_add_f32_dpp v129, v129, v129 quad_perm:[1,0,3,2] row_mask:0xf bank_mask:0xf bound_ctrl:1
	v_add_f32_dpp v190, v190, v190 quad_perm:[2,3,0,1] row_mask:0xf bank_mask:0xf bound_ctrl:1
	v_add_f32_dpp v191, v191, v191 quad_perm:[2,3,0,1] row_mask:0xf bank_mask:0xf bound_ctrl:1
	v_add_f32_dpp v128, v128, v128 quad_perm:[2,3,0,1] row_mask:0xf bank_mask:0xf bound_ctrl:1
	v_add_f32_dpp v129, v129, v129 quad_perm:[2,3,0,1] row_mask:0xf bank_mask:0xf bound_ctrl:1
	v_add_f32_dpp v190, v190, v190 row_half_mirror row_mask:0xf bank_mask:0xf bound_ctrl:1
	v_add_f32_dpp v191, v191, v191 row_half_mirror row_mask:0xf bank_mask:0xf bound_ctrl:1
	v_add_f32_dpp v128, v128, v128 row_half_mirror row_mask:0xf bank_mask:0xf bound_ctrl:1
	v_add_f32_dpp v129, v129, v129 row_half_mirror row_mask:0xf bank_mask:0xf bound_ctrl:1
	v_add_f32_dpp v190, v190, v190 row_mirror row_mask:0xf bank_mask:0xf bound_ctrl:1
	v_add_f32_dpp v191, v191, v191 row_mirror row_mask:0xf bank_mask:0xf bound_ctrl:1
	v_fmac_f32_e32 v182, v126, v56
	v_fmac_f32_e32 v183, v126, v57
	v_fmac_f32_e32 v184, v126, v58
	v_fmac_f32_e32 v185, v126, v59
	v_fmac_f32_e32 v186, v127, v56
	v_fmac_f32_e32 v187, v127, v57
	v_fmac_f32_e32 v188, v127, v58
	v_fmac_f32_e32 v189, v127, v59
	v_fmac_f32_e32 v182, v190, v52
	v_fmac_f32_e32 v183, v190, v53
	v_fmac_f32_e32 v184, v190, v54
	v_fmac_f32_e32 v185, v190, v55
	v_fmac_f32_e32 v186, v191, v52
	v_fmac_f32_e32 v187, v191, v53
	v_fmac_f32_e32 v188, v191, v54
	v_fmac_f32_e32 v189, v191, v55
	ds_read_b128 v[48:51], v151 offset:9472
	ds_read_b128 v[52:55], v151 offset:17664
	ds_read_b128 v[56:59], v151 offset:25856
	ds_read_b128 v[60:63], v151 offset:34048
	ds_read_b64 v[126:127], v181 offset:1280
	s_waitcnt lgkmcnt(11)
	v_mul_f32_e32 v190, v182, v8
	v_mul_f32_e32 v191, v186, v8
	v_mul_f32_e32 v238, v182, v20
	v_mul_f32_e32 v239, v186, v20
	v_fmac_f32_e32 v190, v183, v9
	v_fmac_f32_e32 v191, v187, v9
	v_fmac_f32_e32 v238, v183, v21
	v_fmac_f32_e32 v239, v187, v21
	v_fmac_f32_e32 v190, v184, v10
	v_fmac_f32_e32 v191, v188, v10
	v_fmac_f32_e32 v238, v184, v22
	v_fmac_f32_e32 v239, v188, v22
	v_fmac_f32_e32 v190, v185, v11
	v_fmac_f32_e32 v191, v189, v11
	v_fmac_f32_e32 v238, v185, v23
	v_fmac_f32_e32 v239, v189, v23
	v_add_f32_dpp v190, v190, v190 quad_perm:[1,0,3,2] row_mask:0xf bank_mask:0xf bound_ctrl:1
	v_add_f32_dpp v191, v191, v191 quad_perm:[1,0,3,2] row_mask:0xf bank_mask:0xf bound_ctrl:1
	v_add_f32_dpp v238, v238, v238 quad_perm:[1,0,3,2] row_mask:0xf bank_mask:0xf bound_ctrl:1
	v_add_f32_dpp v239, v239, v239 quad_perm:[1,0,3,2] row_mask:0xf bank_mask:0xf bound_ctrl:1
	v_add_f32_dpp v190, v190, v190 quad_perm:[2,3,0,1] row_mask:0xf bank_mask:0xf bound_ctrl:1
	v_add_f32_dpp v191, v191, v191 quad_perm:[2,3,0,1] row_mask:0xf bank_mask:0xf bound_ctrl:1
	v_add_f32_dpp v238, v238, v238 quad_perm:[2,3,0,1] row_mask:0xf bank_mask:0xf bound_ctrl:1
	v_add_f32_dpp v239, v239, v239 quad_perm:[2,3,0,1] row_mask:0xf bank_mask:0xf bound_ctrl:1
	v_add_f32_dpp v190, v190, v190 row_half_mirror row_mask:0xf bank_mask:0xf bound_ctrl:1
	v_add_f32_dpp v191, v191, v191 row_half_mirror row_mask:0xf bank_mask:0xf bound_ctrl:1
	v_add_f32_dpp v238, v238, v238 row_half_mirror row_mask:0xf bank_mask:0xf bound_ctrl:1
	v_add_f32_dpp v239, v239, v239 row_half_mirror row_mask:0xf bank_mask:0xf bound_ctrl:1
	v_add_f32_dpp v190, v190, v190 row_mirror row_mask:0xf bank_mask:0xf bound_ctrl:1
	v_add_f32_dpp v191, v191, v191 row_mirror row_mask:0xf bank_mask:0xf bound_ctrl:1
	v_fmac_f32_e32 v182, v64, v16
	v_fmac_f32_e32 v183, v64, v17
	v_fmac_f32_e32 v184, v64, v18
	v_fmac_f32_e32 v185, v64, v19
	v_fmac_f32_e32 v186, v65, v16
	v_fmac_f32_e32 v187, v65, v17
	v_fmac_f32_e32 v188, v65, v18
	v_fmac_f32_e32 v189, v65, v19
	v_fmac_f32_e32 v182, v190, v12
	v_fmac_f32_e32 v183, v190, v13
	v_fmac_f32_e32 v184, v190, v14
	v_fmac_f32_e32 v185, v190, v15
	v_fmac_f32_e32 v186, v191, v12
	v_fmac_f32_e32 v187, v191, v13
	v_fmac_f32_e32 v188, v191, v14
	v_fmac_f32_e32 v189, v191, v15
	s_mov_b64 exec, s[8:9]
	ds_write2st64_b64 v146, v[128:129], v[238:239] offset0:2 offset1:3
	s_mov_b64 exec, -1
	ds_read_b128 v[8:11], v151 offset:9728
	ds_read_b128 v[12:15], v151 offset:17920
	ds_read_b128 v[16:19], v151 offset:26112
	ds_read_b128 v[20:23], v151 offset:34304
	ds_read_b64 v[64:65], v181 offset:1536
	s_waitcnt lgkmcnt(11)
	v_mul_f32_e32 v190, v182, v28
	v_mul_f32_e32 v191, v186, v28
	v_mul_f32_e32 v128, v182, v40
	v_mul_f32_e32 v129, v186, v40
	v_fmac_f32_e32 v190, v183, v29
	v_fmac_f32_e32 v191, v187, v29
	v_fmac_f32_e32 v128, v183, v41
	v_fmac_f32_e32 v129, v187, v41
	v_fmac_f32_e32 v190, v184, v30
	v_fmac_f32_e32 v191, v188, v30
	v_fmac_f32_e32 v128, v184, v42
	v_fmac_f32_e32 v129, v188, v42
	v_fmac_f32_e32 v190, v185, v31
	v_fmac_f32_e32 v191, v189, v31
	v_fmac_f32_e32 v128, v185, v43
	v_fmac_f32_e32 v129, v189, v43
	v_add_f32_dpp v190, v190, v190 quad_perm:[1,0,3,2] row_mask:0xf bank_mask:0xf bound_ctrl:1
	v_add_f32_dpp v191, v191, v191 quad_perm:[1,0,3,2] row_mask:0xf bank_mask:0xf bound_ctrl:1
	v_add_f32_dpp v128, v128, v128 quad_perm:[1,0,3,2] row_mask:0xf bank_mask:0xf bound_ctrl:1
	v_add_f32_dpp v129, v129, v129 quad_perm:[1,0,3,2] row_mask:0xf bank_mask:0xf bound_ctrl:1
	v_add_f32_dpp v190, v190, v190 quad_perm:[2,3,0,1] row_mask:0xf bank_mask:0xf bound_ctrl:1
	v_add_f32_dpp v191, v191, v191 quad_perm:[2,3,0,1] row_mask:0xf bank_mask:0xf bound_ctrl:1
	v_add_f32_dpp v128, v128, v128 quad_perm:[2,3,0,1] row_mask:0xf bank_mask:0xf bound_ctrl:1
	v_add_f32_dpp v129, v129, v129 quad_perm:[2,3,0,1] row_mask:0xf bank_mask:0xf bound_ctrl:1
	v_add_f32_dpp v190, v190, v190 row_half_mirror row_mask:0xf bank_mask:0xf bound_ctrl:1
	v_add_f32_dpp v191, v191, v191 row_half_mirror row_mask:0xf bank_mask:0xf bound_ctrl:1
	v_add_f32_dpp v128, v128, v128 row_half_mirror row_mask:0xf bank_mask:0xf bound_ctrl:1
	v_add_f32_dpp v129, v129, v129 row_half_mirror row_mask:0xf bank_mask:0xf bound_ctrl:1
	v_add_f32_dpp v190, v190, v190 row_mirror row_mask:0xf bank_mask:0xf bound_ctrl:1
	v_add_f32_dpp v191, v191, v191 row_mirror row_mask:0xf bank_mask:0xf bound_ctrl:1
	v_fmac_f32_e32 v182, v66, v36
	v_fmac_f32_e32 v183, v66, v37
	v_fmac_f32_e32 v184, v66, v38
	v_fmac_f32_e32 v185, v66, v39
	v_fmac_f32_e32 v186, v67, v36
	v_fmac_f32_e32 v187, v67, v37
	v_fmac_f32_e32 v188, v67, v38
	v_fmac_f32_e32 v189, v67, v39
	v_fmac_f32_e32 v182, v190, v32
	v_fmac_f32_e32 v183, v190, v33
	v_fmac_f32_e32 v184, v190, v34
	v_fmac_f32_e32 v185, v190, v35
	v_fmac_f32_e32 v186, v191, v32
	v_fmac_f32_e32 v187, v191, v33
	v_fmac_f32_e32 v188, v191, v34
	v_fmac_f32_e32 v189, v191, v35
	ds_read_b128 v[28:31], v151 offset:9984
	ds_read_b128 v[32:35], v151 offset:18176
	ds_read_b128 v[36:39], v151 offset:26368
	ds_read_b128 v[40:43], v151 offset:34560
	ds_read_b64 v[66:67], v181 offset:1792
	s_waitcnt lgkmcnt(11)
	v_mul_f32_e32 v190, v182, v48
	v_mul_f32_e32 v191, v186, v48
	v_mul_f32_e32 v238, v182, v60
	v_mul_f32_e32 v239, v186, v60
	v_fmac_f32_e32 v190, v183, v49
	v_fmac_f32_e32 v191, v187, v49
	v_fmac_f32_e32 v238, v183, v61
	v_fmac_f32_e32 v239, v187, v61
	v_fmac_f32_e32 v190, v184, v50
	v_fmac_f32_e32 v191, v188, v50
	v_fmac_f32_e32 v238, v184, v62
	v_fmac_f32_e32 v239, v188, v62
	v_fmac_f32_e32 v190, v185, v51
	v_fmac_f32_e32 v191, v189, v51
	v_fmac_f32_e32 v238, v185, v63
	v_fmac_f32_e32 v239, v189, v63
	v_add_f32_dpp v190, v190, v190 quad_perm:[1,0,3,2] row_mask:0xf bank_mask:0xf bound_ctrl:1
	v_add_f32_dpp v191, v191, v191 quad_perm:[1,0,3,2] row_mask:0xf bank_mask:0xf bound_ctrl:1
	v_add_f32_dpp v238, v238, v238 quad_perm:[1,0,3,2] row_mask:0xf bank_mask:0xf bound_ctrl:1
	v_add_f32_dpp v239, v239, v239 quad_perm:[1,0,3,2] row_mask:0xf bank_mask:0xf bound_ctrl:1
	v_add_f32_dpp v190, v190, v190 quad_perm:[2,3,0,1] row_mask:0xf bank_mask:0xf bound_ctrl:1
	v_add_f32_dpp v191, v191, v191 quad_perm:[2,3,0,1] row_mask:0xf bank_mask:0xf bound_ctrl:1
	v_add_f32_dpp v238, v238, v238 quad_perm:[2,3,0,1] row_mask:0xf bank_mask:0xf bound_ctrl:1
	v_add_f32_dpp v239, v239, v239 quad_perm:[2,3,0,1] row_mask:0xf bank_mask:0xf bound_ctrl:1
	v_add_f32_dpp v190, v190, v190 row_half_mirror row_mask:0xf bank_mask:0xf bound_ctrl:1
	v_add_f32_dpp v191, v191, v191 row_half_mirror row_mask:0xf bank_mask:0xf bound_ctrl:1
	v_add_f32_dpp v238, v238, v238 row_half_mirror row_mask:0xf bank_mask:0xf bound_ctrl:1
	v_add_f32_dpp v239, v239, v239 row_half_mirror row_mask:0xf bank_mask:0xf bound_ctrl:1
	v_add_f32_dpp v190, v190, v190 row_mirror row_mask:0xf bank_mask:0xf bound_ctrl:1
	v_add_f32_dpp v191, v191, v191 row_mirror row_mask:0xf bank_mask:0xf bound_ctrl:1
	v_fmac_f32_e32 v182, v126, v56
	v_fmac_f32_e32 v183, v126, v57
	v_fmac_f32_e32 v184, v126, v58
	v_fmac_f32_e32 v185, v126, v59
	v_fmac_f32_e32 v186, v127, v56
	v_fmac_f32_e32 v187, v127, v57
	v_fmac_f32_e32 v188, v127, v58
	v_fmac_f32_e32 v189, v127, v59
	v_fmac_f32_e32 v182, v190, v52
	v_fmac_f32_e32 v183, v190, v53
	v_fmac_f32_e32 v184, v190, v54
	v_fmac_f32_e32 v185, v190, v55
	v_fmac_f32_e32 v186, v191, v52
	v_fmac_f32_e32 v187, v191, v53
	v_fmac_f32_e32 v188, v191, v54
	v_fmac_f32_e32 v189, v191, v55
	s_mov_b64 exec, s[8:9]
	ds_write2st64_b64 v146, v[128:129], v[238:239] offset0:4 offset1:5
	s_mov_b64 exec, -1
	ds_read_b128 v[48:51], v151 offset:10240
	ds_read_b128 v[52:55], v151 offset:18432
	ds_read_b128 v[56:59], v151 offset:26624
	ds_read_b128 v[60:63], v151 offset:34816
	ds_read_b64 v[126:127], v181 offset:2048
	s_waitcnt lgkmcnt(11)
	v_mul_f32_e32 v190, v182, v8
	v_mul_f32_e32 v191, v186, v8
	v_mul_f32_e32 v128, v182, v20
	v_mul_f32_e32 v129, v186, v20
	v_fmac_f32_e32 v190, v183, v9
	v_fmac_f32_e32 v191, v187, v9
	v_fmac_f32_e32 v128, v183, v21
	v_fmac_f32_e32 v129, v187, v21
	v_fmac_f32_e32 v190, v184, v10
	v_fmac_f32_e32 v191, v188, v10
	v_fmac_f32_e32 v128, v184, v22
	v_fmac_f32_e32 v129, v188, v22
	v_fmac_f32_e32 v190, v185, v11
	v_fmac_f32_e32 v191, v189, v11
	v_fmac_f32_e32 v128, v185, v23
	v_fmac_f32_e32 v129, v189, v23
	v_add_f32_dpp v190, v190, v190 quad_perm:[1,0,3,2] row_mask:0xf bank_mask:0xf bound_ctrl:1
	v_add_f32_dpp v191, v191, v191 quad_perm:[1,0,3,2] row_mask:0xf bank_mask:0xf bound_ctrl:1
	v_add_f32_dpp v128, v128, v128 quad_perm:[1,0,3,2] row_mask:0xf bank_mask:0xf bound_ctrl:1
	v_add_f32_dpp v129, v129, v129 quad_perm:[1,0,3,2] row_mask:0xf bank_mask:0xf bound_ctrl:1
	v_add_f32_dpp v190, v190, v190 quad_perm:[2,3,0,1] row_mask:0xf bank_mask:0xf bound_ctrl:1
	v_add_f32_dpp v191, v191, v191 quad_perm:[2,3,0,1] row_mask:0xf bank_mask:0xf bound_ctrl:1
	v_add_f32_dpp v128, v128, v128 quad_perm:[2,3,0,1] row_mask:0xf bank_mask:0xf bound_ctrl:1
	v_add_f32_dpp v129, v129, v129 quad_perm:[2,3,0,1] row_mask:0xf bank_mask:0xf bound_ctrl:1
	v_add_f32_dpp v190, v190, v190 row_half_mirror row_mask:0xf bank_mask:0xf bound_ctrl:1
	v_add_f32_dpp v191, v191, v191 row_half_mirror row_mask:0xf bank_mask:0xf bound_ctrl:1
	v_add_f32_dpp v128, v128, v128 row_half_mirror row_mask:0xf bank_mask:0xf bound_ctrl:1
	v_add_f32_dpp v129, v129, v129 row_half_mirror row_mask:0xf bank_mask:0xf bound_ctrl:1
	v_add_f32_dpp v190, v190, v190 row_mirror row_mask:0xf bank_mask:0xf bound_ctrl:1
	v_add_f32_dpp v191, v191, v191 row_mirror row_mask:0xf bank_mask:0xf bound_ctrl:1
	v_fmac_f32_e32 v182, v64, v16
	v_fmac_f32_e32 v183, v64, v17
	v_fmac_f32_e32 v184, v64, v18
	v_fmac_f32_e32 v185, v64, v19
	v_fmac_f32_e32 v186, v65, v16
	v_fmac_f32_e32 v187, v65, v17
	v_fmac_f32_e32 v188, v65, v18
	v_fmac_f32_e32 v189, v65, v19
	v_fmac_f32_e32 v182, v190, v12
	v_fmac_f32_e32 v183, v190, v13
	v_fmac_f32_e32 v184, v190, v14
	v_fmac_f32_e32 v185, v190, v15
	v_fmac_f32_e32 v186, v191, v12
	v_fmac_f32_e32 v187, v191, v13
	v_fmac_f32_e32 v188, v191, v14
	v_fmac_f32_e32 v189, v191, v15
	ds_read_b128 v[8:11], v151 offset:10496
	ds_read_b128 v[12:15], v151 offset:18688
	ds_read_b128 v[16:19], v151 offset:26880
	ds_read_b128 v[20:23], v151 offset:35072
	ds_read_b64 v[64:65], v181 offset:2304
	s_waitcnt lgkmcnt(11)
	v_mul_f32_e32 v190, v182, v28
	v_mul_f32_e32 v191, v186, v28
	v_mul_f32_e32 v238, v182, v40
	v_mul_f32_e32 v239, v186, v40
	v_fmac_f32_e32 v190, v183, v29
	v_fmac_f32_e32 v191, v187, v29
	v_fmac_f32_e32 v238, v183, v41
	v_fmac_f32_e32 v239, v187, v41
	v_fmac_f32_e32 v190, v184, v30
	v_fmac_f32_e32 v191, v188, v30
	v_fmac_f32_e32 v238, v184, v42
	v_fmac_f32_e32 v239, v188, v42
	v_fmac_f32_e32 v190, v185, v31
	v_fmac_f32_e32 v191, v189, v31
	v_fmac_f32_e32 v238, v185, v43
	v_fmac_f32_e32 v239, v189, v43
	v_add_f32_dpp v190, v190, v190 quad_perm:[1,0,3,2] row_mask:0xf bank_mask:0xf bound_ctrl:1
	v_add_f32_dpp v191, v191, v191 quad_perm:[1,0,3,2] row_mask:0xf bank_mask:0xf bound_ctrl:1
	v_add_f32_dpp v238, v238, v238 quad_perm:[1,0,3,2] row_mask:0xf bank_mask:0xf bound_ctrl:1
	v_add_f32_dpp v239, v239, v239 quad_perm:[1,0,3,2] row_mask:0xf bank_mask:0xf bound_ctrl:1
	v_add_f32_dpp v190, v190, v190 quad_perm:[2,3,0,1] row_mask:0xf bank_mask:0xf bound_ctrl:1
	v_add_f32_dpp v191, v191, v191 quad_perm:[2,3,0,1] row_mask:0xf bank_mask:0xf bound_ctrl:1
	v_add_f32_dpp v238, v238, v238 quad_perm:[2,3,0,1] row_mask:0xf bank_mask:0xf bound_ctrl:1
	v_add_f32_dpp v239, v239, v239 quad_perm:[2,3,0,1] row_mask:0xf bank_mask:0xf bound_ctrl:1
	v_add_f32_dpp v190, v190, v190 row_half_mirror row_mask:0xf bank_mask:0xf bound_ctrl:1
	v_add_f32_dpp v191, v191, v191 row_half_mirror row_mask:0xf bank_mask:0xf bound_ctrl:1
	v_add_f32_dpp v238, v238, v238 row_half_mirror row_mask:0xf bank_mask:0xf bound_ctrl:1
	v_add_f32_dpp v239, v239, v239 row_half_mirror row_mask:0xf bank_mask:0xf bound_ctrl:1
	v_add_f32_dpp v190, v190, v190 row_mirror row_mask:0xf bank_mask:0xf bound_ctrl:1
	v_add_f32_dpp v191, v191, v191 row_mirror row_mask:0xf bank_mask:0xf bound_ctrl:1
	v_fmac_f32_e32 v182, v66, v36
	v_fmac_f32_e32 v183, v66, v37
	v_fmac_f32_e32 v184, v66, v38
	v_fmac_f32_e32 v185, v66, v39
	v_fmac_f32_e32 v186, v67, v36
	v_fmac_f32_e32 v187, v67, v37
	v_fmac_f32_e32 v188, v67, v38
	v_fmac_f32_e32 v189, v67, v39
	v_fmac_f32_e32 v182, v190, v32
	v_fmac_f32_e32 v183, v190, v33
	v_fmac_f32_e32 v184, v190, v34
	v_fmac_f32_e32 v185, v190, v35
	v_fmac_f32_e32 v186, v191, v32
	v_fmac_f32_e32 v187, v191, v33
	v_fmac_f32_e32 v188, v191, v34
	v_fmac_f32_e32 v189, v191, v35
	s_mov_b64 exec, s[8:9]
	ds_write2st64_b64 v146, v[128:129], v[238:239] offset0:6 offset1:7
	s_mov_b64 exec, -1
	ds_read_b128 v[28:31], v151 offset:10752
	ds_read_b128 v[32:35], v151 offset:18944
	ds_read_b128 v[36:39], v151 offset:27136
	ds_read_b128 v[40:43], v151 offset:35328
	ds_read_b64 v[66:67], v181 offset:2560
	s_waitcnt lgkmcnt(11)
	v_mul_f32_e32 v190, v182, v48
	v_mul_f32_e32 v191, v186, v48
	v_mul_f32_e32 v128, v182, v60
	v_mul_f32_e32 v129, v186, v60
	v_fmac_f32_e32 v190, v183, v49
	v_fmac_f32_e32 v191, v187, v49
	v_fmac_f32_e32 v128, v183, v61
	v_fmac_f32_e32 v129, v187, v61
	v_fmac_f32_e32 v190, v184, v50
	v_fmac_f32_e32 v191, v188, v50
	v_fmac_f32_e32 v128, v184, v62
	v_fmac_f32_e32 v129, v188, v62
	v_fmac_f32_e32 v190, v185, v51
	v_fmac_f32_e32 v191, v189, v51
	v_fmac_f32_e32 v128, v185, v63
	v_fmac_f32_e32 v129, v189, v63
	v_add_f32_dpp v190, v190, v190 quad_perm:[1,0,3,2] row_mask:0xf bank_mask:0xf bound_ctrl:1
	v_add_f32_dpp v191, v191, v191 quad_perm:[1,0,3,2] row_mask:0xf bank_mask:0xf bound_ctrl:1
	v_add_f32_dpp v128, v128, v128 quad_perm:[1,0,3,2] row_mask:0xf bank_mask:0xf bound_ctrl:1
	v_add_f32_dpp v129, v129, v129 quad_perm:[1,0,3,2] row_mask:0xf bank_mask:0xf bound_ctrl:1
	v_add_f32_dpp v190, v190, v190 quad_perm:[2,3,0,1] row_mask:0xf bank_mask:0xf bound_ctrl:1
	v_add_f32_dpp v191, v191, v191 quad_perm:[2,3,0,1] row_mask:0xf bank_mask:0xf bound_ctrl:1
	v_add_f32_dpp v128, v128, v128 quad_perm:[2,3,0,1] row_mask:0xf bank_mask:0xf bound_ctrl:1
	v_add_f32_dpp v129, v129, v129 quad_perm:[2,3,0,1] row_mask:0xf bank_mask:0xf bound_ctrl:1
	v_add_f32_dpp v190, v190, v190 row_half_mirror row_mask:0xf bank_mask:0xf bound_ctrl:1
	v_add_f32_dpp v191, v191, v191 row_half_mirror row_mask:0xf bank_mask:0xf bound_ctrl:1
	v_add_f32_dpp v128, v128, v128 row_half_mirror row_mask:0xf bank_mask:0xf bound_ctrl:1
	v_add_f32_dpp v129, v129, v129 row_half_mirror row_mask:0xf bank_mask:0xf bound_ctrl:1
	v_add_f32_dpp v190, v190, v190 row_mirror row_mask:0xf bank_mask:0xf bound_ctrl:1
	v_add_f32_dpp v191, v191, v191 row_mirror row_mask:0xf bank_mask:0xf bound_ctrl:1
	v_fmac_f32_e32 v182, v126, v56
	v_fmac_f32_e32 v183, v126, v57
	v_fmac_f32_e32 v184, v126, v58
	v_fmac_f32_e32 v185, v126, v59
	v_fmac_f32_e32 v186, v127, v56
	v_fmac_f32_e32 v187, v127, v57
	v_fmac_f32_e32 v188, v127, v58
	v_fmac_f32_e32 v189, v127, v59
	v_fmac_f32_e32 v182, v190, v52
	v_fmac_f32_e32 v183, v190, v53
	v_fmac_f32_e32 v184, v190, v54
	v_fmac_f32_e32 v185, v190, v55
	v_fmac_f32_e32 v186, v191, v52
	v_fmac_f32_e32 v187, v191, v53
	v_fmac_f32_e32 v188, v191, v54
	v_fmac_f32_e32 v189, v191, v55
	ds_read_b128 v[48:51], v151 offset:11008
	ds_read_b128 v[52:55], v151 offset:19200
	ds_read_b128 v[56:59], v151 offset:27392
	ds_read_b128 v[60:63], v151 offset:35584
	ds_read_b64 v[126:127], v181 offset:2816
	s_waitcnt lgkmcnt(11)
	v_mul_f32_e32 v190, v182, v8
	v_mul_f32_e32 v191, v186, v8
	v_mul_f32_e32 v238, v182, v20
	v_mul_f32_e32 v239, v186, v20
	v_fmac_f32_e32 v190, v183, v9
	v_fmac_f32_e32 v191, v187, v9
	v_fmac_f32_e32 v238, v183, v21
	v_fmac_f32_e32 v239, v187, v21
	v_fmac_f32_e32 v190, v184, v10
	v_fmac_f32_e32 v191, v188, v10
	v_fmac_f32_e32 v238, v184, v22
	v_fmac_f32_e32 v239, v188, v22
	v_fmac_f32_e32 v190, v185, v11
	v_fmac_f32_e32 v191, v189, v11
	v_fmac_f32_e32 v238, v185, v23
	v_fmac_f32_e32 v239, v189, v23
	v_add_f32_dpp v190, v190, v190 quad_perm:[1,0,3,2] row_mask:0xf bank_mask:0xf bound_ctrl:1
	v_add_f32_dpp v191, v191, v191 quad_perm:[1,0,3,2] row_mask:0xf bank_mask:0xf bound_ctrl:1
	v_add_f32_dpp v238, v238, v238 quad_perm:[1,0,3,2] row_mask:0xf bank_mask:0xf bound_ctrl:1
	v_add_f32_dpp v239, v239, v239 quad_perm:[1,0,3,2] row_mask:0xf bank_mask:0xf bound_ctrl:1
	v_add_f32_dpp v190, v190, v190 quad_perm:[2,3,0,1] row_mask:0xf bank_mask:0xf bound_ctrl:1
	v_add_f32_dpp v191, v191, v191 quad_perm:[2,3,0,1] row_mask:0xf bank_mask:0xf bound_ctrl:1
	v_add_f32_dpp v238, v238, v238 quad_perm:[2,3,0,1] row_mask:0xf bank_mask:0xf bound_ctrl:1
	v_add_f32_dpp v239, v239, v239 quad_perm:[2,3,0,1] row_mask:0xf bank_mask:0xf bound_ctrl:1
	v_add_f32_dpp v190, v190, v190 row_half_mirror row_mask:0xf bank_mask:0xf bound_ctrl:1
	v_add_f32_dpp v191, v191, v191 row_half_mirror row_mask:0xf bank_mask:0xf bound_ctrl:1
	v_add_f32_dpp v238, v238, v238 row_half_mirror row_mask:0xf bank_mask:0xf bound_ctrl:1
	v_add_f32_dpp v239, v239, v239 row_half_mirror row_mask:0xf bank_mask:0xf bound_ctrl:1
	v_add_f32_dpp v190, v190, v190 row_mirror row_mask:0xf bank_mask:0xf bound_ctrl:1
	v_add_f32_dpp v191, v191, v191 row_mirror row_mask:0xf bank_mask:0xf bound_ctrl:1
	v_fmac_f32_e32 v182, v64, v16
	v_fmac_f32_e32 v183, v64, v17
	v_fmac_f32_e32 v184, v64, v18
	v_fmac_f32_e32 v185, v64, v19
	v_fmac_f32_e32 v186, v65, v16
	v_fmac_f32_e32 v187, v65, v17
	v_fmac_f32_e32 v188, v65, v18
	v_fmac_f32_e32 v189, v65, v19
	v_fmac_f32_e32 v182, v190, v12
	v_fmac_f32_e32 v183, v190, v13
	v_fmac_f32_e32 v184, v190, v14
	v_fmac_f32_e32 v185, v190, v15
	v_fmac_f32_e32 v186, v191, v12
	v_fmac_f32_e32 v187, v191, v13
	v_fmac_f32_e32 v188, v191, v14
	v_fmac_f32_e32 v189, v191, v15
	s_mov_b64 exec, s[8:9]
	ds_write2st64_b64 v146, v[128:129], v[238:239] offset0:8 offset1:9
	s_mov_b64 exec, -1
	ds_read_b128 v[8:11], v151 offset:11264
	ds_read_b128 v[12:15], v151 offset:19456
	ds_read_b128 v[16:19], v151 offset:27648
	ds_read_b128 v[20:23], v151 offset:35840
	ds_read_b64 v[64:65], v181 offset:3072
	s_waitcnt lgkmcnt(11)
	v_mul_f32_e32 v190, v182, v28
	v_mul_f32_e32 v191, v186, v28
	v_mul_f32_e32 v128, v182, v40
	v_mul_f32_e32 v129, v186, v40
	v_fmac_f32_e32 v190, v183, v29
	v_fmac_f32_e32 v191, v187, v29
	v_fmac_f32_e32 v128, v183, v41
	v_fmac_f32_e32 v129, v187, v41
	v_fmac_f32_e32 v190, v184, v30
	v_fmac_f32_e32 v191, v188, v30
	v_fmac_f32_e32 v128, v184, v42
	v_fmac_f32_e32 v129, v188, v42
	v_fmac_f32_e32 v190, v185, v31
	v_fmac_f32_e32 v191, v189, v31
	v_fmac_f32_e32 v128, v185, v43
	v_fmac_f32_e32 v129, v189, v43
	v_add_f32_dpp v190, v190, v190 quad_perm:[1,0,3,2] row_mask:0xf bank_mask:0xf bound_ctrl:1
	v_add_f32_dpp v191, v191, v191 quad_perm:[1,0,3,2] row_mask:0xf bank_mask:0xf bound_ctrl:1
	v_add_f32_dpp v128, v128, v128 quad_perm:[1,0,3,2] row_mask:0xf bank_mask:0xf bound_ctrl:1
	v_add_f32_dpp v129, v129, v129 quad_perm:[1,0,3,2] row_mask:0xf bank_mask:0xf bound_ctrl:1
	v_add_f32_dpp v190, v190, v190 quad_perm:[2,3,0,1] row_mask:0xf bank_mask:0xf bound_ctrl:1
	v_add_f32_dpp v191, v191, v191 quad_perm:[2,3,0,1] row_mask:0xf bank_mask:0xf bound_ctrl:1
	v_add_f32_dpp v128, v128, v128 quad_perm:[2,3,0,1] row_mask:0xf bank_mask:0xf bound_ctrl:1
	v_add_f32_dpp v129, v129, v129 quad_perm:[2,3,0,1] row_mask:0xf bank_mask:0xf bound_ctrl:1
	v_add_f32_dpp v190, v190, v190 row_half_mirror row_mask:0xf bank_mask:0xf bound_ctrl:1
	v_add_f32_dpp v191, v191, v191 row_half_mirror row_mask:0xf bank_mask:0xf bound_ctrl:1
	v_add_f32_dpp v128, v128, v128 row_half_mirror row_mask:0xf bank_mask:0xf bound_ctrl:1
	v_add_f32_dpp v129, v129, v129 row_half_mirror row_mask:0xf bank_mask:0xf bound_ctrl:1
	v_add_f32_dpp v190, v190, v190 row_mirror row_mask:0xf bank_mask:0xf bound_ctrl:1
	v_add_f32_dpp v191, v191, v191 row_mirror row_mask:0xf bank_mask:0xf bound_ctrl:1
	v_fmac_f32_e32 v182, v66, v36
	v_fmac_f32_e32 v183, v66, v37
	v_fmac_f32_e32 v184, v66, v38
	v_fmac_f32_e32 v185, v66, v39
	v_fmac_f32_e32 v186, v67, v36
	v_fmac_f32_e32 v187, v67, v37
	v_fmac_f32_e32 v188, v67, v38
	v_fmac_f32_e32 v189, v67, v39
	v_fmac_f32_e32 v182, v190, v32
	v_fmac_f32_e32 v183, v190, v33
	v_fmac_f32_e32 v184, v190, v34
	v_fmac_f32_e32 v185, v190, v35
	v_fmac_f32_e32 v186, v191, v32
	v_fmac_f32_e32 v187, v191, v33
	v_fmac_f32_e32 v188, v191, v34
	v_fmac_f32_e32 v189, v191, v35
	ds_read_b128 v[28:31], v151 offset:11520
	ds_read_b128 v[32:35], v151 offset:19712
	ds_read_b128 v[36:39], v151 offset:27904
	ds_read_b128 v[40:43], v151 offset:36096
	ds_read_b64 v[66:67], v181 offset:3328
	s_waitcnt lgkmcnt(11)
	v_mul_f32_e32 v190, v182, v48
	v_mul_f32_e32 v191, v186, v48
	v_mul_f32_e32 v238, v182, v60
	v_mul_f32_e32 v239, v186, v60
	v_fmac_f32_e32 v190, v183, v49
	v_fmac_f32_e32 v191, v187, v49
	v_fmac_f32_e32 v238, v183, v61
	v_fmac_f32_e32 v239, v187, v61
	v_fmac_f32_e32 v190, v184, v50
	v_fmac_f32_e32 v191, v188, v50
	v_fmac_f32_e32 v238, v184, v62
	v_fmac_f32_e32 v239, v188, v62
	v_fmac_f32_e32 v190, v185, v51
	v_fmac_f32_e32 v191, v189, v51
	v_fmac_f32_e32 v238, v185, v63
	v_fmac_f32_e32 v239, v189, v63
	v_add_f32_dpp v190, v190, v190 quad_perm:[1,0,3,2] row_mask:0xf bank_mask:0xf bound_ctrl:1
	v_add_f32_dpp v191, v191, v191 quad_perm:[1,0,3,2] row_mask:0xf bank_mask:0xf bound_ctrl:1
	v_add_f32_dpp v238, v238, v238 quad_perm:[1,0,3,2] row_mask:0xf bank_mask:0xf bound_ctrl:1
	v_add_f32_dpp v239, v239, v239 quad_perm:[1,0,3,2] row_mask:0xf bank_mask:0xf bound_ctrl:1
	v_add_f32_dpp v190, v190, v190 quad_perm:[2,3,0,1] row_mask:0xf bank_mask:0xf bound_ctrl:1
	v_add_f32_dpp v191, v191, v191 quad_perm:[2,3,0,1] row_mask:0xf bank_mask:0xf bound_ctrl:1
	v_add_f32_dpp v238, v238, v238 quad_perm:[2,3,0,1] row_mask:0xf bank_mask:0xf bound_ctrl:1
	v_add_f32_dpp v239, v239, v239 quad_perm:[2,3,0,1] row_mask:0xf bank_mask:0xf bound_ctrl:1
	v_add_f32_dpp v190, v190, v190 row_half_mirror row_mask:0xf bank_mask:0xf bound_ctrl:1
	v_add_f32_dpp v191, v191, v191 row_half_mirror row_mask:0xf bank_mask:0xf bound_ctrl:1
	v_add_f32_dpp v238, v238, v238 row_half_mirror row_mask:0xf bank_mask:0xf bound_ctrl:1
	v_add_f32_dpp v239, v239, v239 row_half_mirror row_mask:0xf bank_mask:0xf bound_ctrl:1
	v_add_f32_dpp v190, v190, v190 row_mirror row_mask:0xf bank_mask:0xf bound_ctrl:1
	v_add_f32_dpp v191, v191, v191 row_mirror row_mask:0xf bank_mask:0xf bound_ctrl:1
	v_fmac_f32_e32 v182, v126, v56
	v_fmac_f32_e32 v183, v126, v57
	v_fmac_f32_e32 v184, v126, v58
	v_fmac_f32_e32 v185, v126, v59
	v_fmac_f32_e32 v186, v127, v56
	v_fmac_f32_e32 v187, v127, v57
	v_fmac_f32_e32 v188, v127, v58
	v_fmac_f32_e32 v189, v127, v59
	v_fmac_f32_e32 v182, v190, v52
	v_fmac_f32_e32 v183, v190, v53
	v_fmac_f32_e32 v184, v190, v54
	v_fmac_f32_e32 v185, v190, v55
	v_fmac_f32_e32 v186, v191, v52
	v_fmac_f32_e32 v187, v191, v53
	v_fmac_f32_e32 v188, v191, v54
	v_fmac_f32_e32 v189, v191, v55
	s_mov_b64 exec, s[8:9]
	ds_write2st64_b64 v146, v[128:129], v[238:239] offset0:10 offset1:11
	s_mov_b64 exec, -1
	ds_read_b128 v[48:51], v151 offset:11776
	ds_read_b128 v[52:55], v151 offset:19968
	ds_read_b128 v[56:59], v151 offset:28160
	ds_read_b128 v[60:63], v151 offset:36352
	ds_read_b64 v[126:127], v181 offset:3584
	s_waitcnt lgkmcnt(11)
	v_mul_f32_e32 v190, v182, v8
	v_mul_f32_e32 v191, v186, v8
	v_mul_f32_e32 v128, v182, v20
	v_mul_f32_e32 v129, v186, v20
	v_fmac_f32_e32 v190, v183, v9
	v_fmac_f32_e32 v191, v187, v9
	v_fmac_f32_e32 v128, v183, v21
	v_fmac_f32_e32 v129, v187, v21
	v_fmac_f32_e32 v190, v184, v10
	v_fmac_f32_e32 v191, v188, v10
	v_fmac_f32_e32 v128, v184, v22
	v_fmac_f32_e32 v129, v188, v22
	v_fmac_f32_e32 v190, v185, v11
	v_fmac_f32_e32 v191, v189, v11
	v_fmac_f32_e32 v128, v185, v23
	v_fmac_f32_e32 v129, v189, v23
	v_add_f32_dpp v190, v190, v190 quad_perm:[1,0,3,2] row_mask:0xf bank_mask:0xf bound_ctrl:1
	v_add_f32_dpp v191, v191, v191 quad_perm:[1,0,3,2] row_mask:0xf bank_mask:0xf bound_ctrl:1
	v_add_f32_dpp v128, v128, v128 quad_perm:[1,0,3,2] row_mask:0xf bank_mask:0xf bound_ctrl:1
	v_add_f32_dpp v129, v129, v129 quad_perm:[1,0,3,2] row_mask:0xf bank_mask:0xf bound_ctrl:1
	v_add_f32_dpp v190, v190, v190 quad_perm:[2,3,0,1] row_mask:0xf bank_mask:0xf bound_ctrl:1
	v_add_f32_dpp v191, v191, v191 quad_perm:[2,3,0,1] row_mask:0xf bank_mask:0xf bound_ctrl:1
	v_add_f32_dpp v128, v128, v128 quad_perm:[2,3,0,1] row_mask:0xf bank_mask:0xf bound_ctrl:1
	v_add_f32_dpp v129, v129, v129 quad_perm:[2,3,0,1] row_mask:0xf bank_mask:0xf bound_ctrl:1
	v_add_f32_dpp v190, v190, v190 row_half_mirror row_mask:0xf bank_mask:0xf bound_ctrl:1
	v_add_f32_dpp v191, v191, v191 row_half_mirror row_mask:0xf bank_mask:0xf bound_ctrl:1
	v_add_f32_dpp v128, v128, v128 row_half_mirror row_mask:0xf bank_mask:0xf bound_ctrl:1
	v_add_f32_dpp v129, v129, v129 row_half_mirror row_mask:0xf bank_mask:0xf bound_ctrl:1
	v_add_f32_dpp v190, v190, v190 row_mirror row_mask:0xf bank_mask:0xf bound_ctrl:1
	v_add_f32_dpp v191, v191, v191 row_mirror row_mask:0xf bank_mask:0xf bound_ctrl:1
	v_fmac_f32_e32 v182, v64, v16
	v_fmac_f32_e32 v183, v64, v17
	v_fmac_f32_e32 v184, v64, v18
	v_fmac_f32_e32 v185, v64, v19
	v_fmac_f32_e32 v186, v65, v16
	v_fmac_f32_e32 v187, v65, v17
	v_fmac_f32_e32 v188, v65, v18
	v_fmac_f32_e32 v189, v65, v19
	v_fmac_f32_e32 v182, v190, v12
	v_fmac_f32_e32 v183, v190, v13
	v_fmac_f32_e32 v184, v190, v14
	v_fmac_f32_e32 v185, v190, v15
	v_fmac_f32_e32 v186, v191, v12
	v_fmac_f32_e32 v187, v191, v13
	v_fmac_f32_e32 v188, v191, v14
	v_fmac_f32_e32 v189, v191, v15
	ds_read_b128 v[8:11], v151 offset:12032
	ds_read_b128 v[12:15], v151 offset:20224
	ds_read_b128 v[16:19], v151 offset:28416
	ds_read_b128 v[20:23], v151 offset:36608
	ds_read_b64 v[64:65], v181 offset:3840
	s_waitcnt lgkmcnt(11)
	v_mul_f32_e32 v190, v182, v28
	v_mul_f32_e32 v191, v186, v28
	v_mul_f32_e32 v238, v182, v40
	v_mul_f32_e32 v239, v186, v40
	v_fmac_f32_e32 v190, v183, v29
	v_fmac_f32_e32 v191, v187, v29
	v_fmac_f32_e32 v238, v183, v41
	v_fmac_f32_e32 v239, v187, v41
	v_fmac_f32_e32 v190, v184, v30
	v_fmac_f32_e32 v191, v188, v30
	v_fmac_f32_e32 v238, v184, v42
	v_fmac_f32_e32 v239, v188, v42
	v_fmac_f32_e32 v190, v185, v31
	v_fmac_f32_e32 v191, v189, v31
	v_fmac_f32_e32 v238, v185, v43
	v_fmac_f32_e32 v239, v189, v43
	v_add_f32_dpp v190, v190, v190 quad_perm:[1,0,3,2] row_mask:0xf bank_mask:0xf bound_ctrl:1
	v_add_f32_dpp v191, v191, v191 quad_perm:[1,0,3,2] row_mask:0xf bank_mask:0xf bound_ctrl:1
	v_add_f32_dpp v238, v238, v238 quad_perm:[1,0,3,2] row_mask:0xf bank_mask:0xf bound_ctrl:1
	v_add_f32_dpp v239, v239, v239 quad_perm:[1,0,3,2] row_mask:0xf bank_mask:0xf bound_ctrl:1
	v_add_f32_dpp v190, v190, v190 quad_perm:[2,3,0,1] row_mask:0xf bank_mask:0xf bound_ctrl:1
	v_add_f32_dpp v191, v191, v191 quad_perm:[2,3,0,1] row_mask:0xf bank_mask:0xf bound_ctrl:1
	v_add_f32_dpp v238, v238, v238 quad_perm:[2,3,0,1] row_mask:0xf bank_mask:0xf bound_ctrl:1
	v_add_f32_dpp v239, v239, v239 quad_perm:[2,3,0,1] row_mask:0xf bank_mask:0xf bound_ctrl:1
	v_add_f32_dpp v190, v190, v190 row_half_mirror row_mask:0xf bank_mask:0xf bound_ctrl:1
	v_add_f32_dpp v191, v191, v191 row_half_mirror row_mask:0xf bank_mask:0xf bound_ctrl:1
	v_add_f32_dpp v238, v238, v238 row_half_mirror row_mask:0xf bank_mask:0xf bound_ctrl:1
	v_add_f32_dpp v239, v239, v239 row_half_mirror row_mask:0xf bank_mask:0xf bound_ctrl:1
	v_add_f32_dpp v190, v190, v190 row_mirror row_mask:0xf bank_mask:0xf bound_ctrl:1
	v_add_f32_dpp v191, v191, v191 row_mirror row_mask:0xf bank_mask:0xf bound_ctrl:1
	v_fmac_f32_e32 v182, v66, v36
	v_fmac_f32_e32 v183, v66, v37
	v_fmac_f32_e32 v184, v66, v38
	v_fmac_f32_e32 v185, v66, v39
	v_fmac_f32_e32 v186, v67, v36
	v_fmac_f32_e32 v187, v67, v37
	v_fmac_f32_e32 v188, v67, v38
	v_fmac_f32_e32 v189, v67, v39
	v_fmac_f32_e32 v182, v190, v32
	v_fmac_f32_e32 v183, v190, v33
	v_fmac_f32_e32 v184, v190, v34
	v_fmac_f32_e32 v185, v190, v35
	v_fmac_f32_e32 v186, v191, v32
	v_fmac_f32_e32 v187, v191, v33
	v_fmac_f32_e32 v188, v191, v34
	v_fmac_f32_e32 v189, v191, v35
	s_mov_b64 exec, s[8:9]
	ds_write2st64_b64 v146, v[128:129], v[238:239] offset0:12 offset1:13
	s_mov_b64 exec, -1
	ds_read_b128 v[28:31], v151 offset:12288
	ds_read_b128 v[32:35], v151 offset:20480
	ds_read_b128 v[36:39], v151 offset:28672
	ds_read_b128 v[40:43], v151 offset:36864
	ds_read_b64 v[66:67], v181 offset:4096
	s_waitcnt lgkmcnt(11)
	v_mul_f32_e32 v190, v182, v48
	v_mul_f32_e32 v191, v186, v48
	v_mul_f32_e32 v128, v182, v60
	v_mul_f32_e32 v129, v186, v60
	v_fmac_f32_e32 v190, v183, v49
	v_fmac_f32_e32 v191, v187, v49
	v_fmac_f32_e32 v128, v183, v61
	v_fmac_f32_e32 v129, v187, v61
	v_fmac_f32_e32 v190, v184, v50
	v_fmac_f32_e32 v191, v188, v50
	v_fmac_f32_e32 v128, v184, v62
	v_fmac_f32_e32 v129, v188, v62
	v_fmac_f32_e32 v190, v185, v51
	v_fmac_f32_e32 v191, v189, v51
	v_fmac_f32_e32 v128, v185, v63
	v_fmac_f32_e32 v129, v189, v63
	v_add_f32_dpp v190, v190, v190 quad_perm:[1,0,3,2] row_mask:0xf bank_mask:0xf bound_ctrl:1
	v_add_f32_dpp v191, v191, v191 quad_perm:[1,0,3,2] row_mask:0xf bank_mask:0xf bound_ctrl:1
	v_add_f32_dpp v128, v128, v128 quad_perm:[1,0,3,2] row_mask:0xf bank_mask:0xf bound_ctrl:1
	v_add_f32_dpp v129, v129, v129 quad_perm:[1,0,3,2] row_mask:0xf bank_mask:0xf bound_ctrl:1
	v_add_f32_dpp v190, v190, v190 quad_perm:[2,3,0,1] row_mask:0xf bank_mask:0xf bound_ctrl:1
	v_add_f32_dpp v191, v191, v191 quad_perm:[2,3,0,1] row_mask:0xf bank_mask:0xf bound_ctrl:1
	v_add_f32_dpp v128, v128, v128 quad_perm:[2,3,0,1] row_mask:0xf bank_mask:0xf bound_ctrl:1
	v_add_f32_dpp v129, v129, v129 quad_perm:[2,3,0,1] row_mask:0xf bank_mask:0xf bound_ctrl:1
	v_add_f32_dpp v190, v190, v190 row_half_mirror row_mask:0xf bank_mask:0xf bound_ctrl:1
	v_add_f32_dpp v191, v191, v191 row_half_mirror row_mask:0xf bank_mask:0xf bound_ctrl:1
	v_add_f32_dpp v128, v128, v128 row_half_mirror row_mask:0xf bank_mask:0xf bound_ctrl:1
	v_add_f32_dpp v129, v129, v129 row_half_mirror row_mask:0xf bank_mask:0xf bound_ctrl:1
	v_add_f32_dpp v190, v190, v190 row_mirror row_mask:0xf bank_mask:0xf bound_ctrl:1
	v_add_f32_dpp v191, v191, v191 row_mirror row_mask:0xf bank_mask:0xf bound_ctrl:1
	v_fmac_f32_e32 v182, v126, v56
	v_fmac_f32_e32 v183, v126, v57
	v_fmac_f32_e32 v184, v126, v58
	v_fmac_f32_e32 v185, v126, v59
	v_fmac_f32_e32 v186, v127, v56
	v_fmac_f32_e32 v187, v127, v57
	v_fmac_f32_e32 v188, v127, v58
	v_fmac_f32_e32 v189, v127, v59
	v_fmac_f32_e32 v182, v190, v52
	v_fmac_f32_e32 v183, v190, v53
	v_fmac_f32_e32 v184, v190, v54
	v_fmac_f32_e32 v185, v190, v55
	v_fmac_f32_e32 v186, v191, v52
	v_fmac_f32_e32 v187, v191, v53
	v_fmac_f32_e32 v188, v191, v54
	v_fmac_f32_e32 v189, v191, v55
	ds_read_b128 v[48:51], v151 offset:12544
	ds_read_b128 v[52:55], v151 offset:20736
	ds_read_b128 v[56:59], v151 offset:28928
	ds_read_b128 v[60:63], v151 offset:37120
	ds_read_b64 v[126:127], v181 offset:4352
	s_waitcnt lgkmcnt(11)
	v_mul_f32_e32 v190, v182, v8
	v_mul_f32_e32 v191, v186, v8
	v_mul_f32_e32 v238, v182, v20
	v_mul_f32_e32 v239, v186, v20
	v_fmac_f32_e32 v190, v183, v9
	v_fmac_f32_e32 v191, v187, v9
	v_fmac_f32_e32 v238, v183, v21
	v_fmac_f32_e32 v239, v187, v21
	v_fmac_f32_e32 v190, v184, v10
	v_fmac_f32_e32 v191, v188, v10
	v_fmac_f32_e32 v238, v184, v22
	v_fmac_f32_e32 v239, v188, v22
	v_fmac_f32_e32 v190, v185, v11
	v_fmac_f32_e32 v191, v189, v11
	v_fmac_f32_e32 v238, v185, v23
	v_fmac_f32_e32 v239, v189, v23
	v_add_f32_dpp v190, v190, v190 quad_perm:[1,0,3,2] row_mask:0xf bank_mask:0xf bound_ctrl:1
	v_add_f32_dpp v191, v191, v191 quad_perm:[1,0,3,2] row_mask:0xf bank_mask:0xf bound_ctrl:1
	v_add_f32_dpp v238, v238, v238 quad_perm:[1,0,3,2] row_mask:0xf bank_mask:0xf bound_ctrl:1
	v_add_f32_dpp v239, v239, v239 quad_perm:[1,0,3,2] row_mask:0xf bank_mask:0xf bound_ctrl:1
	v_add_f32_dpp v190, v190, v190 quad_perm:[2,3,0,1] row_mask:0xf bank_mask:0xf bound_ctrl:1
	v_add_f32_dpp v191, v191, v191 quad_perm:[2,3,0,1] row_mask:0xf bank_mask:0xf bound_ctrl:1
	v_add_f32_dpp v238, v238, v238 quad_perm:[2,3,0,1] row_mask:0xf bank_mask:0xf bound_ctrl:1
	v_add_f32_dpp v239, v239, v239 quad_perm:[2,3,0,1] row_mask:0xf bank_mask:0xf bound_ctrl:1
	v_add_f32_dpp v190, v190, v190 row_half_mirror row_mask:0xf bank_mask:0xf bound_ctrl:1
	v_add_f32_dpp v191, v191, v191 row_half_mirror row_mask:0xf bank_mask:0xf bound_ctrl:1
	v_add_f32_dpp v238, v238, v238 row_half_mirror row_mask:0xf bank_mask:0xf bound_ctrl:1
	v_add_f32_dpp v239, v239, v239 row_half_mirror row_mask:0xf bank_mask:0xf bound_ctrl:1
	v_add_f32_dpp v190, v190, v190 row_mirror row_mask:0xf bank_mask:0xf bound_ctrl:1
	v_add_f32_dpp v191, v191, v191 row_mirror row_mask:0xf bank_mask:0xf bound_ctrl:1
	v_fmac_f32_e32 v182, v64, v16
	v_fmac_f32_e32 v183, v64, v17
	v_fmac_f32_e32 v184, v64, v18
	v_fmac_f32_e32 v185, v64, v19
	v_fmac_f32_e32 v186, v65, v16
	v_fmac_f32_e32 v187, v65, v17
	v_fmac_f32_e32 v188, v65, v18
	v_fmac_f32_e32 v189, v65, v19
	v_fmac_f32_e32 v182, v190, v12
	v_fmac_f32_e32 v183, v190, v13
	v_fmac_f32_e32 v184, v190, v14
	v_fmac_f32_e32 v185, v190, v15
	v_fmac_f32_e32 v186, v191, v12
	v_fmac_f32_e32 v187, v191, v13
	v_fmac_f32_e32 v188, v191, v14
	v_fmac_f32_e32 v189, v191, v15
	s_mov_b64 exec, s[8:9]
	ds_write2st64_b64 v146, v[128:129], v[238:239] offset0:14 offset1:15
	s_mov_b64 exec, -1
	ds_read_b128 v[8:11], v151 offset:12800
	ds_read_b128 v[12:15], v151 offset:20992
	ds_read_b128 v[16:19], v151 offset:29184
	ds_read_b128 v[20:23], v151 offset:37376
	ds_read_b64 v[64:65], v181 offset:4608
	s_waitcnt lgkmcnt(11)
	v_mul_f32_e32 v190, v182, v28
	v_mul_f32_e32 v191, v186, v28
	v_mul_f32_e32 v128, v182, v40
	v_mul_f32_e32 v129, v186, v40
	v_fmac_f32_e32 v190, v183, v29
	v_fmac_f32_e32 v191, v187, v29
	v_fmac_f32_e32 v128, v183, v41
	v_fmac_f32_e32 v129, v187, v41
	v_fmac_f32_e32 v190, v184, v30
	v_fmac_f32_e32 v191, v188, v30
	v_fmac_f32_e32 v128, v184, v42
	v_fmac_f32_e32 v129, v188, v42
	v_fmac_f32_e32 v190, v185, v31
	v_fmac_f32_e32 v191, v189, v31
	v_fmac_f32_e32 v128, v185, v43
	v_fmac_f32_e32 v129, v189, v43
	v_add_f32_dpp v190, v190, v190 quad_perm:[1,0,3,2] row_mask:0xf bank_mask:0xf bound_ctrl:1
	v_add_f32_dpp v191, v191, v191 quad_perm:[1,0,3,2] row_mask:0xf bank_mask:0xf bound_ctrl:1
	v_add_f32_dpp v128, v128, v128 quad_perm:[1,0,3,2] row_mask:0xf bank_mask:0xf bound_ctrl:1
	v_add_f32_dpp v129, v129, v129 quad_perm:[1,0,3,2] row_mask:0xf bank_mask:0xf bound_ctrl:1
	v_add_f32_dpp v190, v190, v190 quad_perm:[2,3,0,1] row_mask:0xf bank_mask:0xf bound_ctrl:1
	v_add_f32_dpp v191, v191, v191 quad_perm:[2,3,0,1] row_mask:0xf bank_mask:0xf bound_ctrl:1
	v_add_f32_dpp v128, v128, v128 quad_perm:[2,3,0,1] row_mask:0xf bank_mask:0xf bound_ctrl:1
	v_add_f32_dpp v129, v129, v129 quad_perm:[2,3,0,1] row_mask:0xf bank_mask:0xf bound_ctrl:1
	v_add_f32_dpp v190, v190, v190 row_half_mirror row_mask:0xf bank_mask:0xf bound_ctrl:1
	v_add_f32_dpp v191, v191, v191 row_half_mirror row_mask:0xf bank_mask:0xf bound_ctrl:1
	v_add_f32_dpp v128, v128, v128 row_half_mirror row_mask:0xf bank_mask:0xf bound_ctrl:1
	v_add_f32_dpp v129, v129, v129 row_half_mirror row_mask:0xf bank_mask:0xf bound_ctrl:1
	v_add_f32_dpp v190, v190, v190 row_mirror row_mask:0xf bank_mask:0xf bound_ctrl:1
	v_add_f32_dpp v191, v191, v191 row_mirror row_mask:0xf bank_mask:0xf bound_ctrl:1
	v_fmac_f32_e32 v182, v66, v36
	v_fmac_f32_e32 v183, v66, v37
	v_fmac_f32_e32 v184, v66, v38
	v_fmac_f32_e32 v185, v66, v39
	v_fmac_f32_e32 v186, v67, v36
	v_fmac_f32_e32 v187, v67, v37
	v_fmac_f32_e32 v188, v67, v38
	v_fmac_f32_e32 v189, v67, v39
	v_fmac_f32_e32 v182, v190, v32
	v_fmac_f32_e32 v183, v190, v33
	v_fmac_f32_e32 v184, v190, v34
	v_fmac_f32_e32 v185, v190, v35
	v_fmac_f32_e32 v186, v191, v32
	v_fmac_f32_e32 v187, v191, v33
	v_fmac_f32_e32 v188, v191, v34
	v_fmac_f32_e32 v189, v191, v35
	ds_read_b128 v[28:31], v151 offset:13056
	ds_read_b128 v[32:35], v151 offset:21248
	ds_read_b128 v[36:39], v151 offset:29440
	ds_read_b128 v[40:43], v151 offset:37632
	ds_read_b64 v[66:67], v181 offset:4864
	s_waitcnt lgkmcnt(11)
	v_mul_f32_e32 v190, v182, v48
	v_mul_f32_e32 v191, v186, v48
	v_mul_f32_e32 v238, v182, v60
	v_mul_f32_e32 v239, v186, v60
	v_fmac_f32_e32 v190, v183, v49
	v_fmac_f32_e32 v191, v187, v49
	v_fmac_f32_e32 v238, v183, v61
	v_fmac_f32_e32 v239, v187, v61
	v_fmac_f32_e32 v190, v184, v50
	v_fmac_f32_e32 v191, v188, v50
	v_fmac_f32_e32 v238, v184, v62
	v_fmac_f32_e32 v239, v188, v62
	v_fmac_f32_e32 v190, v185, v51
	v_fmac_f32_e32 v191, v189, v51
	v_fmac_f32_e32 v238, v185, v63
	v_fmac_f32_e32 v239, v189, v63
	v_add_f32_dpp v190, v190, v190 quad_perm:[1,0,3,2] row_mask:0xf bank_mask:0xf bound_ctrl:1
	v_add_f32_dpp v191, v191, v191 quad_perm:[1,0,3,2] row_mask:0xf bank_mask:0xf bound_ctrl:1
	v_add_f32_dpp v238, v238, v238 quad_perm:[1,0,3,2] row_mask:0xf bank_mask:0xf bound_ctrl:1
	v_add_f32_dpp v239, v239, v239 quad_perm:[1,0,3,2] row_mask:0xf bank_mask:0xf bound_ctrl:1
	v_add_f32_dpp v190, v190, v190 quad_perm:[2,3,0,1] row_mask:0xf bank_mask:0xf bound_ctrl:1
	v_add_f32_dpp v191, v191, v191 quad_perm:[2,3,0,1] row_mask:0xf bank_mask:0xf bound_ctrl:1
	v_add_f32_dpp v238, v238, v238 quad_perm:[2,3,0,1] row_mask:0xf bank_mask:0xf bound_ctrl:1
	v_add_f32_dpp v239, v239, v239 quad_perm:[2,3,0,1] row_mask:0xf bank_mask:0xf bound_ctrl:1
	v_add_f32_dpp v190, v190, v190 row_half_mirror row_mask:0xf bank_mask:0xf bound_ctrl:1
	v_add_f32_dpp v191, v191, v191 row_half_mirror row_mask:0xf bank_mask:0xf bound_ctrl:1
	v_add_f32_dpp v238, v238, v238 row_half_mirror row_mask:0xf bank_mask:0xf bound_ctrl:1
	v_add_f32_dpp v239, v239, v239 row_half_mirror row_mask:0xf bank_mask:0xf bound_ctrl:1
	v_add_f32_dpp v190, v190, v190 row_mirror row_mask:0xf bank_mask:0xf bound_ctrl:1
	v_add_f32_dpp v191, v191, v191 row_mirror row_mask:0xf bank_mask:0xf bound_ctrl:1
	v_fmac_f32_e32 v182, v126, v56
	v_fmac_f32_e32 v183, v126, v57
	v_fmac_f32_e32 v184, v126, v58
	v_fmac_f32_e32 v185, v126, v59
	v_fmac_f32_e32 v186, v127, v56
	v_fmac_f32_e32 v187, v127, v57
	v_fmac_f32_e32 v188, v127, v58
	v_fmac_f32_e32 v189, v127, v59
	v_fmac_f32_e32 v182, v190, v52
	v_fmac_f32_e32 v183, v190, v53
	v_fmac_f32_e32 v184, v190, v54
	v_fmac_f32_e32 v185, v190, v55
	v_fmac_f32_e32 v186, v191, v52
	v_fmac_f32_e32 v187, v191, v53
	v_fmac_f32_e32 v188, v191, v54
	v_fmac_f32_e32 v189, v191, v55
	s_mov_b64 exec, s[8:9]
	ds_write2st64_b64 v146, v[128:129], v[238:239] offset0:16 offset1:17
	s_mov_b64 exec, -1
	ds_read_b128 v[48:51], v151 offset:13312
	ds_read_b128 v[52:55], v151 offset:21504
	ds_read_b128 v[56:59], v151 offset:29696
	ds_read_b128 v[60:63], v151 offset:37888
	ds_read_b64 v[126:127], v181 offset:5120
	s_waitcnt lgkmcnt(11)
	v_mul_f32_e32 v190, v182, v8
	v_mul_f32_e32 v191, v186, v8
	v_mul_f32_e32 v128, v182, v20
	v_mul_f32_e32 v129, v186, v20
	v_fmac_f32_e32 v190, v183, v9
	v_fmac_f32_e32 v191, v187, v9
	v_fmac_f32_e32 v128, v183, v21
	v_fmac_f32_e32 v129, v187, v21
	v_fmac_f32_e32 v190, v184, v10
	v_fmac_f32_e32 v191, v188, v10
	v_fmac_f32_e32 v128, v184, v22
	v_fmac_f32_e32 v129, v188, v22
	v_fmac_f32_e32 v190, v185, v11
	v_fmac_f32_e32 v191, v189, v11
	v_fmac_f32_e32 v128, v185, v23
	v_fmac_f32_e32 v129, v189, v23
	v_add_f32_dpp v190, v190, v190 quad_perm:[1,0,3,2] row_mask:0xf bank_mask:0xf bound_ctrl:1
	v_add_f32_dpp v191, v191, v191 quad_perm:[1,0,3,2] row_mask:0xf bank_mask:0xf bound_ctrl:1
	v_add_f32_dpp v128, v128, v128 quad_perm:[1,0,3,2] row_mask:0xf bank_mask:0xf bound_ctrl:1
	v_add_f32_dpp v129, v129, v129 quad_perm:[1,0,3,2] row_mask:0xf bank_mask:0xf bound_ctrl:1
	v_add_f32_dpp v190, v190, v190 quad_perm:[2,3,0,1] row_mask:0xf bank_mask:0xf bound_ctrl:1
	v_add_f32_dpp v191, v191, v191 quad_perm:[2,3,0,1] row_mask:0xf bank_mask:0xf bound_ctrl:1
	v_add_f32_dpp v128, v128, v128 quad_perm:[2,3,0,1] row_mask:0xf bank_mask:0xf bound_ctrl:1
	v_add_f32_dpp v129, v129, v129 quad_perm:[2,3,0,1] row_mask:0xf bank_mask:0xf bound_ctrl:1
	v_add_f32_dpp v190, v190, v190 row_half_mirror row_mask:0xf bank_mask:0xf bound_ctrl:1
	v_add_f32_dpp v191, v191, v191 row_half_mirror row_mask:0xf bank_mask:0xf bound_ctrl:1
	v_add_f32_dpp v128, v128, v128 row_half_mirror row_mask:0xf bank_mask:0xf bound_ctrl:1
	v_add_f32_dpp v129, v129, v129 row_half_mirror row_mask:0xf bank_mask:0xf bound_ctrl:1
	v_add_f32_dpp v190, v190, v190 row_mirror row_mask:0xf bank_mask:0xf bound_ctrl:1
	v_add_f32_dpp v191, v191, v191 row_mirror row_mask:0xf bank_mask:0xf bound_ctrl:1
	v_fmac_f32_e32 v182, v64, v16
	v_fmac_f32_e32 v183, v64, v17
	v_fmac_f32_e32 v184, v64, v18
	v_fmac_f32_e32 v185, v64, v19
	v_fmac_f32_e32 v186, v65, v16
	v_fmac_f32_e32 v187, v65, v17
	v_fmac_f32_e32 v188, v65, v18
	v_fmac_f32_e32 v189, v65, v19
	v_fmac_f32_e32 v182, v190, v12
	v_fmac_f32_e32 v183, v190, v13
	v_fmac_f32_e32 v184, v190, v14
	v_fmac_f32_e32 v185, v190, v15
	v_fmac_f32_e32 v186, v191, v12
	v_fmac_f32_e32 v187, v191, v13
	v_fmac_f32_e32 v188, v191, v14
	v_fmac_f32_e32 v189, v191, v15
	ds_read_b128 v[8:11], v151 offset:13568
	ds_read_b128 v[12:15], v151 offset:21760
	ds_read_b128 v[16:19], v151 offset:29952
	ds_read_b128 v[20:23], v151 offset:38144
	ds_read_b64 v[64:65], v181 offset:5376
	s_waitcnt lgkmcnt(11)
	v_mul_f32_e32 v190, v182, v28
	v_mul_f32_e32 v191, v186, v28
	v_mul_f32_e32 v238, v182, v40
	v_mul_f32_e32 v239, v186, v40
	v_fmac_f32_e32 v190, v183, v29
	v_fmac_f32_e32 v191, v187, v29
	v_fmac_f32_e32 v238, v183, v41
	v_fmac_f32_e32 v239, v187, v41
	v_fmac_f32_e32 v190, v184, v30
	v_fmac_f32_e32 v191, v188, v30
	v_fmac_f32_e32 v238, v184, v42
	v_fmac_f32_e32 v239, v188, v42
	v_fmac_f32_e32 v190, v185, v31
	v_fmac_f32_e32 v191, v189, v31
	v_fmac_f32_e32 v238, v185, v43
	v_fmac_f32_e32 v239, v189, v43
	v_add_f32_dpp v190, v190, v190 quad_perm:[1,0,3,2] row_mask:0xf bank_mask:0xf bound_ctrl:1
	v_add_f32_dpp v191, v191, v191 quad_perm:[1,0,3,2] row_mask:0xf bank_mask:0xf bound_ctrl:1
	v_add_f32_dpp v238, v238, v238 quad_perm:[1,0,3,2] row_mask:0xf bank_mask:0xf bound_ctrl:1
	v_add_f32_dpp v239, v239, v239 quad_perm:[1,0,3,2] row_mask:0xf bank_mask:0xf bound_ctrl:1
	v_add_f32_dpp v190, v190, v190 quad_perm:[2,3,0,1] row_mask:0xf bank_mask:0xf bound_ctrl:1
	v_add_f32_dpp v191, v191, v191 quad_perm:[2,3,0,1] row_mask:0xf bank_mask:0xf bound_ctrl:1
	v_add_f32_dpp v238, v238, v238 quad_perm:[2,3,0,1] row_mask:0xf bank_mask:0xf bound_ctrl:1
	v_add_f32_dpp v239, v239, v239 quad_perm:[2,3,0,1] row_mask:0xf bank_mask:0xf bound_ctrl:1
	v_add_f32_dpp v190, v190, v190 row_half_mirror row_mask:0xf bank_mask:0xf bound_ctrl:1
	v_add_f32_dpp v191, v191, v191 row_half_mirror row_mask:0xf bank_mask:0xf bound_ctrl:1
	v_add_f32_dpp v238, v238, v238 row_half_mirror row_mask:0xf bank_mask:0xf bound_ctrl:1
	v_add_f32_dpp v239, v239, v239 row_half_mirror row_mask:0xf bank_mask:0xf bound_ctrl:1
	v_add_f32_dpp v190, v190, v190 row_mirror row_mask:0xf bank_mask:0xf bound_ctrl:1
	v_add_f32_dpp v191, v191, v191 row_mirror row_mask:0xf bank_mask:0xf bound_ctrl:1
	v_fmac_f32_e32 v182, v66, v36
	v_fmac_f32_e32 v183, v66, v37
	v_fmac_f32_e32 v184, v66, v38
	v_fmac_f32_e32 v185, v66, v39
	v_fmac_f32_e32 v186, v67, v36
	v_fmac_f32_e32 v187, v67, v37
	v_fmac_f32_e32 v188, v67, v38
	v_fmac_f32_e32 v189, v67, v39
	v_fmac_f32_e32 v182, v190, v32
	v_fmac_f32_e32 v183, v190, v33
	v_fmac_f32_e32 v184, v190, v34
	v_fmac_f32_e32 v185, v190, v35
	v_fmac_f32_e32 v186, v191, v32
	v_fmac_f32_e32 v187, v191, v33
	v_fmac_f32_e32 v188, v191, v34
	v_fmac_f32_e32 v189, v191, v35
	s_mov_b64 exec, s[8:9]
	ds_write2st64_b64 v146, v[128:129], v[238:239] offset0:18 offset1:19
	s_mov_b64 exec, -1
	ds_read_b128 v[28:31], v151 offset:13824
	ds_read_b128 v[32:35], v151 offset:22016
	ds_read_b128 v[36:39], v151 offset:30208
	ds_read_b128 v[40:43], v151 offset:38400
	ds_read_b64 v[66:67], v181 offset:5632
	s_waitcnt lgkmcnt(11)
	v_mul_f32_e32 v190, v182, v48
	v_mul_f32_e32 v191, v186, v48
	v_mul_f32_e32 v128, v182, v60
	v_mul_f32_e32 v129, v186, v60
	v_fmac_f32_e32 v190, v183, v49
	v_fmac_f32_e32 v191, v187, v49
	v_fmac_f32_e32 v128, v183, v61
	v_fmac_f32_e32 v129, v187, v61
	v_fmac_f32_e32 v190, v184, v50
	v_fmac_f32_e32 v191, v188, v50
	v_fmac_f32_e32 v128, v184, v62
	v_fmac_f32_e32 v129, v188, v62
	v_fmac_f32_e32 v190, v185, v51
	v_fmac_f32_e32 v191, v189, v51
	v_fmac_f32_e32 v128, v185, v63
	v_fmac_f32_e32 v129, v189, v63
	v_add_f32_dpp v190, v190, v190 quad_perm:[1,0,3,2] row_mask:0xf bank_mask:0xf bound_ctrl:1
	v_add_f32_dpp v191, v191, v191 quad_perm:[1,0,3,2] row_mask:0xf bank_mask:0xf bound_ctrl:1
	v_add_f32_dpp v128, v128, v128 quad_perm:[1,0,3,2] row_mask:0xf bank_mask:0xf bound_ctrl:1
	v_add_f32_dpp v129, v129, v129 quad_perm:[1,0,3,2] row_mask:0xf bank_mask:0xf bound_ctrl:1
	v_add_f32_dpp v190, v190, v190 quad_perm:[2,3,0,1] row_mask:0xf bank_mask:0xf bound_ctrl:1
	v_add_f32_dpp v191, v191, v191 quad_perm:[2,3,0,1] row_mask:0xf bank_mask:0xf bound_ctrl:1
	v_add_f32_dpp v128, v128, v128 quad_perm:[2,3,0,1] row_mask:0xf bank_mask:0xf bound_ctrl:1
	v_add_f32_dpp v129, v129, v129 quad_perm:[2,3,0,1] row_mask:0xf bank_mask:0xf bound_ctrl:1
	v_add_f32_dpp v190, v190, v190 row_half_mirror row_mask:0xf bank_mask:0xf bound_ctrl:1
	v_add_f32_dpp v191, v191, v191 row_half_mirror row_mask:0xf bank_mask:0xf bound_ctrl:1
	v_add_f32_dpp v128, v128, v128 row_half_mirror row_mask:0xf bank_mask:0xf bound_ctrl:1
	v_add_f32_dpp v129, v129, v129 row_half_mirror row_mask:0xf bank_mask:0xf bound_ctrl:1
	v_add_f32_dpp v190, v190, v190 row_mirror row_mask:0xf bank_mask:0xf bound_ctrl:1
	v_add_f32_dpp v191, v191, v191 row_mirror row_mask:0xf bank_mask:0xf bound_ctrl:1
	v_fmac_f32_e32 v182, v126, v56
	v_fmac_f32_e32 v183, v126, v57
	v_fmac_f32_e32 v184, v126, v58
	v_fmac_f32_e32 v185, v126, v59
	v_fmac_f32_e32 v186, v127, v56
	v_fmac_f32_e32 v187, v127, v57
	v_fmac_f32_e32 v188, v127, v58
	v_fmac_f32_e32 v189, v127, v59
	v_fmac_f32_e32 v182, v190, v52
	v_fmac_f32_e32 v183, v190, v53
	v_fmac_f32_e32 v184, v190, v54
	v_fmac_f32_e32 v185, v190, v55
	v_fmac_f32_e32 v186, v191, v52
	v_fmac_f32_e32 v187, v191, v53
	v_fmac_f32_e32 v188, v191, v54
	v_fmac_f32_e32 v189, v191, v55
	ds_read_b128 v[48:51], v151 offset:14080
	ds_read_b128 v[52:55], v151 offset:22272
	ds_read_b128 v[56:59], v151 offset:30464
	ds_read_b128 v[60:63], v151 offset:38656
	ds_read_b64 v[126:127], v181 offset:5888
	s_waitcnt lgkmcnt(11)
	v_mul_f32_e32 v190, v182, v8
	v_mul_f32_e32 v191, v186, v8
	v_mul_f32_e32 v238, v182, v20
	v_mul_f32_e32 v239, v186, v20
	v_fmac_f32_e32 v190, v183, v9
	v_fmac_f32_e32 v191, v187, v9
	v_fmac_f32_e32 v238, v183, v21
	v_fmac_f32_e32 v239, v187, v21
	v_fmac_f32_e32 v190, v184, v10
	v_fmac_f32_e32 v191, v188, v10
	v_fmac_f32_e32 v238, v184, v22
	v_fmac_f32_e32 v239, v188, v22
	v_fmac_f32_e32 v190, v185, v11
	v_fmac_f32_e32 v191, v189, v11
	v_fmac_f32_e32 v238, v185, v23
	v_fmac_f32_e32 v239, v189, v23
	v_add_f32_dpp v190, v190, v190 quad_perm:[1,0,3,2] row_mask:0xf bank_mask:0xf bound_ctrl:1
	v_add_f32_dpp v191, v191, v191 quad_perm:[1,0,3,2] row_mask:0xf bank_mask:0xf bound_ctrl:1
	v_add_f32_dpp v238, v238, v238 quad_perm:[1,0,3,2] row_mask:0xf bank_mask:0xf bound_ctrl:1
	v_add_f32_dpp v239, v239, v239 quad_perm:[1,0,3,2] row_mask:0xf bank_mask:0xf bound_ctrl:1
	v_add_f32_dpp v190, v190, v190 quad_perm:[2,3,0,1] row_mask:0xf bank_mask:0xf bound_ctrl:1
	v_add_f32_dpp v191, v191, v191 quad_perm:[2,3,0,1] row_mask:0xf bank_mask:0xf bound_ctrl:1
	v_add_f32_dpp v238, v238, v238 quad_perm:[2,3,0,1] row_mask:0xf bank_mask:0xf bound_ctrl:1
	v_add_f32_dpp v239, v239, v239 quad_perm:[2,3,0,1] row_mask:0xf bank_mask:0xf bound_ctrl:1
	v_add_f32_dpp v190, v190, v190 row_half_mirror row_mask:0xf bank_mask:0xf bound_ctrl:1
	v_add_f32_dpp v191, v191, v191 row_half_mirror row_mask:0xf bank_mask:0xf bound_ctrl:1
	v_add_f32_dpp v238, v238, v238 row_half_mirror row_mask:0xf bank_mask:0xf bound_ctrl:1
	v_add_f32_dpp v239, v239, v239 row_half_mirror row_mask:0xf bank_mask:0xf bound_ctrl:1
	v_add_f32_dpp v190, v190, v190 row_mirror row_mask:0xf bank_mask:0xf bound_ctrl:1
	v_add_f32_dpp v191, v191, v191 row_mirror row_mask:0xf bank_mask:0xf bound_ctrl:1
	v_fmac_f32_e32 v182, v64, v16
	v_fmac_f32_e32 v183, v64, v17
	v_fmac_f32_e32 v184, v64, v18
	v_fmac_f32_e32 v185, v64, v19
	v_fmac_f32_e32 v186, v65, v16
	v_fmac_f32_e32 v187, v65, v17
	v_fmac_f32_e32 v188, v65, v18
	v_fmac_f32_e32 v189, v65, v19
	v_fmac_f32_e32 v182, v190, v12
	v_fmac_f32_e32 v183, v190, v13
	v_fmac_f32_e32 v184, v190, v14
	v_fmac_f32_e32 v185, v190, v15
	v_fmac_f32_e32 v186, v191, v12
	v_fmac_f32_e32 v187, v191, v13
	v_fmac_f32_e32 v188, v191, v14
	v_fmac_f32_e32 v189, v191, v15
	s_mov_b64 exec, s[8:9]
	ds_write2st64_b64 v146, v[128:129], v[238:239] offset0:20 offset1:21
	s_mov_b64 exec, -1
	ds_read_b128 v[8:11], v151 offset:14336
	ds_read_b128 v[12:15], v151 offset:22528
	ds_read_b128 v[16:19], v151 offset:30720
	ds_read_b128 v[20:23], v151 offset:38912
	ds_read_b64 v[64:65], v181 offset:6144
	s_waitcnt lgkmcnt(11)
	v_mul_f32_e32 v190, v182, v28
	v_mul_f32_e32 v191, v186, v28
	v_mul_f32_e32 v128, v182, v40
	v_mul_f32_e32 v129, v186, v40
	v_fmac_f32_e32 v190, v183, v29
	v_fmac_f32_e32 v191, v187, v29
	v_fmac_f32_e32 v128, v183, v41
	v_fmac_f32_e32 v129, v187, v41
	v_fmac_f32_e32 v190, v184, v30
	v_fmac_f32_e32 v191, v188, v30
	v_fmac_f32_e32 v128, v184, v42
	v_fmac_f32_e32 v129, v188, v42
	v_fmac_f32_e32 v190, v185, v31
	v_fmac_f32_e32 v191, v189, v31
	v_fmac_f32_e32 v128, v185, v43
	v_fmac_f32_e32 v129, v189, v43
	v_add_f32_dpp v190, v190, v190 quad_perm:[1,0,3,2] row_mask:0xf bank_mask:0xf bound_ctrl:1
	v_add_f32_dpp v191, v191, v191 quad_perm:[1,0,3,2] row_mask:0xf bank_mask:0xf bound_ctrl:1
	v_add_f32_dpp v128, v128, v128 quad_perm:[1,0,3,2] row_mask:0xf bank_mask:0xf bound_ctrl:1
	v_add_f32_dpp v129, v129, v129 quad_perm:[1,0,3,2] row_mask:0xf bank_mask:0xf bound_ctrl:1
	v_add_f32_dpp v190, v190, v190 quad_perm:[2,3,0,1] row_mask:0xf bank_mask:0xf bound_ctrl:1
	v_add_f32_dpp v191, v191, v191 quad_perm:[2,3,0,1] row_mask:0xf bank_mask:0xf bound_ctrl:1
	v_add_f32_dpp v128, v128, v128 quad_perm:[2,3,0,1] row_mask:0xf bank_mask:0xf bound_ctrl:1
	v_add_f32_dpp v129, v129, v129 quad_perm:[2,3,0,1] row_mask:0xf bank_mask:0xf bound_ctrl:1
	v_add_f32_dpp v190, v190, v190 row_half_mirror row_mask:0xf bank_mask:0xf bound_ctrl:1
	v_add_f32_dpp v191, v191, v191 row_half_mirror row_mask:0xf bank_mask:0xf bound_ctrl:1
	v_add_f32_dpp v128, v128, v128 row_half_mirror row_mask:0xf bank_mask:0xf bound_ctrl:1
	v_add_f32_dpp v129, v129, v129 row_half_mirror row_mask:0xf bank_mask:0xf bound_ctrl:1
	v_add_f32_dpp v190, v190, v190 row_mirror row_mask:0xf bank_mask:0xf bound_ctrl:1
	v_add_f32_dpp v191, v191, v191 row_mirror row_mask:0xf bank_mask:0xf bound_ctrl:1
	v_fmac_f32_e32 v182, v66, v36
	v_fmac_f32_e32 v183, v66, v37
	v_fmac_f32_e32 v184, v66, v38
	v_fmac_f32_e32 v185, v66, v39
	v_fmac_f32_e32 v186, v67, v36
	v_fmac_f32_e32 v187, v67, v37
	v_fmac_f32_e32 v188, v67, v38
	v_fmac_f32_e32 v189, v67, v39
	v_fmac_f32_e32 v182, v190, v32
	v_fmac_f32_e32 v183, v190, v33
	v_fmac_f32_e32 v184, v190, v34
	v_fmac_f32_e32 v185, v190, v35
	v_fmac_f32_e32 v186, v191, v32
	v_fmac_f32_e32 v187, v191, v33
	v_fmac_f32_e32 v188, v191, v34
	v_fmac_f32_e32 v189, v191, v35
	ds_read_b128 v[28:31], v151 offset:14592
	ds_read_b128 v[32:35], v151 offset:22784
	ds_read_b128 v[36:39], v151 offset:30976
	ds_read_b128 v[40:43], v151 offset:39168
	ds_read_b64 v[66:67], v181 offset:6400
	s_waitcnt lgkmcnt(11)
	v_mul_f32_e32 v190, v182, v48
	v_mul_f32_e32 v191, v186, v48
	v_mul_f32_e32 v238, v182, v60
	v_mul_f32_e32 v239, v186, v60
	v_fmac_f32_e32 v190, v183, v49
	v_fmac_f32_e32 v191, v187, v49
	v_fmac_f32_e32 v238, v183, v61
	v_fmac_f32_e32 v239, v187, v61
	v_fmac_f32_e32 v190, v184, v50
	v_fmac_f32_e32 v191, v188, v50
	v_fmac_f32_e32 v238, v184, v62
	v_fmac_f32_e32 v239, v188, v62
	v_fmac_f32_e32 v190, v185, v51
	v_fmac_f32_e32 v191, v189, v51
	v_fmac_f32_e32 v238, v185, v63
	v_fmac_f32_e32 v239, v189, v63
	v_add_f32_dpp v190, v190, v190 quad_perm:[1,0,3,2] row_mask:0xf bank_mask:0xf bound_ctrl:1
	v_add_f32_dpp v191, v191, v191 quad_perm:[1,0,3,2] row_mask:0xf bank_mask:0xf bound_ctrl:1
	v_add_f32_dpp v238, v238, v238 quad_perm:[1,0,3,2] row_mask:0xf bank_mask:0xf bound_ctrl:1
	v_add_f32_dpp v239, v239, v239 quad_perm:[1,0,3,2] row_mask:0xf bank_mask:0xf bound_ctrl:1
	v_add_f32_dpp v190, v190, v190 quad_perm:[2,3,0,1] row_mask:0xf bank_mask:0xf bound_ctrl:1
	v_add_f32_dpp v191, v191, v191 quad_perm:[2,3,0,1] row_mask:0xf bank_mask:0xf bound_ctrl:1
	v_add_f32_dpp v238, v238, v238 quad_perm:[2,3,0,1] row_mask:0xf bank_mask:0xf bound_ctrl:1
	v_add_f32_dpp v239, v239, v239 quad_perm:[2,3,0,1] row_mask:0xf bank_mask:0xf bound_ctrl:1
	v_add_f32_dpp v190, v190, v190 row_half_mirror row_mask:0xf bank_mask:0xf bound_ctrl:1
	v_add_f32_dpp v191, v191, v191 row_half_mirror row_mask:0xf bank_mask:0xf bound_ctrl:1
	v_add_f32_dpp v238, v238, v238 row_half_mirror row_mask:0xf bank_mask:0xf bound_ctrl:1
	v_add_f32_dpp v239, v239, v239 row_half_mirror row_mask:0xf bank_mask:0xf bound_ctrl:1
	v_add_f32_dpp v190, v190, v190 row_mirror row_mask:0xf bank_mask:0xf bound_ctrl:1
	v_add_f32_dpp v191, v191, v191 row_mirror row_mask:0xf bank_mask:0xf bound_ctrl:1
	v_fmac_f32_e32 v182, v126, v56
	v_fmac_f32_e32 v183, v126, v57
	v_fmac_f32_e32 v184, v126, v58
	v_fmac_f32_e32 v185, v126, v59
	v_fmac_f32_e32 v186, v127, v56
	v_fmac_f32_e32 v187, v127, v57
	v_fmac_f32_e32 v188, v127, v58
	v_fmac_f32_e32 v189, v127, v59
	v_fmac_f32_e32 v182, v190, v52
	v_fmac_f32_e32 v183, v190, v53
	v_fmac_f32_e32 v184, v190, v54
	v_fmac_f32_e32 v185, v190, v55
	v_fmac_f32_e32 v186, v191, v52
	v_fmac_f32_e32 v187, v191, v53
	v_fmac_f32_e32 v188, v191, v54
	v_fmac_f32_e32 v189, v191, v55
	s_mov_b64 exec, s[8:9]
	ds_write2st64_b64 v146, v[128:129], v[238:239] offset0:22 offset1:23
	s_mov_b64 exec, -1
	ds_read_b128 v[48:51], v151 offset:14848
	ds_read_b128 v[52:55], v151 offset:23040
	ds_read_b128 v[56:59], v151 offset:31232
	ds_read_b128 v[60:63], v151 offset:39424
	ds_read_b64 v[126:127], v181 offset:6656
	s_waitcnt lgkmcnt(11)
	v_mul_f32_e32 v190, v182, v8
	v_mul_f32_e32 v191, v186, v8
	v_mul_f32_e32 v128, v182, v20
	v_mul_f32_e32 v129, v186, v20
	v_fmac_f32_e32 v190, v183, v9
	v_fmac_f32_e32 v191, v187, v9
	v_fmac_f32_e32 v128, v183, v21
	v_fmac_f32_e32 v129, v187, v21
	v_fmac_f32_e32 v190, v184, v10
	v_fmac_f32_e32 v191, v188, v10
	v_fmac_f32_e32 v128, v184, v22
	v_fmac_f32_e32 v129, v188, v22
	v_fmac_f32_e32 v190, v185, v11
	v_fmac_f32_e32 v191, v189, v11
	v_fmac_f32_e32 v128, v185, v23
	v_fmac_f32_e32 v129, v189, v23
	v_add_f32_dpp v190, v190, v190 quad_perm:[1,0,3,2] row_mask:0xf bank_mask:0xf bound_ctrl:1
	v_add_f32_dpp v191, v191, v191 quad_perm:[1,0,3,2] row_mask:0xf bank_mask:0xf bound_ctrl:1
	v_add_f32_dpp v128, v128, v128 quad_perm:[1,0,3,2] row_mask:0xf bank_mask:0xf bound_ctrl:1
	v_add_f32_dpp v129, v129, v129 quad_perm:[1,0,3,2] row_mask:0xf bank_mask:0xf bound_ctrl:1
	v_add_f32_dpp v190, v190, v190 quad_perm:[2,3,0,1] row_mask:0xf bank_mask:0xf bound_ctrl:1
	v_add_f32_dpp v191, v191, v191 quad_perm:[2,3,0,1] row_mask:0xf bank_mask:0xf bound_ctrl:1
	v_add_f32_dpp v128, v128, v128 quad_perm:[2,3,0,1] row_mask:0xf bank_mask:0xf bound_ctrl:1
	v_add_f32_dpp v129, v129, v129 quad_perm:[2,3,0,1] row_mask:0xf bank_mask:0xf bound_ctrl:1
	v_add_f32_dpp v190, v190, v190 row_half_mirror row_mask:0xf bank_mask:0xf bound_ctrl:1
	v_add_f32_dpp v191, v191, v191 row_half_mirror row_mask:0xf bank_mask:0xf bound_ctrl:1
	v_add_f32_dpp v128, v128, v128 row_half_mirror row_mask:0xf bank_mask:0xf bound_ctrl:1
	v_add_f32_dpp v129, v129, v129 row_half_mirror row_mask:0xf bank_mask:0xf bound_ctrl:1
	v_add_f32_dpp v190, v190, v190 row_mirror row_mask:0xf bank_mask:0xf bound_ctrl:1
	v_add_f32_dpp v191, v191, v191 row_mirror row_mask:0xf bank_mask:0xf bound_ctrl:1
	v_fmac_f32_e32 v182, v64, v16
	v_fmac_f32_e32 v183, v64, v17
	v_fmac_f32_e32 v184, v64, v18
	v_fmac_f32_e32 v185, v64, v19
	v_fmac_f32_e32 v186, v65, v16
	v_fmac_f32_e32 v187, v65, v17
	v_fmac_f32_e32 v188, v65, v18
	v_fmac_f32_e32 v189, v65, v19
	v_fmac_f32_e32 v182, v190, v12
	v_fmac_f32_e32 v183, v190, v13
	v_fmac_f32_e32 v184, v190, v14
	v_fmac_f32_e32 v185, v190, v15
	v_fmac_f32_e32 v186, v191, v12
	v_fmac_f32_e32 v187, v191, v13
	v_fmac_f32_e32 v188, v191, v14
	v_fmac_f32_e32 v189, v191, v15
	ds_read_b128 v[8:11], v151 offset:15104
	ds_read_b128 v[12:15], v151 offset:23296
	ds_read_b128 v[16:19], v151 offset:31488
	ds_read_b128 v[20:23], v151 offset:39680
	ds_read_b64 v[64:65], v181 offset:6912
	s_waitcnt lgkmcnt(11)
	v_mul_f32_e32 v190, v182, v28
	v_mul_f32_e32 v191, v186, v28
	v_mul_f32_e32 v238, v182, v40
	v_mul_f32_e32 v239, v186, v40
	v_fmac_f32_e32 v190, v183, v29
	v_fmac_f32_e32 v191, v187, v29
	v_fmac_f32_e32 v238, v183, v41
	v_fmac_f32_e32 v239, v187, v41
	v_fmac_f32_e32 v190, v184, v30
	v_fmac_f32_e32 v191, v188, v30
	v_fmac_f32_e32 v238, v184, v42
	v_fmac_f32_e32 v239, v188, v42
	v_fmac_f32_e32 v190, v185, v31
	v_fmac_f32_e32 v191, v189, v31
	v_fmac_f32_e32 v238, v185, v43
	v_fmac_f32_e32 v239, v189, v43
	v_add_f32_dpp v190, v190, v190 quad_perm:[1,0,3,2] row_mask:0xf bank_mask:0xf bound_ctrl:1
	v_add_f32_dpp v191, v191, v191 quad_perm:[1,0,3,2] row_mask:0xf bank_mask:0xf bound_ctrl:1
	v_add_f32_dpp v238, v238, v238 quad_perm:[1,0,3,2] row_mask:0xf bank_mask:0xf bound_ctrl:1
	v_add_f32_dpp v239, v239, v239 quad_perm:[1,0,3,2] row_mask:0xf bank_mask:0xf bound_ctrl:1
	v_add_f32_dpp v190, v190, v190 quad_perm:[2,3,0,1] row_mask:0xf bank_mask:0xf bound_ctrl:1
	v_add_f32_dpp v191, v191, v191 quad_perm:[2,3,0,1] row_mask:0xf bank_mask:0xf bound_ctrl:1
	v_add_f32_dpp v238, v238, v238 quad_perm:[2,3,0,1] row_mask:0xf bank_mask:0xf bound_ctrl:1
	v_add_f32_dpp v239, v239, v239 quad_perm:[2,3,0,1] row_mask:0xf bank_mask:0xf bound_ctrl:1
	v_add_f32_dpp v190, v190, v190 row_half_mirror row_mask:0xf bank_mask:0xf bound_ctrl:1
	v_add_f32_dpp v191, v191, v191 row_half_mirror row_mask:0xf bank_mask:0xf bound_ctrl:1
	v_add_f32_dpp v238, v238, v238 row_half_mirror row_mask:0xf bank_mask:0xf bound_ctrl:1
	v_add_f32_dpp v239, v239, v239 row_half_mirror row_mask:0xf bank_mask:0xf bound_ctrl:1
	v_add_f32_dpp v190, v190, v190 row_mirror row_mask:0xf bank_mask:0xf bound_ctrl:1
	v_add_f32_dpp v191, v191, v191 row_mirror row_mask:0xf bank_mask:0xf bound_ctrl:1
	v_fmac_f32_e32 v182, v66, v36
	v_fmac_f32_e32 v183, v66, v37
	v_fmac_f32_e32 v184, v66, v38
	v_fmac_f32_e32 v185, v66, v39
	v_fmac_f32_e32 v186, v67, v36
	v_fmac_f32_e32 v187, v67, v37
	v_fmac_f32_e32 v188, v67, v38
	v_fmac_f32_e32 v189, v67, v39
	v_fmac_f32_e32 v182, v190, v32
	v_fmac_f32_e32 v183, v190, v33
	v_fmac_f32_e32 v184, v190, v34
	v_fmac_f32_e32 v185, v190, v35
	v_fmac_f32_e32 v186, v191, v32
	v_fmac_f32_e32 v187, v191, v33
	v_fmac_f32_e32 v188, v191, v34
	v_fmac_f32_e32 v189, v191, v35
	s_mov_b64 exec, s[8:9]
	ds_write2st64_b64 v146, v[128:129], v[238:239] offset0:24 offset1:25
	s_mov_b64 exec, -1
	ds_read_b128 v[28:31], v151 offset:15360
	ds_read_b128 v[32:35], v151 offset:23552
	ds_read_b128 v[36:39], v151 offset:31744
	ds_read_b128 v[40:43], v151 offset:39936
	ds_read_b64 v[66:67], v181 offset:7168
	s_waitcnt lgkmcnt(11)
	v_mul_f32_e32 v190, v182, v48
	v_mul_f32_e32 v191, v186, v48
	v_mul_f32_e32 v128, v182, v60
	v_mul_f32_e32 v129, v186, v60
	v_fmac_f32_e32 v190, v183, v49
	v_fmac_f32_e32 v191, v187, v49
	v_fmac_f32_e32 v128, v183, v61
	v_fmac_f32_e32 v129, v187, v61
	v_fmac_f32_e32 v190, v184, v50
	v_fmac_f32_e32 v191, v188, v50
	v_fmac_f32_e32 v128, v184, v62
	v_fmac_f32_e32 v129, v188, v62
	v_fmac_f32_e32 v190, v185, v51
	v_fmac_f32_e32 v191, v189, v51
	v_fmac_f32_e32 v128, v185, v63
	v_fmac_f32_e32 v129, v189, v63
	v_add_f32_dpp v190, v190, v190 quad_perm:[1,0,3,2] row_mask:0xf bank_mask:0xf bound_ctrl:1
	v_add_f32_dpp v191, v191, v191 quad_perm:[1,0,3,2] row_mask:0xf bank_mask:0xf bound_ctrl:1
	v_add_f32_dpp v128, v128, v128 quad_perm:[1,0,3,2] row_mask:0xf bank_mask:0xf bound_ctrl:1
	v_add_f32_dpp v129, v129, v129 quad_perm:[1,0,3,2] row_mask:0xf bank_mask:0xf bound_ctrl:1
	v_add_f32_dpp v190, v190, v190 quad_perm:[2,3,0,1] row_mask:0xf bank_mask:0xf bound_ctrl:1
	v_add_f32_dpp v191, v191, v191 quad_perm:[2,3,0,1] row_mask:0xf bank_mask:0xf bound_ctrl:1
	v_add_f32_dpp v128, v128, v128 quad_perm:[2,3,0,1] row_mask:0xf bank_mask:0xf bound_ctrl:1
	v_add_f32_dpp v129, v129, v129 quad_perm:[2,3,0,1] row_mask:0xf bank_mask:0xf bound_ctrl:1
	v_add_f32_dpp v190, v190, v190 row_half_mirror row_mask:0xf bank_mask:0xf bound_ctrl:1
	v_add_f32_dpp v191, v191, v191 row_half_mirror row_mask:0xf bank_mask:0xf bound_ctrl:1
	v_add_f32_dpp v128, v128, v128 row_half_mirror row_mask:0xf bank_mask:0xf bound_ctrl:1
	v_add_f32_dpp v129, v129, v129 row_half_mirror row_mask:0xf bank_mask:0xf bound_ctrl:1
	v_add_f32_dpp v190, v190, v190 row_mirror row_mask:0xf bank_mask:0xf bound_ctrl:1
	v_add_f32_dpp v191, v191, v191 row_mirror row_mask:0xf bank_mask:0xf bound_ctrl:1
	v_fmac_f32_e32 v182, v126, v56
	v_fmac_f32_e32 v183, v126, v57
	v_fmac_f32_e32 v184, v126, v58
	v_fmac_f32_e32 v185, v126, v59
	v_fmac_f32_e32 v186, v127, v56
	v_fmac_f32_e32 v187, v127, v57
	v_fmac_f32_e32 v188, v127, v58
	v_fmac_f32_e32 v189, v127, v59
	v_fmac_f32_e32 v182, v190, v52
	v_fmac_f32_e32 v183, v190, v53
	v_fmac_f32_e32 v184, v190, v54
	v_fmac_f32_e32 v185, v190, v55
	v_fmac_f32_e32 v186, v191, v52
	v_fmac_f32_e32 v187, v191, v53
	v_fmac_f32_e32 v188, v191, v54
	v_fmac_f32_e32 v189, v191, v55
	ds_read_b128 v[48:51], v151 offset:15616
	ds_read_b128 v[52:55], v151 offset:23808
	ds_read_b128 v[56:59], v151 offset:32000
	ds_read_b128 v[60:63], v151 offset:40192
	ds_read_b64 v[126:127], v181 offset:7424
	s_waitcnt lgkmcnt(11)
	v_mul_f32_e32 v190, v182, v8
	v_mul_f32_e32 v191, v186, v8
	v_mul_f32_e32 v238, v182, v20
	v_mul_f32_e32 v239, v186, v20
	v_fmac_f32_e32 v190, v183, v9
	v_fmac_f32_e32 v191, v187, v9
	v_fmac_f32_e32 v238, v183, v21
	v_fmac_f32_e32 v239, v187, v21
	v_fmac_f32_e32 v190, v184, v10
	v_fmac_f32_e32 v191, v188, v10
	v_fmac_f32_e32 v238, v184, v22
	v_fmac_f32_e32 v239, v188, v22
	v_fmac_f32_e32 v190, v185, v11
	v_fmac_f32_e32 v191, v189, v11
	v_fmac_f32_e32 v238, v185, v23
	v_fmac_f32_e32 v239, v189, v23
	v_add_f32_dpp v190, v190, v190 quad_perm:[1,0,3,2] row_mask:0xf bank_mask:0xf bound_ctrl:1
	v_add_f32_dpp v191, v191, v191 quad_perm:[1,0,3,2] row_mask:0xf bank_mask:0xf bound_ctrl:1
	v_add_f32_dpp v238, v238, v238 quad_perm:[1,0,3,2] row_mask:0xf bank_mask:0xf bound_ctrl:1
	v_add_f32_dpp v239, v239, v239 quad_perm:[1,0,3,2] row_mask:0xf bank_mask:0xf bound_ctrl:1
	v_add_f32_dpp v190, v190, v190 quad_perm:[2,3,0,1] row_mask:0xf bank_mask:0xf bound_ctrl:1
	v_add_f32_dpp v191, v191, v191 quad_perm:[2,3,0,1] row_mask:0xf bank_mask:0xf bound_ctrl:1
	v_add_f32_dpp v238, v238, v238 quad_perm:[2,3,0,1] row_mask:0xf bank_mask:0xf bound_ctrl:1
	v_add_f32_dpp v239, v239, v239 quad_perm:[2,3,0,1] row_mask:0xf bank_mask:0xf bound_ctrl:1
	v_add_f32_dpp v190, v190, v190 row_half_mirror row_mask:0xf bank_mask:0xf bound_ctrl:1
	v_add_f32_dpp v191, v191, v191 row_half_mirror row_mask:0xf bank_mask:0xf bound_ctrl:1
	v_add_f32_dpp v238, v238, v238 row_half_mirror row_mask:0xf bank_mask:0xf bound_ctrl:1
	v_add_f32_dpp v239, v239, v239 row_half_mirror row_mask:0xf bank_mask:0xf bound_ctrl:1
	v_add_f32_dpp v190, v190, v190 row_mirror row_mask:0xf bank_mask:0xf bound_ctrl:1
	v_add_f32_dpp v191, v191, v191 row_mirror row_mask:0xf bank_mask:0xf bound_ctrl:1
	v_fmac_f32_e32 v182, v64, v16
	v_fmac_f32_e32 v183, v64, v17
	v_fmac_f32_e32 v184, v64, v18
	v_fmac_f32_e32 v185, v64, v19
	v_fmac_f32_e32 v186, v65, v16
	v_fmac_f32_e32 v187, v65, v17
	v_fmac_f32_e32 v188, v65, v18
	v_fmac_f32_e32 v189, v65, v19
	v_fmac_f32_e32 v182, v190, v12
	v_fmac_f32_e32 v183, v190, v13
	v_fmac_f32_e32 v184, v190, v14
	v_fmac_f32_e32 v185, v190, v15
	v_fmac_f32_e32 v186, v191, v12
	v_fmac_f32_e32 v187, v191, v13
	v_fmac_f32_e32 v188, v191, v14
	v_fmac_f32_e32 v189, v191, v15
	s_mov_b64 exec, s[8:9]
	ds_write2st64_b64 v146, v[128:129], v[238:239] offset0:26 offset1:27
	s_mov_b64 exec, -1
	ds_read_b128 v[8:11], v151 offset:15872
	ds_read_b128 v[12:15], v151 offset:24064
	ds_read_b128 v[16:19], v151 offset:32256
	ds_read_b128 v[20:23], v151 offset:40448
	ds_read_b64 v[64:65], v181 offset:7680
	s_waitcnt lgkmcnt(11)
	v_mul_f32_e32 v190, v182, v28
	v_mul_f32_e32 v191, v186, v28
	v_mul_f32_e32 v128, v182, v40
	v_mul_f32_e32 v129, v186, v40
	v_fmac_f32_e32 v190, v183, v29
	v_fmac_f32_e32 v191, v187, v29
	v_fmac_f32_e32 v128, v183, v41
	v_fmac_f32_e32 v129, v187, v41
	v_fmac_f32_e32 v190, v184, v30
	v_fmac_f32_e32 v191, v188, v30
	v_fmac_f32_e32 v128, v184, v42
	v_fmac_f32_e32 v129, v188, v42
	v_fmac_f32_e32 v190, v185, v31
	v_fmac_f32_e32 v191, v189, v31
	v_fmac_f32_e32 v128, v185, v43
	v_fmac_f32_e32 v129, v189, v43
	v_add_f32_dpp v190, v190, v190 quad_perm:[1,0,3,2] row_mask:0xf bank_mask:0xf bound_ctrl:1
	v_add_f32_dpp v191, v191, v191 quad_perm:[1,0,3,2] row_mask:0xf bank_mask:0xf bound_ctrl:1
	v_add_f32_dpp v128, v128, v128 quad_perm:[1,0,3,2] row_mask:0xf bank_mask:0xf bound_ctrl:1
	v_add_f32_dpp v129, v129, v129 quad_perm:[1,0,3,2] row_mask:0xf bank_mask:0xf bound_ctrl:1
	v_add_f32_dpp v190, v190, v190 quad_perm:[2,3,0,1] row_mask:0xf bank_mask:0xf bound_ctrl:1
	v_add_f32_dpp v191, v191, v191 quad_perm:[2,3,0,1] row_mask:0xf bank_mask:0xf bound_ctrl:1
	v_add_f32_dpp v128, v128, v128 quad_perm:[2,3,0,1] row_mask:0xf bank_mask:0xf bound_ctrl:1
	v_add_f32_dpp v129, v129, v129 quad_perm:[2,3,0,1] row_mask:0xf bank_mask:0xf bound_ctrl:1
	v_add_f32_dpp v190, v190, v190 row_half_mirror row_mask:0xf bank_mask:0xf bound_ctrl:1
	v_add_f32_dpp v191, v191, v191 row_half_mirror row_mask:0xf bank_mask:0xf bound_ctrl:1
	v_add_f32_dpp v128, v128, v128 row_half_mirror row_mask:0xf bank_mask:0xf bound_ctrl:1
	v_add_f32_dpp v129, v129, v129 row_half_mirror row_mask:0xf bank_mask:0xf bound_ctrl:1
	v_add_f32_dpp v190, v190, v190 row_mirror row_mask:0xf bank_mask:0xf bound_ctrl:1
	v_add_f32_dpp v191, v191, v191 row_mirror row_mask:0xf bank_mask:0xf bound_ctrl:1
	v_fmac_f32_e32 v182, v66, v36
	v_fmac_f32_e32 v183, v66, v37
	v_fmac_f32_e32 v184, v66, v38
	v_fmac_f32_e32 v185, v66, v39
	v_fmac_f32_e32 v186, v67, v36
	v_fmac_f32_e32 v187, v67, v37
	v_fmac_f32_e32 v188, v67, v38
	v_fmac_f32_e32 v189, v67, v39
	v_fmac_f32_e32 v182, v190, v32
	v_fmac_f32_e32 v183, v190, v33
	v_fmac_f32_e32 v184, v190, v34
	v_fmac_f32_e32 v185, v190, v35
	v_fmac_f32_e32 v186, v191, v32
	v_fmac_f32_e32 v187, v191, v33
	v_fmac_f32_e32 v188, v191, v34
	v_fmac_f32_e32 v189, v191, v35
	ds_read_b128 v[28:31], v151 offset:16128
	ds_read_b128 v[32:35], v151 offset:24320
	ds_read_b128 v[36:39], v151 offset:32512
	ds_read_b128 v[40:43], v151 offset:40704
	ds_read_b64 v[66:67], v181 offset:7936
	s_waitcnt lgkmcnt(11)
	v_mul_f32_e32 v190, v182, v48
	v_mul_f32_e32 v191, v186, v48
	v_mul_f32_e32 v238, v182, v60
	v_mul_f32_e32 v239, v186, v60
	v_fmac_f32_e32 v190, v183, v49
	v_fmac_f32_e32 v191, v187, v49
	v_fmac_f32_e32 v238, v183, v61
	v_fmac_f32_e32 v239, v187, v61
	v_fmac_f32_e32 v190, v184, v50
	v_fmac_f32_e32 v191, v188, v50
	v_fmac_f32_e32 v238, v184, v62
	v_fmac_f32_e32 v239, v188, v62
	v_fmac_f32_e32 v190, v185, v51
	v_fmac_f32_e32 v191, v189, v51
	v_fmac_f32_e32 v238, v185, v63
	v_fmac_f32_e32 v239, v189, v63
	v_add_f32_dpp v190, v190, v190 quad_perm:[1,0,3,2] row_mask:0xf bank_mask:0xf bound_ctrl:1
	v_add_f32_dpp v191, v191, v191 quad_perm:[1,0,3,2] row_mask:0xf bank_mask:0xf bound_ctrl:1
	v_add_f32_dpp v238, v238, v238 quad_perm:[1,0,3,2] row_mask:0xf bank_mask:0xf bound_ctrl:1
	v_add_f32_dpp v239, v239, v239 quad_perm:[1,0,3,2] row_mask:0xf bank_mask:0xf bound_ctrl:1
	v_add_f32_dpp v190, v190, v190 quad_perm:[2,3,0,1] row_mask:0xf bank_mask:0xf bound_ctrl:1
	v_add_f32_dpp v191, v191, v191 quad_perm:[2,3,0,1] row_mask:0xf bank_mask:0xf bound_ctrl:1
	v_add_f32_dpp v238, v238, v238 quad_perm:[2,3,0,1] row_mask:0xf bank_mask:0xf bound_ctrl:1
	v_add_f32_dpp v239, v239, v239 quad_perm:[2,3,0,1] row_mask:0xf bank_mask:0xf bound_ctrl:1
	v_add_f32_dpp v190, v190, v190 row_half_mirror row_mask:0xf bank_mask:0xf bound_ctrl:1
	v_add_f32_dpp v191, v191, v191 row_half_mirror row_mask:0xf bank_mask:0xf bound_ctrl:1
	v_add_f32_dpp v238, v238, v238 row_half_mirror row_mask:0xf bank_mask:0xf bound_ctrl:1
	v_add_f32_dpp v239, v239, v239 row_half_mirror row_mask:0xf bank_mask:0xf bound_ctrl:1
	v_add_f32_dpp v190, v190, v190 row_mirror row_mask:0xf bank_mask:0xf bound_ctrl:1
	v_add_f32_dpp v191, v191, v191 row_mirror row_mask:0xf bank_mask:0xf bound_ctrl:1
	v_fmac_f32_e32 v182, v126, v56
	v_fmac_f32_e32 v183, v126, v57
	v_fmac_f32_e32 v184, v126, v58
	v_fmac_f32_e32 v185, v126, v59
	v_fmac_f32_e32 v186, v127, v56
	v_fmac_f32_e32 v187, v127, v57
	v_fmac_f32_e32 v188, v127, v58
	v_fmac_f32_e32 v189, v127, v59
	v_fmac_f32_e32 v182, v190, v52
	v_fmac_f32_e32 v183, v190, v53
	v_fmac_f32_e32 v184, v190, v54
	v_fmac_f32_e32 v185, v190, v55
	v_fmac_f32_e32 v186, v191, v52
	v_fmac_f32_e32 v187, v191, v53
	v_fmac_f32_e32 v188, v191, v54
	v_fmac_f32_e32 v189, v191, v55
	s_mov_b64 exec, s[8:9]
	ds_write2st64_b64 v146, v[128:129], v[238:239] offset0:28 offset1:29
	s_mov_b64 exec, -1
	s_waitcnt lgkmcnt(6)
	v_mul_f32_e32 v190, v182, v8
	v_mul_f32_e32 v191, v186, v8
	v_mul_f32_e32 v128, v182, v20
	v_mul_f32_e32 v129, v186, v20
	v_fmac_f32_e32 v190, v183, v9
	v_fmac_f32_e32 v191, v187, v9
	v_fmac_f32_e32 v128, v183, v21
	v_fmac_f32_e32 v129, v187, v21
	v_fmac_f32_e32 v190, v184, v10
	v_fmac_f32_e32 v191, v188, v10
	v_fmac_f32_e32 v128, v184, v22
	v_fmac_f32_e32 v129, v188, v22
	v_fmac_f32_e32 v190, v185, v11
	v_fmac_f32_e32 v191, v189, v11
	v_fmac_f32_e32 v128, v185, v23
	v_fmac_f32_e32 v129, v189, v23
	v_add_f32_dpp v190, v190, v190 quad_perm:[1,0,3,2] row_mask:0xf bank_mask:0xf bound_ctrl:1
	v_add_f32_dpp v191, v191, v191 quad_perm:[1,0,3,2] row_mask:0xf bank_mask:0xf bound_ctrl:1
	v_add_f32_dpp v128, v128, v128 quad_perm:[1,0,3,2] row_mask:0xf bank_mask:0xf bound_ctrl:1
	v_add_f32_dpp v129, v129, v129 quad_perm:[1,0,3,2] row_mask:0xf bank_mask:0xf bound_ctrl:1
	v_add_f32_dpp v190, v190, v190 quad_perm:[2,3,0,1] row_mask:0xf bank_mask:0xf bound_ctrl:1
	v_add_f32_dpp v191, v191, v191 quad_perm:[2,3,0,1] row_mask:0xf bank_mask:0xf bound_ctrl:1
	v_add_f32_dpp v128, v128, v128 quad_perm:[2,3,0,1] row_mask:0xf bank_mask:0xf bound_ctrl:1
	v_add_f32_dpp v129, v129, v129 quad_perm:[2,3,0,1] row_mask:0xf bank_mask:0xf bound_ctrl:1
	v_add_f32_dpp v190, v190, v190 row_half_mirror row_mask:0xf bank_mask:0xf bound_ctrl:1
	v_add_f32_dpp v191, v191, v191 row_half_mirror row_mask:0xf bank_mask:0xf bound_ctrl:1
	v_add_f32_dpp v128, v128, v128 row_half_mirror row_mask:0xf bank_mask:0xf bound_ctrl:1
	v_add_f32_dpp v129, v129, v129 row_half_mirror row_mask:0xf bank_mask:0xf bound_ctrl:1
	v_add_f32_dpp v190, v190, v190 row_mirror row_mask:0xf bank_mask:0xf bound_ctrl:1
	v_add_f32_dpp v191, v191, v191 row_mirror row_mask:0xf bank_mask:0xf bound_ctrl:1
	v_fmac_f32_e32 v182, v64, v16
	v_fmac_f32_e32 v183, v64, v17
	v_fmac_f32_e32 v184, v64, v18
	v_fmac_f32_e32 v185, v64, v19
	v_fmac_f32_e32 v186, v65, v16
	v_fmac_f32_e32 v187, v65, v17
	v_fmac_f32_e32 v188, v65, v18
	v_fmac_f32_e32 v189, v65, v19
	v_fmac_f32_e32 v182, v190, v12
	v_fmac_f32_e32 v183, v190, v13
	v_fmac_f32_e32 v184, v190, v14
	v_fmac_f32_e32 v185, v190, v15
	v_fmac_f32_e32 v186, v191, v12
	v_fmac_f32_e32 v187, v191, v13
	v_fmac_f32_e32 v188, v191, v14
	v_fmac_f32_e32 v189, v191, v15
	s_waitcnt lgkmcnt(1)
	v_mul_f32_e32 v190, v182, v28
	v_mul_f32_e32 v191, v186, v28
	v_mul_f32_e32 v238, v182, v40
	v_mul_f32_e32 v239, v186, v40
	v_fmac_f32_e32 v190, v183, v29
	v_fmac_f32_e32 v191, v187, v29
	v_fmac_f32_e32 v238, v183, v41
	v_fmac_f32_e32 v239, v187, v41
	v_fmac_f32_e32 v190, v184, v30
	v_fmac_f32_e32 v191, v188, v30
	v_fmac_f32_e32 v238, v184, v42
	v_fmac_f32_e32 v239, v188, v42
	v_fmac_f32_e32 v190, v185, v31
	v_fmac_f32_e32 v191, v189, v31
	v_fmac_f32_e32 v238, v185, v43
	v_fmac_f32_e32 v239, v189, v43
	v_add_f32_dpp v190, v190, v190 quad_perm:[1,0,3,2] row_mask:0xf bank_mask:0xf bound_ctrl:1
	v_add_f32_dpp v191, v191, v191 quad_perm:[1,0,3,2] row_mask:0xf bank_mask:0xf bound_ctrl:1
	v_add_f32_dpp v238, v238, v238 quad_perm:[1,0,3,2] row_mask:0xf bank_mask:0xf bound_ctrl:1
	v_add_f32_dpp v239, v239, v239 quad_perm:[1,0,3,2] row_mask:0xf bank_mask:0xf bound_ctrl:1
	v_add_f32_dpp v190, v190, v190 quad_perm:[2,3,0,1] row_mask:0xf bank_mask:0xf bound_ctrl:1
	v_add_f32_dpp v191, v191, v191 quad_perm:[2,3,0,1] row_mask:0xf bank_mask:0xf bound_ctrl:1
	v_add_f32_dpp v238, v238, v238 quad_perm:[2,3,0,1] row_mask:0xf bank_mask:0xf bound_ctrl:1
	v_add_f32_dpp v239, v239, v239 quad_perm:[2,3,0,1] row_mask:0xf bank_mask:0xf bound_ctrl:1
	v_add_f32_dpp v190, v190, v190 row_half_mirror row_mask:0xf bank_mask:0xf bound_ctrl:1
	v_add_f32_dpp v191, v191, v191 row_half_mirror row_mask:0xf bank_mask:0xf bound_ctrl:1
	v_add_f32_dpp v238, v238, v238 row_half_mirror row_mask:0xf bank_mask:0xf bound_ctrl:1
	v_add_f32_dpp v239, v239, v239 row_half_mirror row_mask:0xf bank_mask:0xf bound_ctrl:1
	v_add_f32_dpp v190, v190, v190 row_mirror row_mask:0xf bank_mask:0xf bound_ctrl:1
	v_add_f32_dpp v191, v191, v191 row_mirror row_mask:0xf bank_mask:0xf bound_ctrl:1
	v_fmac_f32_e32 v182, v66, v36
	v_fmac_f32_e32 v183, v66, v37
	v_fmac_f32_e32 v184, v66, v38
	v_fmac_f32_e32 v185, v66, v39
	v_fmac_f32_e32 v186, v67, v36
	v_fmac_f32_e32 v187, v67, v37
	v_fmac_f32_e32 v188, v67, v38
	v_fmac_f32_e32 v189, v67, v39
	v_fmac_f32_e32 v182, v190, v32
	v_fmac_f32_e32 v183, v190, v33
	v_fmac_f32_e32 v184, v190, v34
	v_fmac_f32_e32 v185, v190, v35
	v_fmac_f32_e32 v186, v191, v32
	v_fmac_f32_e32 v187, v191, v33
	v_fmac_f32_e32 v188, v191, v34
	v_fmac_f32_e32 v189, v191, v35
	s_mov_b64 exec, s[8:9]
	ds_write2st64_b64 v146, v[128:129], v[238:239] offset0:30 offset1:31
	s_mov_b64 exec, -1
	ds_read_b128 v[4:7], v151 offset:65280
	s_waitcnt lgkmcnt(0)
	v_mul_f32_e32 v182, v182, v4
	v_mul_f32_e32 v183, v183, v5
	v_mul_f32_e32 v184, v184, v6
	v_mul_f32_e32 v185, v185, v7
	v_mul_f32_e32 v186, v186, v4
	v_mul_f32_e32 v187, v187, v5
	v_mul_f32_e32 v188, v188, v6
	v_mul_f32_e32 v189, v189, v7
	s_branch .LBB0_182

.LBB0_296:
	s_or_b64 exec, exec, s[12:13]
	v_add_u32_e32 v227, 0x100, v146
	ds_read_b128 v[198:201], v146 offset:57344
	ds_read_b128 v[202:205], v227 offset:57344
	ds_read_b128 v[206:209], v146 offset:8192
	ds_read_b128 v[210:213], v146 offset:16384
	ds_read_b128 v[214:217], v146 offset:24576
	ds_read_b128 v[218:221], v146 offset:32768
	v_mov_b32_e32 v226, 1.0
	v_cmp_lt_u32_e32 vcc, 495, v134
	s_waitcnt lgkmcnt(4)
	v_rcp_f32_e32 v222, v198
	v_rcp_f32_e32 v223, v199
	v_rcp_f32_e32 v224, v200
	v_rcp_f32_e32 v225, v201
	v_cndmask_b32_e32 v202, v202, v226, vcc
	v_cndmask_b32_e32 v203, v203, v226, vcc
	v_cndmask_b32_e32 v204, v204, v226, vcc
	v_cndmask_b32_e32 v205, v205, v226, vcc
	s_waitcnt lgkmcnt(0)
	v_mul_f32_e32 v206, v206, v202
	v_mul_f32_e32 v207, v207, v203
	v_mul_f32_e32 v208, v208, v204
	v_mul_f32_e32 v209, v209, v205
	v_mul_f32_e32 v218, v218, v202
	v_mul_f32_e32 v219, v219, v203
	v_mul_f32_e32 v220, v220, v204
	v_mul_f32_e32 v221, v221, v205
	v_mul_f32_e32 v210, v210, v222
	v_mul_f32_e32 v211, v211, v223
	v_mul_f32_e32 v212, v212, v224
	v_mul_f32_e32 v213, v213, v225
	v_mul_f32_e32 v214, v214, v222
	v_mul_f32_e32 v215, v215, v223
	v_mul_f32_e32 v216, v216, v224
	v_mul_f32_e32 v217, v217, v225
	ds_write_b128 v146, v[206:209] offset:8192
	ds_write_b128 v146, v[218:221] offset:32768
	ds_write_b128 v146, v[210:213] offset:16384
	ds_write_b128 v146, v[214:217] offset:24576
	s_waitcnt lgkmcnt(0)
	s_barrier
	v_mbcnt_lo_u32_b32 v186, -1, 0
	v_mbcnt_hi_u32_b32 v186, -1, v186
	v_lshlrev_b32_e32 v186, 2, v186
	v_add_u32_e32 v186, 0xe000, v186
	v_cndmask_b32_e64 v185, v186, v152, s[8:9]
	ds_read_b128 v[8:11], v145 offset:16128
	ds_read_b128 v[12:15], v145 offset:24320
	ds_read_b128 v[16:19], v145 offset:32512
	ds_read_b128 v[20:23], v145 offset:40704
	ds_read2st64_b32 v[240:241], v151 offset0:223 offset1:222
	ds_read_b128 v[28:31], v145 offset:15872
	ds_read_b128 v[32:35], v145 offset:24064
	ds_read_b128 v[36:39], v145 offset:32256
	ds_read_b128 v[40:43], v145 offset:40448
	ds_read_b128 v[48:51], v145 offset:15616
	ds_read_b128 v[52:55], v145 offset:23808
	ds_read_b128 v[56:59], v145 offset:32000
	ds_read_b128 v[60:63], v145 offset:40192
	ds_read2st64_b32 v[242:243], v151 offset0:221 offset1:220
	s_waitcnt lgkmcnt(9)
	v_mul_f32_e32 v183, v179, v8
	v_mul_f32_e32 v184, v179, v20
	v_fmac_f32_e32 v183, v180, v9
	v_fmac_f32_e32 v184, v180, v21
	v_fmac_f32_e32 v183, v181, v10
	v_fmac_f32_e32 v184, v181, v22
	v_fmac_f32_e32 v183, v182, v11
	v_fmac_f32_e32 v184, v182, v23
	v_fmac_f32_e32 v179, v240, v16
	v_add_f32_dpp v183, v183, v183 quad_perm:[1,0,3,2] row_mask:0xf bank_mask:0xf bound_ctrl:1
	v_add_f32_dpp v184, v184, v184 quad_perm:[1,0,3,2] row_mask:0xf bank_mask:0xf bound_ctrl:1
	v_fmac_f32_e32 v180, v240, v17
	v_add_f32_dpp v183, v183, v183 quad_perm:[2,3,0,1] row_mask:0xf bank_mask:0xf bound_ctrl:1
	v_add_f32_dpp v184, v184, v184 quad_perm:[2,3,0,1] row_mask:0xf bank_mask:0xf bound_ctrl:1
	v_fmac_f32_e32 v181, v240, v18
	v_add_f32_dpp v183, v183, v183 row_half_mirror row_mask:0xf bank_mask:0xf bound_ctrl:1
	v_add_f32_dpp v184, v184, v184 row_half_mirror row_mask:0xf bank_mask:0xf bound_ctrl:1
	v_fmac_f32_e32 v182, v240, v19
	v_add_f32_dpp v183, v183, v183 row_mirror row_mask:0xf bank_mask:0xf bound_ctrl:1
	v_fmac_f32_e32 v179, v183, v12
	v_fmac_f32_e32 v180, v183, v13
	v_fmac_f32_e32 v181, v183, v14
	v_fmac_f32_e32 v182, v183, v15
	ds_read_b128 v[8:11], v145 offset:15360
	ds_read_b128 v[12:15], v145 offset:23552
	ds_read_b128 v[16:19], v145 offset:31744
	ds_read_b128 v[20:23], v145 offset:39936
	s_waitcnt lgkmcnt(9)
	v_mul_f32_e32 v183, v179, v28
	v_mul_f32_e32 v238, v179, v40
	v_fmac_f32_e32 v183, v180, v29
	v_fmac_f32_e32 v238, v180, v41
	v_fmac_f32_e32 v183, v181, v30
	v_fmac_f32_e32 v238, v181, v42
	v_fmac_f32_e32 v183, v182, v31
	v_fmac_f32_e32 v238, v182, v43
	v_fmac_f32_e32 v179, v241, v36
	v_add_f32_dpp v183, v183, v183 quad_perm:[1,0,3,2] row_mask:0xf bank_mask:0xf bound_ctrl:1
	v_add_f32_dpp v238, v238, v238 quad_perm:[1,0,3,2] row_mask:0xf bank_mask:0xf bound_ctrl:1
	v_fmac_f32_e32 v180, v241, v37
	v_add_f32_dpp v183, v183, v183 quad_perm:[2,3,0,1] row_mask:0xf bank_mask:0xf bound_ctrl:1
	v_add_f32_dpp v238, v238, v238 quad_perm:[2,3,0,1] row_mask:0xf bank_mask:0xf bound_ctrl:1
	v_fmac_f32_e32 v181, v241, v38
	v_add_f32_dpp v183, v183, v183 row_half_mirror row_mask:0xf bank_mask:0xf bound_ctrl:1
	v_add_f32_dpp v238, v238, v238 row_half_mirror row_mask:0xf bank_mask:0xf bound_ctrl:1
	v_fmac_f32_e32 v182, v241, v39
	v_add_f32_dpp v183, v183, v183 row_mirror row_mask:0xf bank_mask:0xf bound_ctrl:1
	v_fmac_f32_e32 v179, v183, v32
	v_fmac_f32_e32 v180, v183, v33
	v_fmac_f32_e32 v181, v183, v34
	v_fmac_f32_e32 v182, v183, v35
	s_mov_b64 exec, s[8:9]
	ds_write2st64_b32 v152, v184, v238 offset0:62 offset1:60
	s_mov_b64 exec, -1
	ds_read_b128 v[28:31], v145 offset:15104
	ds_read_b128 v[32:35], v145 offset:23296
	ds_read_b128 v[36:39], v145 offset:31488
	ds_read_b128 v[40:43], v145 offset:39680
	ds_read2st64_b32 v[240:241], v151 offset0:219 offset1:218
	s_waitcnt lgkmcnt(10)
	v_mul_f32_e32 v183, v179, v48
	v_mul_f32_e32 v184, v179, v60
	v_fmac_f32_e32 v183, v180, v49
	v_fmac_f32_e32 v184, v180, v61
	v_fmac_f32_e32 v183, v181, v50
	v_fmac_f32_e32 v184, v181, v62
	v_fmac_f32_e32 v183, v182, v51
	v_fmac_f32_e32 v184, v182, v63
	v_fmac_f32_e32 v179, v242, v56
	v_add_f32_dpp v183, v183, v183 quad_perm:[1,0,3,2] row_mask:0xf bank_mask:0xf bound_ctrl:1
	v_add_f32_dpp v184, v184, v184 quad_perm:[1,0,3,2] row_mask:0xf bank_mask:0xf bound_ctrl:1
	v_fmac_f32_e32 v180, v242, v57
	v_add_f32_dpp v183, v183, v183 quad_perm:[2,3,0,1] row_mask:0xf bank_mask:0xf bound_ctrl:1
	v_add_f32_dpp v184, v184, v184 quad_perm:[2,3,0,1] row_mask:0xf bank_mask:0xf bound_ctrl:1
	v_fmac_f32_e32 v181, v242, v58
	v_add_f32_dpp v183, v183, v183 row_half_mirror row_mask:0xf bank_mask:0xf bound_ctrl:1
	v_add_f32_dpp v184, v184, v184 row_half_mirror row_mask:0xf bank_mask:0xf bound_ctrl:1
	v_fmac_f32_e32 v182, v242, v59
	v_add_f32_dpp v183, v183, v183 row_mirror row_mask:0xf bank_mask:0xf bound_ctrl:1
	v_fmac_f32_e32 v179, v183, v52
	v_fmac_f32_e32 v180, v183, v53
	v_fmac_f32_e32 v181, v183, v54
	v_fmac_f32_e32 v182, v183, v55
	ds_read_b128 v[48:51], v145 offset:14848
	ds_read_b128 v[52:55], v145 offset:23040
	ds_read_b128 v[56:59], v145 offset:31232
	ds_read_b128 v[60:63], v145 offset:39424
	s_waitcnt lgkmcnt(10)
	v_mul_f32_e32 v183, v179, v8
	v_mul_f32_e32 v238, v179, v20
	v_fmac_f32_e32 v183, v180, v9
	v_fmac_f32_e32 v238, v180, v21
	v_fmac_f32_e32 v183, v181, v10
	v_fmac_f32_e32 v238, v181, v22
	v_fmac_f32_e32 v183, v182, v11
	v_fmac_f32_e32 v238, v182, v23
	v_fmac_f32_e32 v179, v243, v16
	v_add_f32_dpp v183, v183, v183 quad_perm:[1,0,3,2] row_mask:0xf bank_mask:0xf bound_ctrl:1
	v_add_f32_dpp v238, v238, v238 quad_perm:[1,0,3,2] row_mask:0xf bank_mask:0xf bound_ctrl:1
	v_fmac_f32_e32 v180, v243, v17
	v_add_f32_dpp v183, v183, v183 quad_perm:[2,3,0,1] row_mask:0xf bank_mask:0xf bound_ctrl:1
	v_add_f32_dpp v238, v238, v238 quad_perm:[2,3,0,1] row_mask:0xf bank_mask:0xf bound_ctrl:1
	v_fmac_f32_e32 v181, v243, v18
	v_add_f32_dpp v183, v183, v183 row_half_mirror row_mask:0xf bank_mask:0xf bound_ctrl:1
	v_add_f32_dpp v238, v238, v238 row_half_mirror row_mask:0xf bank_mask:0xf bound_ctrl:1
	v_fmac_f32_e32 v182, v243, v19
	v_add_f32_dpp v183, v183, v183 row_mirror row_mask:0xf bank_mask:0xf bound_ctrl:1
	v_fmac_f32_e32 v179, v183, v12
	v_fmac_f32_e32 v180, v183, v13
	v_fmac_f32_e32 v181, v183, v14
	v_fmac_f32_e32 v182, v183, v15
	s_mov_b64 exec, s[8:9]
	ds_write2st64_b32 v152, v184, v238 offset0:58 offset1:56
	s_mov_b64 exec, -1
	ds_read_b128 v[8:11], v145 offset:14592
	ds_read_b128 v[12:15], v145 offset:22784
	ds_read_b128 v[16:19], v145 offset:30976
	ds_read_b128 v[20:23], v145 offset:39168
	ds_read2st64_b32 v[242:243], v151 offset0:217 offset1:216
	s_waitcnt lgkmcnt(10)
	v_mul_f32_e32 v183, v179, v28
	v_mul_f32_e32 v184, v179, v40
	v_fmac_f32_e32 v183, v180, v29
	v_fmac_f32_e32 v184, v180, v41
	v_fmac_f32_e32 v183, v181, v30
	v_fmac_f32_e32 v184, v181, v42
	v_fmac_f32_e32 v183, v182, v31
	v_fmac_f32_e32 v184, v182, v43
	v_fmac_f32_e32 v179, v240, v36
	v_add_f32_dpp v183, v183, v183 quad_perm:[1,0,3,2] row_mask:0xf bank_mask:0xf bound_ctrl:1
	v_add_f32_dpp v184, v184, v184 quad_perm:[1,0,3,2] row_mask:0xf bank_mask:0xf bound_ctrl:1
	v_fmac_f32_e32 v180, v240, v37
	v_add_f32_dpp v183, v183, v183 quad_perm:[2,3,0,1] row_mask:0xf bank_mask:0xf bound_ctrl:1
	v_add_f32_dpp v184, v184, v184 quad_perm:[2,3,0,1] row_mask:0xf bank_mask:0xf bound_ctrl:1
	v_fmac_f32_e32 v181, v240, v38
	v_add_f32_dpp v183, v183, v183 row_half_mirror row_mask:0xf bank_mask:0xf bound_ctrl:1
	v_add_f32_dpp v184, v184, v184 row_half_mirror row_mask:0xf bank_mask:0xf bound_ctrl:1
	v_fmac_f32_e32 v182, v240, v39
	v_add_f32_dpp v183, v183, v183 row_mirror row_mask:0xf bank_mask:0xf bound_ctrl:1
	v_fmac_f32_e32 v179, v183, v32
	v_fmac_f32_e32 v180, v183, v33
	v_fmac_f32_e32 v181, v183, v34
	v_fmac_f32_e32 v182, v183, v35
	ds_read_b128 v[28:31], v145 offset:14336
	ds_read_b128 v[32:35], v145 offset:22528
	ds_read_b128 v[36:39], v145 offset:30720
	ds_read_b128 v[40:43], v145 offset:38912
	s_waitcnt lgkmcnt(10)
	v_mul_f32_e32 v183, v179, v48
	v_mul_f32_e32 v238, v179, v60
	v_fmac_f32_e32 v183, v180, v49
	v_fmac_f32_e32 v238, v180, v61
	v_fmac_f32_e32 v183, v181, v50
	v_fmac_f32_e32 v238, v181, v62
	v_fmac_f32_e32 v183, v182, v51
	v_fmac_f32_e32 v238, v182, v63
	v_fmac_f32_e32 v179, v241, v56
	v_add_f32_dpp v183, v183, v183 quad_perm:[1,0,3,2] row_mask:0xf bank_mask:0xf bound_ctrl:1
	v_add_f32_dpp v238, v238, v238 quad_perm:[1,0,3,2] row_mask:0xf bank_mask:0xf bound_ctrl:1
	v_fmac_f32_e32 v180, v241, v57
	v_add_f32_dpp v183, v183, v183 quad_perm:[2,3,0,1] row_mask:0xf bank_mask:0xf bound_ctrl:1
	v_add_f32_dpp v238, v238, v238 quad_perm:[2,3,0,1] row_mask:0xf bank_mask:0xf bound_ctrl:1
	v_fmac_f32_e32 v181, v241, v58
	v_add_f32_dpp v183, v183, v183 row_half_mirror row_mask:0xf bank_mask:0xf bound_ctrl:1
	v_add_f32_dpp v238, v238, v238 row_half_mirror row_mask:0xf bank_mask:0xf bound_ctrl:1
	v_fmac_f32_e32 v182, v241, v59
	v_add_f32_dpp v183, v183, v183 row_mirror row_mask:0xf bank_mask:0xf bound_ctrl:1
	v_fmac_f32_e32 v179, v183, v52
	v_fmac_f32_e32 v180, v183, v53
	v_fmac_f32_e32 v181, v183, v54
	v_fmac_f32_e32 v182, v183, v55
	s_mov_b64 exec, s[8:9]
	ds_write2st64_b32 v152, v184, v238 offset0:54 offset1:52
	s_mov_b64 exec, -1
	ds_read_b128 v[48:51], v145 offset:14080
	ds_read_b128 v[52:55], v145 offset:22272
	ds_read_b128 v[56:59], v145 offset:30464
	ds_read_b128 v[60:63], v145 offset:38656
	ds_read2st64_b32 v[240:241], v151 offset0:215 offset1:214
	s_waitcnt lgkmcnt(10)
	v_mul_f32_e32 v183, v179, v8
	v_mul_f32_e32 v184, v179, v20
	v_fmac_f32_e32 v183, v180, v9
	v_fmac_f32_e32 v184, v180, v21
	v_fmac_f32_e32 v183, v181, v10
	v_fmac_f32_e32 v184, v181, v22
	v_fmac_f32_e32 v183, v182, v11
	v_fmac_f32_e32 v184, v182, v23
	v_fmac_f32_e32 v179, v242, v16
	v_add_f32_dpp v183, v183, v183 quad_perm:[1,0,3,2] row_mask:0xf bank_mask:0xf bound_ctrl:1
	v_add_f32_dpp v184, v184, v184 quad_perm:[1,0,3,2] row_mask:0xf bank_mask:0xf bound_ctrl:1
	v_fmac_f32_e32 v180, v242, v17
	v_add_f32_dpp v183, v183, v183 quad_perm:[2,3,0,1] row_mask:0xf bank_mask:0xf bound_ctrl:1
	v_add_f32_dpp v184, v184, v184 quad_perm:[2,3,0,1] row_mask:0xf bank_mask:0xf bound_ctrl:1
	v_fmac_f32_e32 v181, v242, v18
	v_add_f32_dpp v183, v183, v183 row_half_mirror row_mask:0xf bank_mask:0xf bound_ctrl:1
	v_add_f32_dpp v184, v184, v184 row_half_mirror row_mask:0xf bank_mask:0xf bound_ctrl:1
	v_fmac_f32_e32 v182, v242, v19
	v_add_f32_dpp v183, v183, v183 row_mirror row_mask:0xf bank_mask:0xf bound_ctrl:1
	v_fmac_f32_e32 v179, v183, v12
	v_fmac_f32_e32 v180, v183, v13
	v_fmac_f32_e32 v181, v183, v14
	v_fmac_f32_e32 v182, v183, v15
	ds_read_b128 v[8:11], v145 offset:13824
	ds_read_b128 v[12:15], v145 offset:22016
	ds_read_b128 v[16:19], v145 offset:30208
	ds_read_b128 v[20:23], v145 offset:38400
	s_waitcnt lgkmcnt(10)
	v_mul_f32_e32 v183, v179, v28
	v_mul_f32_e32 v238, v179, v40
	v_fmac_f32_e32 v183, v180, v29
	v_fmac_f32_e32 v238, v180, v41
	v_fmac_f32_e32 v183, v181, v30
	v_fmac_f32_e32 v238, v181, v42
	v_fmac_f32_e32 v183, v182, v31
	v_fmac_f32_e32 v238, v182, v43
	v_fmac_f32_e32 v179, v243, v36
	v_add_f32_dpp v183, v183, v183 quad_perm:[1,0,3,2] row_mask:0xf bank_mask:0xf bound_ctrl:1
	v_add_f32_dpp v238, v238, v238 quad_perm:[1,0,3,2] row_mask:0xf bank_mask:0xf bound_ctrl:1
	v_fmac_f32_e32 v180, v243, v37
	v_add_f32_dpp v183, v183, v183 quad_perm:[2,3,0,1] row_mask:0xf bank_mask:0xf bound_ctrl:1
	v_add_f32_dpp v238, v238, v238 quad_perm:[2,3,0,1] row_mask:0xf bank_mask:0xf bound_ctrl:1
	v_fmac_f32_e32 v181, v243, v38
	v_add_f32_dpp v183, v183, v183 row_half_mirror row_mask:0xf bank_mask:0xf bound_ctrl:1
	v_add_f32_dpp v238, v238, v238 row_half_mirror row_mask:0xf bank_mask:0xf bound_ctrl:1
	v_fmac_f32_e32 v182, v243, v39
	v_add_f32_dpp v183, v183, v183 row_mirror row_mask:0xf bank_mask:0xf bound_ctrl:1
	v_fmac_f32_e32 v179, v183, v32
	v_fmac_f32_e32 v180, v183, v33
	v_fmac_f32_e32 v181, v183, v34
	v_fmac_f32_e32 v182, v183, v35
	s_mov_b64 exec, s[8:9]
	ds_write2st64_b32 v152, v184, v238 offset0:50 offset1:48
	s_mov_b64 exec, -1
	ds_read_b128 v[28:31], v145 offset:13568
	ds_read_b128 v[32:35], v145 offset:21760
	ds_read_b128 v[36:39], v145 offset:29952
	ds_read_b128 v[40:43], v145 offset:38144
	ds_read2st64_b32 v[242:243], v151 offset0:213 offset1:212
	s_waitcnt lgkmcnt(10)
	v_mul_f32_e32 v183, v179, v48
	v_mul_f32_e32 v184, v179, v60
	v_fmac_f32_e32 v183, v180, v49
	v_fmac_f32_e32 v184, v180, v61
	v_fmac_f32_e32 v183, v181, v50
	v_fmac_f32_e32 v184, v181, v62
	v_fmac_f32_e32 v183, v182, v51
	v_fmac_f32_e32 v184, v182, v63
	v_fmac_f32_e32 v179, v240, v56
	v_add_f32_dpp v183, v183, v183 quad_perm:[1,0,3,2] row_mask:0xf bank_mask:0xf bound_ctrl:1
	v_add_f32_dpp v184, v184, v184 quad_perm:[1,0,3,2] row_mask:0xf bank_mask:0xf bound_ctrl:1
	v_fmac_f32_e32 v180, v240, v57
	v_add_f32_dpp v183, v183, v183 quad_perm:[2,3,0,1] row_mask:0xf bank_mask:0xf bound_ctrl:1
	v_add_f32_dpp v184, v184, v184 quad_perm:[2,3,0,1] row_mask:0xf bank_mask:0xf bound_ctrl:1
	v_fmac_f32_e32 v181, v240, v58
	v_add_f32_dpp v183, v183, v183 row_half_mirror row_mask:0xf bank_mask:0xf bound_ctrl:1
	v_add_f32_dpp v184, v184, v184 row_half_mirror row_mask:0xf bank_mask:0xf bound_ctrl:1
	v_fmac_f32_e32 v182, v240, v59
	v_add_f32_dpp v183, v183, v183 row_mirror row_mask:0xf bank_mask:0xf bound_ctrl:1
	v_fmac_f32_e32 v179, v183, v52
	v_fmac_f32_e32 v180, v183, v53
	v_fmac_f32_e32 v181, v183, v54
	v_fmac_f32_e32 v182, v183, v55
	ds_read_b128 v[48:51], v145 offset:13312
	ds_read_b128 v[52:55], v145 offset:21504
	ds_read_b128 v[56:59], v145 offset:29696
	ds_read_b128 v[60:63], v145 offset:37888
	s_waitcnt lgkmcnt(10)
	v_mul_f32_e32 v183, v179, v8
	v_mul_f32_e32 v238, v179, v20
	v_fmac_f32_e32 v183, v180, v9
	v_fmac_f32_e32 v238, v180, v21
	v_fmac_f32_e32 v183, v181, v10
	v_fmac_f32_e32 v238, v181, v22
	v_fmac_f32_e32 v183, v182, v11
	v_fmac_f32_e32 v238, v182, v23
	v_fmac_f32_e32 v179, v241, v16
	v_add_f32_dpp v183, v183, v183 quad_perm:[1,0,3,2] row_mask:0xf bank_mask:0xf bound_ctrl:1
	v_add_f32_dpp v238, v238, v238 quad_perm:[1,0,3,2] row_mask:0xf bank_mask:0xf bound_ctrl:1
	v_fmac_f32_e32 v180, v241, v17
	v_add_f32_dpp v183, v183, v183 quad_perm:[2,3,0,1] row_mask:0xf bank_mask:0xf bound_ctrl:1
	v_add_f32_dpp v238, v238, v238 quad_perm:[2,3,0,1] row_mask:0xf bank_mask:0xf bound_ctrl:1
	v_fmac_f32_e32 v181, v241, v18
	v_add_f32_dpp v183, v183, v183 row_half_mirror row_mask:0xf bank_mask:0xf bound_ctrl:1
	v_add_f32_dpp v238, v238, v238 row_half_mirror row_mask:0xf bank_mask:0xf bound_ctrl:1
	v_fmac_f32_e32 v182, v241, v19
	v_add_f32_dpp v183, v183, v183 row_mirror row_mask:0xf bank_mask:0xf bound_ctrl:1
	v_fmac_f32_e32 v179, v183, v12
	v_fmac_f32_e32 v180, v183, v13
	v_fmac_f32_e32 v181, v183, v14
	v_fmac_f32_e32 v182, v183, v15
	s_mov_b64 exec, s[8:9]
	ds_write2st64_b32 v152, v184, v238 offset0:46 offset1:44
	s_mov_b64 exec, -1
	ds_read_b128 v[8:11], v145 offset:13056
	ds_read_b128 v[12:15], v145 offset:21248
	ds_read_b128 v[16:19], v145 offset:29440
	ds_read_b128 v[20:23], v145 offset:37632
	ds_read2st64_b32 v[240:241], v151 offset0:211 offset1:210
	s_waitcnt lgkmcnt(10)
	v_mul_f32_e32 v183, v179, v28
	v_mul_f32_e32 v184, v179, v40
	v_fmac_f32_e32 v183, v180, v29
	v_fmac_f32_e32 v184, v180, v41
	v_fmac_f32_e32 v183, v181, v30
	v_fmac_f32_e32 v184, v181, v42
	v_fmac_f32_e32 v183, v182, v31
	v_fmac_f32_e32 v184, v182, v43
	v_fmac_f32_e32 v179, v242, v36
	v_add_f32_dpp v183, v183, v183 quad_perm:[1,0,3,2] row_mask:0xf bank_mask:0xf bound_ctrl:1
	v_add_f32_dpp v184, v184, v184 quad_perm:[1,0,3,2] row_mask:0xf bank_mask:0xf bound_ctrl:1
	v_fmac_f32_e32 v180, v242, v37
	v_add_f32_dpp v183, v183, v183 quad_perm:[2,3,0,1] row_mask:0xf bank_mask:0xf bound_ctrl:1
	v_add_f32_dpp v184, v184, v184 quad_perm:[2,3,0,1] row_mask:0xf bank_mask:0xf bound_ctrl:1
	v_fmac_f32_e32 v181, v242, v38
	v_add_f32_dpp v183, v183, v183 row_half_mirror row_mask:0xf bank_mask:0xf bound_ctrl:1
	v_add_f32_dpp v184, v184, v184 row_half_mirror row_mask:0xf bank_mask:0xf bound_ctrl:1
	v_fmac_f32_e32 v182, v242, v39
	v_add_f32_dpp v183, v183, v183 row_mirror row_mask:0xf bank_mask:0xf bound_ctrl:1
	v_fmac_f32_e32 v179, v183, v32
	v_fmac_f32_e32 v180, v183, v33
	v_fmac_f32_e32 v181, v183, v34
	v_fmac_f32_e32 v182, v183, v35
	ds_read_b128 v[28:31], v145 offset:12800
	ds_read_b128 v[32:35], v145 offset:20992
	ds_read_b128 v[36:39], v145 offset:29184
	ds_read_b128 v[40:43], v145 offset:37376
	s_waitcnt lgkmcnt(10)
	v_mul_f32_e32 v183, v179, v48
	v_mul_f32_e32 v238, v179, v60
	v_fmac_f32_e32 v183, v180, v49
	v_fmac_f32_e32 v238, v180, v61
	v_fmac_f32_e32 v183, v181, v50
	v_fmac_f32_e32 v238, v181, v62
	v_fmac_f32_e32 v183, v182, v51
	v_fmac_f32_e32 v238, v182, v63
	v_fmac_f32_e32 v179, v243, v56
	v_add_f32_dpp v183, v183, v183 quad_perm:[1,0,3,2] row_mask:0xf bank_mask:0xf bound_ctrl:1
	v_add_f32_dpp v238, v238, v238 quad_perm:[1,0,3,2] row_mask:0xf bank_mask:0xf bound_ctrl:1
	v_fmac_f32_e32 v180, v243, v57
	v_add_f32_dpp v183, v183, v183 quad_perm:[2,3,0,1] row_mask:0xf bank_mask:0xf bound_ctrl:1
	v_add_f32_dpp v238, v238, v238 quad_perm:[2,3,0,1] row_mask:0xf bank_mask:0xf bound_ctrl:1
	v_fmac_f32_e32 v181, v243, v58
	v_add_f32_dpp v183, v183, v183 row_half_mirror row_mask:0xf bank_mask:0xf bound_ctrl:1
	v_add_f32_dpp v238, v238, v238 row_half_mirror row_mask:0xf bank_mask:0xf bound_ctrl:1
	v_fmac_f32_e32 v182, v243, v59
	v_add_f32_dpp v183, v183, v183 row_mirror row_mask:0xf bank_mask:0xf bound_ctrl:1
	v_fmac_f32_e32 v179, v183, v52
	v_fmac_f32_e32 v180, v183, v53
	v_fmac_f32_e32 v181, v183, v54
	v_fmac_f32_e32 v182, v183, v55
	s_mov_b64 exec, s[8:9]
	ds_write2st64_b32 v152, v184, v238 offset0:42 offset1:40
	s_mov_b64 exec, -1
	ds_read_b128 v[48:51], v145 offset:12544
	ds_read_b128 v[52:55], v145 offset:20736
	ds_read_b128 v[56:59], v145 offset:28928
	ds_read_b128 v[60:63], v145 offset:37120
	ds_read2st64_b32 v[242:243], v151 offset0:209 offset1:208
	s_waitcnt lgkmcnt(10)
	v_mul_f32_e32 v183, v179, v8
	v_mul_f32_e32 v184, v179, v20
	v_fmac_f32_e32 v183, v180, v9
	v_fmac_f32_e32 v184, v180, v21
	v_fmac_f32_e32 v183, v181, v10
	v_fmac_f32_e32 v184, v181, v22
	v_fmac_f32_e32 v183, v182, v11
	v_fmac_f32_e32 v184, v182, v23
	v_fmac_f32_e32 v179, v240, v16
	v_add_f32_dpp v183, v183, v183 quad_perm:[1,0,3,2] row_mask:0xf bank_mask:0xf bound_ctrl:1
	v_add_f32_dpp v184, v184, v184 quad_perm:[1,0,3,2] row_mask:0xf bank_mask:0xf bound_ctrl:1
	v_fmac_f32_e32 v180, v240, v17
	v_add_f32_dpp v183, v183, v183 quad_perm:[2,3,0,1] row_mask:0xf bank_mask:0xf bound_ctrl:1
	v_add_f32_dpp v184, v184, v184 quad_perm:[2,3,0,1] row_mask:0xf bank_mask:0xf bound_ctrl:1
	v_fmac_f32_e32 v181, v240, v18
	v_add_f32_dpp v183, v183, v183 row_half_mirror row_mask:0xf bank_mask:0xf bound_ctrl:1
	v_add_f32_dpp v184, v184, v184 row_half_mirror row_mask:0xf bank_mask:0xf bound_ctrl:1
	v_fmac_f32_e32 v182, v240, v19
	v_add_f32_dpp v183, v183, v183 row_mirror row_mask:0xf bank_mask:0xf bound_ctrl:1
	v_fmac_f32_e32 v179, v183, v12
	v_fmac_f32_e32 v180, v183, v13
	v_fmac_f32_e32 v181, v183, v14
	v_fmac_f32_e32 v182, v183, v15
	ds_read_b128 v[8:11], v145 offset:12288
	ds_read_b128 v[12:15], v145 offset:20480
	ds_read_b128 v[16:19], v145 offset:28672
	ds_read_b128 v[20:23], v145 offset:36864
	s_waitcnt lgkmcnt(10)
	v_mul_f32_e32 v183, v179, v28
	v_mul_f32_e32 v238, v179, v40
	v_fmac_f32_e32 v183, v180, v29
	v_fmac_f32_e32 v238, v180, v41
	v_fmac_f32_e32 v183, v181, v30
	v_fmac_f32_e32 v238, v181, v42
	v_fmac_f32_e32 v183, v182, v31
	v_fmac_f32_e32 v238, v182, v43
	v_fmac_f32_e32 v179, v241, v36
	v_add_f32_dpp v183, v183, v183 quad_perm:[1,0,3,2] row_mask:0xf bank_mask:0xf bound_ctrl:1
	v_add_f32_dpp v238, v238, v238 quad_perm:[1,0,3,2] row_mask:0xf bank_mask:0xf bound_ctrl:1
	v_fmac_f32_e32 v180, v241, v37
	v_add_f32_dpp v183, v183, v183 quad_perm:[2,3,0,1] row_mask:0xf bank_mask:0xf bound_ctrl:1
	v_add_f32_dpp v238, v238, v238 quad_perm:[2,3,0,1] row_mask:0xf bank_mask:0xf bound_ctrl:1
	v_fmac_f32_e32 v181, v241, v38
	v_add_f32_dpp v183, v183, v183 row_half_mirror row_mask:0xf bank_mask:0xf bound_ctrl:1
	v_add_f32_dpp v238, v238, v238 row_half_mirror row_mask:0xf bank_mask:0xf bound_ctrl:1
	v_fmac_f32_e32 v182, v241, v39
	v_add_f32_dpp v183, v183, v183 row_mirror row_mask:0xf bank_mask:0xf bound_ctrl:1
	v_fmac_f32_e32 v179, v183, v32
	v_fmac_f32_e32 v180, v183, v33
	v_fmac_f32_e32 v181, v183, v34
	v_fmac_f32_e32 v182, v183, v35
	s_mov_b64 exec, s[8:9]
	ds_write2st64_b32 v152, v184, v238 offset0:38 offset1:36
	s_mov_b64 exec, -1
	ds_read_b128 v[28:31], v145 offset:12032
	ds_read_b128 v[32:35], v145 offset:20224
	ds_read_b128 v[36:39], v145 offset:28416
	ds_read_b128 v[40:43], v145 offset:36608
	ds_read2st64_b32 v[240:241], v151 offset0:207 offset1:206
	s_waitcnt lgkmcnt(10)
	v_mul_f32_e32 v183, v179, v48
	v_mul_f32_e32 v184, v179, v60
	v_fmac_f32_e32 v183, v180, v49
	v_fmac_f32_e32 v184, v180, v61
	v_fmac_f32_e32 v183, v181, v50
	v_fmac_f32_e32 v184, v181, v62
	v_fmac_f32_e32 v183, v182, v51
	v_fmac_f32_e32 v184, v182, v63
	v_fmac_f32_e32 v179, v242, v56
	v_add_f32_dpp v183, v183, v183 quad_perm:[1,0,3,2] row_mask:0xf bank_mask:0xf bound_ctrl:1
	v_add_f32_dpp v184, v184, v184 quad_perm:[1,0,3,2] row_mask:0xf bank_mask:0xf bound_ctrl:1
	v_fmac_f32_e32 v180, v242, v57
	v_add_f32_dpp v183, v183, v183 quad_perm:[2,3,0,1] row_mask:0xf bank_mask:0xf bound_ctrl:1
	v_add_f32_dpp v184, v184, v184 quad_perm:[2,3,0,1] row_mask:0xf bank_mask:0xf bound_ctrl:1
	v_fmac_f32_e32 v181, v242, v58
	v_add_f32_dpp v183, v183, v183 row_half_mirror row_mask:0xf bank_mask:0xf bound_ctrl:1
	v_add_f32_dpp v184, v184, v184 row_half_mirror row_mask:0xf bank_mask:0xf bound_ctrl:1
	v_fmac_f32_e32 v182, v242, v59
	v_add_f32_dpp v183, v183, v183 row_mirror row_mask:0xf bank_mask:0xf bound_ctrl:1
	v_fmac_f32_e32 v179, v183, v52
	v_fmac_f32_e32 v180, v183, v53
	v_fmac_f32_e32 v181, v183, v54
	v_fmac_f32_e32 v182, v183, v55
	ds_read_b128 v[48:51], v145 offset:11776
	ds_read_b128 v[52:55], v145 offset:19968
	ds_read_b128 v[56:59], v145 offset:28160
	ds_read_b128 v[60:63], v145 offset:36352
	s_waitcnt lgkmcnt(10)
	v_mul_f32_e32 v183, v179, v8
	v_mul_f32_e32 v238, v179, v20
	v_fmac_f32_e32 v183, v180, v9
	v_fmac_f32_e32 v238, v180, v21
	v_fmac_f32_e32 v183, v181, v10
	v_fmac_f32_e32 v238, v181, v22
	v_fmac_f32_e32 v183, v182, v11
	v_fmac_f32_e32 v238, v182, v23
	v_fmac_f32_e32 v179, v243, v16
	v_add_f32_dpp v183, v183, v183 quad_perm:[1,0,3,2] row_mask:0xf bank_mask:0xf bound_ctrl:1
	v_add_f32_dpp v238, v238, v238 quad_perm:[1,0,3,2] row_mask:0xf bank_mask:0xf bound_ctrl:1
	v_fmac_f32_e32 v180, v243, v17
	v_add_f32_dpp v183, v183, v183 quad_perm:[2,3,0,1] row_mask:0xf bank_mask:0xf bound_ctrl:1
	v_add_f32_dpp v238, v238, v238 quad_perm:[2,3,0,1] row_mask:0xf bank_mask:0xf bound_ctrl:1
	v_fmac_f32_e32 v181, v243, v18
	v_add_f32_dpp v183, v183, v183 row_half_mirror row_mask:0xf bank_mask:0xf bound_ctrl:1
	v_add_f32_dpp v238, v238, v238 row_half_mirror row_mask:0xf bank_mask:0xf bound_ctrl:1
	v_fmac_f32_e32 v182, v243, v19
	v_add_f32_dpp v183, v183, v183 row_mirror row_mask:0xf bank_mask:0xf bound_ctrl:1
	v_fmac_f32_e32 v179, v183, v12
	v_fmac_f32_e32 v180, v183, v13
	v_fmac_f32_e32 v181, v183, v14
	v_fmac_f32_e32 v182, v183, v15
	s_mov_b64 exec, s[8:9]
	ds_write2st64_b32 v152, v184, v238 offset0:34 offset1:32
	s_mov_b64 exec, -1
	ds_read_b128 v[8:11], v145 offset:11520
	ds_read_b128 v[12:15], v145 offset:19712
	ds_read_b128 v[16:19], v145 offset:27904
	ds_read_b128 v[20:23], v145 offset:36096
	ds_read2st64_b32 v[242:243], v151 offset0:205 offset1:204
	s_waitcnt lgkmcnt(10)
	v_mul_f32_e32 v183, v179, v28
	v_mul_f32_e32 v184, v179, v40
	v_fmac_f32_e32 v183, v180, v29
	v_fmac_f32_e32 v184, v180, v41
	v_fmac_f32_e32 v183, v181, v30
	v_fmac_f32_e32 v184, v181, v42
	v_fmac_f32_e32 v183, v182, v31
	v_fmac_f32_e32 v184, v182, v43
	v_fmac_f32_e32 v179, v240, v36
	v_add_f32_dpp v183, v183, v183 quad_perm:[1,0,3,2] row_mask:0xf bank_mask:0xf bound_ctrl:1
	v_add_f32_dpp v184, v184, v184 quad_perm:[1,0,3,2] row_mask:0xf bank_mask:0xf bound_ctrl:1
	v_fmac_f32_e32 v180, v240, v37
	v_add_f32_dpp v183, v183, v183 quad_perm:[2,3,0,1] row_mask:0xf bank_mask:0xf bound_ctrl:1
	v_add_f32_dpp v184, v184, v184 quad_perm:[2,3,0,1] row_mask:0xf bank_mask:0xf bound_ctrl:1
	v_fmac_f32_e32 v181, v240, v38
	v_add_f32_dpp v183, v183, v183 row_half_mirror row_mask:0xf bank_mask:0xf bound_ctrl:1
	v_add_f32_dpp v184, v184, v184 row_half_mirror row_mask:0xf bank_mask:0xf bound_ctrl:1
	v_fmac_f32_e32 v182, v240, v39
	v_add_f32_dpp v183, v183, v183 row_mirror row_mask:0xf bank_mask:0xf bound_ctrl:1
	v_fmac_f32_e32 v179, v183, v32
	v_fmac_f32_e32 v180, v183, v33
	v_fmac_f32_e32 v181, v183, v34
	v_fmac_f32_e32 v182, v183, v35
	ds_read_b128 v[28:31], v145 offset:11264
	ds_read_b128 v[32:35], v145 offset:19456
	ds_read_b128 v[36:39], v145 offset:27648
	ds_read_b128 v[40:43], v145 offset:35840
	s_waitcnt lgkmcnt(10)
	v_mul_f32_e32 v183, v179, v48
	v_mul_f32_e32 v238, v179, v60
	v_fmac_f32_e32 v183, v180, v49
	v_fmac_f32_e32 v238, v180, v61
	v_fmac_f32_e32 v183, v181, v50
	v_fmac_f32_e32 v238, v181, v62
	v_fmac_f32_e32 v183, v182, v51
	v_fmac_f32_e32 v238, v182, v63
	v_fmac_f32_e32 v179, v241, v56
	v_add_f32_dpp v183, v183, v183 quad_perm:[1,0,3,2] row_mask:0xf bank_mask:0xf bound_ctrl:1
	v_add_f32_dpp v238, v238, v238 quad_perm:[1,0,3,2] row_mask:0xf bank_mask:0xf bound_ctrl:1
	v_fmac_f32_e32 v180, v241, v57
	v_add_f32_dpp v183, v183, v183 quad_perm:[2,3,0,1] row_mask:0xf bank_mask:0xf bound_ctrl:1
	v_add_f32_dpp v238, v238, v238 quad_perm:[2,3,0,1] row_mask:0xf bank_mask:0xf bound_ctrl:1
	v_fmac_f32_e32 v181, v241, v58
	v_add_f32_dpp v183, v183, v183 row_half_mirror row_mask:0xf bank_mask:0xf bound_ctrl:1
	v_add_f32_dpp v238, v238, v238 row_half_mirror row_mask:0xf bank_mask:0xf bound_ctrl:1
	v_fmac_f32_e32 v182, v241, v59
	v_add_f32_dpp v183, v183, v183 row_mirror row_mask:0xf bank_mask:0xf bound_ctrl:1
	v_fmac_f32_e32 v179, v183, v52
	v_fmac_f32_e32 v180, v183, v53
	v_fmac_f32_e32 v181, v183, v54
	v_fmac_f32_e32 v182, v183, v55
	s_mov_b64 exec, s[8:9]
	ds_write2st64_b32 v152, v184, v238 offset0:30 offset1:28
	s_mov_b64 exec, -1
	ds_read_b128 v[48:51], v145 offset:11008
	ds_read_b128 v[52:55], v145 offset:19200
	ds_read_b128 v[56:59], v145 offset:27392
	ds_read_b128 v[60:63], v145 offset:35584
	ds_read2st64_b32 v[240:241], v151 offset0:203 offset1:202
	s_waitcnt lgkmcnt(10)
	v_mul_f32_e32 v183, v179, v8
	v_mul_f32_e32 v184, v179, v20
	v_fmac_f32_e32 v183, v180, v9
	v_fmac_f32_e32 v184, v180, v21
	v_fmac_f32_e32 v183, v181, v10
	v_fmac_f32_e32 v184, v181, v22
	v_fmac_f32_e32 v183, v182, v11
	v_fmac_f32_e32 v184, v182, v23
	v_fmac_f32_e32 v179, v242, v16
	v_add_f32_dpp v183, v183, v183 quad_perm:[1,0,3,2] row_mask:0xf bank_mask:0xf bound_ctrl:1
	v_add_f32_dpp v184, v184, v184 quad_perm:[1,0,3,2] row_mask:0xf bank_mask:0xf bound_ctrl:1
	v_fmac_f32_e32 v180, v242, v17
	v_add_f32_dpp v183, v183, v183 quad_perm:[2,3,0,1] row_mask:0xf bank_mask:0xf bound_ctrl:1
	v_add_f32_dpp v184, v184, v184 quad_perm:[2,3,0,1] row_mask:0xf bank_mask:0xf bound_ctrl:1
	v_fmac_f32_e32 v181, v242, v18
	v_add_f32_dpp v183, v183, v183 row_half_mirror row_mask:0xf bank_mask:0xf bound_ctrl:1
	v_add_f32_dpp v184, v184, v184 row_half_mirror row_mask:0xf bank_mask:0xf bound_ctrl:1
	v_fmac_f32_e32 v182, v242, v19
	v_add_f32_dpp v183, v183, v183 row_mirror row_mask:0xf bank_mask:0xf bound_ctrl:1
	v_fmac_f32_e32 v179, v183, v12
	v_fmac_f32_e32 v180, v183, v13
	v_fmac_f32_e32 v181, v183, v14
	v_fmac_f32_e32 v182, v183, v15
	ds_read_b128 v[8:11], v145 offset:10752
	ds_read_b128 v[12:15], v145 offset:18944
	ds_read_b128 v[16:19], v145 offset:27136
	ds_read_b128 v[20:23], v145 offset:35328
	s_waitcnt lgkmcnt(10)
	v_mul_f32_e32 v183, v179, v28
	v_mul_f32_e32 v238, v179, v40
	v_fmac_f32_e32 v183, v180, v29
	v_fmac_f32_e32 v238, v180, v41
	v_fmac_f32_e32 v183, v181, v30
	v_fmac_f32_e32 v238, v181, v42
	v_fmac_f32_e32 v183, v182, v31
	v_fmac_f32_e32 v238, v182, v43
	v_fmac_f32_e32 v179, v243, v36
	v_add_f32_dpp v183, v183, v183 quad_perm:[1,0,3,2] row_mask:0xf bank_mask:0xf bound_ctrl:1
	v_add_f32_dpp v238, v238, v238 quad_perm:[1,0,3,2] row_mask:0xf bank_mask:0xf bound_ctrl:1
	v_fmac_f32_e32 v180, v243, v37
	v_add_f32_dpp v183, v183, v183 quad_perm:[2,3,0,1] row_mask:0xf bank_mask:0xf bound_ctrl:1
	v_add_f32_dpp v238, v238, v238 quad_perm:[2,3,0,1] row_mask:0xf bank_mask:0xf bound_ctrl:1
	v_fmac_f32_e32 v181, v243, v38
	v_add_f32_dpp v183, v183, v183 row_half_mirror row_mask:0xf bank_mask:0xf bound_ctrl:1
	v_add_f32_dpp v238, v238, v238 row_half_mirror row_mask:0xf bank_mask:0xf bound_ctrl:1
	v_fmac_f32_e32 v182, v243, v39
	v_add_f32_dpp v183, v183, v183 row_mirror row_mask:0xf bank_mask:0xf bound_ctrl:1
	v_fmac_f32_e32 v179, v183, v32
	v_fmac_f32_e32 v180, v183, v33
	v_fmac_f32_e32 v181, v183, v34
	v_fmac_f32_e32 v182, v183, v35
	s_mov_b64 exec, s[8:9]
	ds_write2st64_b32 v152, v184, v238 offset0:26 offset1:24
	s_mov_b64 exec, -1
	ds_read_b128 v[28:31], v145 offset:10496
	ds_read_b128 v[32:35], v145 offset:18688
	ds_read_b128 v[36:39], v145 offset:26880
	ds_read_b128 v[40:43], v145 offset:35072
	ds_read2st64_b32 v[242:243], v151 offset0:201 offset1:200
	s_waitcnt lgkmcnt(10)
	v_mul_f32_e32 v183, v179, v48
	v_mul_f32_e32 v184, v179, v60
	v_fmac_f32_e32 v183, v180, v49
	v_fmac_f32_e32 v184, v180, v61
	v_fmac_f32_e32 v183, v181, v50
	v_fmac_f32_e32 v184, v181, v62
	v_fmac_f32_e32 v183, v182, v51
	v_fmac_f32_e32 v184, v182, v63
	v_fmac_f32_e32 v179, v240, v56
	v_add_f32_dpp v183, v183, v183 quad_perm:[1,0,3,2] row_mask:0xf bank_mask:0xf bound_ctrl:1
	v_add_f32_dpp v184, v184, v184 quad_perm:[1,0,3,2] row_mask:0xf bank_mask:0xf bound_ctrl:1
	v_fmac_f32_e32 v180, v240, v57
	v_add_f32_dpp v183, v183, v183 quad_perm:[2,3,0,1] row_mask:0xf bank_mask:0xf bound_ctrl:1
	v_add_f32_dpp v184, v184, v184 quad_perm:[2,3,0,1] row_mask:0xf bank_mask:0xf bound_ctrl:1
	v_fmac_f32_e32 v181, v240, v58
	v_add_f32_dpp v183, v183, v183 row_half_mirror row_mask:0xf bank_mask:0xf bound_ctrl:1
	v_add_f32_dpp v184, v184, v184 row_half_mirror row_mask:0xf bank_mask:0xf bound_ctrl:1
	v_fmac_f32_e32 v182, v240, v59
	v_add_f32_dpp v183, v183, v183 row_mirror row_mask:0xf bank_mask:0xf bound_ctrl:1
	v_fmac_f32_e32 v179, v183, v52
	v_fmac_f32_e32 v180, v183, v53
	v_fmac_f32_e32 v181, v183, v54
	v_fmac_f32_e32 v182, v183, v55
	ds_read_b128 v[48:51], v145 offset:10240
	ds_read_b128 v[52:55], v145 offset:18432
	ds_read_b128 v[56:59], v145 offset:26624
	ds_read_b128 v[60:63], v145 offset:34816
	s_waitcnt lgkmcnt(10)
	v_mul_f32_e32 v183, v179, v8
	v_mul_f32_e32 v238, v179, v20
	v_fmac_f32_e32 v183, v180, v9
	v_fmac_f32_e32 v238, v180, v21
	v_fmac_f32_e32 v183, v181, v10
	v_fmac_f32_e32 v238, v181, v22
	v_fmac_f32_e32 v183, v182, v11
	v_fmac_f32_e32 v238, v182, v23
	v_fmac_f32_e32 v179, v241, v16
	v_add_f32_dpp v183, v183, v183 quad_perm:[1,0,3,2] row_mask:0xf bank_mask:0xf bound_ctrl:1
	v_add_f32_dpp v238, v238, v238 quad_perm:[1,0,3,2] row_mask:0xf bank_mask:0xf bound_ctrl:1
	v_fmac_f32_e32 v180, v241, v17
	v_add_f32_dpp v183, v183, v183 quad_perm:[2,3,0,1] row_mask:0xf bank_mask:0xf bound_ctrl:1
	v_add_f32_dpp v238, v238, v238 quad_perm:[2,3,0,1] row_mask:0xf bank_mask:0xf bound_ctrl:1
	v_fmac_f32_e32 v181, v241, v18
	v_add_f32_dpp v183, v183, v183 row_half_mirror row_mask:0xf bank_mask:0xf bound_ctrl:1
	v_add_f32_dpp v238, v238, v238 row_half_mirror row_mask:0xf bank_mask:0xf bound_ctrl:1
	v_fmac_f32_e32 v182, v241, v19
	v_add_f32_dpp v183, v183, v183 row_mirror row_mask:0xf bank_mask:0xf bound_ctrl:1
	v_fmac_f32_e32 v179, v183, v12
	v_fmac_f32_e32 v180, v183, v13
	v_fmac_f32_e32 v181, v183, v14
	v_fmac_f32_e32 v182, v183, v15
	s_mov_b64 exec, s[8:9]
	ds_write2st64_b32 v152, v184, v238 offset0:22 offset1:20
	s_mov_b64 exec, -1
	ds_read_b128 v[8:11], v145 offset:9984
	ds_read_b128 v[12:15], v145 offset:18176
	ds_read_b128 v[16:19], v145 offset:26368
	ds_read_b128 v[20:23], v145 offset:34560
	ds_read2st64_b32 v[240:241], v151 offset0:199 offset1:198
	s_waitcnt lgkmcnt(10)
	v_mul_f32_e32 v183, v179, v28
	v_mul_f32_e32 v184, v179, v40
	v_fmac_f32_e32 v183, v180, v29
	v_fmac_f32_e32 v184, v180, v41
	v_fmac_f32_e32 v183, v181, v30
	v_fmac_f32_e32 v184, v181, v42
	v_fmac_f32_e32 v183, v182, v31
	v_fmac_f32_e32 v184, v182, v43
	v_fmac_f32_e32 v179, v242, v36
	v_add_f32_dpp v183, v183, v183 quad_perm:[1,0,3,2] row_mask:0xf bank_mask:0xf bound_ctrl:1
	v_add_f32_dpp v184, v184, v184 quad_perm:[1,0,3,2] row_mask:0xf bank_mask:0xf bound_ctrl:1
	v_fmac_f32_e32 v180, v242, v37
	v_add_f32_dpp v183, v183, v183 quad_perm:[2,3,0,1] row_mask:0xf bank_mask:0xf bound_ctrl:1
	v_add_f32_dpp v184, v184, v184 quad_perm:[2,3,0,1] row_mask:0xf bank_mask:0xf bound_ctrl:1
	v_fmac_f32_e32 v181, v242, v38
	v_add_f32_dpp v183, v183, v183 row_half_mirror row_mask:0xf bank_mask:0xf bound_ctrl:1
	v_add_f32_dpp v184, v184, v184 row_half_mirror row_mask:0xf bank_mask:0xf bound_ctrl:1
	v_fmac_f32_e32 v182, v242, v39
	v_add_f32_dpp v183, v183, v183 row_mirror row_mask:0xf bank_mask:0xf bound_ctrl:1
	v_fmac_f32_e32 v179, v183, v32
	v_fmac_f32_e32 v180, v183, v33
	v_fmac_f32_e32 v181, v183, v34
	v_fmac_f32_e32 v182, v183, v35
	ds_read_b128 v[28:31], v145 offset:9728
	ds_read_b128 v[32:35], v145 offset:17920
	ds_read_b128 v[36:39], v145 offset:26112
	ds_read_b128 v[40:43], v145 offset:34304
	s_waitcnt lgkmcnt(10)
	v_mul_f32_e32 v183, v179, v48
	v_mul_f32_e32 v238, v179, v60
	v_fmac_f32_e32 v183, v180, v49
	v_fmac_f32_e32 v238, v180, v61
	v_fmac_f32_e32 v183, v181, v50
	v_fmac_f32_e32 v238, v181, v62
	v_fmac_f32_e32 v183, v182, v51
	v_fmac_f32_e32 v238, v182, v63
	v_fmac_f32_e32 v179, v243, v56
	v_add_f32_dpp v183, v183, v183 quad_perm:[1,0,3,2] row_mask:0xf bank_mask:0xf bound_ctrl:1
	v_add_f32_dpp v238, v238, v238 quad_perm:[1,0,3,2] row_mask:0xf bank_mask:0xf bound_ctrl:1
	v_fmac_f32_e32 v180, v243, v57
	v_add_f32_dpp v183, v183, v183 quad_perm:[2,3,0,1] row_mask:0xf bank_mask:0xf bound_ctrl:1
	v_add_f32_dpp v238, v238, v238 quad_perm:[2,3,0,1] row_mask:0xf bank_mask:0xf bound_ctrl:1
	v_fmac_f32_e32 v181, v243, v58
	v_add_f32_dpp v183, v183, v183 row_half_mirror row_mask:0xf bank_mask:0xf bound_ctrl:1
	v_add_f32_dpp v238, v238, v238 row_half_mirror row_mask:0xf bank_mask:0xf bound_ctrl:1
	v_fmac_f32_e32 v182, v243, v59
	v_add_f32_dpp v183, v183, v183 row_mirror row_mask:0xf bank_mask:0xf bound_ctrl:1
	v_fmac_f32_e32 v179, v183, v52
	v_fmac_f32_e32 v180, v183, v53
	v_fmac_f32_e32 v181, v183, v54
	v_fmac_f32_e32 v182, v183, v55
	s_mov_b64 exec, s[8:9]
	ds_write2st64_b32 v152, v184, v238 offset0:18 offset1:16
	s_mov_b64 exec, -1
	ds_read_b128 v[48:51], v145 offset:9472
	ds_read_b128 v[52:55], v145 offset:17664
	ds_read_b128 v[56:59], v145 offset:25856
	ds_read_b128 v[60:63], v145 offset:34048
	ds_read2st64_b32 v[242:243], v151 offset0:197 offset1:196
	s_waitcnt lgkmcnt(10)
	v_mul_f32_e32 v183, v179, v8
	v_mul_f32_e32 v184, v179, v20
	v_fmac_f32_e32 v183, v180, v9
	v_fmac_f32_e32 v184, v180, v21
	v_fmac_f32_e32 v183, v181, v10
	v_fmac_f32_e32 v184, v181, v22
	v_fmac_f32_e32 v183, v182, v11
	v_fmac_f32_e32 v184, v182, v23
	v_fmac_f32_e32 v179, v240, v16
	v_add_f32_dpp v183, v183, v183 quad_perm:[1,0,3,2] row_mask:0xf bank_mask:0xf bound_ctrl:1
	v_add_f32_dpp v184, v184, v184 quad_perm:[1,0,3,2] row_mask:0xf bank_mask:0xf bound_ctrl:1
	v_fmac_f32_e32 v180, v240, v17
	v_add_f32_dpp v183, v183, v183 quad_perm:[2,3,0,1] row_mask:0xf bank_mask:0xf bound_ctrl:1
	v_add_f32_dpp v184, v184, v184 quad_perm:[2,3,0,1] row_mask:0xf bank_mask:0xf bound_ctrl:1
	v_fmac_f32_e32 v181, v240, v18
	v_add_f32_dpp v183, v183, v183 row_half_mirror row_mask:0xf bank_mask:0xf bound_ctrl:1
	v_add_f32_dpp v184, v184, v184 row_half_mirror row_mask:0xf bank_mask:0xf bound_ctrl:1
	v_fmac_f32_e32 v182, v240, v19
	v_add_f32_dpp v183, v183, v183 row_mirror row_mask:0xf bank_mask:0xf bound_ctrl:1
	v_fmac_f32_e32 v179, v183, v12
	v_fmac_f32_e32 v180, v183, v13
	v_fmac_f32_e32 v181, v183, v14
	v_fmac_f32_e32 v182, v183, v15
	ds_read_b128 v[8:11], v145 offset:9216
	ds_read_b128 v[12:15], v145 offset:17408
	ds_read_b128 v[16:19], v145 offset:25600
	ds_read_b128 v[20:23], v145 offset:33792
	s_waitcnt lgkmcnt(10)
	v_mul_f32_e32 v183, v179, v28
	v_mul_f32_e32 v238, v179, v40
	v_fmac_f32_e32 v183, v180, v29
	v_fmac_f32_e32 v238, v180, v41
	v_fmac_f32_e32 v183, v181, v30
	v_fmac_f32_e32 v238, v181, v42
	v_fmac_f32_e32 v183, v182, v31
	v_fmac_f32_e32 v238, v182, v43
	v_fmac_f32_e32 v179, v241, v36
	v_add_f32_dpp v183, v183, v183 quad_perm:[1,0,3,2] row_mask:0xf bank_mask:0xf bound_ctrl:1
	v_add_f32_dpp v238, v238, v238 quad_perm:[1,0,3,2] row_mask:0xf bank_mask:0xf bound_ctrl:1
	v_fmac_f32_e32 v180, v241, v37
	v_add_f32_dpp v183, v183, v183 quad_perm:[2,3,0,1] row_mask:0xf bank_mask:0xf bound_ctrl:1
	v_add_f32_dpp v238, v238, v238 quad_perm:[2,3,0,1] row_mask:0xf bank_mask:0xf bound_ctrl:1
	v_fmac_f32_e32 v181, v241, v38
	v_add_f32_dpp v183, v183, v183 row_half_mirror row_mask:0xf bank_mask:0xf bound_ctrl:1
	v_add_f32_dpp v238, v238, v238 row_half_mirror row_mask:0xf bank_mask:0xf bound_ctrl:1
	v_fmac_f32_e32 v182, v241, v39
	v_add_f32_dpp v183, v183, v183 row_mirror row_mask:0xf bank_mask:0xf bound_ctrl:1
	v_fmac_f32_e32 v179, v183, v32
	v_fmac_f32_e32 v180, v183, v33
	v_fmac_f32_e32 v181, v183, v34
	v_fmac_f32_e32 v182, v183, v35
	s_mov_b64 exec, s[8:9]
	ds_write2st64_b32 v152, v184, v238 offset0:14 offset1:12
	s_mov_b64 exec, -1
	ds_read_b128 v[28:31], v145 offset:8960
	ds_read_b128 v[32:35], v145 offset:17152
	ds_read_b128 v[36:39], v145 offset:25344
	ds_read_b128 v[40:43], v145 offset:33536
	ds_read2st64_b32 v[240:241], v151 offset0:195 offset1:194
	s_waitcnt lgkmcnt(10)
	v_mul_f32_e32 v183, v179, v48
	v_mul_f32_e32 v184, v179, v60
	v_fmac_f32_e32 v183, v180, v49
	v_fmac_f32_e32 v184, v180, v61
	v_fmac_f32_e32 v183, v181, v50
	v_fmac_f32_e32 v184, v181, v62
	v_fmac_f32_e32 v183, v182, v51
	v_fmac_f32_e32 v184, v182, v63
	v_fmac_f32_e32 v179, v242, v56
	v_add_f32_dpp v183, v183, v183 quad_perm:[1,0,3,2] row_mask:0xf bank_mask:0xf bound_ctrl:1
	v_add_f32_dpp v184, v184, v184 quad_perm:[1,0,3,2] row_mask:0xf bank_mask:0xf bound_ctrl:1
	v_fmac_f32_e32 v180, v242, v57
	v_add_f32_dpp v183, v183, v183 quad_perm:[2,3,0,1] row_mask:0xf bank_mask:0xf bound_ctrl:1
	v_add_f32_dpp v184, v184, v184 quad_perm:[2,3,0,1] row_mask:0xf bank_mask:0xf bound_ctrl:1
	v_fmac_f32_e32 v181, v242, v58
	v_add_f32_dpp v183, v183, v183 row_half_mirror row_mask:0xf bank_mask:0xf bound_ctrl:1
	v_add_f32_dpp v184, v184, v184 row_half_mirror row_mask:0xf bank_mask:0xf bound_ctrl:1
	v_fmac_f32_e32 v182, v242, v59
	v_add_f32_dpp v183, v183, v183 row_mirror row_mask:0xf bank_mask:0xf bound_ctrl:1
	v_fmac_f32_e32 v179, v183, v52
	v_fmac_f32_e32 v180, v183, v53
	v_fmac_f32_e32 v181, v183, v54
	v_fmac_f32_e32 v182, v183, v55
	ds_read_b128 v[48:51], v145 offset:8704
	ds_read_b128 v[52:55], v145 offset:16896
	ds_read_b128 v[56:59], v145 offset:25088
	ds_read_b128 v[60:63], v145 offset:33280
	s_waitcnt lgkmcnt(10)
	v_mul_f32_e32 v183, v179, v8
	v_mul_f32_e32 v238, v179, v20
	v_fmac_f32_e32 v183, v180, v9
	v_fmac_f32_e32 v238, v180, v21
	v_fmac_f32_e32 v183, v181, v10
	v_fmac_f32_e32 v238, v181, v22
	v_fmac_f32_e32 v183, v182, v11
	v_fmac_f32_e32 v238, v182, v23
	v_fmac_f32_e32 v179, v243, v16
	v_add_f32_dpp v183, v183, v183 quad_perm:[1,0,3,2] row_mask:0xf bank_mask:0xf bound_ctrl:1
	v_add_f32_dpp v238, v238, v238 quad_perm:[1,0,3,2] row_mask:0xf bank_mask:0xf bound_ctrl:1
	v_fmac_f32_e32 v180, v243, v17
	v_add_f32_dpp v183, v183, v183 quad_perm:[2,3,0,1] row_mask:0xf bank_mask:0xf bound_ctrl:1
	v_add_f32_dpp v238, v238, v238 quad_perm:[2,3,0,1] row_mask:0xf bank_mask:0xf bound_ctrl:1
	v_fmac_f32_e32 v181, v243, v18
	v_add_f32_dpp v183, v183, v183 row_half_mirror row_mask:0xf bank_mask:0xf bound_ctrl:1
	v_add_f32_dpp v238, v238, v238 row_half_mirror row_mask:0xf bank_mask:0xf bound_ctrl:1
	v_fmac_f32_e32 v182, v243, v19
	v_add_f32_dpp v183, v183, v183 row_mirror row_mask:0xf bank_mask:0xf bound_ctrl:1
	v_fmac_f32_e32 v179, v183, v12
	v_fmac_f32_e32 v180, v183, v13
	v_fmac_f32_e32 v181, v183, v14
	v_fmac_f32_e32 v182, v183, v15
	s_mov_b64 exec, s[8:9]
	ds_write2st64_b32 v152, v184, v238 offset0:10 offset1:8
	s_mov_b64 exec, -1
	ds_read_b128 v[8:11], v145 offset:8448
	ds_read_b128 v[12:15], v145 offset:16640
	ds_read_b128 v[16:19], v145 offset:24832
	ds_read_b128 v[20:23], v145 offset:33024
	ds_read2st64_b32 v[242:243], v151 offset0:193 offset1:192
	s_waitcnt lgkmcnt(10)
	v_mul_f32_e32 v183, v179, v28
	v_mul_f32_e32 v184, v179, v40
	v_fmac_f32_e32 v183, v180, v29
	v_fmac_f32_e32 v184, v180, v41
	v_fmac_f32_e32 v183, v181, v30
	v_fmac_f32_e32 v184, v181, v42
	v_fmac_f32_e32 v183, v182, v31
	v_fmac_f32_e32 v184, v182, v43
	v_fmac_f32_e32 v179, v240, v36
	v_add_f32_dpp v183, v183, v183 quad_perm:[1,0,3,2] row_mask:0xf bank_mask:0xf bound_ctrl:1
	v_add_f32_dpp v184, v184, v184 quad_perm:[1,0,3,2] row_mask:0xf bank_mask:0xf bound_ctrl:1
	v_fmac_f32_e32 v180, v240, v37
	v_add_f32_dpp v183, v183, v183 quad_perm:[2,3,0,1] row_mask:0xf bank_mask:0xf bound_ctrl:1
	v_add_f32_dpp v184, v184, v184 quad_perm:[2,3,0,1] row_mask:0xf bank_mask:0xf bound_ctrl:1
	v_fmac_f32_e32 v181, v240, v38
	v_add_f32_dpp v183, v183, v183 row_half_mirror row_mask:0xf bank_mask:0xf bound_ctrl:1
	v_add_f32_dpp v184, v184, v184 row_half_mirror row_mask:0xf bank_mask:0xf bound_ctrl:1
	v_fmac_f32_e32 v182, v240, v39
	v_add_f32_dpp v183, v183, v183 row_mirror row_mask:0xf bank_mask:0xf bound_ctrl:1
	v_fmac_f32_e32 v179, v183, v32
	v_fmac_f32_e32 v180, v183, v33
	v_fmac_f32_e32 v181, v183, v34
	v_fmac_f32_e32 v182, v183, v35
	ds_read_b128 v[28:31], v145 offset:8192
	ds_read_b128 v[32:35], v145 offset:16384
	ds_read_b128 v[36:39], v145 offset:24576
	ds_read_b128 v[40:43], v145 offset:32768
	s_waitcnt lgkmcnt(10)
	v_mul_f32_e32 v183, v179, v48
	v_mul_f32_e32 v238, v179, v60
	v_fmac_f32_e32 v183, v180, v49
	v_fmac_f32_e32 v238, v180, v61
	v_fmac_f32_e32 v183, v181, v50
	v_fmac_f32_e32 v238, v181, v62
	v_fmac_f32_e32 v183, v182, v51
	v_fmac_f32_e32 v238, v182, v63
	v_fmac_f32_e32 v179, v241, v56
	v_add_f32_dpp v183, v183, v183 quad_perm:[1,0,3,2] row_mask:0xf bank_mask:0xf bound_ctrl:1
	v_add_f32_dpp v238, v238, v238 quad_perm:[1,0,3,2] row_mask:0xf bank_mask:0xf bound_ctrl:1
	v_fmac_f32_e32 v180, v241, v57
	v_add_f32_dpp v183, v183, v183 quad_perm:[2,3,0,1] row_mask:0xf bank_mask:0xf bound_ctrl:1
	v_add_f32_dpp v238, v238, v238 quad_perm:[2,3,0,1] row_mask:0xf bank_mask:0xf bound_ctrl:1
	v_fmac_f32_e32 v181, v241, v58
	v_add_f32_dpp v183, v183, v183 row_half_mirror row_mask:0xf bank_mask:0xf bound_ctrl:1
	v_add_f32_dpp v238, v238, v238 row_half_mirror row_mask:0xf bank_mask:0xf bound_ctrl:1
	v_fmac_f32_e32 v182, v241, v59
	v_add_f32_dpp v183, v183, v183 row_mirror row_mask:0xf bank_mask:0xf bound_ctrl:1
	v_fmac_f32_e32 v179, v183, v52
	v_fmac_f32_e32 v180, v183, v53
	v_fmac_f32_e32 v181, v183, v54
	v_fmac_f32_e32 v182, v183, v55
	s_mov_b64 exec, s[8:9]
	ds_write2st64_b32 v152, v184, v238 offset0:6 offset1:4
	s_mov_b64 exec, -1
	s_waitcnt lgkmcnt(5)
	v_mul_f32_e32 v183, v179, v8
	v_mul_f32_e32 v184, v179, v20
	v_fmac_f32_e32 v183, v180, v9
	v_fmac_f32_e32 v184, v180, v21
	v_fmac_f32_e32 v183, v181, v10
	v_fmac_f32_e32 v184, v181, v22
	v_fmac_f32_e32 v183, v182, v11
	v_fmac_f32_e32 v184, v182, v23
	v_fmac_f32_e32 v179, v242, v16
	v_add_f32_dpp v183, v183, v183 quad_perm:[1,0,3,2] row_mask:0xf bank_mask:0xf bound_ctrl:1
	v_add_f32_dpp v184, v184, v184 quad_perm:[1,0,3,2] row_mask:0xf bank_mask:0xf bound_ctrl:1
	v_fmac_f32_e32 v180, v242, v17
	v_add_f32_dpp v183, v183, v183 quad_perm:[2,3,0,1] row_mask:0xf bank_mask:0xf bound_ctrl:1
	v_add_f32_dpp v184, v184, v184 quad_perm:[2,3,0,1] row_mask:0xf bank_mask:0xf bound_ctrl:1
	v_fmac_f32_e32 v181, v242, v18
	v_add_f32_dpp v183, v183, v183 row_half_mirror row_mask:0xf bank_mask:0xf bound_ctrl:1
	v_add_f32_dpp v184, v184, v184 row_half_mirror row_mask:0xf bank_mask:0xf bound_ctrl:1
	v_fmac_f32_e32 v182, v242, v19
	v_add_f32_dpp v183, v183, v183 row_mirror row_mask:0xf bank_mask:0xf bound_ctrl:1
	v_fmac_f32_e32 v179, v183, v12
	v_fmac_f32_e32 v180, v183, v13
	v_fmac_f32_e32 v181, v183, v14
	v_fmac_f32_e32 v182, v183, v15
	s_waitcnt lgkmcnt(1)
	v_mul_f32_e32 v183, v179, v28
	v_mul_f32_e32 v238, v179, v40
	v_fmac_f32_e32 v183, v180, v29
	v_fmac_f32_e32 v238, v180, v41
	v_fmac_f32_e32 v183, v181, v30
	v_fmac_f32_e32 v238, v181, v42
	v_fmac_f32_e32 v183, v182, v31
	v_fmac_f32_e32 v238, v182, v43
	v_fmac_f32_e32 v179, v243, v36
	v_add_f32_dpp v183, v183, v183 quad_perm:[1,0,3,2] row_mask:0xf bank_mask:0xf bound_ctrl:1
	v_add_f32_dpp v238, v238, v238 quad_perm:[1,0,3,2] row_mask:0xf bank_mask:0xf bound_ctrl:1
	v_fmac_f32_e32 v180, v243, v37
	v_add_f32_dpp v183, v183, v183 quad_perm:[2,3,0,1] row_mask:0xf bank_mask:0xf bound_ctrl:1
	v_add_f32_dpp v238, v238, v238 quad_perm:[2,3,0,1] row_mask:0xf bank_mask:0xf bound_ctrl:1
	v_fmac_f32_e32 v181, v243, v38
	v_add_f32_dpp v183, v183, v183 row_half_mirror row_mask:0xf bank_mask:0xf bound_ctrl:1
	v_add_f32_dpp v238, v238, v238 row_half_mirror row_mask:0xf bank_mask:0xf bound_ctrl:1
	v_fmac_f32_e32 v182, v243, v39
	v_add_f32_dpp v183, v183, v183 row_mirror row_mask:0xf bank_mask:0xf bound_ctrl:1
	v_fmac_f32_e32 v179, v183, v32
	v_fmac_f32_e32 v180, v183, v33
	v_fmac_f32_e32 v181, v183, v34
	v_fmac_f32_e32 v182, v183, v35
	s_mov_b64 exec, s[8:9]
	ds_write2st64_b32 v152, v184, v238 offset0:2 offset1:0
	s_mov_b64 exec, -1
	ds_read_b128 v[4:7], v145 offset:57344
	s_waitcnt lgkmcnt(0)
	v_mul_f32_e32 v179, v179, v4
	v_mul_f32_e32 v180, v180, v5
	v_mul_f32_e32 v181, v181, v6
	v_mul_f32_e32 v182, v182, v7
	s_waitcnt lgkmcnt(0)
	s_barrier
	s_and_saveexec_b64 s[12:13], s[10:11]
	s_cbranch_execz .LBB0_265
	ds_read_b128 v[4:7], v153
	ds_read_b128 v[8:11], v153 offset:256
	s_waitcnt lgkmcnt(0)
	v_pk_add_f32 v[10:11], v[6:7], v[10:11]
	v_pk_add_f32 v[8:9], v[4:5], v[8:9]
	ds_read_b128 v[4:7], v150
	s_waitcnt lgkmcnt(0)
	v_pk_add_f32 v[6:7], v[10:11], v[6:7]
	v_pk_add_f32 v[4:5], v[8:9], v[4:5]
	s_nop 0
	v_cvt_pk_bf16_f32 v4, v4, v5
	v_cvt_pk_bf16_f32 v5, v6, v7
	v_lshlrev_b64 v[6:7], 11, v[124:125]
	v_lshl_add_u64 v[6:7], v[106:107], 0, v[6:7]
	global_store_dwordx2 v[6:7], v[4:5], off
	s_branch .LBB0_265

.LBB0_380:
	s_or_b64 exec, exec, s[10:11]
	v_add_u32_e32 v227, 0xffffff00, v143
	ds_read_b128 v[198:201], v143 offset:57344
	ds_read_b128 v[202:205], v227 offset:57344
	ds_read_b128 v[206:209], v143 offset:8192
	ds_read_b128 v[210:213], v143 offset:16384
	ds_read_b128 v[214:217], v143 offset:24576
	ds_read_b128 v[218:221], v143 offset:32768
	v_mov_b32_e32 v226, 1.0
	v_cmp_gt_u32_e32 vcc, 16, v134
	s_waitcnt lgkmcnt(4)
	v_rcp_f32_e32 v222, v198
	v_rcp_f32_e32 v223, v199
	v_rcp_f32_e32 v224, v200
	v_rcp_f32_e32 v225, v201
	v_cndmask_b32_e32 v202, v202, v226, vcc
	v_cndmask_b32_e32 v203, v203, v226, vcc
	v_cndmask_b32_e32 v204, v204, v226, vcc
	v_cndmask_b32_e32 v205, v205, v226, vcc
	s_waitcnt lgkmcnt(0)
	v_mul_f32_e32 v206, v206, v202
	v_mul_f32_e32 v207, v207, v203
	v_mul_f32_e32 v208, v208, v204
	v_mul_f32_e32 v209, v209, v205
	v_mul_f32_e32 v218, v218, v202
	v_mul_f32_e32 v219, v219, v203
	v_mul_f32_e32 v220, v220, v204
	v_mul_f32_e32 v221, v221, v205
	v_mul_f32_e32 v210, v210, v222
	v_mul_f32_e32 v211, v211, v223
	v_mul_f32_e32 v212, v212, v224
	v_mul_f32_e32 v213, v213, v225
	v_mul_f32_e32 v214, v214, v222
	v_mul_f32_e32 v215, v215, v223
	v_mul_f32_e32 v216, v216, v224
	v_mul_f32_e32 v217, v217, v225
	ds_write_b128 v143, v[206:209] offset:8192
	ds_write_b128 v143, v[218:221] offset:32768
	ds_write_b128 v143, v[210:213] offset:16384
	ds_write_b128 v143, v[214:217] offset:24576
	s_waitcnt lgkmcnt(0)
	s_barrier
	v_mbcnt_lo_u32_b32 v177, -1, 0
	v_mbcnt_hi_u32_b32 v177, -1, v177
	v_lshlrev_b32_e32 v177, 2, v177
	v_add_u32_e32 v177, 0xe000, v177
	v_cndmask_b32_e64 v176, v177, v149, s[6:7]
	ds_read_b128 v[8:11], v142 offset:8192
	ds_read_b128 v[12:15], v142 offset:16384
	ds_read_b128 v[16:19], v142 offset:24576
	ds_read_b128 v[20:23], v142 offset:32768
	ds_read2st64_b32 v[240:241], v148 offset0:192 offset1:193
	ds_read_b128 v[28:31], v142 offset:8448
	ds_read_b128 v[32:35], v142 offset:16640
	ds_read_b128 v[36:39], v142 offset:24832
	ds_read_b128 v[40:43], v142 offset:33024
	ds_read_b128 v[48:51], v142 offset:8704
	ds_read_b128 v[52:55], v142 offset:16896
	ds_read_b128 v[56:59], v142 offset:25088
	ds_read_b128 v[60:63], v142 offset:33280
	ds_read2st64_b32 v[242:243], v148 offset0:194 offset1:195
	s_waitcnt lgkmcnt(9)
	v_mul_f32_e32 v174, v170, v8
	v_mul_f32_e32 v175, v170, v20
	v_fmac_f32_e32 v174, v171, v9
	v_fmac_f32_e32 v175, v171, v21
	v_fmac_f32_e32 v174, v172, v10
	v_fmac_f32_e32 v175, v172, v22
	v_fmac_f32_e32 v174, v173, v11
	v_fmac_f32_e32 v175, v173, v23
	v_fmac_f32_e32 v170, v240, v16
	v_add_f32_dpp v174, v174, v174 quad_perm:[1,0,3,2] row_mask:0xf bank_mask:0xf bound_ctrl:1
	v_add_f32_dpp v175, v175, v175 quad_perm:[1,0,3,2] row_mask:0xf bank_mask:0xf bound_ctrl:1
	v_fmac_f32_e32 v171, v240, v17
	v_add_f32_dpp v174, v174, v174 quad_perm:[2,3,0,1] row_mask:0xf bank_mask:0xf bound_ctrl:1
	v_add_f32_dpp v175, v175, v175 quad_perm:[2,3,0,1] row_mask:0xf bank_mask:0xf bound_ctrl:1
	v_fmac_f32_e32 v172, v240, v18
	v_add_f32_dpp v174, v174, v174 row_half_mirror row_mask:0xf bank_mask:0xf bound_ctrl:1
	v_add_f32_dpp v175, v175, v175 row_half_mirror row_mask:0xf bank_mask:0xf bound_ctrl:1
	v_fmac_f32_e32 v173, v240, v19
	v_add_f32_dpp v174, v174, v174 row_mirror row_mask:0xf bank_mask:0xf bound_ctrl:1
	v_fmac_f32_e32 v170, v174, v12
	v_fmac_f32_e32 v171, v174, v13
	v_fmac_f32_e32 v172, v174, v14
	v_fmac_f32_e32 v173, v174, v15
	ds_read_b128 v[8:11], v142 offset:8960
	ds_read_b128 v[12:15], v142 offset:17152
	ds_read_b128 v[16:19], v142 offset:25344
	ds_read_b128 v[20:23], v142 offset:33536
	s_waitcnt lgkmcnt(9)
	v_mul_f32_e32 v174, v170, v28
	v_mul_f32_e32 v238, v170, v40
	v_fmac_f32_e32 v174, v171, v29
	v_fmac_f32_e32 v238, v171, v41
	v_fmac_f32_e32 v174, v172, v30
	v_fmac_f32_e32 v238, v172, v42
	v_fmac_f32_e32 v174, v173, v31
	v_fmac_f32_e32 v238, v173, v43
	v_fmac_f32_e32 v170, v241, v36
	v_add_f32_dpp v174, v174, v174 quad_perm:[1,0,3,2] row_mask:0xf bank_mask:0xf bound_ctrl:1
	v_add_f32_dpp v238, v238, v238 quad_perm:[1,0,3,2] row_mask:0xf bank_mask:0xf bound_ctrl:1
	v_fmac_f32_e32 v171, v241, v37
	v_add_f32_dpp v174, v174, v174 quad_perm:[2,3,0,1] row_mask:0xf bank_mask:0xf bound_ctrl:1
	v_add_f32_dpp v238, v238, v238 quad_perm:[2,3,0,1] row_mask:0xf bank_mask:0xf bound_ctrl:1
	v_fmac_f32_e32 v172, v241, v38
	v_add_f32_dpp v174, v174, v174 row_half_mirror row_mask:0xf bank_mask:0xf bound_ctrl:1
	v_add_f32_dpp v238, v238, v238 row_half_mirror row_mask:0xf bank_mask:0xf bound_ctrl:1
	v_fmac_f32_e32 v173, v241, v39
	v_add_f32_dpp v174, v174, v174 row_mirror row_mask:0xf bank_mask:0xf bound_ctrl:1
	v_fmac_f32_e32 v170, v174, v32
	v_fmac_f32_e32 v171, v174, v33
	v_fmac_f32_e32 v172, v174, v34
	v_fmac_f32_e32 v173, v174, v35
	s_mov_b64 exec, s[6:7]
	ds_write2st64_b32 v149, v175, v238 offset0:0 offset1:2
	s_mov_b64 exec, -1
	ds_read_b128 v[28:31], v142 offset:9216
	ds_read_b128 v[32:35], v142 offset:17408
	ds_read_b128 v[36:39], v142 offset:25600
	ds_read_b128 v[40:43], v142 offset:33792
	ds_read2st64_b32 v[240:241], v148 offset0:196 offset1:197
	s_waitcnt lgkmcnt(10)
	v_mul_f32_e32 v174, v170, v48
	v_mul_f32_e32 v175, v170, v60
	v_fmac_f32_e32 v174, v171, v49
	v_fmac_f32_e32 v175, v171, v61
	v_fmac_f32_e32 v174, v172, v50
	v_fmac_f32_e32 v175, v172, v62
	v_fmac_f32_e32 v174, v173, v51
	v_fmac_f32_e32 v175, v173, v63
	v_fmac_f32_e32 v170, v242, v56
	v_add_f32_dpp v174, v174, v174 quad_perm:[1,0,3,2] row_mask:0xf bank_mask:0xf bound_ctrl:1
	v_add_f32_dpp v175, v175, v175 quad_perm:[1,0,3,2] row_mask:0xf bank_mask:0xf bound_ctrl:1
	v_fmac_f32_e32 v171, v242, v57
	v_add_f32_dpp v174, v174, v174 quad_perm:[2,3,0,1] row_mask:0xf bank_mask:0xf bound_ctrl:1
	v_add_f32_dpp v175, v175, v175 quad_perm:[2,3,0,1] row_mask:0xf bank_mask:0xf bound_ctrl:1
	v_fmac_f32_e32 v172, v242, v58
	v_add_f32_dpp v174, v174, v174 row_half_mirror row_mask:0xf bank_mask:0xf bound_ctrl:1
	v_add_f32_dpp v175, v175, v175 row_half_mirror row_mask:0xf bank_mask:0xf bound_ctrl:1
	v_fmac_f32_e32 v173, v242, v59
	v_add_f32_dpp v174, v174, v174 row_mirror row_mask:0xf bank_mask:0xf bound_ctrl:1
	v_fmac_f32_e32 v170, v174, v52
	v_fmac_f32_e32 v171, v174, v53
	v_fmac_f32_e32 v172, v174, v54
	v_fmac_f32_e32 v173, v174, v55
	ds_read_b128 v[48:51], v142 offset:9472
	ds_read_b128 v[52:55], v142 offset:17664
	ds_read_b128 v[56:59], v142 offset:25856
	ds_read_b128 v[60:63], v142 offset:34048
	s_waitcnt lgkmcnt(10)
	v_mul_f32_e32 v174, v170, v8
	v_mul_f32_e32 v238, v170, v20
	v_fmac_f32_e32 v174, v171, v9
	v_fmac_f32_e32 v238, v171, v21
	v_fmac_f32_e32 v174, v172, v10
	v_fmac_f32_e32 v238, v172, v22
	v_fmac_f32_e32 v174, v173, v11
	v_fmac_f32_e32 v238, v173, v23
	v_fmac_f32_e32 v170, v243, v16
	v_add_f32_dpp v174, v174, v174 quad_perm:[1,0,3,2] row_mask:0xf bank_mask:0xf bound_ctrl:1
	v_add_f32_dpp v238, v238, v238 quad_perm:[1,0,3,2] row_mask:0xf bank_mask:0xf bound_ctrl:1
	v_fmac_f32_e32 v171, v243, v17
	v_add_f32_dpp v174, v174, v174 quad_perm:[2,3,0,1] row_mask:0xf bank_mask:0xf bound_ctrl:1
	v_add_f32_dpp v238, v238, v238 quad_perm:[2,3,0,1] row_mask:0xf bank_mask:0xf bound_ctrl:1
	v_fmac_f32_e32 v172, v243, v18
	v_add_f32_dpp v174, v174, v174 row_half_mirror row_mask:0xf bank_mask:0xf bound_ctrl:1
	v_add_f32_dpp v238, v238, v238 row_half_mirror row_mask:0xf bank_mask:0xf bound_ctrl:1
	v_fmac_f32_e32 v173, v243, v19
	v_add_f32_dpp v174, v174, v174 row_mirror row_mask:0xf bank_mask:0xf bound_ctrl:1
	v_fmac_f32_e32 v170, v174, v12
	v_fmac_f32_e32 v171, v174, v13
	v_fmac_f32_e32 v172, v174, v14
	v_fmac_f32_e32 v173, v174, v15
	s_mov_b64 exec, s[6:7]
	ds_write2st64_b32 v149, v175, v238 offset0:4 offset1:6
	s_mov_b64 exec, -1
	ds_read_b128 v[8:11], v142 offset:9728
	ds_read_b128 v[12:15], v142 offset:17920
	ds_read_b128 v[16:19], v142 offset:26112
	ds_read_b128 v[20:23], v142 offset:34304
	ds_read2st64_b32 v[242:243], v148 offset0:198 offset1:199
	s_waitcnt lgkmcnt(10)
	v_mul_f32_e32 v174, v170, v28
	v_mul_f32_e32 v175, v170, v40
	v_fmac_f32_e32 v174, v171, v29
	v_fmac_f32_e32 v175, v171, v41
	v_fmac_f32_e32 v174, v172, v30
	v_fmac_f32_e32 v175, v172, v42
	v_fmac_f32_e32 v174, v173, v31
	v_fmac_f32_e32 v175, v173, v43
	v_fmac_f32_e32 v170, v240, v36
	v_add_f32_dpp v174, v174, v174 quad_perm:[1,0,3,2] row_mask:0xf bank_mask:0xf bound_ctrl:1
	v_add_f32_dpp v175, v175, v175 quad_perm:[1,0,3,2] row_mask:0xf bank_mask:0xf bound_ctrl:1
	v_fmac_f32_e32 v171, v240, v37
	v_add_f32_dpp v174, v174, v174 quad_perm:[2,3,0,1] row_mask:0xf bank_mask:0xf bound_ctrl:1
	v_add_f32_dpp v175, v175, v175 quad_perm:[2,3,0,1] row_mask:0xf bank_mask:0xf bound_ctrl:1
	v_fmac_f32_e32 v172, v240, v38
	v_add_f32_dpp v174, v174, v174 row_half_mirror row_mask:0xf bank_mask:0xf bound_ctrl:1
	v_add_f32_dpp v175, v175, v175 row_half_mirror row_mask:0xf bank_mask:0xf bound_ctrl:1
	v_fmac_f32_e32 v173, v240, v39
	v_add_f32_dpp v174, v174, v174 row_mirror row_mask:0xf bank_mask:0xf bound_ctrl:1
	v_fmac_f32_e32 v170, v174, v32
	v_fmac_f32_e32 v171, v174, v33
	v_fmac_f32_e32 v172, v174, v34
	v_fmac_f32_e32 v173, v174, v35
	ds_read_b128 v[28:31], v142 offset:9984
	ds_read_b128 v[32:35], v142 offset:18176
	ds_read_b128 v[36:39], v142 offset:26368
	ds_read_b128 v[40:43], v142 offset:34560
	s_waitcnt lgkmcnt(10)
	v_mul_f32_e32 v174, v170, v48
	v_mul_f32_e32 v238, v170, v60
	v_fmac_f32_e32 v174, v171, v49
	v_fmac_f32_e32 v238, v171, v61
	v_fmac_f32_e32 v174, v172, v50
	v_fmac_f32_e32 v238, v172, v62
	v_fmac_f32_e32 v174, v173, v51
	v_fmac_f32_e32 v238, v173, v63
	v_fmac_f32_e32 v170, v241, v56
	v_add_f32_dpp v174, v174, v174 quad_perm:[1,0,3,2] row_mask:0xf bank_mask:0xf bound_ctrl:1
	v_add_f32_dpp v238, v238, v238 quad_perm:[1,0,3,2] row_mask:0xf bank_mask:0xf bound_ctrl:1
	v_fmac_f32_e32 v171, v241, v57
	v_add_f32_dpp v174, v174, v174 quad_perm:[2,3,0,1] row_mask:0xf bank_mask:0xf bound_ctrl:1
	v_add_f32_dpp v238, v238, v238 quad_perm:[2,3,0,1] row_mask:0xf bank_mask:0xf bound_ctrl:1
	v_fmac_f32_e32 v172, v241, v58
	v_add_f32_dpp v174, v174, v174 row_half_mirror row_mask:0xf bank_mask:0xf bound_ctrl:1
	v_add_f32_dpp v238, v238, v238 row_half_mirror row_mask:0xf bank_mask:0xf bound_ctrl:1
	v_fmac_f32_e32 v173, v241, v59
	v_add_f32_dpp v174, v174, v174 row_mirror row_mask:0xf bank_mask:0xf bound_ctrl:1
	v_fmac_f32_e32 v170, v174, v52
	v_fmac_f32_e32 v171, v174, v53
	v_fmac_f32_e32 v172, v174, v54
	v_fmac_f32_e32 v173, v174, v55
	s_mov_b64 exec, s[6:7]
	ds_write2st64_b32 v149, v175, v238 offset0:8 offset1:10
	s_mov_b64 exec, -1
	ds_read_b128 v[48:51], v142 offset:10240
	ds_read_b128 v[52:55], v142 offset:18432
	ds_read_b128 v[56:59], v142 offset:26624
	ds_read_b128 v[60:63], v142 offset:34816
	ds_read2st64_b32 v[240:241], v148 offset0:200 offset1:201
	s_waitcnt lgkmcnt(10)
	v_mul_f32_e32 v174, v170, v8
	v_mul_f32_e32 v175, v170, v20
	v_fmac_f32_e32 v174, v171, v9
	v_fmac_f32_e32 v175, v171, v21
	v_fmac_f32_e32 v174, v172, v10
	v_fmac_f32_e32 v175, v172, v22
	v_fmac_f32_e32 v174, v173, v11
	v_fmac_f32_e32 v175, v173, v23
	v_fmac_f32_e32 v170, v242, v16
	v_add_f32_dpp v174, v174, v174 quad_perm:[1,0,3,2] row_mask:0xf bank_mask:0xf bound_ctrl:1
	v_add_f32_dpp v175, v175, v175 quad_perm:[1,0,3,2] row_mask:0xf bank_mask:0xf bound_ctrl:1
	v_fmac_f32_e32 v171, v242, v17
	v_add_f32_dpp v174, v174, v174 quad_perm:[2,3,0,1] row_mask:0xf bank_mask:0xf bound_ctrl:1
	v_add_f32_dpp v175, v175, v175 quad_perm:[2,3,0,1] row_mask:0xf bank_mask:0xf bound_ctrl:1
	v_fmac_f32_e32 v172, v242, v18
	v_add_f32_dpp v174, v174, v174 row_half_mirror row_mask:0xf bank_mask:0xf bound_ctrl:1
	v_add_f32_dpp v175, v175, v175 row_half_mirror row_mask:0xf bank_mask:0xf bound_ctrl:1
	v_fmac_f32_e32 v173, v242, v19
	v_add_f32_dpp v174, v174, v174 row_mirror row_mask:0xf bank_mask:0xf bound_ctrl:1
	v_fmac_f32_e32 v170, v174, v12
	v_fmac_f32_e32 v171, v174, v13
	v_fmac_f32_e32 v172, v174, v14
	v_fmac_f32_e32 v173, v174, v15
	ds_read_b128 v[8:11], v142 offset:10496
	ds_read_b128 v[12:15], v142 offset:18688
	ds_read_b128 v[16:19], v142 offset:26880
	ds_read_b128 v[20:23], v142 offset:35072
	s_waitcnt lgkmcnt(10)
	v_mul_f32_e32 v174, v170, v28
	v_mul_f32_e32 v238, v170, v40
	v_fmac_f32_e32 v174, v171, v29
	v_fmac_f32_e32 v238, v171, v41
	v_fmac_f32_e32 v174, v172, v30
	v_fmac_f32_e32 v238, v172, v42
	v_fmac_f32_e32 v174, v173, v31
	v_fmac_f32_e32 v238, v173, v43
	v_fmac_f32_e32 v170, v243, v36
	v_add_f32_dpp v174, v174, v174 quad_perm:[1,0,3,2] row_mask:0xf bank_mask:0xf bound_ctrl:1
	v_add_f32_dpp v238, v238, v238 quad_perm:[1,0,3,2] row_mask:0xf bank_mask:0xf bound_ctrl:1
	v_fmac_f32_e32 v171, v243, v37
	v_add_f32_dpp v174, v174, v174 quad_perm:[2,3,0,1] row_mask:0xf bank_mask:0xf bound_ctrl:1
	v_add_f32_dpp v238, v238, v238 quad_perm:[2,3,0,1] row_mask:0xf bank_mask:0xf bound_ctrl:1
	v_fmac_f32_e32 v172, v243, v38
	v_add_f32_dpp v174, v174, v174 row_half_mirror row_mask:0xf bank_mask:0xf bound_ctrl:1
	v_add_f32_dpp v238, v238, v238 row_half_mirror row_mask:0xf bank_mask:0xf bound_ctrl:1
	v_fmac_f32_e32 v173, v243, v39
	v_add_f32_dpp v174, v174, v174 row_mirror row_mask:0xf bank_mask:0xf bound_ctrl:1
	v_fmac_f32_e32 v170, v174, v32
	v_fmac_f32_e32 v171, v174, v33
	v_fmac_f32_e32 v172, v174, v34
	v_fmac_f32_e32 v173, v174, v35
	s_mov_b64 exec, s[6:7]
	ds_write2st64_b32 v149, v175, v238 offset0:12 offset1:14
	s_mov_b64 exec, -1
	ds_read_b128 v[28:31], v142 offset:10752
	ds_read_b128 v[32:35], v142 offset:18944
	ds_read_b128 v[36:39], v142 offset:27136
	ds_read_b128 v[40:43], v142 offset:35328
	ds_read2st64_b32 v[242:243], v148 offset0:202 offset1:203
	s_waitcnt lgkmcnt(10)
	v_mul_f32_e32 v174, v170, v48
	v_mul_f32_e32 v175, v170, v60
	v_fmac_f32_e32 v174, v171, v49
	v_fmac_f32_e32 v175, v171, v61
	v_fmac_f32_e32 v174, v172, v50
	v_fmac_f32_e32 v175, v172, v62
	v_fmac_f32_e32 v174, v173, v51
	v_fmac_f32_e32 v175, v173, v63
	v_fmac_f32_e32 v170, v240, v56
	v_add_f32_dpp v174, v174, v174 quad_perm:[1,0,3,2] row_mask:0xf bank_mask:0xf bound_ctrl:1
	v_add_f32_dpp v175, v175, v175 quad_perm:[1,0,3,2] row_mask:0xf bank_mask:0xf bound_ctrl:1
	v_fmac_f32_e32 v171, v240, v57
	v_add_f32_dpp v174, v174, v174 quad_perm:[2,3,0,1] row_mask:0xf bank_mask:0xf bound_ctrl:1
	v_add_f32_dpp v175, v175, v175 quad_perm:[2,3,0,1] row_mask:0xf bank_mask:0xf bound_ctrl:1
	v_fmac_f32_e32 v172, v240, v58
	v_add_f32_dpp v174, v174, v174 row_half_mirror row_mask:0xf bank_mask:0xf bound_ctrl:1
	v_add_f32_dpp v175, v175, v175 row_half_mirror row_mask:0xf bank_mask:0xf bound_ctrl:1
	v_fmac_f32_e32 v173, v240, v59
	v_add_f32_dpp v174, v174, v174 row_mirror row_mask:0xf bank_mask:0xf bound_ctrl:1
	v_fmac_f32_e32 v170, v174, v52
	v_fmac_f32_e32 v171, v174, v53
	v_fmac_f32_e32 v172, v174, v54
	v_fmac_f32_e32 v173, v174, v55
	ds_read_b128 v[48:51], v142 offset:11008
	ds_read_b128 v[52:55], v142 offset:19200
	ds_read_b128 v[56:59], v142 offset:27392
	ds_read_b128 v[60:63], v142 offset:35584
	s_waitcnt lgkmcnt(10)
	v_mul_f32_e32 v174, v170, v8
	v_mul_f32_e32 v238, v170, v20
	v_fmac_f32_e32 v174, v171, v9
	v_fmac_f32_e32 v238, v171, v21
	v_fmac_f32_e32 v174, v172, v10
	v_fmac_f32_e32 v238, v172, v22
	v_fmac_f32_e32 v174, v173, v11
	v_fmac_f32_e32 v238, v173, v23
	v_fmac_f32_e32 v170, v241, v16
	v_add_f32_dpp v174, v174, v174 quad_perm:[1,0,3,2] row_mask:0xf bank_mask:0xf bound_ctrl:1
	v_add_f32_dpp v238, v238, v238 quad_perm:[1,0,3,2] row_mask:0xf bank_mask:0xf bound_ctrl:1
	v_fmac_f32_e32 v171, v241, v17
	v_add_f32_dpp v174, v174, v174 quad_perm:[2,3,0,1] row_mask:0xf bank_mask:0xf bound_ctrl:1
	v_add_f32_dpp v238, v238, v238 quad_perm:[2,3,0,1] row_mask:0xf bank_mask:0xf bound_ctrl:1
	v_fmac_f32_e32 v172, v241, v18
	v_add_f32_dpp v174, v174, v174 row_half_mirror row_mask:0xf bank_mask:0xf bound_ctrl:1
	v_add_f32_dpp v238, v238, v238 row_half_mirror row_mask:0xf bank_mask:0xf bound_ctrl:1
	v_fmac_f32_e32 v173, v241, v19
	v_add_f32_dpp v174, v174, v174 row_mirror row_mask:0xf bank_mask:0xf bound_ctrl:1
	v_fmac_f32_e32 v170, v174, v12
	v_fmac_f32_e32 v171, v174, v13
	v_fmac_f32_e32 v172, v174, v14
	v_fmac_f32_e32 v173, v174, v15
	s_mov_b64 exec, s[6:7]
	ds_write2st64_b32 v149, v175, v238 offset0:16 offset1:18
	s_mov_b64 exec, -1
	ds_read_b128 v[8:11], v142 offset:11264
	ds_read_b128 v[12:15], v142 offset:19456
	ds_read_b128 v[16:19], v142 offset:27648
	ds_read_b128 v[20:23], v142 offset:35840
	ds_read2st64_b32 v[240:241], v148 offset0:204 offset1:205
	s_waitcnt lgkmcnt(10)
	v_mul_f32_e32 v174, v170, v28
	v_mul_f32_e32 v175, v170, v40
	v_fmac_f32_e32 v174, v171, v29
	v_fmac_f32_e32 v175, v171, v41
	v_fmac_f32_e32 v174, v172, v30
	v_fmac_f32_e32 v175, v172, v42
	v_fmac_f32_e32 v174, v173, v31
	v_fmac_f32_e32 v175, v173, v43
	v_fmac_f32_e32 v170, v242, v36
	v_add_f32_dpp v174, v174, v174 quad_perm:[1,0,3,2] row_mask:0xf bank_mask:0xf bound_ctrl:1
	v_add_f32_dpp v175, v175, v175 quad_perm:[1,0,3,2] row_mask:0xf bank_mask:0xf bound_ctrl:1
	v_fmac_f32_e32 v171, v242, v37
	v_add_f32_dpp v174, v174, v174 quad_perm:[2,3,0,1] row_mask:0xf bank_mask:0xf bound_ctrl:1
	v_add_f32_dpp v175, v175, v175 quad_perm:[2,3,0,1] row_mask:0xf bank_mask:0xf bound_ctrl:1
	v_fmac_f32_e32 v172, v242, v38
	v_add_f32_dpp v174, v174, v174 row_half_mirror row_mask:0xf bank_mask:0xf bound_ctrl:1
	v_add_f32_dpp v175, v175, v175 row_half_mirror row_mask:0xf bank_mask:0xf bound_ctrl:1
	v_fmac_f32_e32 v173, v242, v39
	v_add_f32_dpp v174, v174, v174 row_mirror row_mask:0xf bank_mask:0xf bound_ctrl:1
	v_fmac_f32_e32 v170, v174, v32
	v_fmac_f32_e32 v171, v174, v33
	v_fmac_f32_e32 v172, v174, v34
	v_fmac_f32_e32 v173, v174, v35
	ds_read_b128 v[28:31], v142 offset:11520
	ds_read_b128 v[32:35], v142 offset:19712
	ds_read_b128 v[36:39], v142 offset:27904
	ds_read_b128 v[40:43], v142 offset:36096
	s_waitcnt lgkmcnt(10)
	v_mul_f32_e32 v174, v170, v48
	v_mul_f32_e32 v238, v170, v60
	v_fmac_f32_e32 v174, v171, v49
	v_fmac_f32_e32 v238, v171, v61
	v_fmac_f32_e32 v174, v172, v50
	v_fmac_f32_e32 v238, v172, v62
	v_fmac_f32_e32 v174, v173, v51
	v_fmac_f32_e32 v238, v173, v63
	v_fmac_f32_e32 v170, v243, v56
	v_add_f32_dpp v174, v174, v174 quad_perm:[1,0,3,2] row_mask:0xf bank_mask:0xf bound_ctrl:1
	v_add_f32_dpp v238, v238, v238 quad_perm:[1,0,3,2] row_mask:0xf bank_mask:0xf bound_ctrl:1
	v_fmac_f32_e32 v171, v243, v57
	v_add_f32_dpp v174, v174, v174 quad_perm:[2,3,0,1] row_mask:0xf bank_mask:0xf bound_ctrl:1
	v_add_f32_dpp v238, v238, v238 quad_perm:[2,3,0,1] row_mask:0xf bank_mask:0xf bound_ctrl:1
	v_fmac_f32_e32 v172, v243, v58
	v_add_f32_dpp v174, v174, v174 row_half_mirror row_mask:0xf bank_mask:0xf bound_ctrl:1
	v_add_f32_dpp v238, v238, v238 row_half_mirror row_mask:0xf bank_mask:0xf bound_ctrl:1
	v_fmac_f32_e32 v173, v243, v59
	v_add_f32_dpp v174, v174, v174 row_mirror row_mask:0xf bank_mask:0xf bound_ctrl:1
	v_fmac_f32_e32 v170, v174, v52
	v_fmac_f32_e32 v171, v174, v53
	v_fmac_f32_e32 v172, v174, v54
	v_fmac_f32_e32 v173, v174, v55
	s_mov_b64 exec, s[6:7]
	ds_write2st64_b32 v149, v175, v238 offset0:20 offset1:22
	s_mov_b64 exec, -1
	ds_read_b128 v[48:51], v142 offset:11776
	ds_read_b128 v[52:55], v142 offset:19968
	ds_read_b128 v[56:59], v142 offset:28160
	ds_read_b128 v[60:63], v142 offset:36352
	ds_read2st64_b32 v[242:243], v148 offset0:206 offset1:207
	s_waitcnt lgkmcnt(10)
	v_mul_f32_e32 v174, v170, v8
	v_mul_f32_e32 v175, v170, v20
	v_fmac_f32_e32 v174, v171, v9
	v_fmac_f32_e32 v175, v171, v21
	v_fmac_f32_e32 v174, v172, v10
	v_fmac_f32_e32 v175, v172, v22
	v_fmac_f32_e32 v174, v173, v11
	v_fmac_f32_e32 v175, v173, v23
	v_fmac_f32_e32 v170, v240, v16
	v_add_f32_dpp v174, v174, v174 quad_perm:[1,0,3,2] row_mask:0xf bank_mask:0xf bound_ctrl:1
	v_add_f32_dpp v175, v175, v175 quad_perm:[1,0,3,2] row_mask:0xf bank_mask:0xf bound_ctrl:1
	v_fmac_f32_e32 v171, v240, v17
	v_add_f32_dpp v174, v174, v174 quad_perm:[2,3,0,1] row_mask:0xf bank_mask:0xf bound_ctrl:1
	v_add_f32_dpp v175, v175, v175 quad_perm:[2,3,0,1] row_mask:0xf bank_mask:0xf bound_ctrl:1
	v_fmac_f32_e32 v172, v240, v18
	v_add_f32_dpp v174, v174, v174 row_half_mirror row_mask:0xf bank_mask:0xf bound_ctrl:1
	v_add_f32_dpp v175, v175, v175 row_half_mirror row_mask:0xf bank_mask:0xf bound_ctrl:1
	v_fmac_f32_e32 v173, v240, v19
	v_add_f32_dpp v174, v174, v174 row_mirror row_mask:0xf bank_mask:0xf bound_ctrl:1
	v_fmac_f32_e32 v170, v174, v12
	v_fmac_f32_e32 v171, v174, v13
	v_fmac_f32_e32 v172, v174, v14
	v_fmac_f32_e32 v173, v174, v15
	ds_read_b128 v[8:11], v142 offset:12032
	ds_read_b128 v[12:15], v142 offset:20224
	ds_read_b128 v[16:19], v142 offset:28416
	ds_read_b128 v[20:23], v142 offset:36608
	s_waitcnt lgkmcnt(10)
	v_mul_f32_e32 v174, v170, v28
	v_mul_f32_e32 v238, v170, v40
	v_fmac_f32_e32 v174, v171, v29
	v_fmac_f32_e32 v238, v171, v41
	v_fmac_f32_e32 v174, v172, v30
	v_fmac_f32_e32 v238, v172, v42
	v_fmac_f32_e32 v174, v173, v31
	v_fmac_f32_e32 v238, v173, v43
	v_fmac_f32_e32 v170, v241, v36
	v_add_f32_dpp v174, v174, v174 quad_perm:[1,0,3,2] row_mask:0xf bank_mask:0xf bound_ctrl:1
	v_add_f32_dpp v238, v238, v238 quad_perm:[1,0,3,2] row_mask:0xf bank_mask:0xf bound_ctrl:1
	v_fmac_f32_e32 v171, v241, v37
	v_add_f32_dpp v174, v174, v174 quad_perm:[2,3,0,1] row_mask:0xf bank_mask:0xf bound_ctrl:1
	v_add_f32_dpp v238, v238, v238 quad_perm:[2,3,0,1] row_mask:0xf bank_mask:0xf bound_ctrl:1
	v_fmac_f32_e32 v172, v241, v38
	v_add_f32_dpp v174, v174, v174 row_half_mirror row_mask:0xf bank_mask:0xf bound_ctrl:1
	v_add_f32_dpp v238, v238, v238 row_half_mirror row_mask:0xf bank_mask:0xf bound_ctrl:1
	v_fmac_f32_e32 v173, v241, v39
	v_add_f32_dpp v174, v174, v174 row_mirror row_mask:0xf bank_mask:0xf bound_ctrl:1
	v_fmac_f32_e32 v170, v174, v32
	v_fmac_f32_e32 v171, v174, v33
	v_fmac_f32_e32 v172, v174, v34
	v_fmac_f32_e32 v173, v174, v35
	s_mov_b64 exec, s[6:7]
	ds_write2st64_b32 v149, v175, v238 offset0:24 offset1:26
	s_mov_b64 exec, -1
	ds_read_b128 v[28:31], v142 offset:12288
	ds_read_b128 v[32:35], v142 offset:20480
	ds_read_b128 v[36:39], v142 offset:28672
	ds_read_b128 v[40:43], v142 offset:36864
	ds_read2st64_b32 v[240:241], v148 offset0:208 offset1:209
	s_waitcnt lgkmcnt(10)
	v_mul_f32_e32 v174, v170, v48
	v_mul_f32_e32 v175, v170, v60
	v_fmac_f32_e32 v174, v171, v49
	v_fmac_f32_e32 v175, v171, v61
	v_fmac_f32_e32 v174, v172, v50
	v_fmac_f32_e32 v175, v172, v62
	v_fmac_f32_e32 v174, v173, v51
	v_fmac_f32_e32 v175, v173, v63
	v_fmac_f32_e32 v170, v242, v56
	v_add_f32_dpp v174, v174, v174 quad_perm:[1,0,3,2] row_mask:0xf bank_mask:0xf bound_ctrl:1
	v_add_f32_dpp v175, v175, v175 quad_perm:[1,0,3,2] row_mask:0xf bank_mask:0xf bound_ctrl:1
	v_fmac_f32_e32 v171, v242, v57
	v_add_f32_dpp v174, v174, v174 quad_perm:[2,3,0,1] row_mask:0xf bank_mask:0xf bound_ctrl:1
	v_add_f32_dpp v175, v175, v175 quad_perm:[2,3,0,1] row_mask:0xf bank_mask:0xf bound_ctrl:1
	v_fmac_f32_e32 v172, v242, v58
	v_add_f32_dpp v174, v174, v174 row_half_mirror row_mask:0xf bank_mask:0xf bound_ctrl:1
	v_add_f32_dpp v175, v175, v175 row_half_mirror row_mask:0xf bank_mask:0xf bound_ctrl:1
	v_fmac_f32_e32 v173, v242, v59
	v_add_f32_dpp v174, v174, v174 row_mirror row_mask:0xf bank_mask:0xf bound_ctrl:1
	v_fmac_f32_e32 v170, v174, v52
	v_fmac_f32_e32 v171, v174, v53
	v_fmac_f32_e32 v172, v174, v54
	v_fmac_f32_e32 v173, v174, v55
	ds_read_b128 v[48:51], v142 offset:12544
	ds_read_b128 v[52:55], v142 offset:20736
	ds_read_b128 v[56:59], v142 offset:28928
	ds_read_b128 v[60:63], v142 offset:37120
	s_waitcnt lgkmcnt(10)
	v_mul_f32_e32 v174, v170, v8
	v_mul_f32_e32 v238, v170, v20
	v_fmac_f32_e32 v174, v171, v9
	v_fmac_f32_e32 v238, v171, v21
	v_fmac_f32_e32 v174, v172, v10
	v_fmac_f32_e32 v238, v172, v22
	v_fmac_f32_e32 v174, v173, v11
	v_fmac_f32_e32 v238, v173, v23
	v_fmac_f32_e32 v170, v243, v16
	v_add_f32_dpp v174, v174, v174 quad_perm:[1,0,3,2] row_mask:0xf bank_mask:0xf bound_ctrl:1
	v_add_f32_dpp v238, v238, v238 quad_perm:[1,0,3,2] row_mask:0xf bank_mask:0xf bound_ctrl:1
	v_fmac_f32_e32 v171, v243, v17
	v_add_f32_dpp v174, v174, v174 quad_perm:[2,3,0,1] row_mask:0xf bank_mask:0xf bound_ctrl:1
	v_add_f32_dpp v238, v238, v238 quad_perm:[2,3,0,1] row_mask:0xf bank_mask:0xf bound_ctrl:1
	v_fmac_f32_e32 v172, v243, v18
	v_add_f32_dpp v174, v174, v174 row_half_mirror row_mask:0xf bank_mask:0xf bound_ctrl:1
	v_add_f32_dpp v238, v238, v238 row_half_mirror row_mask:0xf bank_mask:0xf bound_ctrl:1
	v_fmac_f32_e32 v173, v243, v19
	v_add_f32_dpp v174, v174, v174 row_mirror row_mask:0xf bank_mask:0xf bound_ctrl:1
	v_fmac_f32_e32 v170, v174, v12
	v_fmac_f32_e32 v171, v174, v13
	v_fmac_f32_e32 v172, v174, v14
	v_fmac_f32_e32 v173, v174, v15
	s_mov_b64 exec, s[6:7]
	ds_write2st64_b32 v149, v175, v238 offset0:28 offset1:30
	s_mov_b64 exec, -1
	ds_read_b128 v[8:11], v142 offset:12800
	ds_read_b128 v[12:15], v142 offset:20992
	ds_read_b128 v[16:19], v142 offset:29184
	ds_read_b128 v[20:23], v142 offset:37376
	ds_read2st64_b32 v[242:243], v148 offset0:210 offset1:211
	s_waitcnt lgkmcnt(10)
	v_mul_f32_e32 v174, v170, v28
	v_mul_f32_e32 v175, v170, v40
	v_fmac_f32_e32 v174, v171, v29
	v_fmac_f32_e32 v175, v171, v41
	v_fmac_f32_e32 v174, v172, v30
	v_fmac_f32_e32 v175, v172, v42
	v_fmac_f32_e32 v174, v173, v31
	v_fmac_f32_e32 v175, v173, v43
	v_fmac_f32_e32 v170, v240, v36
	v_add_f32_dpp v174, v174, v174 quad_perm:[1,0,3,2] row_mask:0xf bank_mask:0xf bound_ctrl:1
	v_add_f32_dpp v175, v175, v175 quad_perm:[1,0,3,2] row_mask:0xf bank_mask:0xf bound_ctrl:1
	v_fmac_f32_e32 v171, v240, v37
	v_add_f32_dpp v174, v174, v174 quad_perm:[2,3,0,1] row_mask:0xf bank_mask:0xf bound_ctrl:1
	v_add_f32_dpp v175, v175, v175 quad_perm:[2,3,0,1] row_mask:0xf bank_mask:0xf bound_ctrl:1
	v_fmac_f32_e32 v172, v240, v38
	v_add_f32_dpp v174, v174, v174 row_half_mirror row_mask:0xf bank_mask:0xf bound_ctrl:1
	v_add_f32_dpp v175, v175, v175 row_half_mirror row_mask:0xf bank_mask:0xf bound_ctrl:1
	v_fmac_f32_e32 v173, v240, v39
	v_add_f32_dpp v174, v174, v174 row_mirror row_mask:0xf bank_mask:0xf bound_ctrl:1
	v_fmac_f32_e32 v170, v174, v32
	v_fmac_f32_e32 v171, v174, v33
	v_fmac_f32_e32 v172, v174, v34
	v_fmac_f32_e32 v173, v174, v35
	ds_read_b128 v[28:31], v142 offset:13056
	ds_read_b128 v[32:35], v142 offset:21248
	ds_read_b128 v[36:39], v142 offset:29440
	ds_read_b128 v[40:43], v142 offset:37632
	s_waitcnt lgkmcnt(10)
	v_mul_f32_e32 v174, v170, v48
	v_mul_f32_e32 v238, v170, v60
	v_fmac_f32_e32 v174, v171, v49
	v_fmac_f32_e32 v238, v171, v61
	v_fmac_f32_e32 v174, v172, v50
	v_fmac_f32_e32 v238, v172, v62
	v_fmac_f32_e32 v174, v173, v51
	v_fmac_f32_e32 v238, v173, v63
	v_fmac_f32_e32 v170, v241, v56
	v_add_f32_dpp v174, v174, v174 quad_perm:[1,0,3,2] row_mask:0xf bank_mask:0xf bound_ctrl:1
	v_add_f32_dpp v238, v238, v238 quad_perm:[1,0,3,2] row_mask:0xf bank_mask:0xf bound_ctrl:1
	v_fmac_f32_e32 v171, v241, v57
	v_add_f32_dpp v174, v174, v174 quad_perm:[2,3,0,1] row_mask:0xf bank_mask:0xf bound_ctrl:1
	v_add_f32_dpp v238, v238, v238 quad_perm:[2,3,0,1] row_mask:0xf bank_mask:0xf bound_ctrl:1
	v_fmac_f32_e32 v172, v241, v58
	v_add_f32_dpp v174, v174, v174 row_half_mirror row_mask:0xf bank_mask:0xf bound_ctrl:1
	v_add_f32_dpp v238, v238, v238 row_half_mirror row_mask:0xf bank_mask:0xf bound_ctrl:1
	v_fmac_f32_e32 v173, v241, v59
	v_add_f32_dpp v174, v174, v174 row_mirror row_mask:0xf bank_mask:0xf bound_ctrl:1
	v_fmac_f32_e32 v170, v174, v52
	v_fmac_f32_e32 v171, v174, v53
	v_fmac_f32_e32 v172, v174, v54
	v_fmac_f32_e32 v173, v174, v55
	s_mov_b64 exec, s[6:7]
	ds_write2st64_b32 v149, v175, v238 offset0:32 offset1:34
	s_mov_b64 exec, -1
	ds_read_b128 v[48:51], v142 offset:13312
	ds_read_b128 v[52:55], v142 offset:21504
	ds_read_b128 v[56:59], v142 offset:29696
	ds_read_b128 v[60:63], v142 offset:37888
	ds_read2st64_b32 v[240:241], v148 offset0:212 offset1:213
	s_waitcnt lgkmcnt(10)
	v_mul_f32_e32 v174, v170, v8
	v_mul_f32_e32 v175, v170, v20
	v_fmac_f32_e32 v174, v171, v9
	v_fmac_f32_e32 v175, v171, v21
	v_fmac_f32_e32 v174, v172, v10
	v_fmac_f32_e32 v175, v172, v22
	v_fmac_f32_e32 v174, v173, v11
	v_fmac_f32_e32 v175, v173, v23
	v_fmac_f32_e32 v170, v242, v16
	v_add_f32_dpp v174, v174, v174 quad_perm:[1,0,3,2] row_mask:0xf bank_mask:0xf bound_ctrl:1
	v_add_f32_dpp v175, v175, v175 quad_perm:[1,0,3,2] row_mask:0xf bank_mask:0xf bound_ctrl:1
	v_fmac_f32_e32 v171, v242, v17
	v_add_f32_dpp v174, v174, v174 quad_perm:[2,3,0,1] row_mask:0xf bank_mask:0xf bound_ctrl:1
	v_add_f32_dpp v175, v175, v175 quad_perm:[2,3,0,1] row_mask:0xf bank_mask:0xf bound_ctrl:1
	v_fmac_f32_e32 v172, v242, v18
	v_add_f32_dpp v174, v174, v174 row_half_mirror row_mask:0xf bank_mask:0xf bound_ctrl:1
	v_add_f32_dpp v175, v175, v175 row_half_mirror row_mask:0xf bank_mask:0xf bound_ctrl:1
	v_fmac_f32_e32 v173, v242, v19
	v_add_f32_dpp v174, v174, v174 row_mirror row_mask:0xf bank_mask:0xf bound_ctrl:1
	v_fmac_f32_e32 v170, v174, v12
	v_fmac_f32_e32 v171, v174, v13
	v_fmac_f32_e32 v172, v174, v14
	v_fmac_f32_e32 v173, v174, v15
	ds_read_b128 v[8:11], v142 offset:13568
	ds_read_b128 v[12:15], v142 offset:21760
	ds_read_b128 v[16:19], v142 offset:29952
	ds_read_b128 v[20:23], v142 offset:38144
	s_waitcnt lgkmcnt(10)
	v_mul_f32_e32 v174, v170, v28
	v_mul_f32_e32 v238, v170, v40
	v_fmac_f32_e32 v174, v171, v29
	v_fmac_f32_e32 v238, v171, v41
	v_fmac_f32_e32 v174, v172, v30
	v_fmac_f32_e32 v238, v172, v42
	v_fmac_f32_e32 v174, v173, v31
	v_fmac_f32_e32 v238, v173, v43
	v_fmac_f32_e32 v170, v243, v36
	v_add_f32_dpp v174, v174, v174 quad_perm:[1,0,3,2] row_mask:0xf bank_mask:0xf bound_ctrl:1
	v_add_f32_dpp v238, v238, v238 quad_perm:[1,0,3,2] row_mask:0xf bank_mask:0xf bound_ctrl:1
	v_fmac_f32_e32 v171, v243, v37
	v_add_f32_dpp v174, v174, v174 quad_perm:[2,3,0,1] row_mask:0xf bank_mask:0xf bound_ctrl:1
	v_add_f32_dpp v238, v238, v238 quad_perm:[2,3,0,1] row_mask:0xf bank_mask:0xf bound_ctrl:1
	v_fmac_f32_e32 v172, v243, v38
	v_add_f32_dpp v174, v174, v174 row_half_mirror row_mask:0xf bank_mask:0xf bound_ctrl:1
	v_add_f32_dpp v238, v238, v238 row_half_mirror row_mask:0xf bank_mask:0xf bound_ctrl:1
	v_fmac_f32_e32 v173, v243, v39
	v_add_f32_dpp v174, v174, v174 row_mirror row_mask:0xf bank_mask:0xf bound_ctrl:1
	v_fmac_f32_e32 v170, v174, v32
	v_fmac_f32_e32 v171, v174, v33
	v_fmac_f32_e32 v172, v174, v34
	v_fmac_f32_e32 v173, v174, v35
	s_mov_b64 exec, s[6:7]
	ds_write2st64_b32 v149, v175, v238 offset0:36 offset1:38
	s_mov_b64 exec, -1
	ds_read_b128 v[28:31], v142 offset:13824
	ds_read_b128 v[32:35], v142 offset:22016
	ds_read_b128 v[36:39], v142 offset:30208
	ds_read_b128 v[40:43], v142 offset:38400
	ds_read2st64_b32 v[242:243], v148 offset0:214 offset1:215
	s_waitcnt lgkmcnt(10)
	v_mul_f32_e32 v174, v170, v48
	v_mul_f32_e32 v175, v170, v60
	v_fmac_f32_e32 v174, v171, v49
	v_fmac_f32_e32 v175, v171, v61
	v_fmac_f32_e32 v174, v172, v50
	v_fmac_f32_e32 v175, v172, v62
	v_fmac_f32_e32 v174, v173, v51
	v_fmac_f32_e32 v175, v173, v63
	v_fmac_f32_e32 v170, v240, v56
	v_add_f32_dpp v174, v174, v174 quad_perm:[1,0,3,2] row_mask:0xf bank_mask:0xf bound_ctrl:1
	v_add_f32_dpp v175, v175, v175 quad_perm:[1,0,3,2] row_mask:0xf bank_mask:0xf bound_ctrl:1
	v_fmac_f32_e32 v171, v240, v57
	v_add_f32_dpp v174, v174, v174 quad_perm:[2,3,0,1] row_mask:0xf bank_mask:0xf bound_ctrl:1
	v_add_f32_dpp v175, v175, v175 quad_perm:[2,3,0,1] row_mask:0xf bank_mask:0xf bound_ctrl:1
	v_fmac_f32_e32 v172, v240, v58
	v_add_f32_dpp v174, v174, v174 row_half_mirror row_mask:0xf bank_mask:0xf bound_ctrl:1
	v_add_f32_dpp v175, v175, v175 row_half_mirror row_mask:0xf bank_mask:0xf bound_ctrl:1
	v_fmac_f32_e32 v173, v240, v59
	v_add_f32_dpp v174, v174, v174 row_mirror row_mask:0xf bank_mask:0xf bound_ctrl:1
	v_fmac_f32_e32 v170, v174, v52
	v_fmac_f32_e32 v171, v174, v53
	v_fmac_f32_e32 v172, v174, v54
	v_fmac_f32_e32 v173, v174, v55
	ds_read_b128 v[48:51], v142 offset:14080
	ds_read_b128 v[52:55], v142 offset:22272
	ds_read_b128 v[56:59], v142 offset:30464
	ds_read_b128 v[60:63], v142 offset:38656
	s_waitcnt lgkmcnt(10)
	v_mul_f32_e32 v174, v170, v8
	v_mul_f32_e32 v238, v170, v20
	v_fmac_f32_e32 v174, v171, v9
	v_fmac_f32_e32 v238, v171, v21
	v_fmac_f32_e32 v174, v172, v10
	v_fmac_f32_e32 v238, v172, v22
	v_fmac_f32_e32 v174, v173, v11
	v_fmac_f32_e32 v238, v173, v23
	v_fmac_f32_e32 v170, v241, v16
	v_add_f32_dpp v174, v174, v174 quad_perm:[1,0,3,2] row_mask:0xf bank_mask:0xf bound_ctrl:1
	v_add_f32_dpp v238, v238, v238 quad_perm:[1,0,3,2] row_mask:0xf bank_mask:0xf bound_ctrl:1
	v_fmac_f32_e32 v171, v241, v17
	v_add_f32_dpp v174, v174, v174 quad_perm:[2,3,0,1] row_mask:0xf bank_mask:0xf bound_ctrl:1
	v_add_f32_dpp v238, v238, v238 quad_perm:[2,3,0,1] row_mask:0xf bank_mask:0xf bound_ctrl:1
	v_fmac_f32_e32 v172, v241, v18
	v_add_f32_dpp v174, v174, v174 row_half_mirror row_mask:0xf bank_mask:0xf bound_ctrl:1
	v_add_f32_dpp v238, v238, v238 row_half_mirror row_mask:0xf bank_mask:0xf bound_ctrl:1
	v_fmac_f32_e32 v173, v241, v19
	v_add_f32_dpp v174, v174, v174 row_mirror row_mask:0xf bank_mask:0xf bound_ctrl:1
	v_fmac_f32_e32 v170, v174, v12
	v_fmac_f32_e32 v171, v174, v13
	v_fmac_f32_e32 v172, v174, v14
	v_fmac_f32_e32 v173, v174, v15
	s_mov_b64 exec, s[6:7]
	ds_write2st64_b32 v149, v175, v238 offset0:40 offset1:42
	s_mov_b64 exec, -1
	ds_read_b128 v[8:11], v142 offset:14336
	ds_read_b128 v[12:15], v142 offset:22528
	ds_read_b128 v[16:19], v142 offset:30720
	ds_read_b128 v[20:23], v142 offset:38912
	ds_read2st64_b32 v[240:241], v148 offset0:216 offset1:217
	s_waitcnt lgkmcnt(10)
	v_mul_f32_e32 v174, v170, v28
	v_mul_f32_e32 v175, v170, v40
	v_fmac_f32_e32 v174, v171, v29
	v_fmac_f32_e32 v175, v171, v41
	v_fmac_f32_e32 v174, v172, v30
	v_fmac_f32_e32 v175, v172, v42
	v_fmac_f32_e32 v174, v173, v31
	v_fmac_f32_e32 v175, v173, v43
	v_fmac_f32_e32 v170, v242, v36
	v_add_f32_dpp v174, v174, v174 quad_perm:[1,0,3,2] row_mask:0xf bank_mask:0xf bound_ctrl:1
	v_add_f32_dpp v175, v175, v175 quad_perm:[1,0,3,2] row_mask:0xf bank_mask:0xf bound_ctrl:1
	v_fmac_f32_e32 v171, v242, v37
	v_add_f32_dpp v174, v174, v174 quad_perm:[2,3,0,1] row_mask:0xf bank_mask:0xf bound_ctrl:1
	v_add_f32_dpp v175, v175, v175 quad_perm:[2,3,0,1] row_mask:0xf bank_mask:0xf bound_ctrl:1
	v_fmac_f32_e32 v172, v242, v38
	v_add_f32_dpp v174, v174, v174 row_half_mirror row_mask:0xf bank_mask:0xf bound_ctrl:1
	v_add_f32_dpp v175, v175, v175 row_half_mirror row_mask:0xf bank_mask:0xf bound_ctrl:1
	v_fmac_f32_e32 v173, v242, v39
	v_add_f32_dpp v174, v174, v174 row_mirror row_mask:0xf bank_mask:0xf bound_ctrl:1
	v_fmac_f32_e32 v170, v174, v32
	v_fmac_f32_e32 v171, v174, v33
	v_fmac_f32_e32 v172, v174, v34
	v_fmac_f32_e32 v173, v174, v35
	ds_read_b128 v[28:31], v142 offset:14592
	ds_read_b128 v[32:35], v142 offset:22784
	ds_read_b128 v[36:39], v142 offset:30976
	ds_read_b128 v[40:43], v142 offset:39168
	s_waitcnt lgkmcnt(10)
	v_mul_f32_e32 v174, v170, v48
	v_mul_f32_e32 v238, v170, v60
	v_fmac_f32_e32 v174, v171, v49
	v_fmac_f32_e32 v238, v171, v61
	v_fmac_f32_e32 v174, v172, v50
	v_fmac_f32_e32 v238, v172, v62
	v_fmac_f32_e32 v174, v173, v51
	v_fmac_f32_e32 v238, v173, v63
	v_fmac_f32_e32 v170, v243, v56
	v_add_f32_dpp v174, v174, v174 quad_perm:[1,0,3,2] row_mask:0xf bank_mask:0xf bound_ctrl:1
	v_add_f32_dpp v238, v238, v238 quad_perm:[1,0,3,2] row_mask:0xf bank_mask:0xf bound_ctrl:1
	v_fmac_f32_e32 v171, v243, v57
	v_add_f32_dpp v174, v174, v174 quad_perm:[2,3,0,1] row_mask:0xf bank_mask:0xf bound_ctrl:1
	v_add_f32_dpp v238, v238, v238 quad_perm:[2,3,0,1] row_mask:0xf bank_mask:0xf bound_ctrl:1
	v_fmac_f32_e32 v172, v243, v58
	v_add_f32_dpp v174, v174, v174 row_half_mirror row_mask:0xf bank_mask:0xf bound_ctrl:1
	v_add_f32_dpp v238, v238, v238 row_half_mirror row_mask:0xf bank_mask:0xf bound_ctrl:1
	v_fmac_f32_e32 v173, v243, v59
	v_add_f32_dpp v174, v174, v174 row_mirror row_mask:0xf bank_mask:0xf bound_ctrl:1
	v_fmac_f32_e32 v170, v174, v52
	v_fmac_f32_e32 v171, v174, v53
	v_fmac_f32_e32 v172, v174, v54
	v_fmac_f32_e32 v173, v174, v55
	s_mov_b64 exec, s[6:7]
	ds_write2st64_b32 v149, v175, v238 offset0:44 offset1:46
	s_mov_b64 exec, -1
	ds_read_b128 v[48:51], v142 offset:14848
	ds_read_b128 v[52:55], v142 offset:23040
	ds_read_b128 v[56:59], v142 offset:31232
	ds_read_b128 v[60:63], v142 offset:39424
	ds_read2st64_b32 v[242:243], v148 offset0:218 offset1:219
	s_waitcnt lgkmcnt(10)
	v_mul_f32_e32 v174, v170, v8
	v_mul_f32_e32 v175, v170, v20
	v_fmac_f32_e32 v174, v171, v9
	v_fmac_f32_e32 v175, v171, v21
	v_fmac_f32_e32 v174, v172, v10
	v_fmac_f32_e32 v175, v172, v22
	v_fmac_f32_e32 v174, v173, v11
	v_fmac_f32_e32 v175, v173, v23
	v_fmac_f32_e32 v170, v240, v16
	v_add_f32_dpp v174, v174, v174 quad_perm:[1,0,3,2] row_mask:0xf bank_mask:0xf bound_ctrl:1
	v_add_f32_dpp v175, v175, v175 quad_perm:[1,0,3,2] row_mask:0xf bank_mask:0xf bound_ctrl:1
	v_fmac_f32_e32 v171, v240, v17
	v_add_f32_dpp v174, v174, v174 quad_perm:[2,3,0,1] row_mask:0xf bank_mask:0xf bound_ctrl:1
	v_add_f32_dpp v175, v175, v175 quad_perm:[2,3,0,1] row_mask:0xf bank_mask:0xf bound_ctrl:1
	v_fmac_f32_e32 v172, v240, v18
	v_add_f32_dpp v174, v174, v174 row_half_mirror row_mask:0xf bank_mask:0xf bound_ctrl:1
	v_add_f32_dpp v175, v175, v175 row_half_mirror row_mask:0xf bank_mask:0xf bound_ctrl:1
	v_fmac_f32_e32 v173, v240, v19
	v_add_f32_dpp v174, v174, v174 row_mirror row_mask:0xf bank_mask:0xf bound_ctrl:1
	v_fmac_f32_e32 v170, v174, v12
	v_fmac_f32_e32 v171, v174, v13
	v_fmac_f32_e32 v172, v174, v14
	v_fmac_f32_e32 v173, v174, v15
	ds_read_b128 v[8:11], v142 offset:15104
	ds_read_b128 v[12:15], v142 offset:23296
	ds_read_b128 v[16:19], v142 offset:31488
	ds_read_b128 v[20:23], v142 offset:39680
	s_waitcnt lgkmcnt(10)
	v_mul_f32_e32 v174, v170, v28
	v_mul_f32_e32 v238, v170, v40
	v_fmac_f32_e32 v174, v171, v29
	v_fmac_f32_e32 v238, v171, v41
	v_fmac_f32_e32 v174, v172, v30
	v_fmac_f32_e32 v238, v172, v42
	v_fmac_f32_e32 v174, v173, v31
	v_fmac_f32_e32 v238, v173, v43
	v_fmac_f32_e32 v170, v241, v36
	v_add_f32_dpp v174, v174, v174 quad_perm:[1,0,3,2] row_mask:0xf bank_mask:0xf bound_ctrl:1
	v_add_f32_dpp v238, v238, v238 quad_perm:[1,0,3,2] row_mask:0xf bank_mask:0xf bound_ctrl:1
	v_fmac_f32_e32 v171, v241, v37
	v_add_f32_dpp v174, v174, v174 quad_perm:[2,3,0,1] row_mask:0xf bank_mask:0xf bound_ctrl:1
	v_add_f32_dpp v238, v238, v238 quad_perm:[2,3,0,1] row_mask:0xf bank_mask:0xf bound_ctrl:1
	v_fmac_f32_e32 v172, v241, v38
	v_add_f32_dpp v174, v174, v174 row_half_mirror row_mask:0xf bank_mask:0xf bound_ctrl:1
	v_add_f32_dpp v238, v238, v238 row_half_mirror row_mask:0xf bank_mask:0xf bound_ctrl:1
	v_fmac_f32_e32 v173, v241, v39
	v_add_f32_dpp v174, v174, v174 row_mirror row_mask:0xf bank_mask:0xf bound_ctrl:1
	v_fmac_f32_e32 v170, v174, v32
	v_fmac_f32_e32 v171, v174, v33
	v_fmac_f32_e32 v172, v174, v34
	v_fmac_f32_e32 v173, v174, v35
	s_mov_b64 exec, s[6:7]
	ds_write2st64_b32 v149, v175, v238 offset0:48 offset1:50
	s_mov_b64 exec, -1
	ds_read_b128 v[28:31], v142 offset:15360
	ds_read_b128 v[32:35], v142 offset:23552
	ds_read_b128 v[36:39], v142 offset:31744
	ds_read_b128 v[40:43], v142 offset:39936
	ds_read2st64_b32 v[240:241], v148 offset0:220 offset1:221
	s_waitcnt lgkmcnt(10)
	v_mul_f32_e32 v174, v170, v48
	v_mul_f32_e32 v175, v170, v60
	v_fmac_f32_e32 v174, v171, v49
	v_fmac_f32_e32 v175, v171, v61
	v_fmac_f32_e32 v174, v172, v50
	v_fmac_f32_e32 v175, v172, v62
	v_fmac_f32_e32 v174, v173, v51
	v_fmac_f32_e32 v175, v173, v63
	v_fmac_f32_e32 v170, v242, v56
	v_add_f32_dpp v174, v174, v174 quad_perm:[1,0,3,2] row_mask:0xf bank_mask:0xf bound_ctrl:1
	v_add_f32_dpp v175, v175, v175 quad_perm:[1,0,3,2] row_mask:0xf bank_mask:0xf bound_ctrl:1
	v_fmac_f32_e32 v171, v242, v57
	v_add_f32_dpp v174, v174, v174 quad_perm:[2,3,0,1] row_mask:0xf bank_mask:0xf bound_ctrl:1
	v_add_f32_dpp v175, v175, v175 quad_perm:[2,3,0,1] row_mask:0xf bank_mask:0xf bound_ctrl:1
	v_fmac_f32_e32 v172, v242, v58
	v_add_f32_dpp v174, v174, v174 row_half_mirror row_mask:0xf bank_mask:0xf bound_ctrl:1
	v_add_f32_dpp v175, v175, v175 row_half_mirror row_mask:0xf bank_mask:0xf bound_ctrl:1
	v_fmac_f32_e32 v173, v242, v59
	v_add_f32_dpp v174, v174, v174 row_mirror row_mask:0xf bank_mask:0xf bound_ctrl:1
	v_fmac_f32_e32 v170, v174, v52
	v_fmac_f32_e32 v171, v174, v53
	v_fmac_f32_e32 v172, v174, v54
	v_fmac_f32_e32 v173, v174, v55
	ds_read_b128 v[48:51], v142 offset:15616
	ds_read_b128 v[52:55], v142 offset:23808
	ds_read_b128 v[56:59], v142 offset:32000
	ds_read_b128 v[60:63], v142 offset:40192
	s_waitcnt lgkmcnt(10)
	v_mul_f32_e32 v174, v170, v8
	v_mul_f32_e32 v238, v170, v20
	v_fmac_f32_e32 v174, v171, v9
	v_fmac_f32_e32 v238, v171, v21
	v_fmac_f32_e32 v174, v172, v10
	v_fmac_f32_e32 v238, v172, v22
	v_fmac_f32_e32 v174, v173, v11
	v_fmac_f32_e32 v238, v173, v23
	v_fmac_f32_e32 v170, v243, v16
	v_add_f32_dpp v174, v174, v174 quad_perm:[1,0,3,2] row_mask:0xf bank_mask:0xf bound_ctrl:1
	v_add_f32_dpp v238, v238, v238 quad_perm:[1,0,3,2] row_mask:0xf bank_mask:0xf bound_ctrl:1
	v_fmac_f32_e32 v171, v243, v17
	v_add_f32_dpp v174, v174, v174 quad_perm:[2,3,0,1] row_mask:0xf bank_mask:0xf bound_ctrl:1
	v_add_f32_dpp v238, v238, v238 quad_perm:[2,3,0,1] row_mask:0xf bank_mask:0xf bound_ctrl:1
	v_fmac_f32_e32 v172, v243, v18
	v_add_f32_dpp v174, v174, v174 row_half_mirror row_mask:0xf bank_mask:0xf bound_ctrl:1
	v_add_f32_dpp v238, v238, v238 row_half_mirror row_mask:0xf bank_mask:0xf bound_ctrl:1
	v_fmac_f32_e32 v173, v243, v19
	v_add_f32_dpp v174, v174, v174 row_mirror row_mask:0xf bank_mask:0xf bound_ctrl:1
	v_fmac_f32_e32 v170, v174, v12
	v_fmac_f32_e32 v171, v174, v13
	v_fmac_f32_e32 v172, v174, v14
	v_fmac_f32_e32 v173, v174, v15
	s_mov_b64 exec, s[6:7]
	ds_write2st64_b32 v149, v175, v238 offset0:52 offset1:54
	s_mov_b64 exec, -1
	ds_read_b128 v[8:11], v142 offset:15872
	ds_read_b128 v[12:15], v142 offset:24064
	ds_read_b128 v[16:19], v142 offset:32256
	ds_read_b128 v[20:23], v142 offset:40448
	ds_read2st64_b32 v[242:243], v148 offset0:222 offset1:223
	s_waitcnt lgkmcnt(10)
	v_mul_f32_e32 v174, v170, v28
	v_mul_f32_e32 v175, v170, v40
	v_fmac_f32_e32 v174, v171, v29
	v_fmac_f32_e32 v175, v171, v41
	v_fmac_f32_e32 v174, v172, v30
	v_fmac_f32_e32 v175, v172, v42
	v_fmac_f32_e32 v174, v173, v31
	v_fmac_f32_e32 v175, v173, v43
	v_fmac_f32_e32 v170, v240, v36
	v_add_f32_dpp v174, v174, v174 quad_perm:[1,0,3,2] row_mask:0xf bank_mask:0xf bound_ctrl:1
	v_add_f32_dpp v175, v175, v175 quad_perm:[1,0,3,2] row_mask:0xf bank_mask:0xf bound_ctrl:1
	v_fmac_f32_e32 v171, v240, v37
	v_add_f32_dpp v174, v174, v174 quad_perm:[2,3,0,1] row_mask:0xf bank_mask:0xf bound_ctrl:1
	v_add_f32_dpp v175, v175, v175 quad_perm:[2,3,0,1] row_mask:0xf bank_mask:0xf bound_ctrl:1
	v_fmac_f32_e32 v172, v240, v38
	v_add_f32_dpp v174, v174, v174 row_half_mirror row_mask:0xf bank_mask:0xf bound_ctrl:1
	v_add_f32_dpp v175, v175, v175 row_half_mirror row_mask:0xf bank_mask:0xf bound_ctrl:1
	v_fmac_f32_e32 v173, v240, v39
	v_add_f32_dpp v174, v174, v174 row_mirror row_mask:0xf bank_mask:0xf bound_ctrl:1
	v_fmac_f32_e32 v170, v174, v32
	v_fmac_f32_e32 v171, v174, v33
	v_fmac_f32_e32 v172, v174, v34
	v_fmac_f32_e32 v173, v174, v35
	ds_read_b128 v[28:31], v142 offset:16128
	ds_read_b128 v[32:35], v142 offset:24320
	ds_read_b128 v[36:39], v142 offset:32512
	ds_read_b128 v[40:43], v142 offset:40704
	s_waitcnt lgkmcnt(10)
	v_mul_f32_e32 v174, v170, v48
	v_mul_f32_e32 v238, v170, v60
	v_fmac_f32_e32 v174, v171, v49
	v_fmac_f32_e32 v238, v171, v61
	v_fmac_f32_e32 v174, v172, v50
	v_fmac_f32_e32 v238, v172, v62
	v_fmac_f32_e32 v174, v173, v51
	v_fmac_f32_e32 v238, v173, v63
	v_fmac_f32_e32 v170, v241, v56
	v_add_f32_dpp v174, v174, v174 quad_perm:[1,0,3,2] row_mask:0xf bank_mask:0xf bound_ctrl:1
	v_add_f32_dpp v238, v238, v238 quad_perm:[1,0,3,2] row_mask:0xf bank_mask:0xf bound_ctrl:1
	v_fmac_f32_e32 v171, v241, v57
	v_add_f32_dpp v174, v174, v174 quad_perm:[2,3,0,1] row_mask:0xf bank_mask:0xf bound_ctrl:1
	v_add_f32_dpp v238, v238, v238 quad_perm:[2,3,0,1] row_mask:0xf bank_mask:0xf bound_ctrl:1
	v_fmac_f32_e32 v172, v241, v58
	v_add_f32_dpp v174, v174, v174 row_half_mirror row_mask:0xf bank_mask:0xf bound_ctrl:1
	v_add_f32_dpp v238, v238, v238 row_half_mirror row_mask:0xf bank_mask:0xf bound_ctrl:1
	v_fmac_f32_e32 v173, v241, v59
	v_add_f32_dpp v174, v174, v174 row_mirror row_mask:0xf bank_mask:0xf bound_ctrl:1
	v_fmac_f32_e32 v170, v174, v52
	v_fmac_f32_e32 v171, v174, v53
	v_fmac_f32_e32 v172, v174, v54
	v_fmac_f32_e32 v173, v174, v55
	s_mov_b64 exec, s[6:7]
	ds_write2st64_b32 v149, v175, v238 offset0:56 offset1:58
	s_mov_b64 exec, -1
	s_waitcnt lgkmcnt(5)
	v_mul_f32_e32 v174, v170, v8
	v_mul_f32_e32 v175, v170, v20
	v_fmac_f32_e32 v174, v171, v9
	v_fmac_f32_e32 v175, v171, v21
	v_fmac_f32_e32 v174, v172, v10
	v_fmac_f32_e32 v175, v172, v22
	v_fmac_f32_e32 v174, v173, v11
	v_fmac_f32_e32 v175, v173, v23
	v_fmac_f32_e32 v170, v242, v16
	v_add_f32_dpp v174, v174, v174 quad_perm:[1,0,3,2] row_mask:0xf bank_mask:0xf bound_ctrl:1
	v_add_f32_dpp v175, v175, v175 quad_perm:[1,0,3,2] row_mask:0xf bank_mask:0xf bound_ctrl:1
	v_fmac_f32_e32 v171, v242, v17
	v_add_f32_dpp v174, v174, v174 quad_perm:[2,3,0,1] row_mask:0xf bank_mask:0xf bound_ctrl:1
	v_add_f32_dpp v175, v175, v175 quad_perm:[2,3,0,1] row_mask:0xf bank_mask:0xf bound_ctrl:1
	v_fmac_f32_e32 v172, v242, v18
	v_add_f32_dpp v174, v174, v174 row_half_mirror row_mask:0xf bank_mask:0xf bound_ctrl:1
	v_add_f32_dpp v175, v175, v175 row_half_mirror row_mask:0xf bank_mask:0xf bound_ctrl:1
	v_fmac_f32_e32 v173, v242, v19
	v_add_f32_dpp v174, v174, v174 row_mirror row_mask:0xf bank_mask:0xf bound_ctrl:1
	v_fmac_f32_e32 v170, v174, v12
	v_fmac_f32_e32 v171, v174, v13
	v_fmac_f32_e32 v172, v174, v14
	v_fmac_f32_e32 v173, v174, v15
	s_waitcnt lgkmcnt(1)
	v_mul_f32_e32 v174, v170, v28
	v_mul_f32_e32 v238, v170, v40
	v_fmac_f32_e32 v174, v171, v29
	v_fmac_f32_e32 v238, v171, v41
	v_fmac_f32_e32 v174, v172, v30
	v_fmac_f32_e32 v238, v172, v42
	v_fmac_f32_e32 v174, v173, v31
	v_fmac_f32_e32 v238, v173, v43
	v_fmac_f32_e32 v170, v243, v36
	v_add_f32_dpp v174, v174, v174 quad_perm:[1,0,3,2] row_mask:0xf bank_mask:0xf bound_ctrl:1
	v_add_f32_dpp v238, v238, v238 quad_perm:[1,0,3,2] row_mask:0xf bank_mask:0xf bound_ctrl:1
	v_fmac_f32_e32 v171, v243, v37
	v_add_f32_dpp v174, v174, v174 quad_perm:[2,3,0,1] row_mask:0xf bank_mask:0xf bound_ctrl:1
	v_add_f32_dpp v238, v238, v238 quad_perm:[2,3,0,1] row_mask:0xf bank_mask:0xf bound_ctrl:1
	v_fmac_f32_e32 v172, v243, v38
	v_add_f32_dpp v174, v174, v174 row_half_mirror row_mask:0xf bank_mask:0xf bound_ctrl:1
	v_add_f32_dpp v238, v238, v238 row_half_mirror row_mask:0xf bank_mask:0xf bound_ctrl:1
	v_fmac_f32_e32 v173, v243, v39
	v_add_f32_dpp v174, v174, v174 row_mirror row_mask:0xf bank_mask:0xf bound_ctrl:1
	v_fmac_f32_e32 v170, v174, v32
	v_fmac_f32_e32 v171, v174, v33
	v_fmac_f32_e32 v172, v174, v34
	v_fmac_f32_e32 v173, v174, v35
	s_mov_b64 exec, s[6:7]
	ds_write2st64_b32 v149, v175, v238 offset0:60 offset1:62
	s_mov_b64 exec, -1
	ds_read_b128 v[4:7], v142 offset:65280
	s_waitcnt lgkmcnt(0)
	v_mul_f32_e32 v170, v170, v4
	v_mul_f32_e32 v171, v171, v5
	v_mul_f32_e32 v172, v172, v6
	v_mul_f32_e32 v173, v173, v7
	s_waitcnt lgkmcnt(0)
	s_barrier
	s_and_saveexec_b64 s[10:11], s[8:9]
	s_cbranch_execz .LBB0_349
	ds_read_b128 v[4:7], v150
	ds_read_b128 v[8:11], v150 offset:256
	s_waitcnt lgkmcnt(0)
	v_pk_add_f32 v[10:11], v[6:7], v[10:11]
	v_pk_add_f32 v[8:9], v[4:5], v[8:9]
	ds_read_b128 v[4:7], v147
	s_waitcnt lgkmcnt(0)
	v_pk_add_f32 v[6:7], v[10:11], v[6:7]
	v_pk_add_f32 v[4:5], v[8:9], v[4:5]
	s_nop 0
	v_cvt_pk_bf16_f32 v4, v4, v5
	v_cvt_pk_bf16_f32 v5, v6, v7
	v_lshlrev_b64 v[6:7], 11, v[120:121]
	v_lshl_add_u64 v[6:7], v[102:103], 0, v[6:7]
	global_store_dwordx2 v[6:7], v[4:5], off
	s_branch .LBB0_349

	.amdhsa_kernel _Z14fwd_megakernel6Params
		.amdhsa_group_segment_fixed_size 0
		.amdhsa_private_segment_fixed_size 0
		.amdhsa_kernarg_size 512
		.amdhsa_user_sgpr_count 2
		.amdhsa_user_sgpr_dispatch_ptr 0
		.amdhsa_user_sgpr_queue_ptr 0
		.amdhsa_user_sgpr_kernarg_segment_ptr 1
		.amdhsa_user_sgpr_dispatch_id 0
		.amdhsa_user_sgpr_kernarg_preload_length 0
		.amdhsa_user_sgpr_kernarg_preload_offset 0
		.amdhsa_user_sgpr_private_segment_size 0
		.amdhsa_uses_dynamic_stack 0
		.amdhsa_enable_private_segment 0
		.amdhsa_system_sgpr_workgroup_id_x 1
		.amdhsa_system_sgpr_workgroup_id_y 0
		.amdhsa_system_sgpr_workgroup_id_z 0
		.amdhsa_system_sgpr_workgroup_info 0
		.amdhsa_system_vgpr_workitem_id 2
		.amdhsa_next_free_vgpr 248
		.amdhsa_next_free_sgpr 98
		.amdhsa_accum_offset 248
		.amdhsa_reserve_vcc 1
		.amdhsa_float_round_mode_32 0
		.amdhsa_float_round_mode_16_64 0
		.amdhsa_float_denorm_mode_32 3
		.amdhsa_float_denorm_mode_16_64 3
		.amdhsa_dx10_clamp 1
		.amdhsa_ieee_mode 1
		.amdhsa_fp16_overflow 0
		.amdhsa_tg_split 0
		.amdhsa_exception_fp_ieee_invalid_op 0
		.amdhsa_exception_fp_denorm_src 0
		.amdhsa_exception_fp_ieee_div_zero 0
		.amdhsa_exception_fp_ieee_overflow 0
		.amdhsa_exception_fp_ieee_underflow 0
		.amdhsa_exception_fp_ieee_inexact 0
		.amdhsa_exception_int_div_zero 0
	.end_amdhsa_kernel

amdhsa.kernels:
  - .agpr_count:     0
    .args:
      - .offset:         0
        .size:           256
        .value_kind:     by_value
      - .offset:         256
        .size:           4
        .value_kind:     hidden_block_count_x
      - .offset:         260
        .size:           4
        .value_kind:     hidden_block_count_y
      - .offset:         264
        .size:           4
        .value_kind:     hidden_block_count_z
      - .offset:         268
        .size:           2
        .value_kind:     hidden_group_size_x
      - .offset:         270
        .size:           2
        .value_kind:     hidden_group_size_y
      - .offset:         272
        .size:           2
        .value_kind:     hidden_group_size_z
      - .offset:         274
        .size:           2
        .value_kind:     hidden_remainder_x
      - .offset:         276
        .size:           2
        .value_kind:     hidden_remainder_y
      - .offset:         278
        .size:           2
        .value_kind:     hidden_remainder_z
      - .offset:         296
        .size:           8
        .value_kind:     hidden_global_offset_x
      - .offset:         304
        .size:           8
        .value_kind:     hidden_global_offset_y
      - .offset:         312
        .size:           8
        .value_kind:     hidden_global_offset_z
      - .offset:         320
        .size:           2
        .value_kind:     hidden_grid_dims
      - .offset:         344
        .size:           8
        .value_kind:     hidden_multigrid_sync_arg
      - .offset:         376
        .size:           4
        .value_kind:     hidden_dynamic_lds_size
    .group_segment_fixed_size: 0
    .kernarg_segment_align: 8
    .kernarg_segment_size: 512
    .language:       OpenCL C
    .language_version:
      - 2
      - 0
    .max_flat_workgroup_size: 512
    .name:           _Z14fwd_megakernel6Params
    .private_segment_fixed_size: 0
    .sgpr_count:     104
    .sgpr_spill_count: 51
    .symbol:         _Z14fwd_megakernel6Params.kd
    .uniform_work_group_size: 1
    .uses_dynamic_stack: false
    .vgpr_count:     248
    .vgpr_spill_count: 0
    .wavefront_size: 64
